# recurrence loops unrolled x3 over the 3 rotating LDS chunk buffers: static ds offsets, no per-chunk address rotation
# baseline (speedup 1.0000x reference)
.Lret2_item:
	s_lshr_b32 s0, s23, 5
	s_and_b32 s1, s23, 31
	s_lshr_b32 s2, s0, 2
	s_and_b32 s3, s0, 3
	s_lshl_b32 s4, s1, 4
	v_lshl_add_u32 v46, v5, 2, s4
	s_and_b32 s4, s1, 3
	s_lshl_b32 s4, s4, 5
	s_add_u32 s4, s4, 128
	v_lshl_add_u32 v3, v5, 3, s4
	s_lshl_b32 s4, s3, 8
	s_add_u32 s4, s4, 1024
	v_lshl_add_u32 v32, v198, 2, s4
	s_add_u32 s4, s4, 4096
	v_lshl_add_u32 v33, v198, 2, s4
	s_lshl_b32 s4, s3, 9
	s_and_b32 s5, s1, 28
	s_lshl_b32 s5, s5, 4
	s_add_u32 s4, s4, s5
	s_add_u32 s4, s4, 2048
	v_min_u32_e32 v42, 31, v198
	v_lshl_add_u32 v34, v42, 2, s4
	v_cmp_lt_u32_e32 vcc, 15, v198
	v_add_u32_e32 v44, 4032, v34
	s_nop 1
	v_cndmask_b32_e32 v34, v34, v44, vcc
	v_readlane_b32 s5, v255, 15
	s_mul_i32 s4, s2, 0x1800000
	s_mul_i32 s1, s5, 0x3000
	s_add_u32 s4, s4, s1
	s_add_u32 s4, s4, 0x3bc0400
	s_add_u32 s10, s8, s4
	s_addc_u32 s11, s9, 0
	s_lshl_b32 s4, s2, 22
	s_lshl_b32 s1, s5, 11
	s_add_u32 s4, s4, s1
	s_lshl_b32 s1, s3, 9
	s_add_u32 s4, s4, s1
	s_add_u32 s4, s4, 0xfd40400
	s_add_u32 s12, s8, s4
	s_addc_u32 s13, s9, 0
	s_lshl_b32 s4, s2, 23
	s_add_u32 s4, s4, s1
	s_add_u32 s4, s4, 333188096
	s_add_u32 s14, s8, s4
	s_addc_u32 s15, s9, 0
	s_lshr_b32 s4, 0x80000, s3
	s_sub_u32 s4, 0x3f800000, s4
	v_mov_b32_e32 v43, s4
	v_rcp_f32_e32 v42, v43
	v_mov_b32_e32 v40, 1.0
	v_mov_b32_e32 v41, 1.0
	s_movk_i32 s20, 256
	s_movk_i32 s21, 24832
	s_mov_b32 s22, 49408
	v_add_u32_e32 v26, s20, v29
	v_add_u32_e32 v27, s20, v30
	v_add_u32_e32 v28, s20, v31
	global_load_dword v84, v32, s[10:11]
	global_load_dword v85, v32, s[10:11] offset:-1024
	global_load_dword v86, v33, s[10:11]
	global_load_dword v87, v33, s[10:11] offset:-1024
	global_load_dword v88, v34, s[10:11]
	global_load_dword v90, v35, s[12:13]
	global_load_dword v91, v35, s[12:13] offset:4
	s_add_u32 s10, s10, 0x18000
	s_addc_u32 s11, s11, 0
	s_add_u32 s12, s12, 0x4000
	s_addc_u32 s13, s13, 0
	s_waitcnt vmcnt(0)
	v_lshlrev_b32_e32 v108, 16, v84
	v_lshlrev_b32_e32 v109, 16, v85
	v_and_b32_e32 v110, s17, v84
	v_and_b32_e32 v111, s17, v85
	v_lshlrev_b32_e32 v112, 16, v86
	v_lshlrev_b32_e32 v113, 16, v87
	v_and_b32_e32 v114, s17, v86
	v_and_b32_e32 v115, s17, v87
	v_lshlrev_b32_e32 v116, 16, v88
	v_and_b32_e32 v117, s17, v88
	ds_write_b128 v29, v[108:111] offset:256
	ds_write_b128 v29, v[112:115] offset:8448
	ds_write_b64 v30, v[90:91] offset:256
	ds_write_b64 v31, v[116:117] offset:256
	v_add_u32_e32 v26, s21, v29
	v_add_u32_e32 v27, s21, v30
	v_add_u32_e32 v28, s21, v31
	global_load_dword v84, v32, s[10:11]
	global_load_dword v85, v32, s[10:11] offset:-1024
	global_load_dword v86, v33, s[10:11]
	global_load_dword v87, v33, s[10:11] offset:-1024
	global_load_dword v88, v34, s[10:11]
	global_load_dword v90, v35, s[12:13]
	global_load_dword v91, v35, s[12:13] offset:4
	s_add_u32 s10, s10, 0x18000
	s_addc_u32 s11, s11, 0
	s_add_u32 s12, s12, 0x4000
	s_addc_u32 s13, s13, 0
	s_waitcnt vmcnt(0)
	v_lshlrev_b32_e32 v108, 16, v84
	v_lshlrev_b32_e32 v109, 16, v85
	v_and_b32_e32 v110, s17, v84
	v_and_b32_e32 v111, s17, v85
	v_lshlrev_b32_e32 v112, 16, v86
	v_lshlrev_b32_e32 v113, 16, v87
	v_and_b32_e32 v114, s17, v86
	v_and_b32_e32 v115, s17, v87
	v_lshlrev_b32_e32 v116, 16, v88
	v_and_b32_e32 v117, s17, v88
	ds_write_b128 v29, v[108:111] offset:24832
	ds_write_b128 v29, v[112:115] offset:33024
	ds_write_b64 v30, v[90:91] offset:24832
	ds_write_b64 v31, v[116:117] offset:24832
	v_add_u32_e32 v26, s22, v29
	v_add_u32_e32 v27, s22, v30
	v_add_u32_e32 v28, s22, v31
	v_add_u32_e32 v22, 0x8000, v2
	v_add_u32_e32 v23, 0x8000, v3
	v_mov_b32_e32 v6, 0
	v_mov_b32_e32 v7, 0
	v_mov_b32_e32 v8, 0
	v_mov_b32_e32 v9, 0
	v_mov_b32_e32 v10, 0
	v_mov_b32_e32 v11, 0
	v_mov_b32_e32 v12, 0
	v_mov_b32_e32 v13, 0
	v_mov_b32_e32 v14, 0
	v_mov_b32_e32 v15, 0
	v_mov_b32_e32 v16, 0
	v_mov_b32_e32 v17, 0
	v_mov_b32_e32 v18, 0
	v_mov_b32_e32 v19, 0
	v_mov_b32_e32 v20, 0
	v_mov_b32_e32 v21, 0
	s_mov_b32 s16, 0
	s_mov_b32 s2, 0x10001
	s_mov_b32 s3, 0x10001
	s_waitcnt vmcnt(0) lgkmcnt(0)
	s_barrier
	ds_read_b128 v[48:51], v2 offset:8448
	ds_read_b128 v[52:55], v2 offset:8704
	ds_read_b128 v[56:59], v2 offset:8960
	ds_read_b128 v[60:63], v2 offset:9216
	ds_read_b64 v[64:65], v3 offset:20736
.Lret2_loop:
	global_load_dword v84, v32, s[10:11]
	global_load_dword v85, v32, s[10:11] offset:-1024
	global_load_dword v86, v33, s[10:11]
	global_load_dword v87, v33, s[10:11] offset:-1024
	global_load_dword v88, v34, s[10:11]
	global_load_dword v90, v35, s[12:13]
	global_load_dword v91, v35, s[12:13] offset:4
	s_add_u32 s10, s10, 0x18000
	s_addc_u32 s11, s11, 0
	s_add_u32 s12, s12, 0x4000
	s_addc_u32 s13, s13, 0
	s_waitcnt lgkmcnt(0)
	v_pk_mul_f32 v[40:41], v[40:41], v[42:43]
	v_rcp_f32_e32 v40, v41
	s_nop 0
	v_pk_mul_f32 v[44:45], v[64:65], v[40:41] op_sel_hi:[1,0]
	v_pk_fma_f32 v[6:7], v[44:45], v[48:49], v[6:7] op_sel_hi:[1,0,1]
	v_pk_mul_f32 v[38:39], v[6:7], v[48:49] op_sel:[0,1] op_sel_hi:[1,1]
	v_pk_fma_f32 v[8:9], v[44:45], v[50:51], v[8:9] op_sel_hi:[1,0,1]
	v_pk_fma_f32 v[38:39], v[8:9], v[50:51], v[38:39] op_sel:[0,1,0] op_sel_hi:[1,1,1]
	v_pk_fma_f32 v[10:11], v[44:45], v[52:53], v[10:11] op_sel_hi:[1,0,1]
	v_pk_fma_f32 v[38:39], v[10:11], v[52:53], v[38:39] op_sel:[0,1,0] op_sel_hi:[1,1,1]
	v_pk_fma_f32 v[12:13], v[44:45], v[54:55], v[12:13] op_sel_hi:[1,0,1]
	v_pk_fma_f32 v[38:39], v[12:13], v[54:55], v[38:39] op_sel:[0,1,0] op_sel_hi:[1,1,1]
	v_pk_fma_f32 v[14:15], v[44:45], v[56:57], v[14:15] op_sel_hi:[1,0,1]
	v_pk_fma_f32 v[38:39], v[14:15], v[56:57], v[38:39] op_sel:[0,1,0] op_sel_hi:[1,1,1]
	v_pk_fma_f32 v[16:17], v[44:45], v[58:59], v[16:17] op_sel_hi:[1,0,1]
	v_pk_fma_f32 v[38:39], v[16:17], v[58:59], v[38:39] op_sel:[0,1,0] op_sel_hi:[1,1,1]
	v_pk_fma_f32 v[18:19], v[44:45], v[60:61], v[18:19] op_sel_hi:[1,0,1]
	v_pk_fma_f32 v[38:39], v[18:19], v[60:61], v[38:39] op_sel:[0,1,0] op_sel_hi:[1,1,1]
	v_pk_fma_f32 v[20:21], v[44:45], v[62:63], v[20:21] op_sel_hi:[1,0,1]
	v_pk_fma_f32 v[38:39], v[20:21], v[62:63], v[38:39] op_sel:[0,1,0] op_sel_hi:[1,1,1]
	s_add_u32 s14, s14, 0x1000
	s_addc_u32 s15, s15, 0
	v_add_f32_dpp v38, v38, v38 row_ror:8 row_mask:0xf bank_mask:0x3 bound_ctrl:1
	v_add_f32_dpp v38, v39, v39 row_ror:8 row_mask:0xf bank_mask:0xc bound_ctrl:1
	ds_read_b128 v[66:69], v2 offset:9472
	ds_read_b128 v[70:73], v2 offset:9728
	v_add_f32_dpp v38, v38, v38 row_half_mirror row_mask:0xf bank_mask:0xf bound_ctrl:1
	ds_read_b128 v[74:77], v2 offset:9984
	ds_read_b128 v[78:81], v2 offset:10240
	v_add_f32_dpp v38, v38, v38 quad_perm:[1,0,3,2] row_mask:0xf bank_mask:0xf bound_ctrl:1
	ds_read_b64 v[82:83], v3 offset:20992
	s_nop 0
	v_add_f32_dpp v38, v38, v38 quad_perm:[2,3,0,1] row_mask:0xf bank_mask:0xf bound_ctrl:1
	s_nop 1
	v_mov_b32_dpp v39, v38 row_ror:8 row_mask:0xf bank_mask:0xf bound_ctrl:1
	v_pk_mul_f32 v[38:39], v[38:39], v[40:41] op_sel:[0,1] op_sel_hi:[1,1]
	v_cvt_pk_bf16_f32 v47, v38, v39
	s_mov_b64 exec, s[2:3]
	global_store_dword v46, v47, s[14:15] offset:-4096
	s_mov_b64 exec, -1
	s_waitcnt lgkmcnt(0)
	v_pk_mul_f32 v[40:41], v[40:41], v[42:43]
	v_pk_mul_f32 v[44:45], v[82:83], v[40:41] op_sel_hi:[1,0]
	v_pk_fma_f32 v[6:7], v[44:45], v[66:67], v[6:7] op_sel_hi:[1,0,1]
	v_pk_mul_f32 v[38:39], v[6:7], v[66:67] op_sel:[0,1] op_sel_hi:[1,1]
	v_pk_fma_f32 v[8:9], v[44:45], v[68:69], v[8:9] op_sel_hi:[1,0,1]
	v_pk_fma_f32 v[38:39], v[8:9], v[68:69], v[38:39] op_sel:[0,1,0] op_sel_hi:[1,1,1]
	v_pk_fma_f32 v[10:11], v[44:45], v[70:71], v[10:11] op_sel_hi:[1,0,1]
	v_pk_fma_f32 v[38:39], v[10:11], v[70:71], v[38:39] op_sel:[0,1,0] op_sel_hi:[1,1,1]
	v_pk_fma_f32 v[12:13], v[44:45], v[72:73], v[12:13] op_sel_hi:[1,0,1]
	v_pk_fma_f32 v[38:39], v[12:13], v[72:73], v[38:39] op_sel:[0,1,0] op_sel_hi:[1,1,1]
	v_pk_fma_f32 v[14:15], v[44:45], v[74:75], v[14:15] op_sel_hi:[1,0,1]
	v_pk_fma_f32 v[38:39], v[14:15], v[74:75], v[38:39] op_sel:[0,1,0] op_sel_hi:[1,1,1]
	v_pk_fma_f32 v[16:17], v[44:45], v[76:77], v[16:17] op_sel_hi:[1,0,1]
	v_pk_fma_f32 v[38:39], v[16:17], v[76:77], v[38:39] op_sel:[0,1,0] op_sel_hi:[1,1,1]
	v_pk_fma_f32 v[18:19], v[44:45], v[78:79], v[18:19] op_sel_hi:[1,0,1]
	v_pk_fma_f32 v[38:39], v[18:19], v[78:79], v[38:39] op_sel:[0,1,0] op_sel_hi:[1,1,1]
	v_pk_fma_f32 v[20:21], v[44:45], v[80:81], v[20:21] op_sel_hi:[1,0,1]
	v_pk_fma_f32 v[38:39], v[20:21], v[80:81], v[38:39] op_sel:[0,1,0] op_sel_hi:[1,1,1]
	s_add_u32 s14, s14, 0x1000
	s_addc_u32 s15, s15, 0
	v_add_f32_dpp v38, v38, v38 row_ror:8 row_mask:0xf bank_mask:0x3 bound_ctrl:1
	v_add_f32_dpp v38, v39, v39 row_ror:8 row_mask:0xf bank_mask:0xc bound_ctrl:1
	ds_read_b128 v[48:51], v2 offset:10496
	ds_read_b128 v[52:55], v2 offset:10752
	v_add_f32_dpp v38, v38, v38 row_half_mirror row_mask:0xf bank_mask:0xf bound_ctrl:1
	ds_read_b128 v[56:59], v2 offset:11008
	ds_read_b128 v[60:63], v2 offset:11264
	v_add_f32_dpp v38, v38, v38 quad_perm:[1,0,3,2] row_mask:0xf bank_mask:0xf bound_ctrl:1
	ds_read_b64 v[64:65], v3 offset:21248
	s_nop 0
	v_add_f32_dpp v38, v38, v38 quad_perm:[2,3,0,1] row_mask:0xf bank_mask:0xf bound_ctrl:1
	s_nop 1
	v_mov_b32_dpp v39, v38 row_ror:8 row_mask:0xf bank_mask:0xf bound_ctrl:1
	v_pk_mul_f32 v[38:39], v[38:39], v[40:41] op_sel:[0,1] op_sel_hi:[1,1]
	v_cvt_pk_bf16_f32 v47, v38, v39
	s_mov_b64 exec, s[2:3]
	global_store_dword v46, v47, s[14:15] offset:-4096
	s_mov_b64 exec, -1
	s_waitcnt lgkmcnt(0)
	v_pk_mul_f32 v[40:41], v[40:41], v[42:43]
	v_pk_mul_f32 v[44:45], v[64:65], v[40:41] op_sel_hi:[1,0]
	v_pk_fma_f32 v[6:7], v[44:45], v[48:49], v[6:7] op_sel_hi:[1,0,1]
	v_pk_mul_f32 v[38:39], v[6:7], v[48:49] op_sel:[0,1] op_sel_hi:[1,1]
	v_pk_fma_f32 v[8:9], v[44:45], v[50:51], v[8:9] op_sel_hi:[1,0,1]
	v_pk_fma_f32 v[38:39], v[8:9], v[50:51], v[38:39] op_sel:[0,1,0] op_sel_hi:[1,1,1]
	v_pk_fma_f32 v[10:11], v[44:45], v[52:53], v[10:11] op_sel_hi:[1,0,1]
	v_pk_fma_f32 v[38:39], v[10:11], v[52:53], v[38:39] op_sel:[0,1,0] op_sel_hi:[1,1,1]
	v_pk_fma_f32 v[12:13], v[44:45], v[54:55], v[12:13] op_sel_hi:[1,0,1]
	v_pk_fma_f32 v[38:39], v[12:13], v[54:55], v[38:39] op_sel:[0,1,0] op_sel_hi:[1,1,1]
	v_pk_fma_f32 v[14:15], v[44:45], v[56:57], v[14:15] op_sel_hi:[1,0,1]
	v_pk_fma_f32 v[38:39], v[14:15], v[56:57], v[38:39] op_sel:[0,1,0] op_sel_hi:[1,1,1]
	v_pk_fma_f32 v[16:17], v[44:45], v[58:59], v[16:17] op_sel_hi:[1,0,1]
	v_pk_fma_f32 v[38:39], v[16:17], v[58:59], v[38:39] op_sel:[0,1,0] op_sel_hi:[1,1,1]
	v_pk_fma_f32 v[18:19], v[44:45], v[60:61], v[18:19] op_sel_hi:[1,0,1]
	v_pk_fma_f32 v[38:39], v[18:19], v[60:61], v[38:39] op_sel:[0,1,0] op_sel_hi:[1,1,1]
	v_pk_fma_f32 v[20:21], v[44:45], v[62:63], v[20:21] op_sel_hi:[1,0,1]
	v_pk_fma_f32 v[38:39], v[20:21], v[62:63], v[38:39] op_sel:[0,1,0] op_sel_hi:[1,1,1]
	s_add_u32 s14, s14, 0x1000
	s_addc_u32 s15, s15, 0
	v_add_f32_dpp v38, v38, v38 row_ror:8 row_mask:0xf bank_mask:0x3 bound_ctrl:1
	v_add_f32_dpp v38, v39, v39 row_ror:8 row_mask:0xf bank_mask:0xc bound_ctrl:1
	ds_read_b128 v[66:69], v2 offset:11520
	ds_read_b128 v[70:73], v2 offset:11776
	v_add_f32_dpp v38, v38, v38 row_half_mirror row_mask:0xf bank_mask:0xf bound_ctrl:1
	ds_read_b128 v[74:77], v2 offset:12032
	ds_read_b128 v[78:81], v2 offset:12288
	v_add_f32_dpp v38, v38, v38 quad_perm:[1,0,3,2] row_mask:0xf bank_mask:0xf bound_ctrl:1
	ds_read_b64 v[82:83], v3 offset:21504
	s_nop 0
	v_add_f32_dpp v38, v38, v38 quad_perm:[2,3,0,1] row_mask:0xf bank_mask:0xf bound_ctrl:1
	s_nop 1
	v_mov_b32_dpp v39, v38 row_ror:8 row_mask:0xf bank_mask:0xf bound_ctrl:1
	v_pk_mul_f32 v[38:39], v[38:39], v[40:41] op_sel:[0,1] op_sel_hi:[1,1]
	v_cvt_pk_bf16_f32 v47, v38, v39
	s_mov_b64 exec, s[2:3]
	global_store_dword v46, v47, s[14:15] offset:-4096
	s_mov_b64 exec, -1
	s_waitcnt lgkmcnt(0)
	v_pk_mul_f32 v[40:41], v[40:41], v[42:43]
	v_pk_mul_f32 v[44:45], v[82:83], v[40:41] op_sel_hi:[1,0]
	v_pk_fma_f32 v[6:7], v[44:45], v[66:67], v[6:7] op_sel_hi:[1,0,1]
	v_pk_mul_f32 v[38:39], v[6:7], v[66:67] op_sel:[0,1] op_sel_hi:[1,1]
	v_pk_fma_f32 v[8:9], v[44:45], v[68:69], v[8:9] op_sel_hi:[1,0,1]
	v_pk_fma_f32 v[38:39], v[8:9], v[68:69], v[38:39] op_sel:[0,1,0] op_sel_hi:[1,1,1]
	v_pk_fma_f32 v[10:11], v[44:45], v[70:71], v[10:11] op_sel_hi:[1,0,1]
	v_pk_fma_f32 v[38:39], v[10:11], v[70:71], v[38:39] op_sel:[0,1,0] op_sel_hi:[1,1,1]
	v_pk_fma_f32 v[12:13], v[44:45], v[72:73], v[12:13] op_sel_hi:[1,0,1]
	v_pk_fma_f32 v[38:39], v[12:13], v[72:73], v[38:39] op_sel:[0,1,0] op_sel_hi:[1,1,1]
	v_pk_fma_f32 v[14:15], v[44:45], v[74:75], v[14:15] op_sel_hi:[1,0,1]
	v_pk_fma_f32 v[38:39], v[14:15], v[74:75], v[38:39] op_sel:[0,1,0] op_sel_hi:[1,1,1]
	v_pk_fma_f32 v[16:17], v[44:45], v[76:77], v[16:17] op_sel_hi:[1,0,1]
	v_pk_fma_f32 v[38:39], v[16:17], v[76:77], v[38:39] op_sel:[0,1,0] op_sel_hi:[1,1,1]
	v_pk_fma_f32 v[18:19], v[44:45], v[78:79], v[18:19] op_sel_hi:[1,0,1]
	v_pk_fma_f32 v[38:39], v[18:19], v[78:79], v[38:39] op_sel:[0,1,0] op_sel_hi:[1,1,1]
	v_pk_fma_f32 v[20:21], v[44:45], v[80:81], v[20:21] op_sel_hi:[1,0,1]
	v_pk_fma_f32 v[38:39], v[20:21], v[80:81], v[38:39] op_sel:[0,1,0] op_sel_hi:[1,1,1]
	s_add_u32 s14, s14, 0x1000
	s_addc_u32 s15, s15, 0
	v_add_f32_dpp v38, v38, v38 row_ror:8 row_mask:0xf bank_mask:0x3 bound_ctrl:1
	v_add_f32_dpp v38, v39, v39 row_ror:8 row_mask:0xf bank_mask:0xc bound_ctrl:1
	ds_read_b128 v[48:51], v2 offset:12544
	ds_read_b128 v[52:55], v2 offset:12800
	v_add_f32_dpp v38, v38, v38 row_half_mirror row_mask:0xf bank_mask:0xf bound_ctrl:1
	ds_read_b128 v[56:59], v2 offset:13056
	ds_read_b128 v[60:63], v2 offset:13312
	v_add_f32_dpp v38, v38, v38 quad_perm:[1,0,3,2] row_mask:0xf bank_mask:0xf bound_ctrl:1
	ds_read_b64 v[64:65], v3 offset:21760
	s_nop 0
	v_add_f32_dpp v38, v38, v38 quad_perm:[2,3,0,1] row_mask:0xf bank_mask:0xf bound_ctrl:1
	s_nop 1
	v_mov_b32_dpp v39, v38 row_ror:8 row_mask:0xf bank_mask:0xf bound_ctrl:1
	v_pk_mul_f32 v[38:39], v[38:39], v[40:41] op_sel:[0,1] op_sel_hi:[1,1]
	v_cvt_pk_bf16_f32 v47, v38, v39
	s_mov_b64 exec, s[2:3]
	global_store_dword v46, v47, s[14:15] offset:-4096
	s_mov_b64 exec, -1
	s_waitcnt lgkmcnt(0)
	v_pk_mul_f32 v[40:41], v[40:41], v[42:43]
	v_pk_mul_f32 v[44:45], v[64:65], v[40:41] op_sel_hi:[1,0]
	v_pk_fma_f32 v[6:7], v[44:45], v[48:49], v[6:7] op_sel_hi:[1,0,1]
	v_pk_mul_f32 v[38:39], v[6:7], v[48:49] op_sel:[0,1] op_sel_hi:[1,1]
	v_pk_fma_f32 v[8:9], v[44:45], v[50:51], v[8:9] op_sel_hi:[1,0,1]
	v_pk_fma_f32 v[38:39], v[8:9], v[50:51], v[38:39] op_sel:[0,1,0] op_sel_hi:[1,1,1]
	v_pk_fma_f32 v[10:11], v[44:45], v[52:53], v[10:11] op_sel_hi:[1,0,1]
	v_pk_fma_f32 v[38:39], v[10:11], v[52:53], v[38:39] op_sel:[0,1,0] op_sel_hi:[1,1,1]
	v_pk_fma_f32 v[12:13], v[44:45], v[54:55], v[12:13] op_sel_hi:[1,0,1]
	v_pk_fma_f32 v[38:39], v[12:13], v[54:55], v[38:39] op_sel:[0,1,0] op_sel_hi:[1,1,1]
	v_pk_fma_f32 v[14:15], v[44:45], v[56:57], v[14:15] op_sel_hi:[1,0,1]
	v_pk_fma_f32 v[38:39], v[14:15], v[56:57], v[38:39] op_sel:[0,1,0] op_sel_hi:[1,1,1]
	v_pk_fma_f32 v[16:17], v[44:45], v[58:59], v[16:17] op_sel_hi:[1,0,1]
	v_pk_fma_f32 v[38:39], v[16:17], v[58:59], v[38:39] op_sel:[0,1,0] op_sel_hi:[1,1,1]
	v_pk_fma_f32 v[18:19], v[44:45], v[60:61], v[18:19] op_sel_hi:[1,0,1]
	v_pk_fma_f32 v[38:39], v[18:19], v[60:61], v[38:39] op_sel:[0,1,0] op_sel_hi:[1,1,1]
	v_pk_fma_f32 v[20:21], v[44:45], v[62:63], v[20:21] op_sel_hi:[1,0,1]
	v_pk_fma_f32 v[38:39], v[20:21], v[62:63], v[38:39] op_sel:[0,1,0] op_sel_hi:[1,1,1]
	s_add_u32 s14, s14, 0x1000
	s_addc_u32 s15, s15, 0
	v_add_f32_dpp v38, v38, v38 row_ror:8 row_mask:0xf bank_mask:0x3 bound_ctrl:1
	v_add_f32_dpp v38, v39, v39 row_ror:8 row_mask:0xf bank_mask:0xc bound_ctrl:1
	ds_read_b128 v[66:69], v2 offset:13568
	ds_read_b128 v[70:73], v2 offset:13824
	v_add_f32_dpp v38, v38, v38 row_half_mirror row_mask:0xf bank_mask:0xf bound_ctrl:1
	ds_read_b128 v[74:77], v2 offset:14080
	ds_read_b128 v[78:81], v2 offset:14336
	v_add_f32_dpp v38, v38, v38 quad_perm:[1,0,3,2] row_mask:0xf bank_mask:0xf bound_ctrl:1
	ds_read_b64 v[82:83], v3 offset:22016
	s_nop 0
	v_add_f32_dpp v38, v38, v38 quad_perm:[2,3,0,1] row_mask:0xf bank_mask:0xf bound_ctrl:1
	s_nop 1
	v_mov_b32_dpp v39, v38 row_ror:8 row_mask:0xf bank_mask:0xf bound_ctrl:1
	v_pk_mul_f32 v[38:39], v[38:39], v[40:41] op_sel:[0,1] op_sel_hi:[1,1]
	v_cvt_pk_bf16_f32 v47, v38, v39
	s_mov_b64 exec, s[2:3]
	global_store_dword v46, v47, s[14:15] offset:-4096
	s_mov_b64 exec, -1
	s_waitcnt lgkmcnt(0)
	v_pk_mul_f32 v[40:41], v[40:41], v[42:43]
	v_pk_mul_f32 v[44:45], v[82:83], v[40:41] op_sel_hi:[1,0]
	v_pk_fma_f32 v[6:7], v[44:45], v[66:67], v[6:7] op_sel_hi:[1,0,1]
	v_pk_mul_f32 v[38:39], v[6:7], v[66:67] op_sel:[0,1] op_sel_hi:[1,1]
	v_pk_fma_f32 v[8:9], v[44:45], v[68:69], v[8:9] op_sel_hi:[1,0,1]
	v_pk_fma_f32 v[38:39], v[8:9], v[68:69], v[38:39] op_sel:[0,1,0] op_sel_hi:[1,1,1]
	v_pk_fma_f32 v[10:11], v[44:45], v[70:71], v[10:11] op_sel_hi:[1,0,1]
	v_pk_fma_f32 v[38:39], v[10:11], v[70:71], v[38:39] op_sel:[0,1,0] op_sel_hi:[1,1,1]
	v_pk_fma_f32 v[12:13], v[44:45], v[72:73], v[12:13] op_sel_hi:[1,0,1]
	v_pk_fma_f32 v[38:39], v[12:13], v[72:73], v[38:39] op_sel:[0,1,0] op_sel_hi:[1,1,1]
	v_pk_fma_f32 v[14:15], v[44:45], v[74:75], v[14:15] op_sel_hi:[1,0,1]
	v_pk_fma_f32 v[38:39], v[14:15], v[74:75], v[38:39] op_sel:[0,1,0] op_sel_hi:[1,1,1]
	v_pk_fma_f32 v[16:17], v[44:45], v[76:77], v[16:17] op_sel_hi:[1,0,1]
	v_pk_fma_f32 v[38:39], v[16:17], v[76:77], v[38:39] op_sel:[0,1,0] op_sel_hi:[1,1,1]
	v_pk_fma_f32 v[18:19], v[44:45], v[78:79], v[18:19] op_sel_hi:[1,0,1]
	v_pk_fma_f32 v[38:39], v[18:19], v[78:79], v[38:39] op_sel:[0,1,0] op_sel_hi:[1,1,1]
	v_pk_fma_f32 v[20:21], v[44:45], v[80:81], v[20:21] op_sel_hi:[1,0,1]
	v_pk_fma_f32 v[38:39], v[20:21], v[80:81], v[38:39] op_sel:[0,1,0] op_sel_hi:[1,1,1]
	s_add_u32 s14, s14, 0x1000
	s_addc_u32 s15, s15, 0
	v_add_f32_dpp v38, v38, v38 row_ror:8 row_mask:0xf bank_mask:0x3 bound_ctrl:1
	v_add_f32_dpp v38, v39, v39 row_ror:8 row_mask:0xf bank_mask:0xc bound_ctrl:1
	ds_read_b128 v[48:51], v2 offset:14592
	ds_read_b128 v[52:55], v2 offset:14848
	v_add_f32_dpp v38, v38, v38 row_half_mirror row_mask:0xf bank_mask:0xf bound_ctrl:1
	ds_read_b128 v[56:59], v2 offset:15104
	ds_read_b128 v[60:63], v2 offset:15360
	v_add_f32_dpp v38, v38, v38 quad_perm:[1,0,3,2] row_mask:0xf bank_mask:0xf bound_ctrl:1
	ds_read_b64 v[64:65], v3 offset:22272
	s_nop 0
	v_add_f32_dpp v38, v38, v38 quad_perm:[2,3,0,1] row_mask:0xf bank_mask:0xf bound_ctrl:1
	s_nop 1
	v_mov_b32_dpp v39, v38 row_ror:8 row_mask:0xf bank_mask:0xf bound_ctrl:1
	v_pk_mul_f32 v[38:39], v[38:39], v[40:41] op_sel:[0,1] op_sel_hi:[1,1]
	v_cvt_pk_bf16_f32 v47, v38, v39
	s_mov_b64 exec, s[2:3]
	global_store_dword v46, v47, s[14:15] offset:-4096
	s_mov_b64 exec, -1
	s_waitcnt lgkmcnt(0)
	v_pk_mul_f32 v[40:41], v[40:41], v[42:43]
	v_pk_mul_f32 v[44:45], v[64:65], v[40:41] op_sel_hi:[1,0]
	v_pk_fma_f32 v[6:7], v[44:45], v[48:49], v[6:7] op_sel_hi:[1,0,1]
	v_pk_mul_f32 v[38:39], v[6:7], v[48:49] op_sel:[0,1] op_sel_hi:[1,1]
	v_pk_fma_f32 v[8:9], v[44:45], v[50:51], v[8:9] op_sel_hi:[1,0,1]
	v_pk_fma_f32 v[38:39], v[8:9], v[50:51], v[38:39] op_sel:[0,1,0] op_sel_hi:[1,1,1]
	v_pk_fma_f32 v[10:11], v[44:45], v[52:53], v[10:11] op_sel_hi:[1,0,1]
	v_pk_fma_f32 v[38:39], v[10:11], v[52:53], v[38:39] op_sel:[0,1,0] op_sel_hi:[1,1,1]
	v_pk_fma_f32 v[12:13], v[44:45], v[54:55], v[12:13] op_sel_hi:[1,0,1]
	v_pk_fma_f32 v[38:39], v[12:13], v[54:55], v[38:39] op_sel:[0,1,0] op_sel_hi:[1,1,1]
	v_pk_fma_f32 v[14:15], v[44:45], v[56:57], v[14:15] op_sel_hi:[1,0,1]
	v_pk_fma_f32 v[38:39], v[14:15], v[56:57], v[38:39] op_sel:[0,1,0] op_sel_hi:[1,1,1]
	v_pk_fma_f32 v[16:17], v[44:45], v[58:59], v[16:17] op_sel_hi:[1,0,1]
	v_pk_fma_f32 v[38:39], v[16:17], v[58:59], v[38:39] op_sel:[0,1,0] op_sel_hi:[1,1,1]
	v_pk_fma_f32 v[18:19], v[44:45], v[60:61], v[18:19] op_sel_hi:[1,0,1]
	v_pk_fma_f32 v[38:39], v[18:19], v[60:61], v[38:39] op_sel:[0,1,0] op_sel_hi:[1,1,1]
	v_pk_fma_f32 v[20:21], v[44:45], v[62:63], v[20:21] op_sel_hi:[1,0,1]
	v_pk_fma_f32 v[38:39], v[20:21], v[62:63], v[38:39] op_sel:[0,1,0] op_sel_hi:[1,1,1]
	s_add_u32 s14, s14, 0x1000
	s_addc_u32 s15, s15, 0
	v_add_f32_dpp v38, v38, v38 row_ror:8 row_mask:0xf bank_mask:0x3 bound_ctrl:1
	v_add_f32_dpp v38, v39, v39 row_ror:8 row_mask:0xf bank_mask:0xc bound_ctrl:1
	ds_read_b128 v[66:69], v2 offset:15616
	ds_read_b128 v[70:73], v2 offset:15872
	v_add_f32_dpp v38, v38, v38 row_half_mirror row_mask:0xf bank_mask:0xf bound_ctrl:1
	ds_read_b128 v[74:77], v2 offset:16128
	ds_read_b128 v[78:81], v2 offset:16384
	v_add_f32_dpp v38, v38, v38 quad_perm:[1,0,3,2] row_mask:0xf bank_mask:0xf bound_ctrl:1
	ds_read_b64 v[82:83], v3 offset:22528
	s_nop 0
	v_add_f32_dpp v38, v38, v38 quad_perm:[2,3,0,1] row_mask:0xf bank_mask:0xf bound_ctrl:1
	s_nop 1
	v_mov_b32_dpp v39, v38 row_ror:8 row_mask:0xf bank_mask:0xf bound_ctrl:1
	v_pk_mul_f32 v[38:39], v[38:39], v[40:41] op_sel:[0,1] op_sel_hi:[1,1]
	v_cvt_pk_bf16_f32 v47, v38, v39
	s_mov_b64 exec, s[2:3]
	global_store_dword v46, v47, s[14:15] offset:-4096
	s_mov_b64 exec, -1
	s_waitcnt lgkmcnt(0)
	v_pk_mul_f32 v[40:41], v[40:41], v[42:43]
	v_pk_mul_f32 v[44:45], v[82:83], v[40:41] op_sel_hi:[1,0]
	v_pk_fma_f32 v[6:7], v[44:45], v[66:67], v[6:7] op_sel_hi:[1,0,1]
	v_pk_mul_f32 v[38:39], v[6:7], v[66:67] op_sel:[0,1] op_sel_hi:[1,1]
	v_pk_fma_f32 v[8:9], v[44:45], v[68:69], v[8:9] op_sel_hi:[1,0,1]
	v_pk_fma_f32 v[38:39], v[8:9], v[68:69], v[38:39] op_sel:[0,1,0] op_sel_hi:[1,1,1]
	v_pk_fma_f32 v[10:11], v[44:45], v[70:71], v[10:11] op_sel_hi:[1,0,1]
	v_pk_fma_f32 v[38:39], v[10:11], v[70:71], v[38:39] op_sel:[0,1,0] op_sel_hi:[1,1,1]
	v_pk_fma_f32 v[12:13], v[44:45], v[72:73], v[12:13] op_sel_hi:[1,0,1]
	v_pk_fma_f32 v[38:39], v[12:13], v[72:73], v[38:39] op_sel:[0,1,0] op_sel_hi:[1,1,1]
	v_pk_fma_f32 v[14:15], v[44:45], v[74:75], v[14:15] op_sel_hi:[1,0,1]
	v_pk_fma_f32 v[38:39], v[14:15], v[74:75], v[38:39] op_sel:[0,1,0] op_sel_hi:[1,1,1]
	v_pk_fma_f32 v[16:17], v[44:45], v[76:77], v[16:17] op_sel_hi:[1,0,1]
	v_pk_fma_f32 v[38:39], v[16:17], v[76:77], v[38:39] op_sel:[0,1,0] op_sel_hi:[1,1,1]
	v_pk_fma_f32 v[18:19], v[44:45], v[78:79], v[18:19] op_sel_hi:[1,0,1]
	v_pk_fma_f32 v[38:39], v[18:19], v[78:79], v[38:39] op_sel:[0,1,0] op_sel_hi:[1,1,1]
	v_pk_fma_f32 v[20:21], v[44:45], v[80:81], v[20:21] op_sel_hi:[1,0,1]
	v_pk_fma_f32 v[38:39], v[20:21], v[80:81], v[38:39] op_sel:[0,1,0] op_sel_hi:[1,1,1]
	s_add_u32 s14, s14, 0x1000
	s_addc_u32 s15, s15, 0
	v_add_f32_dpp v38, v38, v38 row_ror:8 row_mask:0xf bank_mask:0x3 bound_ctrl:1
	v_add_f32_dpp v38, v39, v39 row_ror:8 row_mask:0xf bank_mask:0xc bound_ctrl:1
	ds_read_b128 v[48:51], v2 offset:33024
	ds_read_b128 v[52:55], v2 offset:33280
	v_add_f32_dpp v38, v38, v38 row_half_mirror row_mask:0xf bank_mask:0xf bound_ctrl:1
	ds_read_b128 v[56:59], v2 offset:33536
	ds_read_b128 v[60:63], v2 offset:33792
	v_add_f32_dpp v38, v38, v38 quad_perm:[1,0,3,2] row_mask:0xf bank_mask:0xf bound_ctrl:1
	ds_read_b64 v[64:65], v3 offset:45312
	s_nop 0
	v_add_f32_dpp v38, v38, v38 quad_perm:[2,3,0,1] row_mask:0xf bank_mask:0xf bound_ctrl:1
	s_nop 1
	v_mov_b32_dpp v39, v38 row_ror:8 row_mask:0xf bank_mask:0xf bound_ctrl:1
	v_pk_mul_f32 v[38:39], v[38:39], v[40:41] op_sel:[0,1] op_sel_hi:[1,1]
	v_cvt_pk_bf16_f32 v47, v38, v39
	s_mov_b64 exec, s[2:3]
	global_store_dword v46, v47, s[14:15] offset:-4096
	s_mov_b64 exec, -1
	s_waitcnt vmcnt(8)
	v_lshlrev_b32_e32 v108, 16, v84
	v_lshlrev_b32_e32 v109, 16, v85
	v_and_b32_e32 v110, s17, v84
	v_and_b32_e32 v111, s17, v85
	v_lshlrev_b32_e32 v112, 16, v86
	v_lshlrev_b32_e32 v113, 16, v87
	v_and_b32_e32 v114, s17, v86
	v_and_b32_e32 v115, s17, v87
	v_lshlrev_b32_e32 v116, 16, v88
	v_and_b32_e32 v117, s17, v88
	ds_write_b128 v29, v[108:111] offset:49408
	ds_write_b128 v29, v[112:115] offset:57600
	ds_write_b64 v30, v[90:91] offset:49408
	ds_write_b64 v31, v[116:117] offset:49408
	s_add_i32 s16, s16, 8
	s_waitcnt lgkmcnt(0)
	s_barrier
	s_cmpk_lt_u32 s16, 0x800
	s_cbranch_scc0 .Lret2_done
	global_load_dword v84, v32, s[10:11]
	global_load_dword v85, v32, s[10:11] offset:-1024
	global_load_dword v86, v33, s[10:11]
	global_load_dword v87, v33, s[10:11] offset:-1024
	global_load_dword v88, v34, s[10:11]
	global_load_dword v90, v35, s[12:13]
	global_load_dword v91, v35, s[12:13] offset:4
	s_add_u32 s10, s10, 0x18000
	s_addc_u32 s11, s11, 0
	s_add_u32 s12, s12, 0x4000
	s_addc_u32 s13, s13, 0
	s_waitcnt lgkmcnt(0)
	v_pk_mul_f32 v[40:41], v[40:41], v[42:43]
	v_rcp_f32_e32 v40, v41
	s_nop 0
	v_pk_mul_f32 v[44:45], v[64:65], v[40:41] op_sel_hi:[1,0]
	v_pk_fma_f32 v[6:7], v[44:45], v[48:49], v[6:7] op_sel_hi:[1,0,1]
	v_pk_mul_f32 v[38:39], v[6:7], v[48:49] op_sel:[0,1] op_sel_hi:[1,1]
	v_pk_fma_f32 v[8:9], v[44:45], v[50:51], v[8:9] op_sel_hi:[1,0,1]
	v_pk_fma_f32 v[38:39], v[8:9], v[50:51], v[38:39] op_sel:[0,1,0] op_sel_hi:[1,1,1]
	v_pk_fma_f32 v[10:11], v[44:45], v[52:53], v[10:11] op_sel_hi:[1,0,1]
	v_pk_fma_f32 v[38:39], v[10:11], v[52:53], v[38:39] op_sel:[0,1,0] op_sel_hi:[1,1,1]
	v_pk_fma_f32 v[12:13], v[44:45], v[54:55], v[12:13] op_sel_hi:[1,0,1]
	v_pk_fma_f32 v[38:39], v[12:13], v[54:55], v[38:39] op_sel:[0,1,0] op_sel_hi:[1,1,1]
	v_pk_fma_f32 v[14:15], v[44:45], v[56:57], v[14:15] op_sel_hi:[1,0,1]
	v_pk_fma_f32 v[38:39], v[14:15], v[56:57], v[38:39] op_sel:[0,1,0] op_sel_hi:[1,1,1]
	v_pk_fma_f32 v[16:17], v[44:45], v[58:59], v[16:17] op_sel_hi:[1,0,1]
	v_pk_fma_f32 v[38:39], v[16:17], v[58:59], v[38:39] op_sel:[0,1,0] op_sel_hi:[1,1,1]
	v_pk_fma_f32 v[18:19], v[44:45], v[60:61], v[18:19] op_sel_hi:[1,0,1]
	v_pk_fma_f32 v[38:39], v[18:19], v[60:61], v[38:39] op_sel:[0,1,0] op_sel_hi:[1,1,1]
	v_pk_fma_f32 v[20:21], v[44:45], v[62:63], v[20:21] op_sel_hi:[1,0,1]
	v_pk_fma_f32 v[38:39], v[20:21], v[62:63], v[38:39] op_sel:[0,1,0] op_sel_hi:[1,1,1]
	s_add_u32 s14, s14, 0x1000
	s_addc_u32 s15, s15, 0
	v_add_f32_dpp v38, v38, v38 row_ror:8 row_mask:0xf bank_mask:0x3 bound_ctrl:1
	v_add_f32_dpp v38, v39, v39 row_ror:8 row_mask:0xf bank_mask:0xc bound_ctrl:1
	ds_read_b128 v[66:69], v2 offset:34048
	ds_read_b128 v[70:73], v2 offset:34304
	v_add_f32_dpp v38, v38, v38 row_half_mirror row_mask:0xf bank_mask:0xf bound_ctrl:1
	ds_read_b128 v[74:77], v2 offset:34560
	ds_read_b128 v[78:81], v2 offset:34816
	v_add_f32_dpp v38, v38, v38 quad_perm:[1,0,3,2] row_mask:0xf bank_mask:0xf bound_ctrl:1
	ds_read_b64 v[82:83], v3 offset:45568
	s_nop 0
	v_add_f32_dpp v38, v38, v38 quad_perm:[2,3,0,1] row_mask:0xf bank_mask:0xf bound_ctrl:1
	s_nop 1
	v_mov_b32_dpp v39, v38 row_ror:8 row_mask:0xf bank_mask:0xf bound_ctrl:1
	v_pk_mul_f32 v[38:39], v[38:39], v[40:41] op_sel:[0,1] op_sel_hi:[1,1]
	v_cvt_pk_bf16_f32 v47, v38, v39
	s_mov_b64 exec, s[2:3]
	global_store_dword v46, v47, s[14:15] offset:-4096
	s_mov_b64 exec, -1
	s_waitcnt lgkmcnt(0)
	v_pk_mul_f32 v[40:41], v[40:41], v[42:43]
	v_pk_mul_f32 v[44:45], v[82:83], v[40:41] op_sel_hi:[1,0]
	v_pk_fma_f32 v[6:7], v[44:45], v[66:67], v[6:7] op_sel_hi:[1,0,1]
	v_pk_mul_f32 v[38:39], v[6:7], v[66:67] op_sel:[0,1] op_sel_hi:[1,1]
	v_pk_fma_f32 v[8:9], v[44:45], v[68:69], v[8:9] op_sel_hi:[1,0,1]
	v_pk_fma_f32 v[38:39], v[8:9], v[68:69], v[38:39] op_sel:[0,1,0] op_sel_hi:[1,1,1]
	v_pk_fma_f32 v[10:11], v[44:45], v[70:71], v[10:11] op_sel_hi:[1,0,1]
	v_pk_fma_f32 v[38:39], v[10:11], v[70:71], v[38:39] op_sel:[0,1,0] op_sel_hi:[1,1,1]
	v_pk_fma_f32 v[12:13], v[44:45], v[72:73], v[12:13] op_sel_hi:[1,0,1]
	v_pk_fma_f32 v[38:39], v[12:13], v[72:73], v[38:39] op_sel:[0,1,0] op_sel_hi:[1,1,1]
	v_pk_fma_f32 v[14:15], v[44:45], v[74:75], v[14:15] op_sel_hi:[1,0,1]
	v_pk_fma_f32 v[38:39], v[14:15], v[74:75], v[38:39] op_sel:[0,1,0] op_sel_hi:[1,1,1]
	v_pk_fma_f32 v[16:17], v[44:45], v[76:77], v[16:17] op_sel_hi:[1,0,1]
	v_pk_fma_f32 v[38:39], v[16:17], v[76:77], v[38:39] op_sel:[0,1,0] op_sel_hi:[1,1,1]
	v_pk_fma_f32 v[18:19], v[44:45], v[78:79], v[18:19] op_sel_hi:[1,0,1]
	v_pk_fma_f32 v[38:39], v[18:19], v[78:79], v[38:39] op_sel:[0,1,0] op_sel_hi:[1,1,1]
	v_pk_fma_f32 v[20:21], v[44:45], v[80:81], v[20:21] op_sel_hi:[1,0,1]
	v_pk_fma_f32 v[38:39], v[20:21], v[80:81], v[38:39] op_sel:[0,1,0] op_sel_hi:[1,1,1]
	s_add_u32 s14, s14, 0x1000
	s_addc_u32 s15, s15, 0
	v_add_f32_dpp v38, v38, v38 row_ror:8 row_mask:0xf bank_mask:0x3 bound_ctrl:1
	v_add_f32_dpp v38, v39, v39 row_ror:8 row_mask:0xf bank_mask:0xc bound_ctrl:1
	ds_read_b128 v[48:51], v2 offset:35072
	ds_read_b128 v[52:55], v2 offset:35328
	v_add_f32_dpp v38, v38, v38 row_half_mirror row_mask:0xf bank_mask:0xf bound_ctrl:1
	ds_read_b128 v[56:59], v2 offset:35584
	ds_read_b128 v[60:63], v2 offset:35840
	v_add_f32_dpp v38, v38, v38 quad_perm:[1,0,3,2] row_mask:0xf bank_mask:0xf bound_ctrl:1
	ds_read_b64 v[64:65], v3 offset:45824
	s_nop 0
	v_add_f32_dpp v38, v38, v38 quad_perm:[2,3,0,1] row_mask:0xf bank_mask:0xf bound_ctrl:1
	s_nop 1
	v_mov_b32_dpp v39, v38 row_ror:8 row_mask:0xf bank_mask:0xf bound_ctrl:1
	v_pk_mul_f32 v[38:39], v[38:39], v[40:41] op_sel:[0,1] op_sel_hi:[1,1]
	v_cvt_pk_bf16_f32 v47, v38, v39
	s_mov_b64 exec, s[2:3]
	global_store_dword v46, v47, s[14:15] offset:-4096
	s_mov_b64 exec, -1
	s_waitcnt lgkmcnt(0)
	v_pk_mul_f32 v[40:41], v[40:41], v[42:43]
	v_pk_mul_f32 v[44:45], v[64:65], v[40:41] op_sel_hi:[1,0]
	v_pk_fma_f32 v[6:7], v[44:45], v[48:49], v[6:7] op_sel_hi:[1,0,1]
	v_pk_mul_f32 v[38:39], v[6:7], v[48:49] op_sel:[0,1] op_sel_hi:[1,1]
	v_pk_fma_f32 v[8:9], v[44:45], v[50:51], v[8:9] op_sel_hi:[1,0,1]
	v_pk_fma_f32 v[38:39], v[8:9], v[50:51], v[38:39] op_sel:[0,1,0] op_sel_hi:[1,1,1]
	v_pk_fma_f32 v[10:11], v[44:45], v[52:53], v[10:11] op_sel_hi:[1,0,1]
	v_pk_fma_f32 v[38:39], v[10:11], v[52:53], v[38:39] op_sel:[0,1,0] op_sel_hi:[1,1,1]
	v_pk_fma_f32 v[12:13], v[44:45], v[54:55], v[12:13] op_sel_hi:[1,0,1]
	v_pk_fma_f32 v[38:39], v[12:13], v[54:55], v[38:39] op_sel:[0,1,0] op_sel_hi:[1,1,1]
	v_pk_fma_f32 v[14:15], v[44:45], v[56:57], v[14:15] op_sel_hi:[1,0,1]
	v_pk_fma_f32 v[38:39], v[14:15], v[56:57], v[38:39] op_sel:[0,1,0] op_sel_hi:[1,1,1]
	v_pk_fma_f32 v[16:17], v[44:45], v[58:59], v[16:17] op_sel_hi:[1,0,1]
	v_pk_fma_f32 v[38:39], v[16:17], v[58:59], v[38:39] op_sel:[0,1,0] op_sel_hi:[1,1,1]
	v_pk_fma_f32 v[18:19], v[44:45], v[60:61], v[18:19] op_sel_hi:[1,0,1]
	v_pk_fma_f32 v[38:39], v[18:19], v[60:61], v[38:39] op_sel:[0,1,0] op_sel_hi:[1,1,1]
	v_pk_fma_f32 v[20:21], v[44:45], v[62:63], v[20:21] op_sel_hi:[1,0,1]
	v_pk_fma_f32 v[38:39], v[20:21], v[62:63], v[38:39] op_sel:[0,1,0] op_sel_hi:[1,1,1]
	s_add_u32 s14, s14, 0x1000
	s_addc_u32 s15, s15, 0
	v_add_f32_dpp v38, v38, v38 row_ror:8 row_mask:0xf bank_mask:0x3 bound_ctrl:1
	v_add_f32_dpp v38, v39, v39 row_ror:8 row_mask:0xf bank_mask:0xc bound_ctrl:1
	ds_read_b128 v[66:69], v2 offset:36096
	ds_read_b128 v[70:73], v2 offset:36352
	v_add_f32_dpp v38, v38, v38 row_half_mirror row_mask:0xf bank_mask:0xf bound_ctrl:1
	ds_read_b128 v[74:77], v2 offset:36608
	ds_read_b128 v[78:81], v2 offset:36864
	v_add_f32_dpp v38, v38, v38 quad_perm:[1,0,3,2] row_mask:0xf bank_mask:0xf bound_ctrl:1
	ds_read_b64 v[82:83], v3 offset:46080
	s_nop 0
	v_add_f32_dpp v38, v38, v38 quad_perm:[2,3,0,1] row_mask:0xf bank_mask:0xf bound_ctrl:1
	s_nop 1
	v_mov_b32_dpp v39, v38 row_ror:8 row_mask:0xf bank_mask:0xf bound_ctrl:1
	v_pk_mul_f32 v[38:39], v[38:39], v[40:41] op_sel:[0,1] op_sel_hi:[1,1]
	v_cvt_pk_bf16_f32 v47, v38, v39
	s_mov_b64 exec, s[2:3]
	global_store_dword v46, v47, s[14:15] offset:-4096
	s_mov_b64 exec, -1
	s_waitcnt lgkmcnt(0)
	v_pk_mul_f32 v[40:41], v[40:41], v[42:43]
	v_pk_mul_f32 v[44:45], v[82:83], v[40:41] op_sel_hi:[1,0]
	v_pk_fma_f32 v[6:7], v[44:45], v[66:67], v[6:7] op_sel_hi:[1,0,1]
	v_pk_mul_f32 v[38:39], v[6:7], v[66:67] op_sel:[0,1] op_sel_hi:[1,1]
	v_pk_fma_f32 v[8:9], v[44:45], v[68:69], v[8:9] op_sel_hi:[1,0,1]
	v_pk_fma_f32 v[38:39], v[8:9], v[68:69], v[38:39] op_sel:[0,1,0] op_sel_hi:[1,1,1]
	v_pk_fma_f32 v[10:11], v[44:45], v[70:71], v[10:11] op_sel_hi:[1,0,1]
	v_pk_fma_f32 v[38:39], v[10:11], v[70:71], v[38:39] op_sel:[0,1,0] op_sel_hi:[1,1,1]
	v_pk_fma_f32 v[12:13], v[44:45], v[72:73], v[12:13] op_sel_hi:[1,0,1]
	v_pk_fma_f32 v[38:39], v[12:13], v[72:73], v[38:39] op_sel:[0,1,0] op_sel_hi:[1,1,1]
	v_pk_fma_f32 v[14:15], v[44:45], v[74:75], v[14:15] op_sel_hi:[1,0,1]
	v_pk_fma_f32 v[38:39], v[14:15], v[74:75], v[38:39] op_sel:[0,1,0] op_sel_hi:[1,1,1]
	v_pk_fma_f32 v[16:17], v[44:45], v[76:77], v[16:17] op_sel_hi:[1,0,1]
	v_pk_fma_f32 v[38:39], v[16:17], v[76:77], v[38:39] op_sel:[0,1,0] op_sel_hi:[1,1,1]
	v_pk_fma_f32 v[18:19], v[44:45], v[78:79], v[18:19] op_sel_hi:[1,0,1]
	v_pk_fma_f32 v[38:39], v[18:19], v[78:79], v[38:39] op_sel:[0,1,0] op_sel_hi:[1,1,1]
	v_pk_fma_f32 v[20:21], v[44:45], v[80:81], v[20:21] op_sel_hi:[1,0,1]
	v_pk_fma_f32 v[38:39], v[20:21], v[80:81], v[38:39] op_sel:[0,1,0] op_sel_hi:[1,1,1]
	s_add_u32 s14, s14, 0x1000
	s_addc_u32 s15, s15, 0
	v_add_f32_dpp v38, v38, v38 row_ror:8 row_mask:0xf bank_mask:0x3 bound_ctrl:1
	v_add_f32_dpp v38, v39, v39 row_ror:8 row_mask:0xf bank_mask:0xc bound_ctrl:1
	ds_read_b128 v[48:51], v2 offset:37120
	ds_read_b128 v[52:55], v2 offset:37376
	v_add_f32_dpp v38, v38, v38 row_half_mirror row_mask:0xf bank_mask:0xf bound_ctrl:1
	ds_read_b128 v[56:59], v2 offset:37632
	ds_read_b128 v[60:63], v2 offset:37888
	v_add_f32_dpp v38, v38, v38 quad_perm:[1,0,3,2] row_mask:0xf bank_mask:0xf bound_ctrl:1
	ds_read_b64 v[64:65], v3 offset:46336
	s_nop 0
	v_add_f32_dpp v38, v38, v38 quad_perm:[2,3,0,1] row_mask:0xf bank_mask:0xf bound_ctrl:1
	s_nop 1
	v_mov_b32_dpp v39, v38 row_ror:8 row_mask:0xf bank_mask:0xf bound_ctrl:1
	v_pk_mul_f32 v[38:39], v[38:39], v[40:41] op_sel:[0,1] op_sel_hi:[1,1]
	v_cvt_pk_bf16_f32 v47, v38, v39
	s_mov_b64 exec, s[2:3]
	global_store_dword v46, v47, s[14:15] offset:-4096
	s_mov_b64 exec, -1
	s_waitcnt lgkmcnt(0)
	v_pk_mul_f32 v[40:41], v[40:41], v[42:43]
	v_pk_mul_f32 v[44:45], v[64:65], v[40:41] op_sel_hi:[1,0]
	v_pk_fma_f32 v[6:7], v[44:45], v[48:49], v[6:7] op_sel_hi:[1,0,1]
	v_pk_mul_f32 v[38:39], v[6:7], v[48:49] op_sel:[0,1] op_sel_hi:[1,1]
	v_pk_fma_f32 v[8:9], v[44:45], v[50:51], v[8:9] op_sel_hi:[1,0,1]
	v_pk_fma_f32 v[38:39], v[8:9], v[50:51], v[38:39] op_sel:[0,1,0] op_sel_hi:[1,1,1]
	v_pk_fma_f32 v[10:11], v[44:45], v[52:53], v[10:11] op_sel_hi:[1,0,1]
	v_pk_fma_f32 v[38:39], v[10:11], v[52:53], v[38:39] op_sel:[0,1,0] op_sel_hi:[1,1,1]
	v_pk_fma_f32 v[12:13], v[44:45], v[54:55], v[12:13] op_sel_hi:[1,0,1]
	v_pk_fma_f32 v[38:39], v[12:13], v[54:55], v[38:39] op_sel:[0,1,0] op_sel_hi:[1,1,1]
	v_pk_fma_f32 v[14:15], v[44:45], v[56:57], v[14:15] op_sel_hi:[1,0,1]
	v_pk_fma_f32 v[38:39], v[14:15], v[56:57], v[38:39] op_sel:[0,1,0] op_sel_hi:[1,1,1]
	v_pk_fma_f32 v[16:17], v[44:45], v[58:59], v[16:17] op_sel_hi:[1,0,1]
	v_pk_fma_f32 v[38:39], v[16:17], v[58:59], v[38:39] op_sel:[0,1,0] op_sel_hi:[1,1,1]
	v_pk_fma_f32 v[18:19], v[44:45], v[60:61], v[18:19] op_sel_hi:[1,0,1]
	v_pk_fma_f32 v[38:39], v[18:19], v[60:61], v[38:39] op_sel:[0,1,0] op_sel_hi:[1,1,1]
	v_pk_fma_f32 v[20:21], v[44:45], v[62:63], v[20:21] op_sel_hi:[1,0,1]
	v_pk_fma_f32 v[38:39], v[20:21], v[62:63], v[38:39] op_sel:[0,1,0] op_sel_hi:[1,1,1]
	s_add_u32 s14, s14, 0x1000
	s_addc_u32 s15, s15, 0
	v_add_f32_dpp v38, v38, v38 row_ror:8 row_mask:0xf bank_mask:0x3 bound_ctrl:1
	v_add_f32_dpp v38, v39, v39 row_ror:8 row_mask:0xf bank_mask:0xc bound_ctrl:1
	ds_read_b128 v[66:69], v2 offset:38144
	ds_read_b128 v[70:73], v2 offset:38400
	v_add_f32_dpp v38, v38, v38 row_half_mirror row_mask:0xf bank_mask:0xf bound_ctrl:1
	ds_read_b128 v[74:77], v2 offset:38656
	ds_read_b128 v[78:81], v2 offset:38912
	v_add_f32_dpp v38, v38, v38 quad_perm:[1,0,3,2] row_mask:0xf bank_mask:0xf bound_ctrl:1
	ds_read_b64 v[82:83], v3 offset:46592
	s_nop 0
	v_add_f32_dpp v38, v38, v38 quad_perm:[2,3,0,1] row_mask:0xf bank_mask:0xf bound_ctrl:1
	s_nop 1
	v_mov_b32_dpp v39, v38 row_ror:8 row_mask:0xf bank_mask:0xf bound_ctrl:1
	v_pk_mul_f32 v[38:39], v[38:39], v[40:41] op_sel:[0,1] op_sel_hi:[1,1]
	v_cvt_pk_bf16_f32 v47, v38, v39
	s_mov_b64 exec, s[2:3]
	global_store_dword v46, v47, s[14:15] offset:-4096
	s_mov_b64 exec, -1
	s_waitcnt lgkmcnt(0)
	v_pk_mul_f32 v[40:41], v[40:41], v[42:43]
	v_pk_mul_f32 v[44:45], v[82:83], v[40:41] op_sel_hi:[1,0]
	v_pk_fma_f32 v[6:7], v[44:45], v[66:67], v[6:7] op_sel_hi:[1,0,1]
	v_pk_mul_f32 v[38:39], v[6:7], v[66:67] op_sel:[0,1] op_sel_hi:[1,1]
	v_pk_fma_f32 v[8:9], v[44:45], v[68:69], v[8:9] op_sel_hi:[1,0,1]
	v_pk_fma_f32 v[38:39], v[8:9], v[68:69], v[38:39] op_sel:[0,1,0] op_sel_hi:[1,1,1]
	v_pk_fma_f32 v[10:11], v[44:45], v[70:71], v[10:11] op_sel_hi:[1,0,1]
	v_pk_fma_f32 v[38:39], v[10:11], v[70:71], v[38:39] op_sel:[0,1,0] op_sel_hi:[1,1,1]
	v_pk_fma_f32 v[12:13], v[44:45], v[72:73], v[12:13] op_sel_hi:[1,0,1]
	v_pk_fma_f32 v[38:39], v[12:13], v[72:73], v[38:39] op_sel:[0,1,0] op_sel_hi:[1,1,1]
	v_pk_fma_f32 v[14:15], v[44:45], v[74:75], v[14:15] op_sel_hi:[1,0,1]
	v_pk_fma_f32 v[38:39], v[14:15], v[74:75], v[38:39] op_sel:[0,1,0] op_sel_hi:[1,1,1]
	v_pk_fma_f32 v[16:17], v[44:45], v[76:77], v[16:17] op_sel_hi:[1,0,1]
	v_pk_fma_f32 v[38:39], v[16:17], v[76:77], v[38:39] op_sel:[0,1,0] op_sel_hi:[1,1,1]
	v_pk_fma_f32 v[18:19], v[44:45], v[78:79], v[18:19] op_sel_hi:[1,0,1]
	v_pk_fma_f32 v[38:39], v[18:19], v[78:79], v[38:39] op_sel:[0,1,0] op_sel_hi:[1,1,1]
	v_pk_fma_f32 v[20:21], v[44:45], v[80:81], v[20:21] op_sel_hi:[1,0,1]
	v_pk_fma_f32 v[38:39], v[20:21], v[80:81], v[38:39] op_sel:[0,1,0] op_sel_hi:[1,1,1]
	s_add_u32 s14, s14, 0x1000
	s_addc_u32 s15, s15, 0
	v_add_f32_dpp v38, v38, v38 row_ror:8 row_mask:0xf bank_mask:0x3 bound_ctrl:1
	v_add_f32_dpp v38, v39, v39 row_ror:8 row_mask:0xf bank_mask:0xc bound_ctrl:1
	ds_read_b128 v[48:51], v2 offset:39168
	ds_read_b128 v[52:55], v2 offset:39424
	v_add_f32_dpp v38, v38, v38 row_half_mirror row_mask:0xf bank_mask:0xf bound_ctrl:1
	ds_read_b128 v[56:59], v2 offset:39680
	ds_read_b128 v[60:63], v2 offset:39936
	v_add_f32_dpp v38, v38, v38 quad_perm:[1,0,3,2] row_mask:0xf bank_mask:0xf bound_ctrl:1
	ds_read_b64 v[64:65], v3 offset:46848
	s_nop 0
	v_add_f32_dpp v38, v38, v38 quad_perm:[2,3,0,1] row_mask:0xf bank_mask:0xf bound_ctrl:1
	s_nop 1
	v_mov_b32_dpp v39, v38 row_ror:8 row_mask:0xf bank_mask:0xf bound_ctrl:1
	v_pk_mul_f32 v[38:39], v[38:39], v[40:41] op_sel:[0,1] op_sel_hi:[1,1]
	v_cvt_pk_bf16_f32 v47, v38, v39
	s_mov_b64 exec, s[2:3]
	global_store_dword v46, v47, s[14:15] offset:-4096
	s_mov_b64 exec, -1
	s_waitcnt lgkmcnt(0)
	v_pk_mul_f32 v[40:41], v[40:41], v[42:43]
	v_pk_mul_f32 v[44:45], v[64:65], v[40:41] op_sel_hi:[1,0]
	v_pk_fma_f32 v[6:7], v[44:45], v[48:49], v[6:7] op_sel_hi:[1,0,1]
	v_pk_mul_f32 v[38:39], v[6:7], v[48:49] op_sel:[0,1] op_sel_hi:[1,1]
	v_pk_fma_f32 v[8:9], v[44:45], v[50:51], v[8:9] op_sel_hi:[1,0,1]
	v_pk_fma_f32 v[38:39], v[8:9], v[50:51], v[38:39] op_sel:[0,1,0] op_sel_hi:[1,1,1]
	v_pk_fma_f32 v[10:11], v[44:45], v[52:53], v[10:11] op_sel_hi:[1,0,1]
	v_pk_fma_f32 v[38:39], v[10:11], v[52:53], v[38:39] op_sel:[0,1,0] op_sel_hi:[1,1,1]
	v_pk_fma_f32 v[12:13], v[44:45], v[54:55], v[12:13] op_sel_hi:[1,0,1]
	v_pk_fma_f32 v[38:39], v[12:13], v[54:55], v[38:39] op_sel:[0,1,0] op_sel_hi:[1,1,1]
	v_pk_fma_f32 v[14:15], v[44:45], v[56:57], v[14:15] op_sel_hi:[1,0,1]
	v_pk_fma_f32 v[38:39], v[14:15], v[56:57], v[38:39] op_sel:[0,1,0] op_sel_hi:[1,1,1]
	v_pk_fma_f32 v[16:17], v[44:45], v[58:59], v[16:17] op_sel_hi:[1,0,1]
	v_pk_fma_f32 v[38:39], v[16:17], v[58:59], v[38:39] op_sel:[0,1,0] op_sel_hi:[1,1,1]
	v_pk_fma_f32 v[18:19], v[44:45], v[60:61], v[18:19] op_sel_hi:[1,0,1]
	v_pk_fma_f32 v[38:39], v[18:19], v[60:61], v[38:39] op_sel:[0,1,0] op_sel_hi:[1,1,1]
	v_pk_fma_f32 v[20:21], v[44:45], v[62:63], v[20:21] op_sel_hi:[1,0,1]
	v_pk_fma_f32 v[38:39], v[20:21], v[62:63], v[38:39] op_sel:[0,1,0] op_sel_hi:[1,1,1]
	s_add_u32 s14, s14, 0x1000
	s_addc_u32 s15, s15, 0
	v_add_f32_dpp v38, v38, v38 row_ror:8 row_mask:0xf bank_mask:0x3 bound_ctrl:1
	v_add_f32_dpp v38, v39, v39 row_ror:8 row_mask:0xf bank_mask:0xc bound_ctrl:1
	ds_read_b128 v[66:69], v2 offset:40192
	ds_read_b128 v[70:73], v2 offset:40448
	v_add_f32_dpp v38, v38, v38 row_half_mirror row_mask:0xf bank_mask:0xf bound_ctrl:1
	ds_read_b128 v[74:77], v2 offset:40704
	ds_read_b128 v[78:81], v2 offset:40960
	v_add_f32_dpp v38, v38, v38 quad_perm:[1,0,3,2] row_mask:0xf bank_mask:0xf bound_ctrl:1
	ds_read_b64 v[82:83], v3 offset:47104
	s_nop 0
	v_add_f32_dpp v38, v38, v38 quad_perm:[2,3,0,1] row_mask:0xf bank_mask:0xf bound_ctrl:1
	s_nop 1
	v_mov_b32_dpp v39, v38 row_ror:8 row_mask:0xf bank_mask:0xf bound_ctrl:1
	v_pk_mul_f32 v[38:39], v[38:39], v[40:41] op_sel:[0,1] op_sel_hi:[1,1]
	v_cvt_pk_bf16_f32 v47, v38, v39
	s_mov_b64 exec, s[2:3]
	global_store_dword v46, v47, s[14:15] offset:-4096
	s_mov_b64 exec, -1
	s_waitcnt lgkmcnt(0)
	v_pk_mul_f32 v[40:41], v[40:41], v[42:43]
	v_pk_mul_f32 v[44:45], v[82:83], v[40:41] op_sel_hi:[1,0]
	v_pk_fma_f32 v[6:7], v[44:45], v[66:67], v[6:7] op_sel_hi:[1,0,1]
	v_pk_mul_f32 v[38:39], v[6:7], v[66:67] op_sel:[0,1] op_sel_hi:[1,1]
	v_pk_fma_f32 v[8:9], v[44:45], v[68:69], v[8:9] op_sel_hi:[1,0,1]
	v_pk_fma_f32 v[38:39], v[8:9], v[68:69], v[38:39] op_sel:[0,1,0] op_sel_hi:[1,1,1]
	v_pk_fma_f32 v[10:11], v[44:45], v[70:71], v[10:11] op_sel_hi:[1,0,1]
	v_pk_fma_f32 v[38:39], v[10:11], v[70:71], v[38:39] op_sel:[0,1,0] op_sel_hi:[1,1,1]
	v_pk_fma_f32 v[12:13], v[44:45], v[72:73], v[12:13] op_sel_hi:[1,0,1]
	v_pk_fma_f32 v[38:39], v[12:13], v[72:73], v[38:39] op_sel:[0,1,0] op_sel_hi:[1,1,1]
	v_pk_fma_f32 v[14:15], v[44:45], v[74:75], v[14:15] op_sel_hi:[1,0,1]
	v_pk_fma_f32 v[38:39], v[14:15], v[74:75], v[38:39] op_sel:[0,1,0] op_sel_hi:[1,1,1]
	v_pk_fma_f32 v[16:17], v[44:45], v[76:77], v[16:17] op_sel_hi:[1,0,1]
	v_pk_fma_f32 v[38:39], v[16:17], v[76:77], v[38:39] op_sel:[0,1,0] op_sel_hi:[1,1,1]
	v_pk_fma_f32 v[18:19], v[44:45], v[78:79], v[18:19] op_sel_hi:[1,0,1]
	v_pk_fma_f32 v[38:39], v[18:19], v[78:79], v[38:39] op_sel:[0,1,0] op_sel_hi:[1,1,1]
	v_pk_fma_f32 v[20:21], v[44:45], v[80:81], v[20:21] op_sel_hi:[1,0,1]
	v_pk_fma_f32 v[38:39], v[20:21], v[80:81], v[38:39] op_sel:[0,1,0] op_sel_hi:[1,1,1]
	s_add_u32 s14, s14, 0x1000
	s_addc_u32 s15, s15, 0
	v_add_f32_dpp v38, v38, v38 row_ror:8 row_mask:0xf bank_mask:0x3 bound_ctrl:1
	v_add_f32_dpp v38, v39, v39 row_ror:8 row_mask:0xf bank_mask:0xc bound_ctrl:1
	ds_read_b128 v[48:51], v2 offset:57600
	ds_read_b128 v[52:55], v2 offset:57856
	v_add_f32_dpp v38, v38, v38 row_half_mirror row_mask:0xf bank_mask:0xf bound_ctrl:1
	ds_read_b128 v[56:59], v2 offset:58112
	ds_read_b128 v[60:63], v2 offset:58368
	v_add_f32_dpp v38, v38, v38 quad_perm:[1,0,3,2] row_mask:0xf bank_mask:0xf bound_ctrl:1
	ds_read_b64 v[64:65], v23 offset:37120
	s_nop 0
	v_add_f32_dpp v38, v38, v38 quad_perm:[2,3,0,1] row_mask:0xf bank_mask:0xf bound_ctrl:1
	s_nop 1
	v_mov_b32_dpp v39, v38 row_ror:8 row_mask:0xf bank_mask:0xf bound_ctrl:1
	v_pk_mul_f32 v[38:39], v[38:39], v[40:41] op_sel:[0,1] op_sel_hi:[1,1]
	v_cvt_pk_bf16_f32 v47, v38, v39
	s_mov_b64 exec, s[2:3]
	global_store_dword v46, v47, s[14:15] offset:-4096
	s_mov_b64 exec, -1
	s_waitcnt vmcnt(8)
	v_lshlrev_b32_e32 v108, 16, v84
	v_lshlrev_b32_e32 v109, 16, v85
	v_and_b32_e32 v110, s17, v84
	v_and_b32_e32 v111, s17, v85
	v_lshlrev_b32_e32 v112, 16, v86
	v_lshlrev_b32_e32 v113, 16, v87
	v_and_b32_e32 v114, s17, v86
	v_and_b32_e32 v115, s17, v87
	v_lshlrev_b32_e32 v116, 16, v88
	v_and_b32_e32 v117, s17, v88
	ds_write_b128 v29, v[108:111] offset:256
	ds_write_b128 v29, v[112:115] offset:8448
	ds_write_b64 v30, v[90:91] offset:256
	ds_write_b64 v31, v[116:117] offset:256
	s_add_i32 s16, s16, 8
	s_waitcnt lgkmcnt(0)
	s_barrier
	s_cmpk_lt_u32 s16, 0x800
	s_cbranch_scc0 .Lret2_done
	global_load_dword v84, v32, s[10:11]
	global_load_dword v85, v32, s[10:11] offset:-1024
	global_load_dword v86, v33, s[10:11]
	global_load_dword v87, v33, s[10:11] offset:-1024
	global_load_dword v88, v34, s[10:11]
	global_load_dword v90, v35, s[12:13]
	global_load_dword v91, v35, s[12:13] offset:4
	s_add_u32 s10, s10, 0x18000
	s_addc_u32 s11, s11, 0
	s_add_u32 s12, s12, 0x4000
	s_addc_u32 s13, s13, 0
	s_waitcnt lgkmcnt(0)
	v_pk_mul_f32 v[40:41], v[40:41], v[42:43]
	v_rcp_f32_e32 v40, v41
	s_nop 0
	v_pk_mul_f32 v[44:45], v[64:65], v[40:41] op_sel_hi:[1,0]
	v_pk_fma_f32 v[6:7], v[44:45], v[48:49], v[6:7] op_sel_hi:[1,0,1]
	v_pk_mul_f32 v[38:39], v[6:7], v[48:49] op_sel:[0,1] op_sel_hi:[1,1]
	v_pk_fma_f32 v[8:9], v[44:45], v[50:51], v[8:9] op_sel_hi:[1,0,1]
	v_pk_fma_f32 v[38:39], v[8:9], v[50:51], v[38:39] op_sel:[0,1,0] op_sel_hi:[1,1,1]
	v_pk_fma_f32 v[10:11], v[44:45], v[52:53], v[10:11] op_sel_hi:[1,0,1]
	v_pk_fma_f32 v[38:39], v[10:11], v[52:53], v[38:39] op_sel:[0,1,0] op_sel_hi:[1,1,1]
	v_pk_fma_f32 v[12:13], v[44:45], v[54:55], v[12:13] op_sel_hi:[1,0,1]
	v_pk_fma_f32 v[38:39], v[12:13], v[54:55], v[38:39] op_sel:[0,1,0] op_sel_hi:[1,1,1]
	v_pk_fma_f32 v[14:15], v[44:45], v[56:57], v[14:15] op_sel_hi:[1,0,1]
	v_pk_fma_f32 v[38:39], v[14:15], v[56:57], v[38:39] op_sel:[0,1,0] op_sel_hi:[1,1,1]
	v_pk_fma_f32 v[16:17], v[44:45], v[58:59], v[16:17] op_sel_hi:[1,0,1]
	v_pk_fma_f32 v[38:39], v[16:17], v[58:59], v[38:39] op_sel:[0,1,0] op_sel_hi:[1,1,1]
	v_pk_fma_f32 v[18:19], v[44:45], v[60:61], v[18:19] op_sel_hi:[1,0,1]
	v_pk_fma_f32 v[38:39], v[18:19], v[60:61], v[38:39] op_sel:[0,1,0] op_sel_hi:[1,1,1]
	v_pk_fma_f32 v[20:21], v[44:45], v[62:63], v[20:21] op_sel_hi:[1,0,1]
	v_pk_fma_f32 v[38:39], v[20:21], v[62:63], v[38:39] op_sel:[0,1,0] op_sel_hi:[1,1,1]
	s_add_u32 s14, s14, 0x1000
	s_addc_u32 s15, s15, 0
	v_add_f32_dpp v38, v38, v38 row_ror:8 row_mask:0xf bank_mask:0x3 bound_ctrl:1
	v_add_f32_dpp v38, v39, v39 row_ror:8 row_mask:0xf bank_mask:0xc bound_ctrl:1
	ds_read_b128 v[66:69], v2 offset:58624
	ds_read_b128 v[70:73], v2 offset:58880
	v_add_f32_dpp v38, v38, v38 row_half_mirror row_mask:0xf bank_mask:0xf bound_ctrl:1
	ds_read_b128 v[74:77], v2 offset:59136
	ds_read_b128 v[78:81], v2 offset:59392
	v_add_f32_dpp v38, v38, v38 quad_perm:[1,0,3,2] row_mask:0xf bank_mask:0xf bound_ctrl:1
	ds_read_b64 v[82:83], v23 offset:37376
	s_nop 0
	v_add_f32_dpp v38, v38, v38 quad_perm:[2,3,0,1] row_mask:0xf bank_mask:0xf bound_ctrl:1
	s_nop 1
	v_mov_b32_dpp v39, v38 row_ror:8 row_mask:0xf bank_mask:0xf bound_ctrl:1
	v_pk_mul_f32 v[38:39], v[38:39], v[40:41] op_sel:[0,1] op_sel_hi:[1,1]
	v_cvt_pk_bf16_f32 v47, v38, v39
	s_mov_b64 exec, s[2:3]
	global_store_dword v46, v47, s[14:15] offset:-4096
	s_mov_b64 exec, -1
	s_waitcnt lgkmcnt(0)
	v_pk_mul_f32 v[40:41], v[40:41], v[42:43]
	v_pk_mul_f32 v[44:45], v[82:83], v[40:41] op_sel_hi:[1,0]
	v_pk_fma_f32 v[6:7], v[44:45], v[66:67], v[6:7] op_sel_hi:[1,0,1]
	v_pk_mul_f32 v[38:39], v[6:7], v[66:67] op_sel:[0,1] op_sel_hi:[1,1]
	v_pk_fma_f32 v[8:9], v[44:45], v[68:69], v[8:9] op_sel_hi:[1,0,1]
	v_pk_fma_f32 v[38:39], v[8:9], v[68:69], v[38:39] op_sel:[0,1,0] op_sel_hi:[1,1,1]
	v_pk_fma_f32 v[10:11], v[44:45], v[70:71], v[10:11] op_sel_hi:[1,0,1]
	v_pk_fma_f32 v[38:39], v[10:11], v[70:71], v[38:39] op_sel:[0,1,0] op_sel_hi:[1,1,1]
	v_pk_fma_f32 v[12:13], v[44:45], v[72:73], v[12:13] op_sel_hi:[1,0,1]
	v_pk_fma_f32 v[38:39], v[12:13], v[72:73], v[38:39] op_sel:[0,1,0] op_sel_hi:[1,1,1]
	v_pk_fma_f32 v[14:15], v[44:45], v[74:75], v[14:15] op_sel_hi:[1,0,1]
	v_pk_fma_f32 v[38:39], v[14:15], v[74:75], v[38:39] op_sel:[0,1,0] op_sel_hi:[1,1,1]
	v_pk_fma_f32 v[16:17], v[44:45], v[76:77], v[16:17] op_sel_hi:[1,0,1]
	v_pk_fma_f32 v[38:39], v[16:17], v[76:77], v[38:39] op_sel:[0,1,0] op_sel_hi:[1,1,1]
	v_pk_fma_f32 v[18:19], v[44:45], v[78:79], v[18:19] op_sel_hi:[1,0,1]
	v_pk_fma_f32 v[38:39], v[18:19], v[78:79], v[38:39] op_sel:[0,1,0] op_sel_hi:[1,1,1]
	v_pk_fma_f32 v[20:21], v[44:45], v[80:81], v[20:21] op_sel_hi:[1,0,1]
	v_pk_fma_f32 v[38:39], v[20:21], v[80:81], v[38:39] op_sel:[0,1,0] op_sel_hi:[1,1,1]
	s_add_u32 s14, s14, 0x1000
	s_addc_u32 s15, s15, 0
	v_add_f32_dpp v38, v38, v38 row_ror:8 row_mask:0xf bank_mask:0x3 bound_ctrl:1
	v_add_f32_dpp v38, v39, v39 row_ror:8 row_mask:0xf bank_mask:0xc bound_ctrl:1
	ds_read_b128 v[48:51], v2 offset:59648
	ds_read_b128 v[52:55], v2 offset:59904
	v_add_f32_dpp v38, v38, v38 row_half_mirror row_mask:0xf bank_mask:0xf bound_ctrl:1
	ds_read_b128 v[56:59], v2 offset:60160
	ds_read_b128 v[60:63], v2 offset:60416
	v_add_f32_dpp v38, v38, v38 quad_perm:[1,0,3,2] row_mask:0xf bank_mask:0xf bound_ctrl:1
	ds_read_b64 v[64:65], v23 offset:37632
	s_nop 0
	v_add_f32_dpp v38, v38, v38 quad_perm:[2,3,0,1] row_mask:0xf bank_mask:0xf bound_ctrl:1
	s_nop 1
	v_mov_b32_dpp v39, v38 row_ror:8 row_mask:0xf bank_mask:0xf bound_ctrl:1
	v_pk_mul_f32 v[38:39], v[38:39], v[40:41] op_sel:[0,1] op_sel_hi:[1,1]
	v_cvt_pk_bf16_f32 v47, v38, v39
	s_mov_b64 exec, s[2:3]
	global_store_dword v46, v47, s[14:15] offset:-4096
	s_mov_b64 exec, -1
	s_waitcnt lgkmcnt(0)
	v_pk_mul_f32 v[40:41], v[40:41], v[42:43]
	v_pk_mul_f32 v[44:45], v[64:65], v[40:41] op_sel_hi:[1,0]
	v_pk_fma_f32 v[6:7], v[44:45], v[48:49], v[6:7] op_sel_hi:[1,0,1]
	v_pk_mul_f32 v[38:39], v[6:7], v[48:49] op_sel:[0,1] op_sel_hi:[1,1]
	v_pk_fma_f32 v[8:9], v[44:45], v[50:51], v[8:9] op_sel_hi:[1,0,1]
	v_pk_fma_f32 v[38:39], v[8:9], v[50:51], v[38:39] op_sel:[0,1,0] op_sel_hi:[1,1,1]
	v_pk_fma_f32 v[10:11], v[44:45], v[52:53], v[10:11] op_sel_hi:[1,0,1]
	v_pk_fma_f32 v[38:39], v[10:11], v[52:53], v[38:39] op_sel:[0,1,0] op_sel_hi:[1,1,1]
	v_pk_fma_f32 v[12:13], v[44:45], v[54:55], v[12:13] op_sel_hi:[1,0,1]
	v_pk_fma_f32 v[38:39], v[12:13], v[54:55], v[38:39] op_sel:[0,1,0] op_sel_hi:[1,1,1]
	v_pk_fma_f32 v[14:15], v[44:45], v[56:57], v[14:15] op_sel_hi:[1,0,1]
	v_pk_fma_f32 v[38:39], v[14:15], v[56:57], v[38:39] op_sel:[0,1,0] op_sel_hi:[1,1,1]
	v_pk_fma_f32 v[16:17], v[44:45], v[58:59], v[16:17] op_sel_hi:[1,0,1]
	v_pk_fma_f32 v[38:39], v[16:17], v[58:59], v[38:39] op_sel:[0,1,0] op_sel_hi:[1,1,1]
	v_pk_fma_f32 v[18:19], v[44:45], v[60:61], v[18:19] op_sel_hi:[1,0,1]
	v_pk_fma_f32 v[38:39], v[18:19], v[60:61], v[38:39] op_sel:[0,1,0] op_sel_hi:[1,1,1]
	v_pk_fma_f32 v[20:21], v[44:45], v[62:63], v[20:21] op_sel_hi:[1,0,1]
	v_pk_fma_f32 v[38:39], v[20:21], v[62:63], v[38:39] op_sel:[0,1,0] op_sel_hi:[1,1,1]
	s_add_u32 s14, s14, 0x1000
	s_addc_u32 s15, s15, 0
	v_add_f32_dpp v38, v38, v38 row_ror:8 row_mask:0xf bank_mask:0x3 bound_ctrl:1
	v_add_f32_dpp v38, v39, v39 row_ror:8 row_mask:0xf bank_mask:0xc bound_ctrl:1
	ds_read_b128 v[66:69], v2 offset:60672
	ds_read_b128 v[70:73], v2 offset:60928
	v_add_f32_dpp v38, v38, v38 row_half_mirror row_mask:0xf bank_mask:0xf bound_ctrl:1
	ds_read_b128 v[74:77], v2 offset:61184
	ds_read_b128 v[78:81], v2 offset:61440
	v_add_f32_dpp v38, v38, v38 quad_perm:[1,0,3,2] row_mask:0xf bank_mask:0xf bound_ctrl:1
	ds_read_b64 v[82:83], v23 offset:37888
	s_nop 0
	v_add_f32_dpp v38, v38, v38 quad_perm:[2,3,0,1] row_mask:0xf bank_mask:0xf bound_ctrl:1
	s_nop 1
	v_mov_b32_dpp v39, v38 row_ror:8 row_mask:0xf bank_mask:0xf bound_ctrl:1
	v_pk_mul_f32 v[38:39], v[38:39], v[40:41] op_sel:[0,1] op_sel_hi:[1,1]
	v_cvt_pk_bf16_f32 v47, v38, v39
	s_mov_b64 exec, s[2:3]
	global_store_dword v46, v47, s[14:15] offset:-4096
	s_mov_b64 exec, -1
	s_waitcnt lgkmcnt(0)
	v_pk_mul_f32 v[40:41], v[40:41], v[42:43]
	v_pk_mul_f32 v[44:45], v[82:83], v[40:41] op_sel_hi:[1,0]
	v_pk_fma_f32 v[6:7], v[44:45], v[66:67], v[6:7] op_sel_hi:[1,0,1]
	v_pk_mul_f32 v[38:39], v[6:7], v[66:67] op_sel:[0,1] op_sel_hi:[1,1]
	v_pk_fma_f32 v[8:9], v[44:45], v[68:69], v[8:9] op_sel_hi:[1,0,1]
	v_pk_fma_f32 v[38:39], v[8:9], v[68:69], v[38:39] op_sel:[0,1,0] op_sel_hi:[1,1,1]
	v_pk_fma_f32 v[10:11], v[44:45], v[70:71], v[10:11] op_sel_hi:[1,0,1]
	v_pk_fma_f32 v[38:39], v[10:11], v[70:71], v[38:39] op_sel:[0,1,0] op_sel_hi:[1,1,1]
	v_pk_fma_f32 v[12:13], v[44:45], v[72:73], v[12:13] op_sel_hi:[1,0,1]
	v_pk_fma_f32 v[38:39], v[12:13], v[72:73], v[38:39] op_sel:[0,1,0] op_sel_hi:[1,1,1]
	v_pk_fma_f32 v[14:15], v[44:45], v[74:75], v[14:15] op_sel_hi:[1,0,1]
	v_pk_fma_f32 v[38:39], v[14:15], v[74:75], v[38:39] op_sel:[0,1,0] op_sel_hi:[1,1,1]
	v_pk_fma_f32 v[16:17], v[44:45], v[76:77], v[16:17] op_sel_hi:[1,0,1]
	v_pk_fma_f32 v[38:39], v[16:17], v[76:77], v[38:39] op_sel:[0,1,0] op_sel_hi:[1,1,1]
	v_pk_fma_f32 v[18:19], v[44:45], v[78:79], v[18:19] op_sel_hi:[1,0,1]
	v_pk_fma_f32 v[38:39], v[18:19], v[78:79], v[38:39] op_sel:[0,1,0] op_sel_hi:[1,1,1]
	v_pk_fma_f32 v[20:21], v[44:45], v[80:81], v[20:21] op_sel_hi:[1,0,1]
	v_pk_fma_f32 v[38:39], v[20:21], v[80:81], v[38:39] op_sel:[0,1,0] op_sel_hi:[1,1,1]
	s_add_u32 s14, s14, 0x1000
	s_addc_u32 s15, s15, 0
	v_add_f32_dpp v38, v38, v38 row_ror:8 row_mask:0xf bank_mask:0x3 bound_ctrl:1
	v_add_f32_dpp v38, v39, v39 row_ror:8 row_mask:0xf bank_mask:0xc bound_ctrl:1
	ds_read_b128 v[48:51], v2 offset:61696
	ds_read_b128 v[52:55], v2 offset:61952
	v_add_f32_dpp v38, v38, v38 row_half_mirror row_mask:0xf bank_mask:0xf bound_ctrl:1
	ds_read_b128 v[56:59], v2 offset:62208
	ds_read_b128 v[60:63], v2 offset:62464
	v_add_f32_dpp v38, v38, v38 quad_perm:[1,0,3,2] row_mask:0xf bank_mask:0xf bound_ctrl:1
	ds_read_b64 v[64:65], v23 offset:38144
	s_nop 0
	v_add_f32_dpp v38, v38, v38 quad_perm:[2,3,0,1] row_mask:0xf bank_mask:0xf bound_ctrl:1
	s_nop 1
	v_mov_b32_dpp v39, v38 row_ror:8 row_mask:0xf bank_mask:0xf bound_ctrl:1
	v_pk_mul_f32 v[38:39], v[38:39], v[40:41] op_sel:[0,1] op_sel_hi:[1,1]
	v_cvt_pk_bf16_f32 v47, v38, v39
	s_mov_b64 exec, s[2:3]
	global_store_dword v46, v47, s[14:15] offset:-4096
	s_mov_b64 exec, -1
	s_waitcnt lgkmcnt(0)
	v_pk_mul_f32 v[40:41], v[40:41], v[42:43]
	v_pk_mul_f32 v[44:45], v[64:65], v[40:41] op_sel_hi:[1,0]
	v_pk_fma_f32 v[6:7], v[44:45], v[48:49], v[6:7] op_sel_hi:[1,0,1]
	v_pk_mul_f32 v[38:39], v[6:7], v[48:49] op_sel:[0,1] op_sel_hi:[1,1]
	v_pk_fma_f32 v[8:9], v[44:45], v[50:51], v[8:9] op_sel_hi:[1,0,1]
	v_pk_fma_f32 v[38:39], v[8:9], v[50:51], v[38:39] op_sel:[0,1,0] op_sel_hi:[1,1,1]
	v_pk_fma_f32 v[10:11], v[44:45], v[52:53], v[10:11] op_sel_hi:[1,0,1]
	v_pk_fma_f32 v[38:39], v[10:11], v[52:53], v[38:39] op_sel:[0,1,0] op_sel_hi:[1,1,1]
	v_pk_fma_f32 v[12:13], v[44:45], v[54:55], v[12:13] op_sel_hi:[1,0,1]
	v_pk_fma_f32 v[38:39], v[12:13], v[54:55], v[38:39] op_sel:[0,1,0] op_sel_hi:[1,1,1]
	v_pk_fma_f32 v[14:15], v[44:45], v[56:57], v[14:15] op_sel_hi:[1,0,1]
	v_pk_fma_f32 v[38:39], v[14:15], v[56:57], v[38:39] op_sel:[0,1,0] op_sel_hi:[1,1,1]
	v_pk_fma_f32 v[16:17], v[44:45], v[58:59], v[16:17] op_sel_hi:[1,0,1]
	v_pk_fma_f32 v[38:39], v[16:17], v[58:59], v[38:39] op_sel:[0,1,0] op_sel_hi:[1,1,1]
	v_pk_fma_f32 v[18:19], v[44:45], v[60:61], v[18:19] op_sel_hi:[1,0,1]
	v_pk_fma_f32 v[38:39], v[18:19], v[60:61], v[38:39] op_sel:[0,1,0] op_sel_hi:[1,1,1]
	v_pk_fma_f32 v[20:21], v[44:45], v[62:63], v[20:21] op_sel_hi:[1,0,1]
	v_pk_fma_f32 v[38:39], v[20:21], v[62:63], v[38:39] op_sel:[0,1,0] op_sel_hi:[1,1,1]
	s_add_u32 s14, s14, 0x1000
	s_addc_u32 s15, s15, 0
	v_add_f32_dpp v38, v38, v38 row_ror:8 row_mask:0xf bank_mask:0x3 bound_ctrl:1
	v_add_f32_dpp v38, v39, v39 row_ror:8 row_mask:0xf bank_mask:0xc bound_ctrl:1
	ds_read_b128 v[66:69], v2 offset:62720
	ds_read_b128 v[70:73], v2 offset:62976
	v_add_f32_dpp v38, v38, v38 row_half_mirror row_mask:0xf bank_mask:0xf bound_ctrl:1
	ds_read_b128 v[74:77], v2 offset:63232
	ds_read_b128 v[78:81], v2 offset:63488
	v_add_f32_dpp v38, v38, v38 quad_perm:[1,0,3,2] row_mask:0xf bank_mask:0xf bound_ctrl:1
	ds_read_b64 v[82:83], v23 offset:38400
	s_nop 0
	v_add_f32_dpp v38, v38, v38 quad_perm:[2,3,0,1] row_mask:0xf bank_mask:0xf bound_ctrl:1
	s_nop 1
	v_mov_b32_dpp v39, v38 row_ror:8 row_mask:0xf bank_mask:0xf bound_ctrl:1
	v_pk_mul_f32 v[38:39], v[38:39], v[40:41] op_sel:[0,1] op_sel_hi:[1,1]
	v_cvt_pk_bf16_f32 v47, v38, v39
	s_mov_b64 exec, s[2:3]
	global_store_dword v46, v47, s[14:15] offset:-4096
	s_mov_b64 exec, -1
	s_waitcnt lgkmcnt(0)
	v_pk_mul_f32 v[40:41], v[40:41], v[42:43]
	v_pk_mul_f32 v[44:45], v[82:83], v[40:41] op_sel_hi:[1,0]
	v_pk_fma_f32 v[6:7], v[44:45], v[66:67], v[6:7] op_sel_hi:[1,0,1]
	v_pk_mul_f32 v[38:39], v[6:7], v[66:67] op_sel:[0,1] op_sel_hi:[1,1]
	v_pk_fma_f32 v[8:9], v[44:45], v[68:69], v[8:9] op_sel_hi:[1,0,1]
	v_pk_fma_f32 v[38:39], v[8:9], v[68:69], v[38:39] op_sel:[0,1,0] op_sel_hi:[1,1,1]
	v_pk_fma_f32 v[10:11], v[44:45], v[70:71], v[10:11] op_sel_hi:[1,0,1]
	v_pk_fma_f32 v[38:39], v[10:11], v[70:71], v[38:39] op_sel:[0,1,0] op_sel_hi:[1,1,1]
	v_pk_fma_f32 v[12:13], v[44:45], v[72:73], v[12:13] op_sel_hi:[1,0,1]
	v_pk_fma_f32 v[38:39], v[12:13], v[72:73], v[38:39] op_sel:[0,1,0] op_sel_hi:[1,1,1]
	v_pk_fma_f32 v[14:15], v[44:45], v[74:75], v[14:15] op_sel_hi:[1,0,1]
	v_pk_fma_f32 v[38:39], v[14:15], v[74:75], v[38:39] op_sel:[0,1,0] op_sel_hi:[1,1,1]
	v_pk_fma_f32 v[16:17], v[44:45], v[76:77], v[16:17] op_sel_hi:[1,0,1]
	v_pk_fma_f32 v[38:39], v[16:17], v[76:77], v[38:39] op_sel:[0,1,0] op_sel_hi:[1,1,1]
	v_pk_fma_f32 v[18:19], v[44:45], v[78:79], v[18:19] op_sel_hi:[1,0,1]
	v_pk_fma_f32 v[38:39], v[18:19], v[78:79], v[38:39] op_sel:[0,1,0] op_sel_hi:[1,1,1]
	v_pk_fma_f32 v[20:21], v[44:45], v[80:81], v[20:21] op_sel_hi:[1,0,1]
	v_pk_fma_f32 v[38:39], v[20:21], v[80:81], v[38:39] op_sel:[0,1,0] op_sel_hi:[1,1,1]
	s_add_u32 s14, s14, 0x1000
	s_addc_u32 s15, s15, 0
	v_add_f32_dpp v38, v38, v38 row_ror:8 row_mask:0xf bank_mask:0x3 bound_ctrl:1
	v_add_f32_dpp v38, v39, v39 row_ror:8 row_mask:0xf bank_mask:0xc bound_ctrl:1
	ds_read_b128 v[48:51], v2 offset:63744
	ds_read_b128 v[52:55], v2 offset:64000
	v_add_f32_dpp v38, v38, v38 row_half_mirror row_mask:0xf bank_mask:0xf bound_ctrl:1
	ds_read_b128 v[56:59], v2 offset:64256
	ds_read_b128 v[60:63], v2 offset:64512
	v_add_f32_dpp v38, v38, v38 quad_perm:[1,0,3,2] row_mask:0xf bank_mask:0xf bound_ctrl:1
	ds_read_b64 v[64:65], v23 offset:38656
	s_nop 0
	v_add_f32_dpp v38, v38, v38 quad_perm:[2,3,0,1] row_mask:0xf bank_mask:0xf bound_ctrl:1
	s_nop 1
	v_mov_b32_dpp v39, v38 row_ror:8 row_mask:0xf bank_mask:0xf bound_ctrl:1
	v_pk_mul_f32 v[38:39], v[38:39], v[40:41] op_sel:[0,1] op_sel_hi:[1,1]
	v_cvt_pk_bf16_f32 v47, v38, v39
	s_mov_b64 exec, s[2:3]
	global_store_dword v46, v47, s[14:15] offset:-4096
	s_mov_b64 exec, -1
	s_waitcnt lgkmcnt(0)
	v_pk_mul_f32 v[40:41], v[40:41], v[42:43]
	v_pk_mul_f32 v[44:45], v[64:65], v[40:41] op_sel_hi:[1,0]
	v_pk_fma_f32 v[6:7], v[44:45], v[48:49], v[6:7] op_sel_hi:[1,0,1]
	v_pk_mul_f32 v[38:39], v[6:7], v[48:49] op_sel:[0,1] op_sel_hi:[1,1]
	v_pk_fma_f32 v[8:9], v[44:45], v[50:51], v[8:9] op_sel_hi:[1,0,1]
	v_pk_fma_f32 v[38:39], v[8:9], v[50:51], v[38:39] op_sel:[0,1,0] op_sel_hi:[1,1,1]
	v_pk_fma_f32 v[10:11], v[44:45], v[52:53], v[10:11] op_sel_hi:[1,0,1]
	v_pk_fma_f32 v[38:39], v[10:11], v[52:53], v[38:39] op_sel:[0,1,0] op_sel_hi:[1,1,1]
	v_pk_fma_f32 v[12:13], v[44:45], v[54:55], v[12:13] op_sel_hi:[1,0,1]
	v_pk_fma_f32 v[38:39], v[12:13], v[54:55], v[38:39] op_sel:[0,1,0] op_sel_hi:[1,1,1]
	v_pk_fma_f32 v[14:15], v[44:45], v[56:57], v[14:15] op_sel_hi:[1,0,1]
	v_pk_fma_f32 v[38:39], v[14:15], v[56:57], v[38:39] op_sel:[0,1,0] op_sel_hi:[1,1,1]
	v_pk_fma_f32 v[16:17], v[44:45], v[58:59], v[16:17] op_sel_hi:[1,0,1]
	v_pk_fma_f32 v[38:39], v[16:17], v[58:59], v[38:39] op_sel:[0,1,0] op_sel_hi:[1,1,1]
	v_pk_fma_f32 v[18:19], v[44:45], v[60:61], v[18:19] op_sel_hi:[1,0,1]
	v_pk_fma_f32 v[38:39], v[18:19], v[60:61], v[38:39] op_sel:[0,1,0] op_sel_hi:[1,1,1]
	v_pk_fma_f32 v[20:21], v[44:45], v[62:63], v[20:21] op_sel_hi:[1,0,1]
	v_pk_fma_f32 v[38:39], v[20:21], v[62:63], v[38:39] op_sel:[0,1,0] op_sel_hi:[1,1,1]
	s_add_u32 s14, s14, 0x1000
	s_addc_u32 s15, s15, 0
	v_add_f32_dpp v38, v38, v38 row_ror:8 row_mask:0xf bank_mask:0x3 bound_ctrl:1
	v_add_f32_dpp v38, v39, v39 row_ror:8 row_mask:0xf bank_mask:0xc bound_ctrl:1
	ds_read_b128 v[66:69], v2 offset:64768
	ds_read_b128 v[70:73], v2 offset:65024
	v_add_f32_dpp v38, v38, v38 row_half_mirror row_mask:0xf bank_mask:0xf bound_ctrl:1
	ds_read_b128 v[74:77], v2 offset:65280
	ds_read_b128 v[78:81], v22 offset:32768
	v_add_f32_dpp v38, v38, v38 quad_perm:[1,0,3,2] row_mask:0xf bank_mask:0xf bound_ctrl:1
	ds_read_b64 v[82:83], v23 offset:38912
	s_nop 0
	v_add_f32_dpp v38, v38, v38 quad_perm:[2,3,0,1] row_mask:0xf bank_mask:0xf bound_ctrl:1
	s_nop 1
	v_mov_b32_dpp v39, v38 row_ror:8 row_mask:0xf bank_mask:0xf bound_ctrl:1
	v_pk_mul_f32 v[38:39], v[38:39], v[40:41] op_sel:[0,1] op_sel_hi:[1,1]
	v_cvt_pk_bf16_f32 v47, v38, v39
	s_mov_b64 exec, s[2:3]
	global_store_dword v46, v47, s[14:15] offset:-4096
	s_mov_b64 exec, -1
	s_waitcnt lgkmcnt(0)
	v_pk_mul_f32 v[40:41], v[40:41], v[42:43]
	v_pk_mul_f32 v[44:45], v[82:83], v[40:41] op_sel_hi:[1,0]
	v_pk_fma_f32 v[6:7], v[44:45], v[66:67], v[6:7] op_sel_hi:[1,0,1]
	v_pk_mul_f32 v[38:39], v[6:7], v[66:67] op_sel:[0,1] op_sel_hi:[1,1]
	v_pk_fma_f32 v[8:9], v[44:45], v[68:69], v[8:9] op_sel_hi:[1,0,1]
	v_pk_fma_f32 v[38:39], v[8:9], v[68:69], v[38:39] op_sel:[0,1,0] op_sel_hi:[1,1,1]
	v_pk_fma_f32 v[10:11], v[44:45], v[70:71], v[10:11] op_sel_hi:[1,0,1]
	v_pk_fma_f32 v[38:39], v[10:11], v[70:71], v[38:39] op_sel:[0,1,0] op_sel_hi:[1,1,1]
	v_pk_fma_f32 v[12:13], v[44:45], v[72:73], v[12:13] op_sel_hi:[1,0,1]
	v_pk_fma_f32 v[38:39], v[12:13], v[72:73], v[38:39] op_sel:[0,1,0] op_sel_hi:[1,1,1]
	v_pk_fma_f32 v[14:15], v[44:45], v[74:75], v[14:15] op_sel_hi:[1,0,1]
	v_pk_fma_f32 v[38:39], v[14:15], v[74:75], v[38:39] op_sel:[0,1,0] op_sel_hi:[1,1,1]
	v_pk_fma_f32 v[16:17], v[44:45], v[76:77], v[16:17] op_sel_hi:[1,0,1]
	v_pk_fma_f32 v[38:39], v[16:17], v[76:77], v[38:39] op_sel:[0,1,0] op_sel_hi:[1,1,1]
	v_pk_fma_f32 v[18:19], v[44:45], v[78:79], v[18:19] op_sel_hi:[1,0,1]
	v_pk_fma_f32 v[38:39], v[18:19], v[78:79], v[38:39] op_sel:[0,1,0] op_sel_hi:[1,1,1]
	v_pk_fma_f32 v[20:21], v[44:45], v[80:81], v[20:21] op_sel_hi:[1,0,1]
	v_pk_fma_f32 v[38:39], v[20:21], v[80:81], v[38:39] op_sel:[0,1,0] op_sel_hi:[1,1,1]
	s_add_u32 s14, s14, 0x1000
	s_addc_u32 s15, s15, 0
	v_add_f32_dpp v38, v38, v38 row_ror:8 row_mask:0xf bank_mask:0x3 bound_ctrl:1
	v_add_f32_dpp v38, v39, v39 row_ror:8 row_mask:0xf bank_mask:0xc bound_ctrl:1
	ds_read_b128 v[48:51], v2 offset:8448
	ds_read_b128 v[52:55], v2 offset:8704
	v_add_f32_dpp v38, v38, v38 row_half_mirror row_mask:0xf bank_mask:0xf bound_ctrl:1
	ds_read_b128 v[56:59], v2 offset:8960
	ds_read_b128 v[60:63], v2 offset:9216
	v_add_f32_dpp v38, v38, v38 quad_perm:[1,0,3,2] row_mask:0xf bank_mask:0xf bound_ctrl:1
	ds_read_b64 v[64:65], v3 offset:20736
	s_nop 0
	v_add_f32_dpp v38, v38, v38 quad_perm:[2,3,0,1] row_mask:0xf bank_mask:0xf bound_ctrl:1
	s_nop 1
	v_mov_b32_dpp v39, v38 row_ror:8 row_mask:0xf bank_mask:0xf bound_ctrl:1
	v_pk_mul_f32 v[38:39], v[38:39], v[40:41] op_sel:[0,1] op_sel_hi:[1,1]
	v_cvt_pk_bf16_f32 v47, v38, v39
	s_mov_b64 exec, s[2:3]
	global_store_dword v46, v47, s[14:15] offset:-4096
	s_mov_b64 exec, -1
	s_waitcnt vmcnt(8)
	v_lshlrev_b32_e32 v108, 16, v84
	v_lshlrev_b32_e32 v109, 16, v85
	v_and_b32_e32 v110, s17, v84
	v_and_b32_e32 v111, s17, v85
	v_lshlrev_b32_e32 v112, 16, v86
	v_lshlrev_b32_e32 v113, 16, v87
	v_and_b32_e32 v114, s17, v86
	v_and_b32_e32 v115, s17, v87
	v_lshlrev_b32_e32 v116, 16, v88
	v_and_b32_e32 v117, s17, v88
	ds_write_b128 v29, v[108:111] offset:24832
	ds_write_b128 v29, v[112:115] offset:33024
	ds_write_b64 v30, v[90:91] offset:24832
	ds_write_b64 v31, v[116:117] offset:24832
	s_add_i32 s16, s16, 8
	s_waitcnt lgkmcnt(0)
	s_barrier
	s_cmpk_lt_u32 s16, 0x800
	s_cbranch_scc1 .Lret2_loop
.Lret2_done:
	v_readlane_b32 s0, v255, 18
	v_readlane_b32 s1, v255, 19
	s_load_dwordx2 s[2:3], s[0:1], 0xe8
	s_lshr_b32 s0, s23, 5
	s_lshl_b32 s4, s0, 17
	s_add_u32 s4, s4, 78430464
	v_lshl_add_u32 v42, v46, 1, v4
	s_waitcnt lgkmcnt(0)
	s_add_u32 s2, s2, s4
	s_addc_u32 s3, s3, 0
	v_pk_mul_f32 v[6:7], v[6:7], v[40:41] op_sel:[0,1] op_sel_hi:[1,1]
	v_pk_mul_f32 v[8:9], v[8:9], v[40:41] op_sel:[0,1] op_sel_hi:[1,1]
	v_pk_mul_f32 v[10:11], v[10:11], v[40:41] op_sel:[0,1] op_sel_hi:[1,1]
	v_pk_mul_f32 v[12:13], v[12:13], v[40:41] op_sel:[0,1] op_sel_hi:[1,1]
	v_pk_mul_f32 v[14:15], v[14:15], v[40:41] op_sel:[0,1] op_sel_hi:[1,1]
	v_pk_mul_f32 v[16:17], v[16:17], v[40:41] op_sel:[0,1] op_sel_hi:[1,1]
	v_pk_mul_f32 v[18:19], v[18:19], v[40:41] op_sel:[0,1] op_sel_hi:[1,1]
	v_pk_mul_f32 v[20:21], v[20:21], v[40:41] op_sel:[0,1] op_sel_hi:[1,1]
	global_store_dwordx2 v42, v[6:7], s[2:3] offset:0
	global_store_dwordx2 v42, v[8:9], s[2:3] offset:1024
	global_store_dwordx2 v42, v[10:11], s[2:3] offset:2048
	global_store_dwordx2 v42, v[12:13], s[2:3] offset:3072
	s_add_u32 s2, s2, 0x1000
	s_addc_u32 s3, s3, 0
	global_store_dwordx2 v42, v[14:15], s[2:3] offset:0
	global_store_dwordx2 v42, v[16:17], s[2:3] offset:1024
	global_store_dwordx2 v42, v[18:19], s[2:3] offset:2048
	global_store_dwordx2 v42, v[20:21], s[2:3] offset:3072
	s_add_i32 s23, s23, s19
	s_waitcnt vmcnt(0)
	s_cmpk_lt_i32 s23, 0x400
	s_cbranch_scc1 .Lret2_item
	s_branch .LBB0_57

.Lgla2_item:
	s_lshr_b32 s0, s18, 5
	s_and_b32 s1, s18, 31
	s_lshr_b32 s2, s0, 2
	s_and_b32 s3, s0, 3
	s_lshl_b32 s4, s1, 4
	v_lshl_add_u32 v46, v5, 2, s4
	s_and_b32 s4, s1, 3
	s_lshl_b32 s4, s4, 5
	v_lshl_add_u32 v3, v5, 3, s4
	s_lshl_b32 s4, s3, 8
	s_add_u32 s4, s4, 1024
	v_lshl_add_u32 v32, v198, 2, s4
	s_add_u32 s4, s4, 4096
	v_lshl_add_u32 v33, v198, 2, s4
	s_lshl_b32 s4, s3, 9
	s_and_b32 s5, s1, 28
	s_lshl_b32 s5, s5, 4
	s_add_u32 s4, s4, s5
	s_add_u32 s4, s4, 2048
	v_min_u32_e32 v42, 31, v198
	v_lshl_add_u32 v34, v42, 2, s4
	v_cmp_lt_u32_e32 vcc, 15, v198
	v_add_u32_e32 v44, 4032, v34
	s_nop 1
	v_cndmask_b32_e32 v34, v34, v44, vcc
	v_readlane_b32 s5, v255, 15
	s_mul_i32 s4, s2, 0x1800000
	s_mul_i32 s1, s5, 0x3000
	s_add_u32 s4, s4, s1
	s_add_u32 s4, s4, 0x3bc0400
	s_add_u32 s10, s8, s4
	s_addc_u32 s11, s9, 0
	s_lshl_b32 s4, s2, 22
	s_lshl_b32 s1, s5, 11
	s_add_u32 s4, s4, s1
	s_lshl_b32 s1, s3, 9
	s_add_u32 s4, s4, s1
	s_add_u32 s4, s4, 0xfd40400
	s_add_u32 s12, s8, s4
	s_addc_u32 s13, s9, 0
	s_lshl_b32 s4, s2, 23
	s_add_u32 s4, s4, s1
	s_add_u32 s4, s4, 333186048
	s_add_u32 s14, s8, s4
	s_addc_u32 s15, s9, 0
	v_mov_b32_e32 v40, 0x3db504f3
	s_movk_i32 s20, 256
	s_movk_i32 s21, 24832
	s_mov_b32 s22, 49408
	v_add_u32_e32 v26, s20, v29
	v_add_u32_e32 v27, s20, v30
	v_add_u32_e32 v28, s20, v31
	global_load_dword v110, v32, s[10:11]
	global_load_dword v111, v32, s[10:11] offset:-1024
	global_load_dword v112, v33, s[10:11]
	global_load_dword v113, v33, s[10:11] offset:-1024
	global_load_dword v114, v34, s[10:11]
	global_load_dword v116, v35, s[12:13]
	global_load_dword v117, v35, s[12:13] offset:4
	s_add_u32 s10, s10, 0x18000
	s_addc_u32 s11, s11, 0
	s_add_u32 s12, s12, 0x4000
	s_addc_u32 s13, s13, 0
	s_waitcnt vmcnt(0)
	v_lshlrev_b32_e32 v144, 16, v110
	v_lshlrev_b32_e32 v145, 16, v111
	v_and_b32_e32 v146, s17, v110
	v_and_b32_e32 v147, s17, v111
	v_lshlrev_b32_e32 v148, 16, v112
	v_lshlrev_b32_e32 v149, 16, v113
	v_and_b32_e32 v150, s17, v112
	v_and_b32_e32 v151, s17, v113
	v_lshlrev_b32_e32 v152, 16, v114
	v_and_b32_e32 v153, s17, v114
	ds_write_b128 v29, v[144:147] offset:256
	ds_write_b128 v29, v[148:151] offset:8448
	ds_write_b64 v30, v[116:117] offset:256
	ds_write_b64 v31, v[152:153] offset:256
	v_add_u32_e32 v26, s21, v29
	v_add_u32_e32 v27, s21, v30
	v_add_u32_e32 v28, s21, v31
	global_load_dword v110, v32, s[10:11]
	global_load_dword v111, v32, s[10:11] offset:-1024
	global_load_dword v112, v33, s[10:11]
	global_load_dword v113, v33, s[10:11] offset:-1024
	global_load_dword v114, v34, s[10:11]
	global_load_dword v116, v35, s[12:13]
	global_load_dword v117, v35, s[12:13] offset:4
	s_add_u32 s10, s10, 0x18000
	s_addc_u32 s11, s11, 0
	s_add_u32 s12, s12, 0x4000
	s_addc_u32 s13, s13, 0
	s_waitcnt vmcnt(0)
	v_lshlrev_b32_e32 v144, 16, v110
	v_lshlrev_b32_e32 v145, 16, v111
	v_and_b32_e32 v146, s17, v110
	v_and_b32_e32 v147, s17, v111
	v_lshlrev_b32_e32 v148, 16, v112
	v_lshlrev_b32_e32 v149, 16, v113
	v_and_b32_e32 v150, s17, v112
	v_and_b32_e32 v151, s17, v113
	v_lshlrev_b32_e32 v152, 16, v114
	v_and_b32_e32 v153, s17, v114
	ds_write_b128 v29, v[144:147] offset:24832
	ds_write_b128 v29, v[148:151] offset:33024
	ds_write_b64 v30, v[116:117] offset:24832
	ds_write_b64 v31, v[152:153] offset:24832
	v_add_u32_e32 v26, s22, v29
	v_add_u32_e32 v27, s22, v30
	v_add_u32_e32 v28, s22, v31
	v_add_u32_e32 v22, 0x8000, v2
	v_add_u32_e32 v23, 0x8000, v3
	v_mov_b32_e32 v6, 0
	v_mov_b32_e32 v7, 0
	v_mov_b32_e32 v8, 0
	v_mov_b32_e32 v9, 0
	v_mov_b32_e32 v10, 0
	v_mov_b32_e32 v11, 0
	v_mov_b32_e32 v12, 0
	v_mov_b32_e32 v13, 0
	v_mov_b32_e32 v14, 0
	v_mov_b32_e32 v15, 0
	v_mov_b32_e32 v16, 0
	v_mov_b32_e32 v17, 0
	v_mov_b32_e32 v18, 0
	v_mov_b32_e32 v19, 0
	v_mov_b32_e32 v20, 0
	v_mov_b32_e32 v21, 0
	s_mov_b32 s16, 0
	s_mov_b32 s2, 0x10001
	s_mov_b32 s3, 0x10001
	s_waitcnt vmcnt(0) lgkmcnt(0)
	s_barrier
	ds_read_b128 v[48:51], v2 offset:256
	ds_read_b128 v[52:55], v2 offset:512
	ds_read_b128 v[56:59], v2 offset:768
	ds_read_b128 v[60:63], v2 offset:1024
	ds_read_b128 v[64:67], v2 offset:16640
	ds_read_b128 v[68:71], v2 offset:16896
	ds_read_b64 v[72:73], v3 offset:20736
.Lgla2_loop:
	global_load_dword v110, v32, s[10:11]
	global_load_dword v111, v32, s[10:11] offset:-1024
	global_load_dword v112, v33, s[10:11]
	global_load_dword v113, v33, s[10:11] offset:-1024
	global_load_dword v114, v34, s[10:11]
	global_load_dword v116, v35, s[12:13]
	global_load_dword v117, v35, s[12:13] offset:4
	s_add_u32 s10, s10, 0x18000
	s_addc_u32 s11, s11, 0
	s_add_u32 s12, s12, 0x4000
	s_addc_u32 s13, s13, 0
	s_waitcnt lgkmcnt(0)
	v_pk_mul_f32 v[42:43], v[72:73], v[48:49] op_sel_hi:[1,0]
	v_pk_fma_f32 v[6:7], v[6:7], v[64:65], v[42:43] op_sel:[0,0,0] op_sel_hi:[1,0,1]
	v_pk_mul_f32 v[38:39], v[6:7], v[48:49] op_sel:[0,1] op_sel_hi:[1,1]
	v_pk_mul_f32 v[44:45], v[72:73], v[50:51] op_sel_hi:[1,0]
	v_pk_fma_f32 v[8:9], v[8:9], v[64:65], v[44:45] op_sel:[0,1,0] op_sel_hi:[1,1,1]
	v_pk_fma_f32 v[38:39], v[8:9], v[50:51], v[38:39] op_sel:[0,1,0] op_sel_hi:[1,1,1]
	v_pk_mul_f32 v[42:43], v[72:73], v[52:53] op_sel_hi:[1,0]
	v_pk_fma_f32 v[10:11], v[10:11], v[66:67], v[42:43] op_sel:[0,0,0] op_sel_hi:[1,0,1]
	v_pk_fma_f32 v[38:39], v[10:11], v[52:53], v[38:39] op_sel:[0,1,0] op_sel_hi:[1,1,1]
	v_pk_mul_f32 v[44:45], v[72:73], v[54:55] op_sel_hi:[1,0]
	v_pk_fma_f32 v[12:13], v[12:13], v[66:67], v[44:45] op_sel:[0,1,0] op_sel_hi:[1,1,1]
	v_pk_fma_f32 v[38:39], v[12:13], v[54:55], v[38:39] op_sel:[0,1,0] op_sel_hi:[1,1,1]
	v_pk_mul_f32 v[42:43], v[72:73], v[56:57] op_sel_hi:[1,0]
	v_pk_fma_f32 v[14:15], v[14:15], v[68:69], v[42:43] op_sel:[0,0,0] op_sel_hi:[1,0,1]
	v_pk_fma_f32 v[38:39], v[14:15], v[56:57], v[38:39] op_sel:[0,1,0] op_sel_hi:[1,1,1]
	v_pk_mul_f32 v[44:45], v[72:73], v[58:59] op_sel_hi:[1,0]
	v_pk_fma_f32 v[16:17], v[16:17], v[68:69], v[44:45] op_sel:[0,1,0] op_sel_hi:[1,1,1]
	v_pk_fma_f32 v[38:39], v[16:17], v[58:59], v[38:39] op_sel:[0,1,0] op_sel_hi:[1,1,1]
	v_pk_mul_f32 v[42:43], v[72:73], v[60:61] op_sel_hi:[1,0]
	v_pk_fma_f32 v[18:19], v[18:19], v[70:71], v[42:43] op_sel:[0,0,0] op_sel_hi:[1,0,1]
	v_pk_fma_f32 v[38:39], v[18:19], v[60:61], v[38:39] op_sel:[0,1,0] op_sel_hi:[1,1,1]
	v_pk_mul_f32 v[44:45], v[72:73], v[62:63] op_sel_hi:[1,0]
	v_pk_fma_f32 v[20:21], v[20:21], v[70:71], v[44:45] op_sel:[0,1,0] op_sel_hi:[1,1,1]
	v_pk_fma_f32 v[38:39], v[20:21], v[62:63], v[38:39] op_sel:[0,1,0] op_sel_hi:[1,1,1]
	s_add_u32 s14, s14, 0x1000
	s_addc_u32 s15, s15, 0
	v_add_f32_dpp v38, v38, v38 row_ror:8 row_mask:0xf bank_mask:0x3 bound_ctrl:1
	v_add_f32_dpp v38, v39, v39 row_ror:8 row_mask:0xf bank_mask:0xc bound_ctrl:1
	ds_read_b128 v[80:83], v2 offset:1280
	ds_read_b128 v[84:87], v2 offset:1536
	v_add_f32_dpp v38, v38, v38 row_half_mirror row_mask:0xf bank_mask:0xf bound_ctrl:1
	ds_read_b128 v[88:91], v2 offset:1792
	ds_read_b128 v[92:95], v2 offset:2048
	v_add_f32_dpp v38, v38, v38 quad_perm:[1,0,3,2] row_mask:0xf bank_mask:0xf bound_ctrl:1
	ds_read_b128 v[96:99], v2 offset:17152
	ds_read_b128 v[100:103], v2 offset:17408
	v_add_f32_dpp v38, v38, v38 quad_perm:[2,3,0,1] row_mask:0xf bank_mask:0xf bound_ctrl:1
	ds_read_b64 v[104:105], v3 offset:20992
	s_nop 0
	v_mov_b32_dpp v39, v38 row_ror:8 row_mask:0xf bank_mask:0xf bound_ctrl:1
	v_pk_mul_f32 v[38:39], v[38:39], v[40:41] op_sel_hi:[1,0]
	v_cvt_pk_bf16_f32 v47, v38, v39
	s_mov_b64 exec, s[2:3]
	global_store_dword v46, v47, s[14:15] offset:-4096
	s_mov_b64 exec, -1
	s_waitcnt lgkmcnt(0)
	v_pk_mul_f32 v[42:43], v[104:105], v[80:81] op_sel_hi:[1,0]
	v_pk_fma_f32 v[6:7], v[6:7], v[96:97], v[42:43] op_sel:[0,0,0] op_sel_hi:[1,0,1]
	v_pk_mul_f32 v[38:39], v[6:7], v[80:81] op_sel:[0,1] op_sel_hi:[1,1]
	v_pk_mul_f32 v[44:45], v[104:105], v[82:83] op_sel_hi:[1,0]
	v_pk_fma_f32 v[8:9], v[8:9], v[96:97], v[44:45] op_sel:[0,1,0] op_sel_hi:[1,1,1]
	v_pk_fma_f32 v[38:39], v[8:9], v[82:83], v[38:39] op_sel:[0,1,0] op_sel_hi:[1,1,1]
	v_pk_mul_f32 v[42:43], v[104:105], v[84:85] op_sel_hi:[1,0]
	v_pk_fma_f32 v[10:11], v[10:11], v[98:99], v[42:43] op_sel:[0,0,0] op_sel_hi:[1,0,1]
	v_pk_fma_f32 v[38:39], v[10:11], v[84:85], v[38:39] op_sel:[0,1,0] op_sel_hi:[1,1,1]
	v_pk_mul_f32 v[44:45], v[104:105], v[86:87] op_sel_hi:[1,0]
	v_pk_fma_f32 v[12:13], v[12:13], v[98:99], v[44:45] op_sel:[0,1,0] op_sel_hi:[1,1,1]
	v_pk_fma_f32 v[38:39], v[12:13], v[86:87], v[38:39] op_sel:[0,1,0] op_sel_hi:[1,1,1]
	v_pk_mul_f32 v[42:43], v[104:105], v[88:89] op_sel_hi:[1,0]
	v_pk_fma_f32 v[14:15], v[14:15], v[100:101], v[42:43] op_sel:[0,0,0] op_sel_hi:[1,0,1]
	v_pk_fma_f32 v[38:39], v[14:15], v[88:89], v[38:39] op_sel:[0,1,0] op_sel_hi:[1,1,1]
	v_pk_mul_f32 v[44:45], v[104:105], v[90:91] op_sel_hi:[1,0]
	v_pk_fma_f32 v[16:17], v[16:17], v[100:101], v[44:45] op_sel:[0,1,0] op_sel_hi:[1,1,1]
	v_pk_fma_f32 v[38:39], v[16:17], v[90:91], v[38:39] op_sel:[0,1,0] op_sel_hi:[1,1,1]
	v_pk_mul_f32 v[42:43], v[104:105], v[92:93] op_sel_hi:[1,0]
	v_pk_fma_f32 v[18:19], v[18:19], v[102:103], v[42:43] op_sel:[0,0,0] op_sel_hi:[1,0,1]
	v_pk_fma_f32 v[38:39], v[18:19], v[92:93], v[38:39] op_sel:[0,1,0] op_sel_hi:[1,1,1]
	v_pk_mul_f32 v[44:45], v[104:105], v[94:95] op_sel_hi:[1,0]
	v_pk_fma_f32 v[20:21], v[20:21], v[102:103], v[44:45] op_sel:[0,1,0] op_sel_hi:[1,1,1]
	v_pk_fma_f32 v[38:39], v[20:21], v[94:95], v[38:39] op_sel:[0,1,0] op_sel_hi:[1,1,1]
	s_add_u32 s14, s14, 0x1000
	s_addc_u32 s15, s15, 0
	v_add_f32_dpp v38, v38, v38 row_ror:8 row_mask:0xf bank_mask:0x3 bound_ctrl:1
	v_add_f32_dpp v38, v39, v39 row_ror:8 row_mask:0xf bank_mask:0xc bound_ctrl:1
	ds_read_b128 v[48:51], v2 offset:2304
	ds_read_b128 v[52:55], v2 offset:2560
	v_add_f32_dpp v38, v38, v38 row_half_mirror row_mask:0xf bank_mask:0xf bound_ctrl:1
	ds_read_b128 v[56:59], v2 offset:2816
	ds_read_b128 v[60:63], v2 offset:3072
	v_add_f32_dpp v38, v38, v38 quad_perm:[1,0,3,2] row_mask:0xf bank_mask:0xf bound_ctrl:1
	ds_read_b128 v[64:67], v2 offset:17664
	ds_read_b128 v[68:71], v2 offset:17920
	v_add_f32_dpp v38, v38, v38 quad_perm:[2,3,0,1] row_mask:0xf bank_mask:0xf bound_ctrl:1
	ds_read_b64 v[72:73], v3 offset:21248
	s_nop 0
	v_mov_b32_dpp v39, v38 row_ror:8 row_mask:0xf bank_mask:0xf bound_ctrl:1
	v_pk_mul_f32 v[38:39], v[38:39], v[40:41] op_sel_hi:[1,0]
	v_cvt_pk_bf16_f32 v47, v38, v39
	s_mov_b64 exec, s[2:3]
	global_store_dword v46, v47, s[14:15] offset:-4096
	s_mov_b64 exec, -1
	s_waitcnt lgkmcnt(0)
	v_pk_mul_f32 v[42:43], v[72:73], v[48:49] op_sel_hi:[1,0]
	v_pk_fma_f32 v[6:7], v[6:7], v[64:65], v[42:43] op_sel:[0,0,0] op_sel_hi:[1,0,1]
	v_pk_mul_f32 v[38:39], v[6:7], v[48:49] op_sel:[0,1] op_sel_hi:[1,1]
	v_pk_mul_f32 v[44:45], v[72:73], v[50:51] op_sel_hi:[1,0]
	v_pk_fma_f32 v[8:9], v[8:9], v[64:65], v[44:45] op_sel:[0,1,0] op_sel_hi:[1,1,1]
	v_pk_fma_f32 v[38:39], v[8:9], v[50:51], v[38:39] op_sel:[0,1,0] op_sel_hi:[1,1,1]
	v_pk_mul_f32 v[42:43], v[72:73], v[52:53] op_sel_hi:[1,0]
	v_pk_fma_f32 v[10:11], v[10:11], v[66:67], v[42:43] op_sel:[0,0,0] op_sel_hi:[1,0,1]
	v_pk_fma_f32 v[38:39], v[10:11], v[52:53], v[38:39] op_sel:[0,1,0] op_sel_hi:[1,1,1]
	v_pk_mul_f32 v[44:45], v[72:73], v[54:55] op_sel_hi:[1,0]
	v_pk_fma_f32 v[12:13], v[12:13], v[66:67], v[44:45] op_sel:[0,1,0] op_sel_hi:[1,1,1]
	v_pk_fma_f32 v[38:39], v[12:13], v[54:55], v[38:39] op_sel:[0,1,0] op_sel_hi:[1,1,1]
	v_pk_mul_f32 v[42:43], v[72:73], v[56:57] op_sel_hi:[1,0]
	v_pk_fma_f32 v[14:15], v[14:15], v[68:69], v[42:43] op_sel:[0,0,0] op_sel_hi:[1,0,1]
	v_pk_fma_f32 v[38:39], v[14:15], v[56:57], v[38:39] op_sel:[0,1,0] op_sel_hi:[1,1,1]
	v_pk_mul_f32 v[44:45], v[72:73], v[58:59] op_sel_hi:[1,0]
	v_pk_fma_f32 v[16:17], v[16:17], v[68:69], v[44:45] op_sel:[0,1,0] op_sel_hi:[1,1,1]
	v_pk_fma_f32 v[38:39], v[16:17], v[58:59], v[38:39] op_sel:[0,1,0] op_sel_hi:[1,1,1]
	v_pk_mul_f32 v[42:43], v[72:73], v[60:61] op_sel_hi:[1,0]
	v_pk_fma_f32 v[18:19], v[18:19], v[70:71], v[42:43] op_sel:[0,0,0] op_sel_hi:[1,0,1]
	v_pk_fma_f32 v[38:39], v[18:19], v[60:61], v[38:39] op_sel:[0,1,0] op_sel_hi:[1,1,1]
	v_pk_mul_f32 v[44:45], v[72:73], v[62:63] op_sel_hi:[1,0]
	v_pk_fma_f32 v[20:21], v[20:21], v[70:71], v[44:45] op_sel:[0,1,0] op_sel_hi:[1,1,1]
	v_pk_fma_f32 v[38:39], v[20:21], v[62:63], v[38:39] op_sel:[0,1,0] op_sel_hi:[1,1,1]
	s_add_u32 s14, s14, 0x1000
	s_addc_u32 s15, s15, 0
	v_add_f32_dpp v38, v38, v38 row_ror:8 row_mask:0xf bank_mask:0x3 bound_ctrl:1
	v_add_f32_dpp v38, v39, v39 row_ror:8 row_mask:0xf bank_mask:0xc bound_ctrl:1
	ds_read_b128 v[80:83], v2 offset:3328
	ds_read_b128 v[84:87], v2 offset:3584
	v_add_f32_dpp v38, v38, v38 row_half_mirror row_mask:0xf bank_mask:0xf bound_ctrl:1
	ds_read_b128 v[88:91], v2 offset:3840
	ds_read_b128 v[92:95], v2 offset:4096
	v_add_f32_dpp v38, v38, v38 quad_perm:[1,0,3,2] row_mask:0xf bank_mask:0xf bound_ctrl:1
	ds_read_b128 v[96:99], v2 offset:18176
	ds_read_b128 v[100:103], v2 offset:18432
	v_add_f32_dpp v38, v38, v38 quad_perm:[2,3,0,1] row_mask:0xf bank_mask:0xf bound_ctrl:1
	ds_read_b64 v[104:105], v3 offset:21504
	s_nop 0
	v_mov_b32_dpp v39, v38 row_ror:8 row_mask:0xf bank_mask:0xf bound_ctrl:1
	v_pk_mul_f32 v[38:39], v[38:39], v[40:41] op_sel_hi:[1,0]
	v_cvt_pk_bf16_f32 v47, v38, v39
	s_mov_b64 exec, s[2:3]
	global_store_dword v46, v47, s[14:15] offset:-4096
	s_mov_b64 exec, -1
	s_waitcnt lgkmcnt(0)
	v_pk_mul_f32 v[42:43], v[104:105], v[80:81] op_sel_hi:[1,0]
	v_pk_fma_f32 v[6:7], v[6:7], v[96:97], v[42:43] op_sel:[0,0,0] op_sel_hi:[1,0,1]
	v_pk_mul_f32 v[38:39], v[6:7], v[80:81] op_sel:[0,1] op_sel_hi:[1,1]
	v_pk_mul_f32 v[44:45], v[104:105], v[82:83] op_sel_hi:[1,0]
	v_pk_fma_f32 v[8:9], v[8:9], v[96:97], v[44:45] op_sel:[0,1,0] op_sel_hi:[1,1,1]
	v_pk_fma_f32 v[38:39], v[8:9], v[82:83], v[38:39] op_sel:[0,1,0] op_sel_hi:[1,1,1]
	v_pk_mul_f32 v[42:43], v[104:105], v[84:85] op_sel_hi:[1,0]
	v_pk_fma_f32 v[10:11], v[10:11], v[98:99], v[42:43] op_sel:[0,0,0] op_sel_hi:[1,0,1]
	v_pk_fma_f32 v[38:39], v[10:11], v[84:85], v[38:39] op_sel:[0,1,0] op_sel_hi:[1,1,1]
	v_pk_mul_f32 v[44:45], v[104:105], v[86:87] op_sel_hi:[1,0]
	v_pk_fma_f32 v[12:13], v[12:13], v[98:99], v[44:45] op_sel:[0,1,0] op_sel_hi:[1,1,1]
	v_pk_fma_f32 v[38:39], v[12:13], v[86:87], v[38:39] op_sel:[0,1,0] op_sel_hi:[1,1,1]
	v_pk_mul_f32 v[42:43], v[104:105], v[88:89] op_sel_hi:[1,0]
	v_pk_fma_f32 v[14:15], v[14:15], v[100:101], v[42:43] op_sel:[0,0,0] op_sel_hi:[1,0,1]
	v_pk_fma_f32 v[38:39], v[14:15], v[88:89], v[38:39] op_sel:[0,1,0] op_sel_hi:[1,1,1]
	v_pk_mul_f32 v[44:45], v[104:105], v[90:91] op_sel_hi:[1,0]
	v_pk_fma_f32 v[16:17], v[16:17], v[100:101], v[44:45] op_sel:[0,1,0] op_sel_hi:[1,1,1]
	v_pk_fma_f32 v[38:39], v[16:17], v[90:91], v[38:39] op_sel:[0,1,0] op_sel_hi:[1,1,1]
	v_pk_mul_f32 v[42:43], v[104:105], v[92:93] op_sel_hi:[1,0]
	v_pk_fma_f32 v[18:19], v[18:19], v[102:103], v[42:43] op_sel:[0,0,0] op_sel_hi:[1,0,1]
	v_pk_fma_f32 v[38:39], v[18:19], v[92:93], v[38:39] op_sel:[0,1,0] op_sel_hi:[1,1,1]
	v_pk_mul_f32 v[44:45], v[104:105], v[94:95] op_sel_hi:[1,0]
	v_pk_fma_f32 v[20:21], v[20:21], v[102:103], v[44:45] op_sel:[0,1,0] op_sel_hi:[1,1,1]
	v_pk_fma_f32 v[38:39], v[20:21], v[94:95], v[38:39] op_sel:[0,1,0] op_sel_hi:[1,1,1]
	s_add_u32 s14, s14, 0x1000
	s_addc_u32 s15, s15, 0
	v_add_f32_dpp v38, v38, v38 row_ror:8 row_mask:0xf bank_mask:0x3 bound_ctrl:1
	v_add_f32_dpp v38, v39, v39 row_ror:8 row_mask:0xf bank_mask:0xc bound_ctrl:1
	ds_read_b128 v[48:51], v2 offset:4352
	ds_read_b128 v[52:55], v2 offset:4608
	v_add_f32_dpp v38, v38, v38 row_half_mirror row_mask:0xf bank_mask:0xf bound_ctrl:1
	ds_read_b128 v[56:59], v2 offset:4864
	ds_read_b128 v[60:63], v2 offset:5120
	v_add_f32_dpp v38, v38, v38 quad_perm:[1,0,3,2] row_mask:0xf bank_mask:0xf bound_ctrl:1
	ds_read_b128 v[64:67], v2 offset:18688
	ds_read_b128 v[68:71], v2 offset:18944
	v_add_f32_dpp v38, v38, v38 quad_perm:[2,3,0,1] row_mask:0xf bank_mask:0xf bound_ctrl:1
	ds_read_b64 v[72:73], v3 offset:21760
	s_nop 0
	v_mov_b32_dpp v39, v38 row_ror:8 row_mask:0xf bank_mask:0xf bound_ctrl:1
	v_pk_mul_f32 v[38:39], v[38:39], v[40:41] op_sel_hi:[1,0]
	v_cvt_pk_bf16_f32 v47, v38, v39
	s_mov_b64 exec, s[2:3]
	global_store_dword v46, v47, s[14:15] offset:-4096
	s_mov_b64 exec, -1
	s_waitcnt lgkmcnt(0)
	v_pk_mul_f32 v[42:43], v[72:73], v[48:49] op_sel_hi:[1,0]
	v_pk_fma_f32 v[6:7], v[6:7], v[64:65], v[42:43] op_sel:[0,0,0] op_sel_hi:[1,0,1]
	v_pk_mul_f32 v[38:39], v[6:7], v[48:49] op_sel:[0,1] op_sel_hi:[1,1]
	v_pk_mul_f32 v[44:45], v[72:73], v[50:51] op_sel_hi:[1,0]
	v_pk_fma_f32 v[8:9], v[8:9], v[64:65], v[44:45] op_sel:[0,1,0] op_sel_hi:[1,1,1]
	v_pk_fma_f32 v[38:39], v[8:9], v[50:51], v[38:39] op_sel:[0,1,0] op_sel_hi:[1,1,1]
	v_pk_mul_f32 v[42:43], v[72:73], v[52:53] op_sel_hi:[1,0]
	v_pk_fma_f32 v[10:11], v[10:11], v[66:67], v[42:43] op_sel:[0,0,0] op_sel_hi:[1,0,1]
	v_pk_fma_f32 v[38:39], v[10:11], v[52:53], v[38:39] op_sel:[0,1,0] op_sel_hi:[1,1,1]
	v_pk_mul_f32 v[44:45], v[72:73], v[54:55] op_sel_hi:[1,0]
	v_pk_fma_f32 v[12:13], v[12:13], v[66:67], v[44:45] op_sel:[0,1,0] op_sel_hi:[1,1,1]
	v_pk_fma_f32 v[38:39], v[12:13], v[54:55], v[38:39] op_sel:[0,1,0] op_sel_hi:[1,1,1]
	v_pk_mul_f32 v[42:43], v[72:73], v[56:57] op_sel_hi:[1,0]
	v_pk_fma_f32 v[14:15], v[14:15], v[68:69], v[42:43] op_sel:[0,0,0] op_sel_hi:[1,0,1]
	v_pk_fma_f32 v[38:39], v[14:15], v[56:57], v[38:39] op_sel:[0,1,0] op_sel_hi:[1,1,1]
	v_pk_mul_f32 v[44:45], v[72:73], v[58:59] op_sel_hi:[1,0]
	v_pk_fma_f32 v[16:17], v[16:17], v[68:69], v[44:45] op_sel:[0,1,0] op_sel_hi:[1,1,1]
	v_pk_fma_f32 v[38:39], v[16:17], v[58:59], v[38:39] op_sel:[0,1,0] op_sel_hi:[1,1,1]
	v_pk_mul_f32 v[42:43], v[72:73], v[60:61] op_sel_hi:[1,0]
	v_pk_fma_f32 v[18:19], v[18:19], v[70:71], v[42:43] op_sel:[0,0,0] op_sel_hi:[1,0,1]
	v_pk_fma_f32 v[38:39], v[18:19], v[60:61], v[38:39] op_sel:[0,1,0] op_sel_hi:[1,1,1]
	v_pk_mul_f32 v[44:45], v[72:73], v[62:63] op_sel_hi:[1,0]
	v_pk_fma_f32 v[20:21], v[20:21], v[70:71], v[44:45] op_sel:[0,1,0] op_sel_hi:[1,1,1]
	v_pk_fma_f32 v[38:39], v[20:21], v[62:63], v[38:39] op_sel:[0,1,0] op_sel_hi:[1,1,1]
	s_add_u32 s14, s14, 0x1000
	s_addc_u32 s15, s15, 0
	v_add_f32_dpp v38, v38, v38 row_ror:8 row_mask:0xf bank_mask:0x3 bound_ctrl:1
	v_add_f32_dpp v38, v39, v39 row_ror:8 row_mask:0xf bank_mask:0xc bound_ctrl:1
	ds_read_b128 v[80:83], v2 offset:5376
	ds_read_b128 v[84:87], v2 offset:5632
	v_add_f32_dpp v38, v38, v38 row_half_mirror row_mask:0xf bank_mask:0xf bound_ctrl:1
	ds_read_b128 v[88:91], v2 offset:5888
	ds_read_b128 v[92:95], v2 offset:6144
	v_add_f32_dpp v38, v38, v38 quad_perm:[1,0,3,2] row_mask:0xf bank_mask:0xf bound_ctrl:1
	ds_read_b128 v[96:99], v2 offset:19200
	ds_read_b128 v[100:103], v2 offset:19456
	v_add_f32_dpp v38, v38, v38 quad_perm:[2,3,0,1] row_mask:0xf bank_mask:0xf bound_ctrl:1
	ds_read_b64 v[104:105], v3 offset:22016
	s_nop 0
	v_mov_b32_dpp v39, v38 row_ror:8 row_mask:0xf bank_mask:0xf bound_ctrl:1
	v_pk_mul_f32 v[38:39], v[38:39], v[40:41] op_sel_hi:[1,0]
	v_cvt_pk_bf16_f32 v47, v38, v39
	s_mov_b64 exec, s[2:3]
	global_store_dword v46, v47, s[14:15] offset:-4096
	s_mov_b64 exec, -1
	s_waitcnt lgkmcnt(0)
	v_pk_mul_f32 v[42:43], v[104:105], v[80:81] op_sel_hi:[1,0]
	v_pk_fma_f32 v[6:7], v[6:7], v[96:97], v[42:43] op_sel:[0,0,0] op_sel_hi:[1,0,1]
	v_pk_mul_f32 v[38:39], v[6:7], v[80:81] op_sel:[0,1] op_sel_hi:[1,1]
	v_pk_mul_f32 v[44:45], v[104:105], v[82:83] op_sel_hi:[1,0]
	v_pk_fma_f32 v[8:9], v[8:9], v[96:97], v[44:45] op_sel:[0,1,0] op_sel_hi:[1,1,1]
	v_pk_fma_f32 v[38:39], v[8:9], v[82:83], v[38:39] op_sel:[0,1,0] op_sel_hi:[1,1,1]
	v_pk_mul_f32 v[42:43], v[104:105], v[84:85] op_sel_hi:[1,0]
	v_pk_fma_f32 v[10:11], v[10:11], v[98:99], v[42:43] op_sel:[0,0,0] op_sel_hi:[1,0,1]
	v_pk_fma_f32 v[38:39], v[10:11], v[84:85], v[38:39] op_sel:[0,1,0] op_sel_hi:[1,1,1]
	v_pk_mul_f32 v[44:45], v[104:105], v[86:87] op_sel_hi:[1,0]
	v_pk_fma_f32 v[12:13], v[12:13], v[98:99], v[44:45] op_sel:[0,1,0] op_sel_hi:[1,1,1]
	v_pk_fma_f32 v[38:39], v[12:13], v[86:87], v[38:39] op_sel:[0,1,0] op_sel_hi:[1,1,1]
	v_pk_mul_f32 v[42:43], v[104:105], v[88:89] op_sel_hi:[1,0]
	v_pk_fma_f32 v[14:15], v[14:15], v[100:101], v[42:43] op_sel:[0,0,0] op_sel_hi:[1,0,1]
	v_pk_fma_f32 v[38:39], v[14:15], v[88:89], v[38:39] op_sel:[0,1,0] op_sel_hi:[1,1,1]
	v_pk_mul_f32 v[44:45], v[104:105], v[90:91] op_sel_hi:[1,0]
	v_pk_fma_f32 v[16:17], v[16:17], v[100:101], v[44:45] op_sel:[0,1,0] op_sel_hi:[1,1,1]
	v_pk_fma_f32 v[38:39], v[16:17], v[90:91], v[38:39] op_sel:[0,1,0] op_sel_hi:[1,1,1]
	v_pk_mul_f32 v[42:43], v[104:105], v[92:93] op_sel_hi:[1,0]
	v_pk_fma_f32 v[18:19], v[18:19], v[102:103], v[42:43] op_sel:[0,0,0] op_sel_hi:[1,0,1]
	v_pk_fma_f32 v[38:39], v[18:19], v[92:93], v[38:39] op_sel:[0,1,0] op_sel_hi:[1,1,1]
	v_pk_mul_f32 v[44:45], v[104:105], v[94:95] op_sel_hi:[1,0]
	v_pk_fma_f32 v[20:21], v[20:21], v[102:103], v[44:45] op_sel:[0,1,0] op_sel_hi:[1,1,1]
	v_pk_fma_f32 v[38:39], v[20:21], v[94:95], v[38:39] op_sel:[0,1,0] op_sel_hi:[1,1,1]
	s_add_u32 s14, s14, 0x1000
	s_addc_u32 s15, s15, 0
	v_add_f32_dpp v38, v38, v38 row_ror:8 row_mask:0xf bank_mask:0x3 bound_ctrl:1
	v_add_f32_dpp v38, v39, v39 row_ror:8 row_mask:0xf bank_mask:0xc bound_ctrl:1
	ds_read_b128 v[48:51], v2 offset:6400
	ds_read_b128 v[52:55], v2 offset:6656
	v_add_f32_dpp v38, v38, v38 row_half_mirror row_mask:0xf bank_mask:0xf bound_ctrl:1
	ds_read_b128 v[56:59], v2 offset:6912
	ds_read_b128 v[60:63], v2 offset:7168
	v_add_f32_dpp v38, v38, v38 quad_perm:[1,0,3,2] row_mask:0xf bank_mask:0xf bound_ctrl:1
	ds_read_b128 v[64:67], v2 offset:19712
	ds_read_b128 v[68:71], v2 offset:19968
	v_add_f32_dpp v38, v38, v38 quad_perm:[2,3,0,1] row_mask:0xf bank_mask:0xf bound_ctrl:1
	ds_read_b64 v[72:73], v3 offset:22272
	s_nop 0
	v_mov_b32_dpp v39, v38 row_ror:8 row_mask:0xf bank_mask:0xf bound_ctrl:1
	v_pk_mul_f32 v[38:39], v[38:39], v[40:41] op_sel_hi:[1,0]
	v_cvt_pk_bf16_f32 v47, v38, v39
	s_mov_b64 exec, s[2:3]
	global_store_dword v46, v47, s[14:15] offset:-4096
	s_mov_b64 exec, -1
	s_waitcnt lgkmcnt(0)
	v_pk_mul_f32 v[42:43], v[72:73], v[48:49] op_sel_hi:[1,0]
	v_pk_fma_f32 v[6:7], v[6:7], v[64:65], v[42:43] op_sel:[0,0,0] op_sel_hi:[1,0,1]
	v_pk_mul_f32 v[38:39], v[6:7], v[48:49] op_sel:[0,1] op_sel_hi:[1,1]
	v_pk_mul_f32 v[44:45], v[72:73], v[50:51] op_sel_hi:[1,0]
	v_pk_fma_f32 v[8:9], v[8:9], v[64:65], v[44:45] op_sel:[0,1,0] op_sel_hi:[1,1,1]
	v_pk_fma_f32 v[38:39], v[8:9], v[50:51], v[38:39] op_sel:[0,1,0] op_sel_hi:[1,1,1]
	v_pk_mul_f32 v[42:43], v[72:73], v[52:53] op_sel_hi:[1,0]
	v_pk_fma_f32 v[10:11], v[10:11], v[66:67], v[42:43] op_sel:[0,0,0] op_sel_hi:[1,0,1]
	v_pk_fma_f32 v[38:39], v[10:11], v[52:53], v[38:39] op_sel:[0,1,0] op_sel_hi:[1,1,1]
	v_pk_mul_f32 v[44:45], v[72:73], v[54:55] op_sel_hi:[1,0]
	v_pk_fma_f32 v[12:13], v[12:13], v[66:67], v[44:45] op_sel:[0,1,0] op_sel_hi:[1,1,1]
	v_pk_fma_f32 v[38:39], v[12:13], v[54:55], v[38:39] op_sel:[0,1,0] op_sel_hi:[1,1,1]
	v_pk_mul_f32 v[42:43], v[72:73], v[56:57] op_sel_hi:[1,0]
	v_pk_fma_f32 v[14:15], v[14:15], v[68:69], v[42:43] op_sel:[0,0,0] op_sel_hi:[1,0,1]
	v_pk_fma_f32 v[38:39], v[14:15], v[56:57], v[38:39] op_sel:[0,1,0] op_sel_hi:[1,1,1]
	v_pk_mul_f32 v[44:45], v[72:73], v[58:59] op_sel_hi:[1,0]
	v_pk_fma_f32 v[16:17], v[16:17], v[68:69], v[44:45] op_sel:[0,1,0] op_sel_hi:[1,1,1]
	v_pk_fma_f32 v[38:39], v[16:17], v[58:59], v[38:39] op_sel:[0,1,0] op_sel_hi:[1,1,1]
	v_pk_mul_f32 v[42:43], v[72:73], v[60:61] op_sel_hi:[1,0]
	v_pk_fma_f32 v[18:19], v[18:19], v[70:71], v[42:43] op_sel:[0,0,0] op_sel_hi:[1,0,1]
	v_pk_fma_f32 v[38:39], v[18:19], v[60:61], v[38:39] op_sel:[0,1,0] op_sel_hi:[1,1,1]
	v_pk_mul_f32 v[44:45], v[72:73], v[62:63] op_sel_hi:[1,0]
	v_pk_fma_f32 v[20:21], v[20:21], v[70:71], v[44:45] op_sel:[0,1,0] op_sel_hi:[1,1,1]
	v_pk_fma_f32 v[38:39], v[20:21], v[62:63], v[38:39] op_sel:[0,1,0] op_sel_hi:[1,1,1]
	s_add_u32 s14, s14, 0x1000
	s_addc_u32 s15, s15, 0
	v_add_f32_dpp v38, v38, v38 row_ror:8 row_mask:0xf bank_mask:0x3 bound_ctrl:1
	v_add_f32_dpp v38, v39, v39 row_ror:8 row_mask:0xf bank_mask:0xc bound_ctrl:1
	ds_read_b128 v[80:83], v2 offset:7424
	ds_read_b128 v[84:87], v2 offset:7680
	v_add_f32_dpp v38, v38, v38 row_half_mirror row_mask:0xf bank_mask:0xf bound_ctrl:1
	ds_read_b128 v[88:91], v2 offset:7936
	ds_read_b128 v[92:95], v2 offset:8192
	v_add_f32_dpp v38, v38, v38 quad_perm:[1,0,3,2] row_mask:0xf bank_mask:0xf bound_ctrl:1
	ds_read_b128 v[96:99], v2 offset:20224
	ds_read_b128 v[100:103], v2 offset:20480
	v_add_f32_dpp v38, v38, v38 quad_perm:[2,3,0,1] row_mask:0xf bank_mask:0xf bound_ctrl:1
	ds_read_b64 v[104:105], v3 offset:22528
	s_nop 0
	v_mov_b32_dpp v39, v38 row_ror:8 row_mask:0xf bank_mask:0xf bound_ctrl:1
	v_pk_mul_f32 v[38:39], v[38:39], v[40:41] op_sel_hi:[1,0]
	v_cvt_pk_bf16_f32 v47, v38, v39
	s_mov_b64 exec, s[2:3]
	global_store_dword v46, v47, s[14:15] offset:-4096
	s_mov_b64 exec, -1
	s_waitcnt lgkmcnt(0)
	v_pk_mul_f32 v[42:43], v[104:105], v[80:81] op_sel_hi:[1,0]
	v_pk_fma_f32 v[6:7], v[6:7], v[96:97], v[42:43] op_sel:[0,0,0] op_sel_hi:[1,0,1]
	v_pk_mul_f32 v[38:39], v[6:7], v[80:81] op_sel:[0,1] op_sel_hi:[1,1]
	v_pk_mul_f32 v[44:45], v[104:105], v[82:83] op_sel_hi:[1,0]
	v_pk_fma_f32 v[8:9], v[8:9], v[96:97], v[44:45] op_sel:[0,1,0] op_sel_hi:[1,1,1]
	v_pk_fma_f32 v[38:39], v[8:9], v[82:83], v[38:39] op_sel:[0,1,0] op_sel_hi:[1,1,1]
	v_pk_mul_f32 v[42:43], v[104:105], v[84:85] op_sel_hi:[1,0]
	v_pk_fma_f32 v[10:11], v[10:11], v[98:99], v[42:43] op_sel:[0,0,0] op_sel_hi:[1,0,1]
	v_pk_fma_f32 v[38:39], v[10:11], v[84:85], v[38:39] op_sel:[0,1,0] op_sel_hi:[1,1,1]
	v_pk_mul_f32 v[44:45], v[104:105], v[86:87] op_sel_hi:[1,0]
	v_pk_fma_f32 v[12:13], v[12:13], v[98:99], v[44:45] op_sel:[0,1,0] op_sel_hi:[1,1,1]
	v_pk_fma_f32 v[38:39], v[12:13], v[86:87], v[38:39] op_sel:[0,1,0] op_sel_hi:[1,1,1]
	v_pk_mul_f32 v[42:43], v[104:105], v[88:89] op_sel_hi:[1,0]
	v_pk_fma_f32 v[14:15], v[14:15], v[100:101], v[42:43] op_sel:[0,0,0] op_sel_hi:[1,0,1]
	v_pk_fma_f32 v[38:39], v[14:15], v[88:89], v[38:39] op_sel:[0,1,0] op_sel_hi:[1,1,1]
	v_pk_mul_f32 v[44:45], v[104:105], v[90:91] op_sel_hi:[1,0]
	v_pk_fma_f32 v[16:17], v[16:17], v[100:101], v[44:45] op_sel:[0,1,0] op_sel_hi:[1,1,1]
	v_pk_fma_f32 v[38:39], v[16:17], v[90:91], v[38:39] op_sel:[0,1,0] op_sel_hi:[1,1,1]
	v_pk_mul_f32 v[42:43], v[104:105], v[92:93] op_sel_hi:[1,0]
	v_pk_fma_f32 v[18:19], v[18:19], v[102:103], v[42:43] op_sel:[0,0,0] op_sel_hi:[1,0,1]
	v_pk_fma_f32 v[38:39], v[18:19], v[92:93], v[38:39] op_sel:[0,1,0] op_sel_hi:[1,1,1]
	v_pk_mul_f32 v[44:45], v[104:105], v[94:95] op_sel_hi:[1,0]
	v_pk_fma_f32 v[20:21], v[20:21], v[102:103], v[44:45] op_sel:[0,1,0] op_sel_hi:[1,1,1]
	v_pk_fma_f32 v[38:39], v[20:21], v[94:95], v[38:39] op_sel:[0,1,0] op_sel_hi:[1,1,1]
	s_add_u32 s14, s14, 0x1000
	s_addc_u32 s15, s15, 0
	v_add_f32_dpp v38, v38, v38 row_ror:8 row_mask:0xf bank_mask:0x3 bound_ctrl:1
	v_add_f32_dpp v38, v39, v39 row_ror:8 row_mask:0xf bank_mask:0xc bound_ctrl:1
	ds_read_b128 v[48:51], v2 offset:24832
	ds_read_b128 v[52:55], v2 offset:25088
	v_add_f32_dpp v38, v38, v38 row_half_mirror row_mask:0xf bank_mask:0xf bound_ctrl:1
	ds_read_b128 v[56:59], v2 offset:25344
	ds_read_b128 v[60:63], v2 offset:25600
	v_add_f32_dpp v38, v38, v38 quad_perm:[1,0,3,2] row_mask:0xf bank_mask:0xf bound_ctrl:1
	ds_read_b128 v[64:67], v2 offset:41216
	ds_read_b128 v[68:71], v2 offset:41472
	v_add_f32_dpp v38, v38, v38 quad_perm:[2,3,0,1] row_mask:0xf bank_mask:0xf bound_ctrl:1
	ds_read_b64 v[72:73], v3 offset:45312
	s_nop 0
	v_mov_b32_dpp v39, v38 row_ror:8 row_mask:0xf bank_mask:0xf bound_ctrl:1
	v_pk_mul_f32 v[38:39], v[38:39], v[40:41] op_sel_hi:[1,0]
	v_cvt_pk_bf16_f32 v47, v38, v39
	s_mov_b64 exec, s[2:3]
	global_store_dword v46, v47, s[14:15] offset:-4096
	s_mov_b64 exec, -1
	s_waitcnt vmcnt(8)
	v_lshlrev_b32_e32 v144, 16, v110
	v_lshlrev_b32_e32 v145, 16, v111
	v_and_b32_e32 v146, s17, v110
	v_and_b32_e32 v147, s17, v111
	v_lshlrev_b32_e32 v148, 16, v112
	v_lshlrev_b32_e32 v149, 16, v113
	v_and_b32_e32 v150, s17, v112
	v_and_b32_e32 v151, s17, v113
	v_lshlrev_b32_e32 v152, 16, v114
	v_and_b32_e32 v153, s17, v114
	ds_write_b128 v29, v[144:147] offset:49408
	ds_write_b128 v29, v[148:151] offset:57600
	ds_write_b64 v30, v[116:117] offset:49408
	ds_write_b64 v31, v[152:153] offset:49408
	s_add_i32 s16, s16, 8
	s_waitcnt lgkmcnt(0)
	s_barrier
	s_cmpk_lt_u32 s16, 0x800
	s_cbranch_scc0 .Lgla2_done
	global_load_dword v110, v32, s[10:11]
	global_load_dword v111, v32, s[10:11] offset:-1024
	global_load_dword v112, v33, s[10:11]
	global_load_dword v113, v33, s[10:11] offset:-1024
	global_load_dword v114, v34, s[10:11]
	global_load_dword v116, v35, s[12:13]
	global_load_dword v117, v35, s[12:13] offset:4
	s_add_u32 s10, s10, 0x18000
	s_addc_u32 s11, s11, 0
	s_add_u32 s12, s12, 0x4000
	s_addc_u32 s13, s13, 0
	s_waitcnt lgkmcnt(0)
	v_pk_mul_f32 v[42:43], v[72:73], v[48:49] op_sel_hi:[1,0]
	v_pk_fma_f32 v[6:7], v[6:7], v[64:65], v[42:43] op_sel:[0,0,0] op_sel_hi:[1,0,1]
	v_pk_mul_f32 v[38:39], v[6:7], v[48:49] op_sel:[0,1] op_sel_hi:[1,1]
	v_pk_mul_f32 v[44:45], v[72:73], v[50:51] op_sel_hi:[1,0]
	v_pk_fma_f32 v[8:9], v[8:9], v[64:65], v[44:45] op_sel:[0,1,0] op_sel_hi:[1,1,1]
	v_pk_fma_f32 v[38:39], v[8:9], v[50:51], v[38:39] op_sel:[0,1,0] op_sel_hi:[1,1,1]
	v_pk_mul_f32 v[42:43], v[72:73], v[52:53] op_sel_hi:[1,0]
	v_pk_fma_f32 v[10:11], v[10:11], v[66:67], v[42:43] op_sel:[0,0,0] op_sel_hi:[1,0,1]
	v_pk_fma_f32 v[38:39], v[10:11], v[52:53], v[38:39] op_sel:[0,1,0] op_sel_hi:[1,1,1]
	v_pk_mul_f32 v[44:45], v[72:73], v[54:55] op_sel_hi:[1,0]
	v_pk_fma_f32 v[12:13], v[12:13], v[66:67], v[44:45] op_sel:[0,1,0] op_sel_hi:[1,1,1]
	v_pk_fma_f32 v[38:39], v[12:13], v[54:55], v[38:39] op_sel:[0,1,0] op_sel_hi:[1,1,1]
	v_pk_mul_f32 v[42:43], v[72:73], v[56:57] op_sel_hi:[1,0]
	v_pk_fma_f32 v[14:15], v[14:15], v[68:69], v[42:43] op_sel:[0,0,0] op_sel_hi:[1,0,1]
	v_pk_fma_f32 v[38:39], v[14:15], v[56:57], v[38:39] op_sel:[0,1,0] op_sel_hi:[1,1,1]
	v_pk_mul_f32 v[44:45], v[72:73], v[58:59] op_sel_hi:[1,0]
	v_pk_fma_f32 v[16:17], v[16:17], v[68:69], v[44:45] op_sel:[0,1,0] op_sel_hi:[1,1,1]
	v_pk_fma_f32 v[38:39], v[16:17], v[58:59], v[38:39] op_sel:[0,1,0] op_sel_hi:[1,1,1]
	v_pk_mul_f32 v[42:43], v[72:73], v[60:61] op_sel_hi:[1,0]
	v_pk_fma_f32 v[18:19], v[18:19], v[70:71], v[42:43] op_sel:[0,0,0] op_sel_hi:[1,0,1]
	v_pk_fma_f32 v[38:39], v[18:19], v[60:61], v[38:39] op_sel:[0,1,0] op_sel_hi:[1,1,1]
	v_pk_mul_f32 v[44:45], v[72:73], v[62:63] op_sel_hi:[1,0]
	v_pk_fma_f32 v[20:21], v[20:21], v[70:71], v[44:45] op_sel:[0,1,0] op_sel_hi:[1,1,1]
	v_pk_fma_f32 v[38:39], v[20:21], v[62:63], v[38:39] op_sel:[0,1,0] op_sel_hi:[1,1,1]
	s_add_u32 s14, s14, 0x1000
	s_addc_u32 s15, s15, 0
	v_add_f32_dpp v38, v38, v38 row_ror:8 row_mask:0xf bank_mask:0x3 bound_ctrl:1
	v_add_f32_dpp v38, v39, v39 row_ror:8 row_mask:0xf bank_mask:0xc bound_ctrl:1
	ds_read_b128 v[80:83], v2 offset:25856
	ds_read_b128 v[84:87], v2 offset:26112
	v_add_f32_dpp v38, v38, v38 row_half_mirror row_mask:0xf bank_mask:0xf bound_ctrl:1
	ds_read_b128 v[88:91], v2 offset:26368
	ds_read_b128 v[92:95], v2 offset:26624
	v_add_f32_dpp v38, v38, v38 quad_perm:[1,0,3,2] row_mask:0xf bank_mask:0xf bound_ctrl:1
	ds_read_b128 v[96:99], v2 offset:41728
	ds_read_b128 v[100:103], v2 offset:41984
	v_add_f32_dpp v38, v38, v38 quad_perm:[2,3,0,1] row_mask:0xf bank_mask:0xf bound_ctrl:1
	ds_read_b64 v[104:105], v3 offset:45568
	s_nop 0
	v_mov_b32_dpp v39, v38 row_ror:8 row_mask:0xf bank_mask:0xf bound_ctrl:1
	v_pk_mul_f32 v[38:39], v[38:39], v[40:41] op_sel_hi:[1,0]
	v_cvt_pk_bf16_f32 v47, v38, v39
	s_mov_b64 exec, s[2:3]
	global_store_dword v46, v47, s[14:15] offset:-4096
	s_mov_b64 exec, -1
	s_waitcnt lgkmcnt(0)
	v_pk_mul_f32 v[42:43], v[104:105], v[80:81] op_sel_hi:[1,0]
	v_pk_fma_f32 v[6:7], v[6:7], v[96:97], v[42:43] op_sel:[0,0,0] op_sel_hi:[1,0,1]
	v_pk_mul_f32 v[38:39], v[6:7], v[80:81] op_sel:[0,1] op_sel_hi:[1,1]
	v_pk_mul_f32 v[44:45], v[104:105], v[82:83] op_sel_hi:[1,0]
	v_pk_fma_f32 v[8:9], v[8:9], v[96:97], v[44:45] op_sel:[0,1,0] op_sel_hi:[1,1,1]
	v_pk_fma_f32 v[38:39], v[8:9], v[82:83], v[38:39] op_sel:[0,1,0] op_sel_hi:[1,1,1]
	v_pk_mul_f32 v[42:43], v[104:105], v[84:85] op_sel_hi:[1,0]
	v_pk_fma_f32 v[10:11], v[10:11], v[98:99], v[42:43] op_sel:[0,0,0] op_sel_hi:[1,0,1]
	v_pk_fma_f32 v[38:39], v[10:11], v[84:85], v[38:39] op_sel:[0,1,0] op_sel_hi:[1,1,1]
	v_pk_mul_f32 v[44:45], v[104:105], v[86:87] op_sel_hi:[1,0]
	v_pk_fma_f32 v[12:13], v[12:13], v[98:99], v[44:45] op_sel:[0,1,0] op_sel_hi:[1,1,1]
	v_pk_fma_f32 v[38:39], v[12:13], v[86:87], v[38:39] op_sel:[0,1,0] op_sel_hi:[1,1,1]
	v_pk_mul_f32 v[42:43], v[104:105], v[88:89] op_sel_hi:[1,0]
	v_pk_fma_f32 v[14:15], v[14:15], v[100:101], v[42:43] op_sel:[0,0,0] op_sel_hi:[1,0,1]
	v_pk_fma_f32 v[38:39], v[14:15], v[88:89], v[38:39] op_sel:[0,1,0] op_sel_hi:[1,1,1]
	v_pk_mul_f32 v[44:45], v[104:105], v[90:91] op_sel_hi:[1,0]
	v_pk_fma_f32 v[16:17], v[16:17], v[100:101], v[44:45] op_sel:[0,1,0] op_sel_hi:[1,1,1]
	v_pk_fma_f32 v[38:39], v[16:17], v[90:91], v[38:39] op_sel:[0,1,0] op_sel_hi:[1,1,1]
	v_pk_mul_f32 v[42:43], v[104:105], v[92:93] op_sel_hi:[1,0]
	v_pk_fma_f32 v[18:19], v[18:19], v[102:103], v[42:43] op_sel:[0,0,0] op_sel_hi:[1,0,1]
	v_pk_fma_f32 v[38:39], v[18:19], v[92:93], v[38:39] op_sel:[0,1,0] op_sel_hi:[1,1,1]
	v_pk_mul_f32 v[44:45], v[104:105], v[94:95] op_sel_hi:[1,0]
	v_pk_fma_f32 v[20:21], v[20:21], v[102:103], v[44:45] op_sel:[0,1,0] op_sel_hi:[1,1,1]
	v_pk_fma_f32 v[38:39], v[20:21], v[94:95], v[38:39] op_sel:[0,1,0] op_sel_hi:[1,1,1]
	s_add_u32 s14, s14, 0x1000
	s_addc_u32 s15, s15, 0
	v_add_f32_dpp v38, v38, v38 row_ror:8 row_mask:0xf bank_mask:0x3 bound_ctrl:1
	v_add_f32_dpp v38, v39, v39 row_ror:8 row_mask:0xf bank_mask:0xc bound_ctrl:1
	ds_read_b128 v[48:51], v2 offset:26880
	ds_read_b128 v[52:55], v2 offset:27136
	v_add_f32_dpp v38, v38, v38 row_half_mirror row_mask:0xf bank_mask:0xf bound_ctrl:1
	ds_read_b128 v[56:59], v2 offset:27392
	ds_read_b128 v[60:63], v2 offset:27648
	v_add_f32_dpp v38, v38, v38 quad_perm:[1,0,3,2] row_mask:0xf bank_mask:0xf bound_ctrl:1
	ds_read_b128 v[64:67], v2 offset:42240
	ds_read_b128 v[68:71], v2 offset:42496
	v_add_f32_dpp v38, v38, v38 quad_perm:[2,3,0,1] row_mask:0xf bank_mask:0xf bound_ctrl:1
	ds_read_b64 v[72:73], v3 offset:45824
	s_nop 0
	v_mov_b32_dpp v39, v38 row_ror:8 row_mask:0xf bank_mask:0xf bound_ctrl:1
	v_pk_mul_f32 v[38:39], v[38:39], v[40:41] op_sel_hi:[1,0]
	v_cvt_pk_bf16_f32 v47, v38, v39
	s_mov_b64 exec, s[2:3]
	global_store_dword v46, v47, s[14:15] offset:-4096
	s_mov_b64 exec, -1
	s_waitcnt lgkmcnt(0)
	v_pk_mul_f32 v[42:43], v[72:73], v[48:49] op_sel_hi:[1,0]
	v_pk_fma_f32 v[6:7], v[6:7], v[64:65], v[42:43] op_sel:[0,0,0] op_sel_hi:[1,0,1]
	v_pk_mul_f32 v[38:39], v[6:7], v[48:49] op_sel:[0,1] op_sel_hi:[1,1]
	v_pk_mul_f32 v[44:45], v[72:73], v[50:51] op_sel_hi:[1,0]
	v_pk_fma_f32 v[8:9], v[8:9], v[64:65], v[44:45] op_sel:[0,1,0] op_sel_hi:[1,1,1]
	v_pk_fma_f32 v[38:39], v[8:9], v[50:51], v[38:39] op_sel:[0,1,0] op_sel_hi:[1,1,1]
	v_pk_mul_f32 v[42:43], v[72:73], v[52:53] op_sel_hi:[1,0]
	v_pk_fma_f32 v[10:11], v[10:11], v[66:67], v[42:43] op_sel:[0,0,0] op_sel_hi:[1,0,1]
	v_pk_fma_f32 v[38:39], v[10:11], v[52:53], v[38:39] op_sel:[0,1,0] op_sel_hi:[1,1,1]
	v_pk_mul_f32 v[44:45], v[72:73], v[54:55] op_sel_hi:[1,0]
	v_pk_fma_f32 v[12:13], v[12:13], v[66:67], v[44:45] op_sel:[0,1,0] op_sel_hi:[1,1,1]
	v_pk_fma_f32 v[38:39], v[12:13], v[54:55], v[38:39] op_sel:[0,1,0] op_sel_hi:[1,1,1]
	v_pk_mul_f32 v[42:43], v[72:73], v[56:57] op_sel_hi:[1,0]
	v_pk_fma_f32 v[14:15], v[14:15], v[68:69], v[42:43] op_sel:[0,0,0] op_sel_hi:[1,0,1]
	v_pk_fma_f32 v[38:39], v[14:15], v[56:57], v[38:39] op_sel:[0,1,0] op_sel_hi:[1,1,1]
	v_pk_mul_f32 v[44:45], v[72:73], v[58:59] op_sel_hi:[1,0]
	v_pk_fma_f32 v[16:17], v[16:17], v[68:69], v[44:45] op_sel:[0,1,0] op_sel_hi:[1,1,1]
	v_pk_fma_f32 v[38:39], v[16:17], v[58:59], v[38:39] op_sel:[0,1,0] op_sel_hi:[1,1,1]
	v_pk_mul_f32 v[42:43], v[72:73], v[60:61] op_sel_hi:[1,0]
	v_pk_fma_f32 v[18:19], v[18:19], v[70:71], v[42:43] op_sel:[0,0,0] op_sel_hi:[1,0,1]
	v_pk_fma_f32 v[38:39], v[18:19], v[60:61], v[38:39] op_sel:[0,1,0] op_sel_hi:[1,1,1]
	v_pk_mul_f32 v[44:45], v[72:73], v[62:63] op_sel_hi:[1,0]
	v_pk_fma_f32 v[20:21], v[20:21], v[70:71], v[44:45] op_sel:[0,1,0] op_sel_hi:[1,1,1]
	v_pk_fma_f32 v[38:39], v[20:21], v[62:63], v[38:39] op_sel:[0,1,0] op_sel_hi:[1,1,1]
	s_add_u32 s14, s14, 0x1000
	s_addc_u32 s15, s15, 0
	v_add_f32_dpp v38, v38, v38 row_ror:8 row_mask:0xf bank_mask:0x3 bound_ctrl:1
	v_add_f32_dpp v38, v39, v39 row_ror:8 row_mask:0xf bank_mask:0xc bound_ctrl:1
	ds_read_b128 v[80:83], v2 offset:27904
	ds_read_b128 v[84:87], v2 offset:28160
	v_add_f32_dpp v38, v38, v38 row_half_mirror row_mask:0xf bank_mask:0xf bound_ctrl:1
	ds_read_b128 v[88:91], v2 offset:28416
	ds_read_b128 v[92:95], v2 offset:28672
	v_add_f32_dpp v38, v38, v38 quad_perm:[1,0,3,2] row_mask:0xf bank_mask:0xf bound_ctrl:1
	ds_read_b128 v[96:99], v2 offset:42752
	ds_read_b128 v[100:103], v2 offset:43008
	v_add_f32_dpp v38, v38, v38 quad_perm:[2,3,0,1] row_mask:0xf bank_mask:0xf bound_ctrl:1
	ds_read_b64 v[104:105], v3 offset:46080
	s_nop 0
	v_mov_b32_dpp v39, v38 row_ror:8 row_mask:0xf bank_mask:0xf bound_ctrl:1
	v_pk_mul_f32 v[38:39], v[38:39], v[40:41] op_sel_hi:[1,0]
	v_cvt_pk_bf16_f32 v47, v38, v39
	s_mov_b64 exec, s[2:3]
	global_store_dword v46, v47, s[14:15] offset:-4096
	s_mov_b64 exec, -1
	s_waitcnt lgkmcnt(0)
	v_pk_mul_f32 v[42:43], v[104:105], v[80:81] op_sel_hi:[1,0]
	v_pk_fma_f32 v[6:7], v[6:7], v[96:97], v[42:43] op_sel:[0,0,0] op_sel_hi:[1,0,1]
	v_pk_mul_f32 v[38:39], v[6:7], v[80:81] op_sel:[0,1] op_sel_hi:[1,1]
	v_pk_mul_f32 v[44:45], v[104:105], v[82:83] op_sel_hi:[1,0]
	v_pk_fma_f32 v[8:9], v[8:9], v[96:97], v[44:45] op_sel:[0,1,0] op_sel_hi:[1,1,1]
	v_pk_fma_f32 v[38:39], v[8:9], v[82:83], v[38:39] op_sel:[0,1,0] op_sel_hi:[1,1,1]
	v_pk_mul_f32 v[42:43], v[104:105], v[84:85] op_sel_hi:[1,0]
	v_pk_fma_f32 v[10:11], v[10:11], v[98:99], v[42:43] op_sel:[0,0,0] op_sel_hi:[1,0,1]
	v_pk_fma_f32 v[38:39], v[10:11], v[84:85], v[38:39] op_sel:[0,1,0] op_sel_hi:[1,1,1]
	v_pk_mul_f32 v[44:45], v[104:105], v[86:87] op_sel_hi:[1,0]
	v_pk_fma_f32 v[12:13], v[12:13], v[98:99], v[44:45] op_sel:[0,1,0] op_sel_hi:[1,1,1]
	v_pk_fma_f32 v[38:39], v[12:13], v[86:87], v[38:39] op_sel:[0,1,0] op_sel_hi:[1,1,1]
	v_pk_mul_f32 v[42:43], v[104:105], v[88:89] op_sel_hi:[1,0]
	v_pk_fma_f32 v[14:15], v[14:15], v[100:101], v[42:43] op_sel:[0,0,0] op_sel_hi:[1,0,1]
	v_pk_fma_f32 v[38:39], v[14:15], v[88:89], v[38:39] op_sel:[0,1,0] op_sel_hi:[1,1,1]
	v_pk_mul_f32 v[44:45], v[104:105], v[90:91] op_sel_hi:[1,0]
	v_pk_fma_f32 v[16:17], v[16:17], v[100:101], v[44:45] op_sel:[0,1,0] op_sel_hi:[1,1,1]
	v_pk_fma_f32 v[38:39], v[16:17], v[90:91], v[38:39] op_sel:[0,1,0] op_sel_hi:[1,1,1]
	v_pk_mul_f32 v[42:43], v[104:105], v[92:93] op_sel_hi:[1,0]
	v_pk_fma_f32 v[18:19], v[18:19], v[102:103], v[42:43] op_sel:[0,0,0] op_sel_hi:[1,0,1]
	v_pk_fma_f32 v[38:39], v[18:19], v[92:93], v[38:39] op_sel:[0,1,0] op_sel_hi:[1,1,1]
	v_pk_mul_f32 v[44:45], v[104:105], v[94:95] op_sel_hi:[1,0]
	v_pk_fma_f32 v[20:21], v[20:21], v[102:103], v[44:45] op_sel:[0,1,0] op_sel_hi:[1,1,1]
	v_pk_fma_f32 v[38:39], v[20:21], v[94:95], v[38:39] op_sel:[0,1,0] op_sel_hi:[1,1,1]
	s_add_u32 s14, s14, 0x1000
	s_addc_u32 s15, s15, 0
	v_add_f32_dpp v38, v38, v38 row_ror:8 row_mask:0xf bank_mask:0x3 bound_ctrl:1
	v_add_f32_dpp v38, v39, v39 row_ror:8 row_mask:0xf bank_mask:0xc bound_ctrl:1
	ds_read_b128 v[48:51], v2 offset:28928
	ds_read_b128 v[52:55], v2 offset:29184
	v_add_f32_dpp v38, v38, v38 row_half_mirror row_mask:0xf bank_mask:0xf bound_ctrl:1
	ds_read_b128 v[56:59], v2 offset:29440
	ds_read_b128 v[60:63], v2 offset:29696
	v_add_f32_dpp v38, v38, v38 quad_perm:[1,0,3,2] row_mask:0xf bank_mask:0xf bound_ctrl:1
	ds_read_b128 v[64:67], v2 offset:43264
	ds_read_b128 v[68:71], v2 offset:43520
	v_add_f32_dpp v38, v38, v38 quad_perm:[2,3,0,1] row_mask:0xf bank_mask:0xf bound_ctrl:1
	ds_read_b64 v[72:73], v3 offset:46336
	s_nop 0
	v_mov_b32_dpp v39, v38 row_ror:8 row_mask:0xf bank_mask:0xf bound_ctrl:1
	v_pk_mul_f32 v[38:39], v[38:39], v[40:41] op_sel_hi:[1,0]
	v_cvt_pk_bf16_f32 v47, v38, v39
	s_mov_b64 exec, s[2:3]
	global_store_dword v46, v47, s[14:15] offset:-4096
	s_mov_b64 exec, -1
	s_waitcnt lgkmcnt(0)
	v_pk_mul_f32 v[42:43], v[72:73], v[48:49] op_sel_hi:[1,0]
	v_pk_fma_f32 v[6:7], v[6:7], v[64:65], v[42:43] op_sel:[0,0,0] op_sel_hi:[1,0,1]
	v_pk_mul_f32 v[38:39], v[6:7], v[48:49] op_sel:[0,1] op_sel_hi:[1,1]
	v_pk_mul_f32 v[44:45], v[72:73], v[50:51] op_sel_hi:[1,0]
	v_pk_fma_f32 v[8:9], v[8:9], v[64:65], v[44:45] op_sel:[0,1,0] op_sel_hi:[1,1,1]
	v_pk_fma_f32 v[38:39], v[8:9], v[50:51], v[38:39] op_sel:[0,1,0] op_sel_hi:[1,1,1]
	v_pk_mul_f32 v[42:43], v[72:73], v[52:53] op_sel_hi:[1,0]
	v_pk_fma_f32 v[10:11], v[10:11], v[66:67], v[42:43] op_sel:[0,0,0] op_sel_hi:[1,0,1]
	v_pk_fma_f32 v[38:39], v[10:11], v[52:53], v[38:39] op_sel:[0,1,0] op_sel_hi:[1,1,1]
	v_pk_mul_f32 v[44:45], v[72:73], v[54:55] op_sel_hi:[1,0]
	v_pk_fma_f32 v[12:13], v[12:13], v[66:67], v[44:45] op_sel:[0,1,0] op_sel_hi:[1,1,1]
	v_pk_fma_f32 v[38:39], v[12:13], v[54:55], v[38:39] op_sel:[0,1,0] op_sel_hi:[1,1,1]
	v_pk_mul_f32 v[42:43], v[72:73], v[56:57] op_sel_hi:[1,0]
	v_pk_fma_f32 v[14:15], v[14:15], v[68:69], v[42:43] op_sel:[0,0,0] op_sel_hi:[1,0,1]
	v_pk_fma_f32 v[38:39], v[14:15], v[56:57], v[38:39] op_sel:[0,1,0] op_sel_hi:[1,1,1]
	v_pk_mul_f32 v[44:45], v[72:73], v[58:59] op_sel_hi:[1,0]
	v_pk_fma_f32 v[16:17], v[16:17], v[68:69], v[44:45] op_sel:[0,1,0] op_sel_hi:[1,1,1]
	v_pk_fma_f32 v[38:39], v[16:17], v[58:59], v[38:39] op_sel:[0,1,0] op_sel_hi:[1,1,1]
	v_pk_mul_f32 v[42:43], v[72:73], v[60:61] op_sel_hi:[1,0]
	v_pk_fma_f32 v[18:19], v[18:19], v[70:71], v[42:43] op_sel:[0,0,0] op_sel_hi:[1,0,1]
	v_pk_fma_f32 v[38:39], v[18:19], v[60:61], v[38:39] op_sel:[0,1,0] op_sel_hi:[1,1,1]
	v_pk_mul_f32 v[44:45], v[72:73], v[62:63] op_sel_hi:[1,0]
	v_pk_fma_f32 v[20:21], v[20:21], v[70:71], v[44:45] op_sel:[0,1,0] op_sel_hi:[1,1,1]
	v_pk_fma_f32 v[38:39], v[20:21], v[62:63], v[38:39] op_sel:[0,1,0] op_sel_hi:[1,1,1]
	s_add_u32 s14, s14, 0x1000
	s_addc_u32 s15, s15, 0
	v_add_f32_dpp v38, v38, v38 row_ror:8 row_mask:0xf bank_mask:0x3 bound_ctrl:1
	v_add_f32_dpp v38, v39, v39 row_ror:8 row_mask:0xf bank_mask:0xc bound_ctrl:1
	ds_read_b128 v[80:83], v2 offset:29952
	ds_read_b128 v[84:87], v2 offset:30208
	v_add_f32_dpp v38, v38, v38 row_half_mirror row_mask:0xf bank_mask:0xf bound_ctrl:1
	ds_read_b128 v[88:91], v2 offset:30464
	ds_read_b128 v[92:95], v2 offset:30720
	v_add_f32_dpp v38, v38, v38 quad_perm:[1,0,3,2] row_mask:0xf bank_mask:0xf bound_ctrl:1
	ds_read_b128 v[96:99], v2 offset:43776
	ds_read_b128 v[100:103], v2 offset:44032
	v_add_f32_dpp v38, v38, v38 quad_perm:[2,3,0,1] row_mask:0xf bank_mask:0xf bound_ctrl:1
	ds_read_b64 v[104:105], v3 offset:46592
	s_nop 0
	v_mov_b32_dpp v39, v38 row_ror:8 row_mask:0xf bank_mask:0xf bound_ctrl:1
	v_pk_mul_f32 v[38:39], v[38:39], v[40:41] op_sel_hi:[1,0]
	v_cvt_pk_bf16_f32 v47, v38, v39
	s_mov_b64 exec, s[2:3]
	global_store_dword v46, v47, s[14:15] offset:-4096
	s_mov_b64 exec, -1
	s_waitcnt lgkmcnt(0)
	v_pk_mul_f32 v[42:43], v[104:105], v[80:81] op_sel_hi:[1,0]
	v_pk_fma_f32 v[6:7], v[6:7], v[96:97], v[42:43] op_sel:[0,0,0] op_sel_hi:[1,0,1]
	v_pk_mul_f32 v[38:39], v[6:7], v[80:81] op_sel:[0,1] op_sel_hi:[1,1]
	v_pk_mul_f32 v[44:45], v[104:105], v[82:83] op_sel_hi:[1,0]
	v_pk_fma_f32 v[8:9], v[8:9], v[96:97], v[44:45] op_sel:[0,1,0] op_sel_hi:[1,1,1]
	v_pk_fma_f32 v[38:39], v[8:9], v[82:83], v[38:39] op_sel:[0,1,0] op_sel_hi:[1,1,1]
	v_pk_mul_f32 v[42:43], v[104:105], v[84:85] op_sel_hi:[1,0]
	v_pk_fma_f32 v[10:11], v[10:11], v[98:99], v[42:43] op_sel:[0,0,0] op_sel_hi:[1,0,1]
	v_pk_fma_f32 v[38:39], v[10:11], v[84:85], v[38:39] op_sel:[0,1,0] op_sel_hi:[1,1,1]
	v_pk_mul_f32 v[44:45], v[104:105], v[86:87] op_sel_hi:[1,0]
	v_pk_fma_f32 v[12:13], v[12:13], v[98:99], v[44:45] op_sel:[0,1,0] op_sel_hi:[1,1,1]
	v_pk_fma_f32 v[38:39], v[12:13], v[86:87], v[38:39] op_sel:[0,1,0] op_sel_hi:[1,1,1]
	v_pk_mul_f32 v[42:43], v[104:105], v[88:89] op_sel_hi:[1,0]
	v_pk_fma_f32 v[14:15], v[14:15], v[100:101], v[42:43] op_sel:[0,0,0] op_sel_hi:[1,0,1]
	v_pk_fma_f32 v[38:39], v[14:15], v[88:89], v[38:39] op_sel:[0,1,0] op_sel_hi:[1,1,1]
	v_pk_mul_f32 v[44:45], v[104:105], v[90:91] op_sel_hi:[1,0]
	v_pk_fma_f32 v[16:17], v[16:17], v[100:101], v[44:45] op_sel:[0,1,0] op_sel_hi:[1,1,1]
	v_pk_fma_f32 v[38:39], v[16:17], v[90:91], v[38:39] op_sel:[0,1,0] op_sel_hi:[1,1,1]
	v_pk_mul_f32 v[42:43], v[104:105], v[92:93] op_sel_hi:[1,0]
	v_pk_fma_f32 v[18:19], v[18:19], v[102:103], v[42:43] op_sel:[0,0,0] op_sel_hi:[1,0,1]
	v_pk_fma_f32 v[38:39], v[18:19], v[92:93], v[38:39] op_sel:[0,1,0] op_sel_hi:[1,1,1]
	v_pk_mul_f32 v[44:45], v[104:105], v[94:95] op_sel_hi:[1,0]
	v_pk_fma_f32 v[20:21], v[20:21], v[102:103], v[44:45] op_sel:[0,1,0] op_sel_hi:[1,1,1]
	v_pk_fma_f32 v[38:39], v[20:21], v[94:95], v[38:39] op_sel:[0,1,0] op_sel_hi:[1,1,1]
	s_add_u32 s14, s14, 0x1000
	s_addc_u32 s15, s15, 0
	v_add_f32_dpp v38, v38, v38 row_ror:8 row_mask:0xf bank_mask:0x3 bound_ctrl:1
	v_add_f32_dpp v38, v39, v39 row_ror:8 row_mask:0xf bank_mask:0xc bound_ctrl:1
	ds_read_b128 v[48:51], v2 offset:30976
	ds_read_b128 v[52:55], v2 offset:31232
	v_add_f32_dpp v38, v38, v38 row_half_mirror row_mask:0xf bank_mask:0xf bound_ctrl:1
	ds_read_b128 v[56:59], v2 offset:31488
	ds_read_b128 v[60:63], v2 offset:31744
	v_add_f32_dpp v38, v38, v38 quad_perm:[1,0,3,2] row_mask:0xf bank_mask:0xf bound_ctrl:1
	ds_read_b128 v[64:67], v2 offset:44288
	ds_read_b128 v[68:71], v2 offset:44544
	v_add_f32_dpp v38, v38, v38 quad_perm:[2,3,0,1] row_mask:0xf bank_mask:0xf bound_ctrl:1
	ds_read_b64 v[72:73], v3 offset:46848
	s_nop 0
	v_mov_b32_dpp v39, v38 row_ror:8 row_mask:0xf bank_mask:0xf bound_ctrl:1
	v_pk_mul_f32 v[38:39], v[38:39], v[40:41] op_sel_hi:[1,0]
	v_cvt_pk_bf16_f32 v47, v38, v39
	s_mov_b64 exec, s[2:3]
	global_store_dword v46, v47, s[14:15] offset:-4096
	s_mov_b64 exec, -1
	s_waitcnt lgkmcnt(0)
	v_pk_mul_f32 v[42:43], v[72:73], v[48:49] op_sel_hi:[1,0]
	v_pk_fma_f32 v[6:7], v[6:7], v[64:65], v[42:43] op_sel:[0,0,0] op_sel_hi:[1,0,1]
	v_pk_mul_f32 v[38:39], v[6:7], v[48:49] op_sel:[0,1] op_sel_hi:[1,1]
	v_pk_mul_f32 v[44:45], v[72:73], v[50:51] op_sel_hi:[1,0]
	v_pk_fma_f32 v[8:9], v[8:9], v[64:65], v[44:45] op_sel:[0,1,0] op_sel_hi:[1,1,1]
	v_pk_fma_f32 v[38:39], v[8:9], v[50:51], v[38:39] op_sel:[0,1,0] op_sel_hi:[1,1,1]
	v_pk_mul_f32 v[42:43], v[72:73], v[52:53] op_sel_hi:[1,0]
	v_pk_fma_f32 v[10:11], v[10:11], v[66:67], v[42:43] op_sel:[0,0,0] op_sel_hi:[1,0,1]
	v_pk_fma_f32 v[38:39], v[10:11], v[52:53], v[38:39] op_sel:[0,1,0] op_sel_hi:[1,1,1]
	v_pk_mul_f32 v[44:45], v[72:73], v[54:55] op_sel_hi:[1,0]
	v_pk_fma_f32 v[12:13], v[12:13], v[66:67], v[44:45] op_sel:[0,1,0] op_sel_hi:[1,1,1]
	v_pk_fma_f32 v[38:39], v[12:13], v[54:55], v[38:39] op_sel:[0,1,0] op_sel_hi:[1,1,1]
	v_pk_mul_f32 v[42:43], v[72:73], v[56:57] op_sel_hi:[1,0]
	v_pk_fma_f32 v[14:15], v[14:15], v[68:69], v[42:43] op_sel:[0,0,0] op_sel_hi:[1,0,1]
	v_pk_fma_f32 v[38:39], v[14:15], v[56:57], v[38:39] op_sel:[0,1,0] op_sel_hi:[1,1,1]
	v_pk_mul_f32 v[44:45], v[72:73], v[58:59] op_sel_hi:[1,0]
	v_pk_fma_f32 v[16:17], v[16:17], v[68:69], v[44:45] op_sel:[0,1,0] op_sel_hi:[1,1,1]
	v_pk_fma_f32 v[38:39], v[16:17], v[58:59], v[38:39] op_sel:[0,1,0] op_sel_hi:[1,1,1]
	v_pk_mul_f32 v[42:43], v[72:73], v[60:61] op_sel_hi:[1,0]
	v_pk_fma_f32 v[18:19], v[18:19], v[70:71], v[42:43] op_sel:[0,0,0] op_sel_hi:[1,0,1]
	v_pk_fma_f32 v[38:39], v[18:19], v[60:61], v[38:39] op_sel:[0,1,0] op_sel_hi:[1,1,1]
	v_pk_mul_f32 v[44:45], v[72:73], v[62:63] op_sel_hi:[1,0]
	v_pk_fma_f32 v[20:21], v[20:21], v[70:71], v[44:45] op_sel:[0,1,0] op_sel_hi:[1,1,1]
	v_pk_fma_f32 v[38:39], v[20:21], v[62:63], v[38:39] op_sel:[0,1,0] op_sel_hi:[1,1,1]
	s_add_u32 s14, s14, 0x1000
	s_addc_u32 s15, s15, 0
	v_add_f32_dpp v38, v38, v38 row_ror:8 row_mask:0xf bank_mask:0x3 bound_ctrl:1
	v_add_f32_dpp v38, v39, v39 row_ror:8 row_mask:0xf bank_mask:0xc bound_ctrl:1
	ds_read_b128 v[80:83], v2 offset:32000
	ds_read_b128 v[84:87], v2 offset:32256
	v_add_f32_dpp v38, v38, v38 row_half_mirror row_mask:0xf bank_mask:0xf bound_ctrl:1
	ds_read_b128 v[88:91], v2 offset:32512
	ds_read_b128 v[92:95], v2 offset:32768
	v_add_f32_dpp v38, v38, v38 quad_perm:[1,0,3,2] row_mask:0xf bank_mask:0xf bound_ctrl:1
	ds_read_b128 v[96:99], v2 offset:44800
	ds_read_b128 v[100:103], v2 offset:45056
	v_add_f32_dpp v38, v38, v38 quad_perm:[2,3,0,1] row_mask:0xf bank_mask:0xf bound_ctrl:1
	ds_read_b64 v[104:105], v3 offset:47104
	s_nop 0
	v_mov_b32_dpp v39, v38 row_ror:8 row_mask:0xf bank_mask:0xf bound_ctrl:1
	v_pk_mul_f32 v[38:39], v[38:39], v[40:41] op_sel_hi:[1,0]
	v_cvt_pk_bf16_f32 v47, v38, v39
	s_mov_b64 exec, s[2:3]
	global_store_dword v46, v47, s[14:15] offset:-4096
	s_mov_b64 exec, -1
	s_waitcnt lgkmcnt(0)
	v_pk_mul_f32 v[42:43], v[104:105], v[80:81] op_sel_hi:[1,0]
	v_pk_fma_f32 v[6:7], v[6:7], v[96:97], v[42:43] op_sel:[0,0,0] op_sel_hi:[1,0,1]
	v_pk_mul_f32 v[38:39], v[6:7], v[80:81] op_sel:[0,1] op_sel_hi:[1,1]
	v_pk_mul_f32 v[44:45], v[104:105], v[82:83] op_sel_hi:[1,0]
	v_pk_fma_f32 v[8:9], v[8:9], v[96:97], v[44:45] op_sel:[0,1,0] op_sel_hi:[1,1,1]
	v_pk_fma_f32 v[38:39], v[8:9], v[82:83], v[38:39] op_sel:[0,1,0] op_sel_hi:[1,1,1]
	v_pk_mul_f32 v[42:43], v[104:105], v[84:85] op_sel_hi:[1,0]
	v_pk_fma_f32 v[10:11], v[10:11], v[98:99], v[42:43] op_sel:[0,0,0] op_sel_hi:[1,0,1]
	v_pk_fma_f32 v[38:39], v[10:11], v[84:85], v[38:39] op_sel:[0,1,0] op_sel_hi:[1,1,1]
	v_pk_mul_f32 v[44:45], v[104:105], v[86:87] op_sel_hi:[1,0]
	v_pk_fma_f32 v[12:13], v[12:13], v[98:99], v[44:45] op_sel:[0,1,0] op_sel_hi:[1,1,1]
	v_pk_fma_f32 v[38:39], v[12:13], v[86:87], v[38:39] op_sel:[0,1,0] op_sel_hi:[1,1,1]
	v_pk_mul_f32 v[42:43], v[104:105], v[88:89] op_sel_hi:[1,0]
	v_pk_fma_f32 v[14:15], v[14:15], v[100:101], v[42:43] op_sel:[0,0,0] op_sel_hi:[1,0,1]
	v_pk_fma_f32 v[38:39], v[14:15], v[88:89], v[38:39] op_sel:[0,1,0] op_sel_hi:[1,1,1]
	v_pk_mul_f32 v[44:45], v[104:105], v[90:91] op_sel_hi:[1,0]
	v_pk_fma_f32 v[16:17], v[16:17], v[100:101], v[44:45] op_sel:[0,1,0] op_sel_hi:[1,1,1]
	v_pk_fma_f32 v[38:39], v[16:17], v[90:91], v[38:39] op_sel:[0,1,0] op_sel_hi:[1,1,1]
	v_pk_mul_f32 v[42:43], v[104:105], v[92:93] op_sel_hi:[1,0]
	v_pk_fma_f32 v[18:19], v[18:19], v[102:103], v[42:43] op_sel:[0,0,0] op_sel_hi:[1,0,1]
	v_pk_fma_f32 v[38:39], v[18:19], v[92:93], v[38:39] op_sel:[0,1,0] op_sel_hi:[1,1,1]
	v_pk_mul_f32 v[44:45], v[104:105], v[94:95] op_sel_hi:[1,0]
	v_pk_fma_f32 v[20:21], v[20:21], v[102:103], v[44:45] op_sel:[0,1,0] op_sel_hi:[1,1,1]
	v_pk_fma_f32 v[38:39], v[20:21], v[94:95], v[38:39] op_sel:[0,1,0] op_sel_hi:[1,1,1]
	s_add_u32 s14, s14, 0x1000
	s_addc_u32 s15, s15, 0
	v_add_f32_dpp v38, v38, v38 row_ror:8 row_mask:0xf bank_mask:0x3 bound_ctrl:1
	v_add_f32_dpp v38, v39, v39 row_ror:8 row_mask:0xf bank_mask:0xc bound_ctrl:1
	ds_read_b128 v[48:51], v2 offset:49408
	ds_read_b128 v[52:55], v2 offset:49664
	v_add_f32_dpp v38, v38, v38 row_half_mirror row_mask:0xf bank_mask:0xf bound_ctrl:1
	ds_read_b128 v[56:59], v2 offset:49920
	ds_read_b128 v[60:63], v2 offset:50176
	v_add_f32_dpp v38, v38, v38 quad_perm:[1,0,3,2] row_mask:0xf bank_mask:0xf bound_ctrl:1
	ds_read_b128 v[64:67], v22 offset:33024
	ds_read_b128 v[68:71], v22 offset:33280
	v_add_f32_dpp v38, v38, v38 quad_perm:[2,3,0,1] row_mask:0xf bank_mask:0xf bound_ctrl:1
	ds_read_b64 v[72:73], v23 offset:37120
	s_nop 0
	v_mov_b32_dpp v39, v38 row_ror:8 row_mask:0xf bank_mask:0xf bound_ctrl:1
	v_pk_mul_f32 v[38:39], v[38:39], v[40:41] op_sel_hi:[1,0]
	v_cvt_pk_bf16_f32 v47, v38, v39
	s_mov_b64 exec, s[2:3]
	global_store_dword v46, v47, s[14:15] offset:-4096
	s_mov_b64 exec, -1
	s_waitcnt vmcnt(8)
	v_lshlrev_b32_e32 v144, 16, v110
	v_lshlrev_b32_e32 v145, 16, v111
	v_and_b32_e32 v146, s17, v110
	v_and_b32_e32 v147, s17, v111
	v_lshlrev_b32_e32 v148, 16, v112
	v_lshlrev_b32_e32 v149, 16, v113
	v_and_b32_e32 v150, s17, v112
	v_and_b32_e32 v151, s17, v113
	v_lshlrev_b32_e32 v152, 16, v114
	v_and_b32_e32 v153, s17, v114
	ds_write_b128 v29, v[144:147] offset:256
	ds_write_b128 v29, v[148:151] offset:8448
	ds_write_b64 v30, v[116:117] offset:256
	ds_write_b64 v31, v[152:153] offset:256
	s_add_i32 s16, s16, 8
	s_waitcnt lgkmcnt(0)
	s_barrier
	s_cmpk_lt_u32 s16, 0x800
	s_cbranch_scc0 .Lgla2_done
	global_load_dword v110, v32, s[10:11]
	global_load_dword v111, v32, s[10:11] offset:-1024
	global_load_dword v112, v33, s[10:11]
	global_load_dword v113, v33, s[10:11] offset:-1024
	global_load_dword v114, v34, s[10:11]
	global_load_dword v116, v35, s[12:13]
	global_load_dword v117, v35, s[12:13] offset:4
	s_add_u32 s10, s10, 0x18000
	s_addc_u32 s11, s11, 0
	s_add_u32 s12, s12, 0x4000
	s_addc_u32 s13, s13, 0
	s_waitcnt lgkmcnt(0)
	v_pk_mul_f32 v[42:43], v[72:73], v[48:49] op_sel_hi:[1,0]
	v_pk_fma_f32 v[6:7], v[6:7], v[64:65], v[42:43] op_sel:[0,0,0] op_sel_hi:[1,0,1]
	v_pk_mul_f32 v[38:39], v[6:7], v[48:49] op_sel:[0,1] op_sel_hi:[1,1]
	v_pk_mul_f32 v[44:45], v[72:73], v[50:51] op_sel_hi:[1,0]
	v_pk_fma_f32 v[8:9], v[8:9], v[64:65], v[44:45] op_sel:[0,1,0] op_sel_hi:[1,1,1]
	v_pk_fma_f32 v[38:39], v[8:9], v[50:51], v[38:39] op_sel:[0,1,0] op_sel_hi:[1,1,1]
	v_pk_mul_f32 v[42:43], v[72:73], v[52:53] op_sel_hi:[1,0]
	v_pk_fma_f32 v[10:11], v[10:11], v[66:67], v[42:43] op_sel:[0,0,0] op_sel_hi:[1,0,1]
	v_pk_fma_f32 v[38:39], v[10:11], v[52:53], v[38:39] op_sel:[0,1,0] op_sel_hi:[1,1,1]
	v_pk_mul_f32 v[44:45], v[72:73], v[54:55] op_sel_hi:[1,0]
	v_pk_fma_f32 v[12:13], v[12:13], v[66:67], v[44:45] op_sel:[0,1,0] op_sel_hi:[1,1,1]
	v_pk_fma_f32 v[38:39], v[12:13], v[54:55], v[38:39] op_sel:[0,1,0] op_sel_hi:[1,1,1]
	v_pk_mul_f32 v[42:43], v[72:73], v[56:57] op_sel_hi:[1,0]
	v_pk_fma_f32 v[14:15], v[14:15], v[68:69], v[42:43] op_sel:[0,0,0] op_sel_hi:[1,0,1]
	v_pk_fma_f32 v[38:39], v[14:15], v[56:57], v[38:39] op_sel:[0,1,0] op_sel_hi:[1,1,1]
	v_pk_mul_f32 v[44:45], v[72:73], v[58:59] op_sel_hi:[1,0]
	v_pk_fma_f32 v[16:17], v[16:17], v[68:69], v[44:45] op_sel:[0,1,0] op_sel_hi:[1,1,1]
	v_pk_fma_f32 v[38:39], v[16:17], v[58:59], v[38:39] op_sel:[0,1,0] op_sel_hi:[1,1,1]
	v_pk_mul_f32 v[42:43], v[72:73], v[60:61] op_sel_hi:[1,0]
	v_pk_fma_f32 v[18:19], v[18:19], v[70:71], v[42:43] op_sel:[0,0,0] op_sel_hi:[1,0,1]
	v_pk_fma_f32 v[38:39], v[18:19], v[60:61], v[38:39] op_sel:[0,1,0] op_sel_hi:[1,1,1]
	v_pk_mul_f32 v[44:45], v[72:73], v[62:63] op_sel_hi:[1,0]
	v_pk_fma_f32 v[20:21], v[20:21], v[70:71], v[44:45] op_sel:[0,1,0] op_sel_hi:[1,1,1]
	v_pk_fma_f32 v[38:39], v[20:21], v[62:63], v[38:39] op_sel:[0,1,0] op_sel_hi:[1,1,1]
	s_add_u32 s14, s14, 0x1000
	s_addc_u32 s15, s15, 0
	v_add_f32_dpp v38, v38, v38 row_ror:8 row_mask:0xf bank_mask:0x3 bound_ctrl:1
	v_add_f32_dpp v38, v39, v39 row_ror:8 row_mask:0xf bank_mask:0xc bound_ctrl:1
	ds_read_b128 v[80:83], v2 offset:50432
	ds_read_b128 v[84:87], v2 offset:50688
	v_add_f32_dpp v38, v38, v38 row_half_mirror row_mask:0xf bank_mask:0xf bound_ctrl:1
	ds_read_b128 v[88:91], v2 offset:50944
	ds_read_b128 v[92:95], v2 offset:51200
	v_add_f32_dpp v38, v38, v38 quad_perm:[1,0,3,2] row_mask:0xf bank_mask:0xf bound_ctrl:1
	ds_read_b128 v[96:99], v22 offset:33536
	ds_read_b128 v[100:103], v22 offset:33792
	v_add_f32_dpp v38, v38, v38 quad_perm:[2,3,0,1] row_mask:0xf bank_mask:0xf bound_ctrl:1
	ds_read_b64 v[104:105], v23 offset:37376
	s_nop 0
	v_mov_b32_dpp v39, v38 row_ror:8 row_mask:0xf bank_mask:0xf bound_ctrl:1
	v_pk_mul_f32 v[38:39], v[38:39], v[40:41] op_sel_hi:[1,0]
	v_cvt_pk_bf16_f32 v47, v38, v39
	s_mov_b64 exec, s[2:3]
	global_store_dword v46, v47, s[14:15] offset:-4096
	s_mov_b64 exec, -1
	s_waitcnt lgkmcnt(0)
	v_pk_mul_f32 v[42:43], v[104:105], v[80:81] op_sel_hi:[1,0]
	v_pk_fma_f32 v[6:7], v[6:7], v[96:97], v[42:43] op_sel:[0,0,0] op_sel_hi:[1,0,1]
	v_pk_mul_f32 v[38:39], v[6:7], v[80:81] op_sel:[0,1] op_sel_hi:[1,1]
	v_pk_mul_f32 v[44:45], v[104:105], v[82:83] op_sel_hi:[1,0]
	v_pk_fma_f32 v[8:9], v[8:9], v[96:97], v[44:45] op_sel:[0,1,0] op_sel_hi:[1,1,1]
	v_pk_fma_f32 v[38:39], v[8:9], v[82:83], v[38:39] op_sel:[0,1,0] op_sel_hi:[1,1,1]
	v_pk_mul_f32 v[42:43], v[104:105], v[84:85] op_sel_hi:[1,0]
	v_pk_fma_f32 v[10:11], v[10:11], v[98:99], v[42:43] op_sel:[0,0,0] op_sel_hi:[1,0,1]
	v_pk_fma_f32 v[38:39], v[10:11], v[84:85], v[38:39] op_sel:[0,1,0] op_sel_hi:[1,1,1]
	v_pk_mul_f32 v[44:45], v[104:105], v[86:87] op_sel_hi:[1,0]
	v_pk_fma_f32 v[12:13], v[12:13], v[98:99], v[44:45] op_sel:[0,1,0] op_sel_hi:[1,1,1]
	v_pk_fma_f32 v[38:39], v[12:13], v[86:87], v[38:39] op_sel:[0,1,0] op_sel_hi:[1,1,1]
	v_pk_mul_f32 v[42:43], v[104:105], v[88:89] op_sel_hi:[1,0]
	v_pk_fma_f32 v[14:15], v[14:15], v[100:101], v[42:43] op_sel:[0,0,0] op_sel_hi:[1,0,1]
	v_pk_fma_f32 v[38:39], v[14:15], v[88:89], v[38:39] op_sel:[0,1,0] op_sel_hi:[1,1,1]
	v_pk_mul_f32 v[44:45], v[104:105], v[90:91] op_sel_hi:[1,0]
	v_pk_fma_f32 v[16:17], v[16:17], v[100:101], v[44:45] op_sel:[0,1,0] op_sel_hi:[1,1,1]
	v_pk_fma_f32 v[38:39], v[16:17], v[90:91], v[38:39] op_sel:[0,1,0] op_sel_hi:[1,1,1]
	v_pk_mul_f32 v[42:43], v[104:105], v[92:93] op_sel_hi:[1,0]
	v_pk_fma_f32 v[18:19], v[18:19], v[102:103], v[42:43] op_sel:[0,0,0] op_sel_hi:[1,0,1]
	v_pk_fma_f32 v[38:39], v[18:19], v[92:93], v[38:39] op_sel:[0,1,0] op_sel_hi:[1,1,1]
	v_pk_mul_f32 v[44:45], v[104:105], v[94:95] op_sel_hi:[1,0]
	v_pk_fma_f32 v[20:21], v[20:21], v[102:103], v[44:45] op_sel:[0,1,0] op_sel_hi:[1,1,1]
	v_pk_fma_f32 v[38:39], v[20:21], v[94:95], v[38:39] op_sel:[0,1,0] op_sel_hi:[1,1,1]
	s_add_u32 s14, s14, 0x1000
	s_addc_u32 s15, s15, 0
	v_add_f32_dpp v38, v38, v38 row_ror:8 row_mask:0xf bank_mask:0x3 bound_ctrl:1
	v_add_f32_dpp v38, v39, v39 row_ror:8 row_mask:0xf bank_mask:0xc bound_ctrl:1
	ds_read_b128 v[48:51], v2 offset:51456
	ds_read_b128 v[52:55], v2 offset:51712
	v_add_f32_dpp v38, v38, v38 row_half_mirror row_mask:0xf bank_mask:0xf bound_ctrl:1
	ds_read_b128 v[56:59], v2 offset:51968
	ds_read_b128 v[60:63], v2 offset:52224
	v_add_f32_dpp v38, v38, v38 quad_perm:[1,0,3,2] row_mask:0xf bank_mask:0xf bound_ctrl:1
	ds_read_b128 v[64:67], v22 offset:34048
	ds_read_b128 v[68:71], v22 offset:34304
	v_add_f32_dpp v38, v38, v38 quad_perm:[2,3,0,1] row_mask:0xf bank_mask:0xf bound_ctrl:1
	ds_read_b64 v[72:73], v23 offset:37632
	s_nop 0
	v_mov_b32_dpp v39, v38 row_ror:8 row_mask:0xf bank_mask:0xf bound_ctrl:1
	v_pk_mul_f32 v[38:39], v[38:39], v[40:41] op_sel_hi:[1,0]
	v_cvt_pk_bf16_f32 v47, v38, v39
	s_mov_b64 exec, s[2:3]
	global_store_dword v46, v47, s[14:15] offset:-4096
	s_mov_b64 exec, -1
	s_waitcnt lgkmcnt(0)
	v_pk_mul_f32 v[42:43], v[72:73], v[48:49] op_sel_hi:[1,0]
	v_pk_fma_f32 v[6:7], v[6:7], v[64:65], v[42:43] op_sel:[0,0,0] op_sel_hi:[1,0,1]
	v_pk_mul_f32 v[38:39], v[6:7], v[48:49] op_sel:[0,1] op_sel_hi:[1,1]
	v_pk_mul_f32 v[44:45], v[72:73], v[50:51] op_sel_hi:[1,0]
	v_pk_fma_f32 v[8:9], v[8:9], v[64:65], v[44:45] op_sel:[0,1,0] op_sel_hi:[1,1,1]
	v_pk_fma_f32 v[38:39], v[8:9], v[50:51], v[38:39] op_sel:[0,1,0] op_sel_hi:[1,1,1]
	v_pk_mul_f32 v[42:43], v[72:73], v[52:53] op_sel_hi:[1,0]
	v_pk_fma_f32 v[10:11], v[10:11], v[66:67], v[42:43] op_sel:[0,0,0] op_sel_hi:[1,0,1]
	v_pk_fma_f32 v[38:39], v[10:11], v[52:53], v[38:39] op_sel:[0,1,0] op_sel_hi:[1,1,1]
	v_pk_mul_f32 v[44:45], v[72:73], v[54:55] op_sel_hi:[1,0]
	v_pk_fma_f32 v[12:13], v[12:13], v[66:67], v[44:45] op_sel:[0,1,0] op_sel_hi:[1,1,1]
	v_pk_fma_f32 v[38:39], v[12:13], v[54:55], v[38:39] op_sel:[0,1,0] op_sel_hi:[1,1,1]
	v_pk_mul_f32 v[42:43], v[72:73], v[56:57] op_sel_hi:[1,0]
	v_pk_fma_f32 v[14:15], v[14:15], v[68:69], v[42:43] op_sel:[0,0,0] op_sel_hi:[1,0,1]
	v_pk_fma_f32 v[38:39], v[14:15], v[56:57], v[38:39] op_sel:[0,1,0] op_sel_hi:[1,1,1]
	v_pk_mul_f32 v[44:45], v[72:73], v[58:59] op_sel_hi:[1,0]
	v_pk_fma_f32 v[16:17], v[16:17], v[68:69], v[44:45] op_sel:[0,1,0] op_sel_hi:[1,1,1]
	v_pk_fma_f32 v[38:39], v[16:17], v[58:59], v[38:39] op_sel:[0,1,0] op_sel_hi:[1,1,1]
	v_pk_mul_f32 v[42:43], v[72:73], v[60:61] op_sel_hi:[1,0]
	v_pk_fma_f32 v[18:19], v[18:19], v[70:71], v[42:43] op_sel:[0,0,0] op_sel_hi:[1,0,1]
	v_pk_fma_f32 v[38:39], v[18:19], v[60:61], v[38:39] op_sel:[0,1,0] op_sel_hi:[1,1,1]
	v_pk_mul_f32 v[44:45], v[72:73], v[62:63] op_sel_hi:[1,0]
	v_pk_fma_f32 v[20:21], v[20:21], v[70:71], v[44:45] op_sel:[0,1,0] op_sel_hi:[1,1,1]
	v_pk_fma_f32 v[38:39], v[20:21], v[62:63], v[38:39] op_sel:[0,1,0] op_sel_hi:[1,1,1]
	s_add_u32 s14, s14, 0x1000
	s_addc_u32 s15, s15, 0
	v_add_f32_dpp v38, v38, v38 row_ror:8 row_mask:0xf bank_mask:0x3 bound_ctrl:1
	v_add_f32_dpp v38, v39, v39 row_ror:8 row_mask:0xf bank_mask:0xc bound_ctrl:1
	ds_read_b128 v[80:83], v2 offset:52480
	ds_read_b128 v[84:87], v2 offset:52736
	v_add_f32_dpp v38, v38, v38 row_half_mirror row_mask:0xf bank_mask:0xf bound_ctrl:1
	ds_read_b128 v[88:91], v2 offset:52992
	ds_read_b128 v[92:95], v2 offset:53248
	v_add_f32_dpp v38, v38, v38 quad_perm:[1,0,3,2] row_mask:0xf bank_mask:0xf bound_ctrl:1
	ds_read_b128 v[96:99], v22 offset:34560
	ds_read_b128 v[100:103], v22 offset:34816
	v_add_f32_dpp v38, v38, v38 quad_perm:[2,3,0,1] row_mask:0xf bank_mask:0xf bound_ctrl:1
	ds_read_b64 v[104:105], v23 offset:37888
	s_nop 0
	v_mov_b32_dpp v39, v38 row_ror:8 row_mask:0xf bank_mask:0xf bound_ctrl:1
	v_pk_mul_f32 v[38:39], v[38:39], v[40:41] op_sel_hi:[1,0]
	v_cvt_pk_bf16_f32 v47, v38, v39
	s_mov_b64 exec, s[2:3]
	global_store_dword v46, v47, s[14:15] offset:-4096
	s_mov_b64 exec, -1
	s_waitcnt lgkmcnt(0)
	v_pk_mul_f32 v[42:43], v[104:105], v[80:81] op_sel_hi:[1,0]
	v_pk_fma_f32 v[6:7], v[6:7], v[96:97], v[42:43] op_sel:[0,0,0] op_sel_hi:[1,0,1]
	v_pk_mul_f32 v[38:39], v[6:7], v[80:81] op_sel:[0,1] op_sel_hi:[1,1]
	v_pk_mul_f32 v[44:45], v[104:105], v[82:83] op_sel_hi:[1,0]
	v_pk_fma_f32 v[8:9], v[8:9], v[96:97], v[44:45] op_sel:[0,1,0] op_sel_hi:[1,1,1]
	v_pk_fma_f32 v[38:39], v[8:9], v[82:83], v[38:39] op_sel:[0,1,0] op_sel_hi:[1,1,1]
	v_pk_mul_f32 v[42:43], v[104:105], v[84:85] op_sel_hi:[1,0]
	v_pk_fma_f32 v[10:11], v[10:11], v[98:99], v[42:43] op_sel:[0,0,0] op_sel_hi:[1,0,1]
	v_pk_fma_f32 v[38:39], v[10:11], v[84:85], v[38:39] op_sel:[0,1,0] op_sel_hi:[1,1,1]
	v_pk_mul_f32 v[44:45], v[104:105], v[86:87] op_sel_hi:[1,0]
	v_pk_fma_f32 v[12:13], v[12:13], v[98:99], v[44:45] op_sel:[0,1,0] op_sel_hi:[1,1,1]
	v_pk_fma_f32 v[38:39], v[12:13], v[86:87], v[38:39] op_sel:[0,1,0] op_sel_hi:[1,1,1]
	v_pk_mul_f32 v[42:43], v[104:105], v[88:89] op_sel_hi:[1,0]
	v_pk_fma_f32 v[14:15], v[14:15], v[100:101], v[42:43] op_sel:[0,0,0] op_sel_hi:[1,0,1]
	v_pk_fma_f32 v[38:39], v[14:15], v[88:89], v[38:39] op_sel:[0,1,0] op_sel_hi:[1,1,1]
	v_pk_mul_f32 v[44:45], v[104:105], v[90:91] op_sel_hi:[1,0]
	v_pk_fma_f32 v[16:17], v[16:17], v[100:101], v[44:45] op_sel:[0,1,0] op_sel_hi:[1,1,1]
	v_pk_fma_f32 v[38:39], v[16:17], v[90:91], v[38:39] op_sel:[0,1,0] op_sel_hi:[1,1,1]
	v_pk_mul_f32 v[42:43], v[104:105], v[92:93] op_sel_hi:[1,0]
	v_pk_fma_f32 v[18:19], v[18:19], v[102:103], v[42:43] op_sel:[0,0,0] op_sel_hi:[1,0,1]
	v_pk_fma_f32 v[38:39], v[18:19], v[92:93], v[38:39] op_sel:[0,1,0] op_sel_hi:[1,1,1]
	v_pk_mul_f32 v[44:45], v[104:105], v[94:95] op_sel_hi:[1,0]
	v_pk_fma_f32 v[20:21], v[20:21], v[102:103], v[44:45] op_sel:[0,1,0] op_sel_hi:[1,1,1]
	v_pk_fma_f32 v[38:39], v[20:21], v[94:95], v[38:39] op_sel:[0,1,0] op_sel_hi:[1,1,1]
	s_add_u32 s14, s14, 0x1000
	s_addc_u32 s15, s15, 0
	v_add_f32_dpp v38, v38, v38 row_ror:8 row_mask:0xf bank_mask:0x3 bound_ctrl:1
	v_add_f32_dpp v38, v39, v39 row_ror:8 row_mask:0xf bank_mask:0xc bound_ctrl:1
	ds_read_b128 v[48:51], v2 offset:53504
	ds_read_b128 v[52:55], v2 offset:53760
	v_add_f32_dpp v38, v38, v38 row_half_mirror row_mask:0xf bank_mask:0xf bound_ctrl:1
	ds_read_b128 v[56:59], v2 offset:54016
	ds_read_b128 v[60:63], v2 offset:54272
	v_add_f32_dpp v38, v38, v38 quad_perm:[1,0,3,2] row_mask:0xf bank_mask:0xf bound_ctrl:1
	ds_read_b128 v[64:67], v22 offset:35072
	ds_read_b128 v[68:71], v22 offset:35328
	v_add_f32_dpp v38, v38, v38 quad_perm:[2,3,0,1] row_mask:0xf bank_mask:0xf bound_ctrl:1
	ds_read_b64 v[72:73], v23 offset:38144
	s_nop 0
	v_mov_b32_dpp v39, v38 row_ror:8 row_mask:0xf bank_mask:0xf bound_ctrl:1
	v_pk_mul_f32 v[38:39], v[38:39], v[40:41] op_sel_hi:[1,0]
	v_cvt_pk_bf16_f32 v47, v38, v39
	s_mov_b64 exec, s[2:3]
	global_store_dword v46, v47, s[14:15] offset:-4096
	s_mov_b64 exec, -1
	s_waitcnt lgkmcnt(0)
	v_pk_mul_f32 v[42:43], v[72:73], v[48:49] op_sel_hi:[1,0]
	v_pk_fma_f32 v[6:7], v[6:7], v[64:65], v[42:43] op_sel:[0,0,0] op_sel_hi:[1,0,1]
	v_pk_mul_f32 v[38:39], v[6:7], v[48:49] op_sel:[0,1] op_sel_hi:[1,1]
	v_pk_mul_f32 v[44:45], v[72:73], v[50:51] op_sel_hi:[1,0]
	v_pk_fma_f32 v[8:9], v[8:9], v[64:65], v[44:45] op_sel:[0,1,0] op_sel_hi:[1,1,1]
	v_pk_fma_f32 v[38:39], v[8:9], v[50:51], v[38:39] op_sel:[0,1,0] op_sel_hi:[1,1,1]
	v_pk_mul_f32 v[42:43], v[72:73], v[52:53] op_sel_hi:[1,0]
	v_pk_fma_f32 v[10:11], v[10:11], v[66:67], v[42:43] op_sel:[0,0,0] op_sel_hi:[1,0,1]
	v_pk_fma_f32 v[38:39], v[10:11], v[52:53], v[38:39] op_sel:[0,1,0] op_sel_hi:[1,1,1]
	v_pk_mul_f32 v[44:45], v[72:73], v[54:55] op_sel_hi:[1,0]
	v_pk_fma_f32 v[12:13], v[12:13], v[66:67], v[44:45] op_sel:[0,1,0] op_sel_hi:[1,1,1]
	v_pk_fma_f32 v[38:39], v[12:13], v[54:55], v[38:39] op_sel:[0,1,0] op_sel_hi:[1,1,1]
	v_pk_mul_f32 v[42:43], v[72:73], v[56:57] op_sel_hi:[1,0]
	v_pk_fma_f32 v[14:15], v[14:15], v[68:69], v[42:43] op_sel:[0,0,0] op_sel_hi:[1,0,1]
	v_pk_fma_f32 v[38:39], v[14:15], v[56:57], v[38:39] op_sel:[0,1,0] op_sel_hi:[1,1,1]
	v_pk_mul_f32 v[44:45], v[72:73], v[58:59] op_sel_hi:[1,0]
	v_pk_fma_f32 v[16:17], v[16:17], v[68:69], v[44:45] op_sel:[0,1,0] op_sel_hi:[1,1,1]
	v_pk_fma_f32 v[38:39], v[16:17], v[58:59], v[38:39] op_sel:[0,1,0] op_sel_hi:[1,1,1]
	v_pk_mul_f32 v[42:43], v[72:73], v[60:61] op_sel_hi:[1,0]
	v_pk_fma_f32 v[18:19], v[18:19], v[70:71], v[42:43] op_sel:[0,0,0] op_sel_hi:[1,0,1]
	v_pk_fma_f32 v[38:39], v[18:19], v[60:61], v[38:39] op_sel:[0,1,0] op_sel_hi:[1,1,1]
	v_pk_mul_f32 v[44:45], v[72:73], v[62:63] op_sel_hi:[1,0]
	v_pk_fma_f32 v[20:21], v[20:21], v[70:71], v[44:45] op_sel:[0,1,0] op_sel_hi:[1,1,1]
	v_pk_fma_f32 v[38:39], v[20:21], v[62:63], v[38:39] op_sel:[0,1,0] op_sel_hi:[1,1,1]
	s_add_u32 s14, s14, 0x1000
	s_addc_u32 s15, s15, 0
	v_add_f32_dpp v38, v38, v38 row_ror:8 row_mask:0xf bank_mask:0x3 bound_ctrl:1
	v_add_f32_dpp v38, v39, v39 row_ror:8 row_mask:0xf bank_mask:0xc bound_ctrl:1
	ds_read_b128 v[80:83], v2 offset:54528
	ds_read_b128 v[84:87], v2 offset:54784
	v_add_f32_dpp v38, v38, v38 row_half_mirror row_mask:0xf bank_mask:0xf bound_ctrl:1
	ds_read_b128 v[88:91], v2 offset:55040
	ds_read_b128 v[92:95], v2 offset:55296
	v_add_f32_dpp v38, v38, v38 quad_perm:[1,0,3,2] row_mask:0xf bank_mask:0xf bound_ctrl:1
	ds_read_b128 v[96:99], v22 offset:35584
	ds_read_b128 v[100:103], v22 offset:35840
	v_add_f32_dpp v38, v38, v38 quad_perm:[2,3,0,1] row_mask:0xf bank_mask:0xf bound_ctrl:1
	ds_read_b64 v[104:105], v23 offset:38400
	s_nop 0
	v_mov_b32_dpp v39, v38 row_ror:8 row_mask:0xf bank_mask:0xf bound_ctrl:1
	v_pk_mul_f32 v[38:39], v[38:39], v[40:41] op_sel_hi:[1,0]
	v_cvt_pk_bf16_f32 v47, v38, v39
	s_mov_b64 exec, s[2:3]
	global_store_dword v46, v47, s[14:15] offset:-4096
	s_mov_b64 exec, -1
	s_waitcnt lgkmcnt(0)
	v_pk_mul_f32 v[42:43], v[104:105], v[80:81] op_sel_hi:[1,0]
	v_pk_fma_f32 v[6:7], v[6:7], v[96:97], v[42:43] op_sel:[0,0,0] op_sel_hi:[1,0,1]
	v_pk_mul_f32 v[38:39], v[6:7], v[80:81] op_sel:[0,1] op_sel_hi:[1,1]
	v_pk_mul_f32 v[44:45], v[104:105], v[82:83] op_sel_hi:[1,0]
	v_pk_fma_f32 v[8:9], v[8:9], v[96:97], v[44:45] op_sel:[0,1,0] op_sel_hi:[1,1,1]
	v_pk_fma_f32 v[38:39], v[8:9], v[82:83], v[38:39] op_sel:[0,1,0] op_sel_hi:[1,1,1]
	v_pk_mul_f32 v[42:43], v[104:105], v[84:85] op_sel_hi:[1,0]
	v_pk_fma_f32 v[10:11], v[10:11], v[98:99], v[42:43] op_sel:[0,0,0] op_sel_hi:[1,0,1]
	v_pk_fma_f32 v[38:39], v[10:11], v[84:85], v[38:39] op_sel:[0,1,0] op_sel_hi:[1,1,1]
	v_pk_mul_f32 v[44:45], v[104:105], v[86:87] op_sel_hi:[1,0]
	v_pk_fma_f32 v[12:13], v[12:13], v[98:99], v[44:45] op_sel:[0,1,0] op_sel_hi:[1,1,1]
	v_pk_fma_f32 v[38:39], v[12:13], v[86:87], v[38:39] op_sel:[0,1,0] op_sel_hi:[1,1,1]
	v_pk_mul_f32 v[42:43], v[104:105], v[88:89] op_sel_hi:[1,0]
	v_pk_fma_f32 v[14:15], v[14:15], v[100:101], v[42:43] op_sel:[0,0,0] op_sel_hi:[1,0,1]
	v_pk_fma_f32 v[38:39], v[14:15], v[88:89], v[38:39] op_sel:[0,1,0] op_sel_hi:[1,1,1]
	v_pk_mul_f32 v[44:45], v[104:105], v[90:91] op_sel_hi:[1,0]
	v_pk_fma_f32 v[16:17], v[16:17], v[100:101], v[44:45] op_sel:[0,1,0] op_sel_hi:[1,1,1]
	v_pk_fma_f32 v[38:39], v[16:17], v[90:91], v[38:39] op_sel:[0,1,0] op_sel_hi:[1,1,1]
	v_pk_mul_f32 v[42:43], v[104:105], v[92:93] op_sel_hi:[1,0]
	v_pk_fma_f32 v[18:19], v[18:19], v[102:103], v[42:43] op_sel:[0,0,0] op_sel_hi:[1,0,1]
	v_pk_fma_f32 v[38:39], v[18:19], v[92:93], v[38:39] op_sel:[0,1,0] op_sel_hi:[1,1,1]
	v_pk_mul_f32 v[44:45], v[104:105], v[94:95] op_sel_hi:[1,0]
	v_pk_fma_f32 v[20:21], v[20:21], v[102:103], v[44:45] op_sel:[0,1,0] op_sel_hi:[1,1,1]
	v_pk_fma_f32 v[38:39], v[20:21], v[94:95], v[38:39] op_sel:[0,1,0] op_sel_hi:[1,1,1]
	s_add_u32 s14, s14, 0x1000
	s_addc_u32 s15, s15, 0
	v_add_f32_dpp v38, v38, v38 row_ror:8 row_mask:0xf bank_mask:0x3 bound_ctrl:1
	v_add_f32_dpp v38, v39, v39 row_ror:8 row_mask:0xf bank_mask:0xc bound_ctrl:1
	ds_read_b128 v[48:51], v2 offset:55552
	ds_read_b128 v[52:55], v2 offset:55808
	v_add_f32_dpp v38, v38, v38 row_half_mirror row_mask:0xf bank_mask:0xf bound_ctrl:1
	ds_read_b128 v[56:59], v2 offset:56064
	ds_read_b128 v[60:63], v2 offset:56320
	v_add_f32_dpp v38, v38, v38 quad_perm:[1,0,3,2] row_mask:0xf bank_mask:0xf bound_ctrl:1
	ds_read_b128 v[64:67], v22 offset:36096
	ds_read_b128 v[68:71], v22 offset:36352
	v_add_f32_dpp v38, v38, v38 quad_perm:[2,3,0,1] row_mask:0xf bank_mask:0xf bound_ctrl:1
	ds_read_b64 v[72:73], v23 offset:38656
	s_nop 0
	v_mov_b32_dpp v39, v38 row_ror:8 row_mask:0xf bank_mask:0xf bound_ctrl:1
	v_pk_mul_f32 v[38:39], v[38:39], v[40:41] op_sel_hi:[1,0]
	v_cvt_pk_bf16_f32 v47, v38, v39
	s_mov_b64 exec, s[2:3]
	global_store_dword v46, v47, s[14:15] offset:-4096
	s_mov_b64 exec, -1
	s_waitcnt lgkmcnt(0)
	v_pk_mul_f32 v[42:43], v[72:73], v[48:49] op_sel_hi:[1,0]
	v_pk_fma_f32 v[6:7], v[6:7], v[64:65], v[42:43] op_sel:[0,0,0] op_sel_hi:[1,0,1]
	v_pk_mul_f32 v[38:39], v[6:7], v[48:49] op_sel:[0,1] op_sel_hi:[1,1]
	v_pk_mul_f32 v[44:45], v[72:73], v[50:51] op_sel_hi:[1,0]
	v_pk_fma_f32 v[8:9], v[8:9], v[64:65], v[44:45] op_sel:[0,1,0] op_sel_hi:[1,1,1]
	v_pk_fma_f32 v[38:39], v[8:9], v[50:51], v[38:39] op_sel:[0,1,0] op_sel_hi:[1,1,1]
	v_pk_mul_f32 v[42:43], v[72:73], v[52:53] op_sel_hi:[1,0]
	v_pk_fma_f32 v[10:11], v[10:11], v[66:67], v[42:43] op_sel:[0,0,0] op_sel_hi:[1,0,1]
	v_pk_fma_f32 v[38:39], v[10:11], v[52:53], v[38:39] op_sel:[0,1,0] op_sel_hi:[1,1,1]
	v_pk_mul_f32 v[44:45], v[72:73], v[54:55] op_sel_hi:[1,0]
	v_pk_fma_f32 v[12:13], v[12:13], v[66:67], v[44:45] op_sel:[0,1,0] op_sel_hi:[1,1,1]
	v_pk_fma_f32 v[38:39], v[12:13], v[54:55], v[38:39] op_sel:[0,1,0] op_sel_hi:[1,1,1]
	v_pk_mul_f32 v[42:43], v[72:73], v[56:57] op_sel_hi:[1,0]
	v_pk_fma_f32 v[14:15], v[14:15], v[68:69], v[42:43] op_sel:[0,0,0] op_sel_hi:[1,0,1]
	v_pk_fma_f32 v[38:39], v[14:15], v[56:57], v[38:39] op_sel:[0,1,0] op_sel_hi:[1,1,1]
	v_pk_mul_f32 v[44:45], v[72:73], v[58:59] op_sel_hi:[1,0]
	v_pk_fma_f32 v[16:17], v[16:17], v[68:69], v[44:45] op_sel:[0,1,0] op_sel_hi:[1,1,1]
	v_pk_fma_f32 v[38:39], v[16:17], v[58:59], v[38:39] op_sel:[0,1,0] op_sel_hi:[1,1,1]
	v_pk_mul_f32 v[42:43], v[72:73], v[60:61] op_sel_hi:[1,0]
	v_pk_fma_f32 v[18:19], v[18:19], v[70:71], v[42:43] op_sel:[0,0,0] op_sel_hi:[1,0,1]
	v_pk_fma_f32 v[38:39], v[18:19], v[60:61], v[38:39] op_sel:[0,1,0] op_sel_hi:[1,1,1]
	v_pk_mul_f32 v[44:45], v[72:73], v[62:63] op_sel_hi:[1,0]
	v_pk_fma_f32 v[20:21], v[20:21], v[70:71], v[44:45] op_sel:[0,1,0] op_sel_hi:[1,1,1]
	v_pk_fma_f32 v[38:39], v[20:21], v[62:63], v[38:39] op_sel:[0,1,0] op_sel_hi:[1,1,1]
	s_add_u32 s14, s14, 0x1000
	s_addc_u32 s15, s15, 0
	v_add_f32_dpp v38, v38, v38 row_ror:8 row_mask:0xf bank_mask:0x3 bound_ctrl:1
	v_add_f32_dpp v38, v39, v39 row_ror:8 row_mask:0xf bank_mask:0xc bound_ctrl:1
	ds_read_b128 v[80:83], v2 offset:56576
	ds_read_b128 v[84:87], v2 offset:56832
	v_add_f32_dpp v38, v38, v38 row_half_mirror row_mask:0xf bank_mask:0xf bound_ctrl:1
	ds_read_b128 v[88:91], v2 offset:57088
	ds_read_b128 v[92:95], v2 offset:57344
	v_add_f32_dpp v38, v38, v38 quad_perm:[1,0,3,2] row_mask:0xf bank_mask:0xf bound_ctrl:1
	ds_read_b128 v[96:99], v22 offset:36608
	ds_read_b128 v[100:103], v22 offset:36864
	v_add_f32_dpp v38, v38, v38 quad_perm:[2,3,0,1] row_mask:0xf bank_mask:0xf bound_ctrl:1
	ds_read_b64 v[104:105], v23 offset:38912
	s_nop 0
	v_mov_b32_dpp v39, v38 row_ror:8 row_mask:0xf bank_mask:0xf bound_ctrl:1
	v_pk_mul_f32 v[38:39], v[38:39], v[40:41] op_sel_hi:[1,0]
	v_cvt_pk_bf16_f32 v47, v38, v39
	s_mov_b64 exec, s[2:3]
	global_store_dword v46, v47, s[14:15] offset:-4096
	s_mov_b64 exec, -1
	s_waitcnt lgkmcnt(0)
	v_pk_mul_f32 v[42:43], v[104:105], v[80:81] op_sel_hi:[1,0]
	v_pk_fma_f32 v[6:7], v[6:7], v[96:97], v[42:43] op_sel:[0,0,0] op_sel_hi:[1,0,1]
	v_pk_mul_f32 v[38:39], v[6:7], v[80:81] op_sel:[0,1] op_sel_hi:[1,1]
	v_pk_mul_f32 v[44:45], v[104:105], v[82:83] op_sel_hi:[1,0]
	v_pk_fma_f32 v[8:9], v[8:9], v[96:97], v[44:45] op_sel:[0,1,0] op_sel_hi:[1,1,1]
	v_pk_fma_f32 v[38:39], v[8:9], v[82:83], v[38:39] op_sel:[0,1,0] op_sel_hi:[1,1,1]
	v_pk_mul_f32 v[42:43], v[104:105], v[84:85] op_sel_hi:[1,0]
	v_pk_fma_f32 v[10:11], v[10:11], v[98:99], v[42:43] op_sel:[0,0,0] op_sel_hi:[1,0,1]
	v_pk_fma_f32 v[38:39], v[10:11], v[84:85], v[38:39] op_sel:[0,1,0] op_sel_hi:[1,1,1]
	v_pk_mul_f32 v[44:45], v[104:105], v[86:87] op_sel_hi:[1,0]
	v_pk_fma_f32 v[12:13], v[12:13], v[98:99], v[44:45] op_sel:[0,1,0] op_sel_hi:[1,1,1]
	v_pk_fma_f32 v[38:39], v[12:13], v[86:87], v[38:39] op_sel:[0,1,0] op_sel_hi:[1,1,1]
	v_pk_mul_f32 v[42:43], v[104:105], v[88:89] op_sel_hi:[1,0]
	v_pk_fma_f32 v[14:15], v[14:15], v[100:101], v[42:43] op_sel:[0,0,0] op_sel_hi:[1,0,1]
	v_pk_fma_f32 v[38:39], v[14:15], v[88:89], v[38:39] op_sel:[0,1,0] op_sel_hi:[1,1,1]
	v_pk_mul_f32 v[44:45], v[104:105], v[90:91] op_sel_hi:[1,0]
	v_pk_fma_f32 v[16:17], v[16:17], v[100:101], v[44:45] op_sel:[0,1,0] op_sel_hi:[1,1,1]
	v_pk_fma_f32 v[38:39], v[16:17], v[90:91], v[38:39] op_sel:[0,1,0] op_sel_hi:[1,1,1]
	v_pk_mul_f32 v[42:43], v[104:105], v[92:93] op_sel_hi:[1,0]
	v_pk_fma_f32 v[18:19], v[18:19], v[102:103], v[42:43] op_sel:[0,0,0] op_sel_hi:[1,0,1]
	v_pk_fma_f32 v[38:39], v[18:19], v[92:93], v[38:39] op_sel:[0,1,0] op_sel_hi:[1,1,1]
	v_pk_mul_f32 v[44:45], v[104:105], v[94:95] op_sel_hi:[1,0]
	v_pk_fma_f32 v[20:21], v[20:21], v[102:103], v[44:45] op_sel:[0,1,0] op_sel_hi:[1,1,1]
	v_pk_fma_f32 v[38:39], v[20:21], v[94:95], v[38:39] op_sel:[0,1,0] op_sel_hi:[1,1,1]
	s_add_u32 s14, s14, 0x1000
	s_addc_u32 s15, s15, 0
	v_add_f32_dpp v38, v38, v38 row_ror:8 row_mask:0xf bank_mask:0x3 bound_ctrl:1
	v_add_f32_dpp v38, v39, v39 row_ror:8 row_mask:0xf bank_mask:0xc bound_ctrl:1
	ds_read_b128 v[48:51], v2 offset:256
	ds_read_b128 v[52:55], v2 offset:512
	v_add_f32_dpp v38, v38, v38 row_half_mirror row_mask:0xf bank_mask:0xf bound_ctrl:1
	ds_read_b128 v[56:59], v2 offset:768
	ds_read_b128 v[60:63], v2 offset:1024
	v_add_f32_dpp v38, v38, v38 quad_perm:[1,0,3,2] row_mask:0xf bank_mask:0xf bound_ctrl:1
	ds_read_b128 v[64:67], v2 offset:16640
	ds_read_b128 v[68:71], v2 offset:16896
	v_add_f32_dpp v38, v38, v38 quad_perm:[2,3,0,1] row_mask:0xf bank_mask:0xf bound_ctrl:1
	ds_read_b64 v[72:73], v3 offset:20736
	s_nop 0
	v_mov_b32_dpp v39, v38 row_ror:8 row_mask:0xf bank_mask:0xf bound_ctrl:1
	v_pk_mul_f32 v[38:39], v[38:39], v[40:41] op_sel_hi:[1,0]
	v_cvt_pk_bf16_f32 v47, v38, v39
	s_mov_b64 exec, s[2:3]
	global_store_dword v46, v47, s[14:15] offset:-4096
	s_mov_b64 exec, -1
	s_waitcnt vmcnt(8)
	v_lshlrev_b32_e32 v144, 16, v110
	v_lshlrev_b32_e32 v145, 16, v111
	v_and_b32_e32 v146, s17, v110
	v_and_b32_e32 v147, s17, v111
	v_lshlrev_b32_e32 v148, 16, v112
	v_lshlrev_b32_e32 v149, 16, v113
	v_and_b32_e32 v150, s17, v112
	v_and_b32_e32 v151, s17, v113
	v_lshlrev_b32_e32 v152, 16, v114
	v_and_b32_e32 v153, s17, v114
	ds_write_b128 v29, v[144:147] offset:24832
	ds_write_b128 v29, v[148:151] offset:33024
	ds_write_b64 v30, v[116:117] offset:24832
	ds_write_b64 v31, v[152:153] offset:24832
	s_add_i32 s16, s16, 8
	s_waitcnt lgkmcnt(0)
	s_barrier
	s_cmpk_lt_u32 s16, 0x800
	s_cbranch_scc1 .Lgla2_loop
.Lgla2_done:
	v_readlane_b32 s0, v255, 18
	v_readlane_b32 s1, v255, 19
	s_load_dwordx2 s[2:3], s[0:1], 0xe8
	s_lshr_b32 s0, s18, 5
	s_lshl_b32 s4, s0, 17
	s_add_u32 s4, s4, 74236160
	v_lshl_add_u32 v42, v46, 1, v4
	s_waitcnt lgkmcnt(0)
	s_add_u32 s2, s2, s4
	s_addc_u32 s3, s3, 0
	global_store_dwordx2 v42, v[6:7], s[2:3] offset:0
	global_store_dwordx2 v42, v[8:9], s[2:3] offset:1024
	global_store_dwordx2 v42, v[10:11], s[2:3] offset:2048
	global_store_dwordx2 v42, v[12:13], s[2:3] offset:3072
	s_add_u32 s2, s2, 0x1000
	s_addc_u32 s3, s3, 0
	global_store_dwordx2 v42, v[14:15], s[2:3] offset:0
	global_store_dwordx2 v42, v[16:17], s[2:3] offset:1024
	global_store_dwordx2 v42, v[18:19], s[2:3] offset:2048
	global_store_dwordx2 v42, v[20:21], s[2:3] offset:3072
	s_add_i32 s18, s18, s19
	s_waitcnt vmcnt(0)
	s_cmpk_lt_i32 s18, 0x400
	s_cbranch_scc1 .Lgla2_item
	s_branch .LBB0_80

.Lml2_nsl0:
	s_add_u32 s22, s22, 0x400
	s_addc_u32 s23, s23, 0
	s_add_u32 s8, s8, 0xc000
	s_addc_u32 s9, s9, 0
	s_add_u32 s10, s10, 0x20000
	s_addc_u32 s11, s11, 0
	s_add_u32 s12, s12, 0x400
	s_addc_u32 s13, s13, 0
	s_waitcnt vmcnt(0)
	v_lshlrev_b32_e32 v88, 16, v80
	v_lshlrev_b32_e32 v89, 16, v81
	v_and_b32_e32 v90, s17, v80
	v_and_b32_e32 v91, s17, v81
	v_lshlrev_b32_e32 v92, 16, v82
	v_and_b32_e32 v93, s17, v82
	v_lshlrev_b32_e32 v94, 16, v83
	v_and_b32_e32 v95, s17, v83
	v_lshlrev_b32_e32 v96, 16, v84
	v_and_b32_e32 v97, s17, v84
	ds_write_b128 v69, v[88:91] offset:256
	ds_write_b64 v70, v[92:93] offset:256
	ds_write_b64 v71, v[94:95] offset:256
	ds_write_b64 v71, v[96:97] offset:384
	ds_write_b32 v72, v85 offset:256
	s_cmp_lg_u32 s36, 4
	s_cbranch_scc1 .Lml2_nsc0
	v_mov_b32_e32 v98, v87
	s_nop 1
	v_add_f32_dpp v98, v98, v98 row_shr:1 row_mask:0xf bank_mask:0xf bound_ctrl:1
	s_nop 1
	v_add_f32_dpp v98, v98, v98 row_shr:2 row_mask:0xf bank_mask:0xf bound_ctrl:1
	s_nop 1
	v_add_f32_dpp v98, v98, v98 row_shr:4 row_mask:0xf bank_mask:0xf bound_ctrl:1
	s_nop 1
	v_sub_f32_e32 v99, v86, v98
	s_nop 1
	v_max_f32_dpp v99, v99, v99 row_shr:1 row_mask:0xf bank_mask:0xf
	s_nop 1
	v_max_f32_dpp v99, v99, v99 row_shr:2 row_mask:0xf bank_mask:0xf
	s_nop 1
	v_max_f32_dpp v99, v99, v99 row_shr:4 row_mask:0xf bank_mask:0xf
	s_nop 1
	v_max_f32_e32 v99, v99, v0
	v_add_f32_e32 v103, v98, v99
	v_mov_b32_e32 v105, v0
	s_nop 1
	v_mov_b32_dpp v105, v103 row_shr:1 row_mask:0xf bank_mask:0xf
	v_sub_f32_e32 v104, v86, v103
	v_add_f32_e32 v105, v87, v105
	v_fma_f32 v104, v104, s29, v29
	v_sub_f32_e32 v105, v105, v103
	v_exp_f32_e32 v101, v104
	v_mul_f32_e32 v105, s29, v105
	v_mul_f32_e32 v104, 0xbfb8aa3b, v103
	v_exp_f32_e32 v100, v105
	v_exp_f32_e32 v102, v104
	v_readlane_b32 s4, v103, 7
	s_nop 3
	v_mov_b32_e32 v0, s4
	ds_write_b128 v73, v[100:103] offset:256

.Lml2_nsl1:
	s_add_u32 s22, s22, 0x400
	s_addc_u32 s23, s23, 0
	s_add_u32 s8, s8, 0xc000
	s_addc_u32 s9, s9, 0
	s_add_u32 s10, s10, 0x20000
	s_addc_u32 s11, s11, 0
	s_add_u32 s12, s12, 0x400
	s_addc_u32 s13, s13, 0
	s_waitcnt vmcnt(0)
	v_lshlrev_b32_e32 v88, 16, v80
	v_lshlrev_b32_e32 v89, 16, v81
	v_and_b32_e32 v90, s17, v80
	v_and_b32_e32 v91, s17, v81
	v_lshlrev_b32_e32 v92, 16, v82
	v_and_b32_e32 v93, s17, v82
	v_lshlrev_b32_e32 v94, 16, v83
	v_and_b32_e32 v95, s17, v83
	v_lshlrev_b32_e32 v96, 16, v84
	v_and_b32_e32 v97, s17, v84
	ds_write_b128 v69, v[88:91] offset:16640
	ds_write_b64 v70, v[92:93] offset:16640
	ds_write_b64 v71, v[94:95] offset:16640
	ds_write_b64 v71, v[96:97] offset:16768
	ds_write_b32 v72, v85 offset:16640
	s_cmp_lg_u32 s36, 4
	s_cbranch_scc1 .Lml2_nsc1
	v_mov_b32_e32 v98, v87
	s_nop 1
	v_add_f32_dpp v98, v98, v98 row_shr:1 row_mask:0xf bank_mask:0xf bound_ctrl:1
	s_nop 1
	v_add_f32_dpp v98, v98, v98 row_shr:2 row_mask:0xf bank_mask:0xf bound_ctrl:1
	s_nop 1
	v_add_f32_dpp v98, v98, v98 row_shr:4 row_mask:0xf bank_mask:0xf bound_ctrl:1
	s_nop 1
	v_sub_f32_e32 v99, v86, v98
	s_nop 1
	v_max_f32_dpp v99, v99, v99 row_shr:1 row_mask:0xf bank_mask:0xf
	s_nop 1
	v_max_f32_dpp v99, v99, v99 row_shr:2 row_mask:0xf bank_mask:0xf
	s_nop 1
	v_max_f32_dpp v99, v99, v99 row_shr:4 row_mask:0xf bank_mask:0xf
	s_nop 1
	v_max_f32_e32 v99, v99, v0
	v_add_f32_e32 v103, v98, v99
	v_mov_b32_e32 v105, v0
	s_nop 1
	v_mov_b32_dpp v105, v103 row_shr:1 row_mask:0xf bank_mask:0xf
	v_sub_f32_e32 v104, v86, v103
	v_add_f32_e32 v105, v87, v105
	v_fma_f32 v104, v104, s29, v29
	v_sub_f32_e32 v105, v105, v103
	v_exp_f32_e32 v101, v104
	v_mul_f32_e32 v105, s29, v105
	v_mul_f32_e32 v104, 0xbfb8aa3b, v103
	v_exp_f32_e32 v100, v105
	v_exp_f32_e32 v102, v104
	v_readlane_b32 s4, v103, 7
	s_nop 3
	v_mov_b32_e32 v0, s4
	ds_write_b128 v73, v[100:103] offset:16640
.Lml2_nsc1:
	v_add_u32_e32 v64, s20, v69
	v_add_u32_e32 v65, s20, v70
	v_add_u32_e32 v66, s20, v71
	v_add_u32_e32 v67, s20, v72
	v_add_u32_e32 v68, s20, v73
	v_add_u32_e32 v58, s18, v2
	v_add_u32_e32 v59, s18, v3
	v_mov_b32_e32 v60, s18
	v_add_u32_e32 v61, s19, v2
	v_add_u32_e32 v62, s19, v3
	v_mov_b32_e32 v63, s19
	v_mov_b32_e32 v6, 0
	v_mov_b32_e32 v7, 0
	v_mov_b32_e32 v8, 0
	v_mov_b32_e32 v9, 0
	v_mov_b32_e32 v10, 0
	v_mov_b32_e32 v11, 0
	v_mov_b32_e32 v12, 0
	v_mov_b32_e32 v13, 0
	v_mov_b32_e32 v14, 0
	v_mov_b32_e32 v15, 0
	v_mov_b32_e32 v16, 0
	v_mov_b32_e32 v17, 0
	s_mov_b32 s16, 0
	s_waitcnt vmcnt(0) lgkmcnt(0)
	s_barrier
	ds_read_b128 v[30:33], v2 offset:8448
	ds_read_b128 v[34:37], v2 offset:8704
	ds_read_b64 v[38:39], v3 offset:12544
	ds_read_b128 v[40:43], v1 offset:14848

.Lml2_nsl2:
	s_add_u32 s22, s22, 0x400
	s_addc_u32 s23, s23, 0
	s_add_u32 s8, s8, 0xc000
	s_addc_u32 s9, s9, 0
	s_add_u32 s10, s10, 0x20000
	s_addc_u32 s11, s11, 0
	s_add_u32 s12, s12, 0x400
	s_addc_u32 s13, s13, 0
	ds_read_b128 v[44:47], v2 offset:8960
	ds_read_b128 v[48:51], v2 offset:9216
	ds_read_b64 v[52:53], v3 offset:12800
	ds_read_b128 v[54:57], v1 offset:14864
	s_waitcnt lgkmcnt(4)
	v_pk_mul_f32 v[18:19], v[30:31], v[40:41] op_sel:[0,1] op_sel_hi:[1,1]
	v_pk_mul_f32 v[20:21], v[32:33], v[40:41] op_sel:[0,1] op_sel_hi:[1,1]
	v_pk_mul_f32 v[22:23], v[38:39], v[18:19] op_sel:[0,0] op_sel_hi:[1,0]
	v_pk_fma_f32 v[6:7], v[6:7], v[40:41], v[22:23] op_sel_hi:[1,0,1]
	v_pk_mul_f32 v[26:27], v[6:7], v[34:35] op_sel_hi:[1,0]
	v_pk_mul_f32 v[24:25], v[38:39], v[18:19] op_sel:[0,1] op_sel_hi:[1,1]
	v_pk_fma_f32 v[8:9], v[8:9], v[40:41], v[24:25] op_sel_hi:[1,0,1]
	v_pk_fma_f32 v[26:27], v[8:9], v[34:35], v[26:27] op_sel:[0,1,0] op_sel_hi:[1,1,1]
	v_pk_mul_f32 v[22:23], v[38:39], v[20:21] op_sel:[0,0] op_sel_hi:[1,0]
	v_pk_fma_f32 v[10:11], v[10:11], v[40:41], v[22:23] op_sel_hi:[1,0,1]
	v_pk_fma_f32 v[26:27], v[10:11], v[36:37], v[26:27] op_sel:[0,0,0] op_sel_hi:[1,0,1]
	v_pk_mul_f32 v[24:25], v[38:39], v[20:21] op_sel:[0,1] op_sel_hi:[1,1]
	v_pk_fma_f32 v[12:13], v[12:13], v[40:41], v[24:25] op_sel_hi:[1,0,1]
	v_pk_fma_f32 v[26:27], v[12:13], v[36:37], v[26:27] op_sel:[0,1,0] op_sel_hi:[1,1,1]
	v_pk_fma_f32 v[14:15], v[14:15], v[40:41], v[18:19] op_sel_hi:[1,0,1]
	v_pk_fma_f32 v[16:17], v[16:17], v[40:41], v[20:21] op_sel_hi:[1,0,1]
	v_add_f32_dpp v26, v26, v26 quad_perm:[1,0,3,2] row_mask:0xf bank_mask:0xf bound_ctrl:1
	v_add_f32_dpp v27, v27, v27 quad_perm:[1,0,3,2] row_mask:0xf bank_mask:0xf bound_ctrl:1
	s_add_u32 s14, s14, 0x1000
	v_add_f32_dpp v26, v26, v26 quad_perm:[2,3,0,1] row_mask:0xf bank_mask:0xf bound_ctrl:1
	v_add_f32_dpp v27, v27, v27 quad_perm:[2,3,0,1] row_mask:0xf bank_mask:0xf bound_ctrl:1
	s_addc_u32 s15, s15, 0
	v_add_f32_dpp v26, v26, v26 row_half_mirror row_mask:0xf bank_mask:0xf bound_ctrl:1
	v_add_f32_dpp v27, v27, v27 row_half_mirror row_mask:0xf bank_mask:0xf bound_ctrl:1
	s_cmp_eq_u32 s21, 0
	v_add_f32_dpp v26, v26, v26 row_mirror row_mask:0xf bank_mask:0xf bound_ctrl:1
	v_add_f32_dpp v27, v27, v27 row_mirror row_mask:0xf bank_mask:0xf bound_ctrl:1
	s_cbranch_scc1 .Lml2_den0_0
.Lml2_back0_0:
	v_cvt_pk_bf16_f32 v28, v26, v27
	global_store_dword v4, v28, s[14:15] offset:-4096
	ds_read_b128 v[30:33], v2 offset:9472
	ds_read_b128 v[34:37], v2 offset:9728
	ds_read_b64 v[38:39], v3 offset:13056
	ds_read_b128 v[40:43], v1 offset:14880
	s_waitcnt lgkmcnt(4)
	v_pk_mul_f32 v[18:19], v[44:45], v[54:55] op_sel:[0,1] op_sel_hi:[1,1]
	v_pk_mul_f32 v[20:21], v[46:47], v[54:55] op_sel:[0,1] op_sel_hi:[1,1]
	v_pk_mul_f32 v[22:23], v[52:53], v[18:19] op_sel:[0,0] op_sel_hi:[1,0]
	v_pk_fma_f32 v[6:7], v[6:7], v[54:55], v[22:23] op_sel_hi:[1,0,1]
	v_pk_mul_f32 v[26:27], v[6:7], v[48:49] op_sel_hi:[1,0]
	v_pk_mul_f32 v[24:25], v[52:53], v[18:19] op_sel:[0,1] op_sel_hi:[1,1]
	v_pk_fma_f32 v[8:9], v[8:9], v[54:55], v[24:25] op_sel_hi:[1,0,1]
	v_pk_fma_f32 v[26:27], v[8:9], v[48:49], v[26:27] op_sel:[0,1,0] op_sel_hi:[1,1,1]
	v_pk_mul_f32 v[22:23], v[52:53], v[20:21] op_sel:[0,0] op_sel_hi:[1,0]
	v_pk_fma_f32 v[10:11], v[10:11], v[54:55], v[22:23] op_sel_hi:[1,0,1]
	v_pk_fma_f32 v[26:27], v[10:11], v[50:51], v[26:27] op_sel:[0,0,0] op_sel_hi:[1,0,1]
	v_pk_mul_f32 v[24:25], v[52:53], v[20:21] op_sel:[0,1] op_sel_hi:[1,1]
	v_pk_fma_f32 v[12:13], v[12:13], v[54:55], v[24:25] op_sel_hi:[1,0,1]
	v_pk_fma_f32 v[26:27], v[12:13], v[50:51], v[26:27] op_sel:[0,1,0] op_sel_hi:[1,1,1]
	v_pk_fma_f32 v[14:15], v[14:15], v[54:55], v[18:19] op_sel_hi:[1,0,1]
	v_pk_fma_f32 v[16:17], v[16:17], v[54:55], v[20:21] op_sel_hi:[1,0,1]
	v_add_f32_dpp v26, v26, v26 quad_perm:[1,0,3,2] row_mask:0xf bank_mask:0xf bound_ctrl:1
	v_add_f32_dpp v27, v27, v27 quad_perm:[1,0,3,2] row_mask:0xf bank_mask:0xf bound_ctrl:1
	s_add_u32 s14, s14, 0x1000
	v_add_f32_dpp v26, v26, v26 quad_perm:[2,3,0,1] row_mask:0xf bank_mask:0xf bound_ctrl:1
	v_add_f32_dpp v27, v27, v27 quad_perm:[2,3,0,1] row_mask:0xf bank_mask:0xf bound_ctrl:1
	s_addc_u32 s15, s15, 0
	v_add_f32_dpp v26, v26, v26 row_half_mirror row_mask:0xf bank_mask:0xf bound_ctrl:1
	v_add_f32_dpp v27, v27, v27 row_half_mirror row_mask:0xf bank_mask:0xf bound_ctrl:1
	s_cmp_eq_u32 s21, 1
	v_add_f32_dpp v26, v26, v26 row_mirror row_mask:0xf bank_mask:0xf bound_ctrl:1
	v_add_f32_dpp v27, v27, v27 row_mirror row_mask:0xf bank_mask:0xf bound_ctrl:1
	s_cbranch_scc1 .Lml2_den0_1
.Lml2_back0_1:
	v_cvt_pk_bf16_f32 v28, v26, v27
	global_store_dword v4, v28, s[14:15] offset:-4096
	ds_read_b128 v[44:47], v2 offset:9984
	ds_read_b128 v[48:51], v2 offset:10240
	ds_read_b64 v[52:53], v3 offset:13312
	ds_read_b128 v[54:57], v1 offset:14896
	s_waitcnt lgkmcnt(4)
	v_pk_mul_f32 v[18:19], v[30:31], v[40:41] op_sel:[0,1] op_sel_hi:[1,1]
	v_pk_mul_f32 v[20:21], v[32:33], v[40:41] op_sel:[0,1] op_sel_hi:[1,1]
	v_pk_mul_f32 v[22:23], v[38:39], v[18:19] op_sel:[0,0] op_sel_hi:[1,0]
	v_pk_fma_f32 v[6:7], v[6:7], v[40:41], v[22:23] op_sel_hi:[1,0,1]
	v_pk_mul_f32 v[26:27], v[6:7], v[34:35] op_sel_hi:[1,0]
	v_pk_mul_f32 v[24:25], v[38:39], v[18:19] op_sel:[0,1] op_sel_hi:[1,1]
	v_pk_fma_f32 v[8:9], v[8:9], v[40:41], v[24:25] op_sel_hi:[1,0,1]
	v_pk_fma_f32 v[26:27], v[8:9], v[34:35], v[26:27] op_sel:[0,1,0] op_sel_hi:[1,1,1]
	v_pk_mul_f32 v[22:23], v[38:39], v[20:21] op_sel:[0,0] op_sel_hi:[1,0]
	v_pk_fma_f32 v[10:11], v[10:11], v[40:41], v[22:23] op_sel_hi:[1,0,1]
	v_pk_fma_f32 v[26:27], v[10:11], v[36:37], v[26:27] op_sel:[0,0,0] op_sel_hi:[1,0,1]
	v_pk_mul_f32 v[24:25], v[38:39], v[20:21] op_sel:[0,1] op_sel_hi:[1,1]
	v_pk_fma_f32 v[12:13], v[12:13], v[40:41], v[24:25] op_sel_hi:[1,0,1]
	v_pk_fma_f32 v[26:27], v[12:13], v[36:37], v[26:27] op_sel:[0,1,0] op_sel_hi:[1,1,1]
	v_pk_fma_f32 v[14:15], v[14:15], v[40:41], v[18:19] op_sel_hi:[1,0,1]
	v_pk_fma_f32 v[16:17], v[16:17], v[40:41], v[20:21] op_sel_hi:[1,0,1]
	v_add_f32_dpp v26, v26, v26 quad_perm:[1,0,3,2] row_mask:0xf bank_mask:0xf bound_ctrl:1
	v_add_f32_dpp v27, v27, v27 quad_perm:[1,0,3,2] row_mask:0xf bank_mask:0xf bound_ctrl:1
	s_add_u32 s14, s14, 0x1000
	v_add_f32_dpp v26, v26, v26 quad_perm:[2,3,0,1] row_mask:0xf bank_mask:0xf bound_ctrl:1
	v_add_f32_dpp v27, v27, v27 quad_perm:[2,3,0,1] row_mask:0xf bank_mask:0xf bound_ctrl:1
	s_addc_u32 s15, s15, 0
	v_add_f32_dpp v26, v26, v26 row_half_mirror row_mask:0xf bank_mask:0xf bound_ctrl:1
	v_add_f32_dpp v27, v27, v27 row_half_mirror row_mask:0xf bank_mask:0xf bound_ctrl:1
	s_cmp_eq_u32 s21, 2
	v_add_f32_dpp v26, v26, v26 row_mirror row_mask:0xf bank_mask:0xf bound_ctrl:1
	v_add_f32_dpp v27, v27, v27 row_mirror row_mask:0xf bank_mask:0xf bound_ctrl:1
	s_cbranch_scc1 .Lml2_den0_2
.Lml2_back0_2:
	v_cvt_pk_bf16_f32 v28, v26, v27
	global_store_dword v4, v28, s[14:15] offset:-4096
	ds_read_b128 v[30:33], v2 offset:10496
	ds_read_b128 v[34:37], v2 offset:10752
	ds_read_b64 v[38:39], v3 offset:13568
	ds_read_b128 v[40:43], v1 offset:14912
	s_waitcnt lgkmcnt(4)
	v_pk_mul_f32 v[18:19], v[44:45], v[54:55] op_sel:[0,1] op_sel_hi:[1,1]
	v_pk_mul_f32 v[20:21], v[46:47], v[54:55] op_sel:[0,1] op_sel_hi:[1,1]
	v_pk_mul_f32 v[22:23], v[52:53], v[18:19] op_sel:[0,0] op_sel_hi:[1,0]
	v_pk_fma_f32 v[6:7], v[6:7], v[54:55], v[22:23] op_sel_hi:[1,0,1]
	v_pk_mul_f32 v[26:27], v[6:7], v[48:49] op_sel_hi:[1,0]
	v_pk_mul_f32 v[24:25], v[52:53], v[18:19] op_sel:[0,1] op_sel_hi:[1,1]
	v_pk_fma_f32 v[8:9], v[8:9], v[54:55], v[24:25] op_sel_hi:[1,0,1]
	v_pk_fma_f32 v[26:27], v[8:9], v[48:49], v[26:27] op_sel:[0,1,0] op_sel_hi:[1,1,1]
	v_pk_mul_f32 v[22:23], v[52:53], v[20:21] op_sel:[0,0] op_sel_hi:[1,0]
	v_pk_fma_f32 v[10:11], v[10:11], v[54:55], v[22:23] op_sel_hi:[1,0,1]
	v_pk_fma_f32 v[26:27], v[10:11], v[50:51], v[26:27] op_sel:[0,0,0] op_sel_hi:[1,0,1]
	v_pk_mul_f32 v[24:25], v[52:53], v[20:21] op_sel:[0,1] op_sel_hi:[1,1]
	v_pk_fma_f32 v[12:13], v[12:13], v[54:55], v[24:25] op_sel_hi:[1,0,1]
	v_pk_fma_f32 v[26:27], v[12:13], v[50:51], v[26:27] op_sel:[0,1,0] op_sel_hi:[1,1,1]
	v_pk_fma_f32 v[14:15], v[14:15], v[54:55], v[18:19] op_sel_hi:[1,0,1]
	v_pk_fma_f32 v[16:17], v[16:17], v[54:55], v[20:21] op_sel_hi:[1,0,1]
	v_add_f32_dpp v26, v26, v26 quad_perm:[1,0,3,2] row_mask:0xf bank_mask:0xf bound_ctrl:1
	v_add_f32_dpp v27, v27, v27 quad_perm:[1,0,3,2] row_mask:0xf bank_mask:0xf bound_ctrl:1
	s_add_u32 s14, s14, 0x1000
	v_add_f32_dpp v26, v26, v26 quad_perm:[2,3,0,1] row_mask:0xf bank_mask:0xf bound_ctrl:1
	v_add_f32_dpp v27, v27, v27 quad_perm:[2,3,0,1] row_mask:0xf bank_mask:0xf bound_ctrl:1
	s_addc_u32 s15, s15, 0
	v_add_f32_dpp v26, v26, v26 row_half_mirror row_mask:0xf bank_mask:0xf bound_ctrl:1
	v_add_f32_dpp v27, v27, v27 row_half_mirror row_mask:0xf bank_mask:0xf bound_ctrl:1
	s_cmp_eq_u32 s21, 3
	v_add_f32_dpp v26, v26, v26 row_mirror row_mask:0xf bank_mask:0xf bound_ctrl:1
	v_add_f32_dpp v27, v27, v27 row_mirror row_mask:0xf bank_mask:0xf bound_ctrl:1
	s_cbranch_scc1 .Lml2_den0_3
.Lml2_back0_3:
	v_cvt_pk_bf16_f32 v28, v26, v27
	global_store_dword v4, v28, s[14:15] offset:-4096
	ds_read_b128 v[44:47], v2 offset:11008
	ds_read_b128 v[48:51], v2 offset:11264
	ds_read_b64 v[52:53], v3 offset:13824
	ds_read_b128 v[54:57], v1 offset:14928
	s_waitcnt lgkmcnt(4)
	v_pk_mul_f32 v[18:19], v[30:31], v[40:41] op_sel:[0,1] op_sel_hi:[1,1]
	v_pk_mul_f32 v[20:21], v[32:33], v[40:41] op_sel:[0,1] op_sel_hi:[1,1]
	v_pk_mul_f32 v[22:23], v[38:39], v[18:19] op_sel:[0,0] op_sel_hi:[1,0]
	v_pk_fma_f32 v[6:7], v[6:7], v[40:41], v[22:23] op_sel_hi:[1,0,1]
	v_pk_mul_f32 v[26:27], v[6:7], v[34:35] op_sel_hi:[1,0]
	v_pk_mul_f32 v[24:25], v[38:39], v[18:19] op_sel:[0,1] op_sel_hi:[1,1]
	v_pk_fma_f32 v[8:9], v[8:9], v[40:41], v[24:25] op_sel_hi:[1,0,1]
	v_pk_fma_f32 v[26:27], v[8:9], v[34:35], v[26:27] op_sel:[0,1,0] op_sel_hi:[1,1,1]
	v_pk_mul_f32 v[22:23], v[38:39], v[20:21] op_sel:[0,0] op_sel_hi:[1,0]
	v_pk_fma_f32 v[10:11], v[10:11], v[40:41], v[22:23] op_sel_hi:[1,0,1]
	v_pk_fma_f32 v[26:27], v[10:11], v[36:37], v[26:27] op_sel:[0,0,0] op_sel_hi:[1,0,1]
	v_pk_mul_f32 v[24:25], v[38:39], v[20:21] op_sel:[0,1] op_sel_hi:[1,1]
	v_pk_fma_f32 v[12:13], v[12:13], v[40:41], v[24:25] op_sel_hi:[1,0,1]
	v_pk_fma_f32 v[26:27], v[12:13], v[36:37], v[26:27] op_sel:[0,1,0] op_sel_hi:[1,1,1]
	v_pk_fma_f32 v[14:15], v[14:15], v[40:41], v[18:19] op_sel_hi:[1,0,1]
	v_pk_fma_f32 v[16:17], v[16:17], v[40:41], v[20:21] op_sel_hi:[1,0,1]
	v_add_f32_dpp v26, v26, v26 quad_perm:[1,0,3,2] row_mask:0xf bank_mask:0xf bound_ctrl:1
	v_add_f32_dpp v27, v27, v27 quad_perm:[1,0,3,2] row_mask:0xf bank_mask:0xf bound_ctrl:1
	s_add_u32 s14, s14, 0x1000
	v_add_f32_dpp v26, v26, v26 quad_perm:[2,3,0,1] row_mask:0xf bank_mask:0xf bound_ctrl:1
	v_add_f32_dpp v27, v27, v27 quad_perm:[2,3,0,1] row_mask:0xf bank_mask:0xf bound_ctrl:1
	s_addc_u32 s15, s15, 0
	v_add_f32_dpp v26, v26, v26 row_half_mirror row_mask:0xf bank_mask:0xf bound_ctrl:1
	v_add_f32_dpp v27, v27, v27 row_half_mirror row_mask:0xf bank_mask:0xf bound_ctrl:1
	s_cmp_eq_u32 s21, 4
	v_add_f32_dpp v26, v26, v26 row_mirror row_mask:0xf bank_mask:0xf bound_ctrl:1
	v_add_f32_dpp v27, v27, v27 row_mirror row_mask:0xf bank_mask:0xf bound_ctrl:1
	s_cbranch_scc1 .Lml2_den0_4
.Lml2_back0_4:
	v_cvt_pk_bf16_f32 v28, v26, v27
	global_store_dword v4, v28, s[14:15] offset:-4096
	ds_read_b128 v[30:33], v2 offset:11520
	ds_read_b128 v[34:37], v2 offset:11776
	ds_read_b64 v[38:39], v3 offset:14080
	ds_read_b128 v[40:43], v1 offset:14944
	s_waitcnt lgkmcnt(4)
	v_pk_mul_f32 v[18:19], v[44:45], v[54:55] op_sel:[0,1] op_sel_hi:[1,1]
	v_pk_mul_f32 v[20:21], v[46:47], v[54:55] op_sel:[0,1] op_sel_hi:[1,1]
	v_pk_mul_f32 v[22:23], v[52:53], v[18:19] op_sel:[0,0] op_sel_hi:[1,0]
	v_pk_fma_f32 v[6:7], v[6:7], v[54:55], v[22:23] op_sel_hi:[1,0,1]
	v_pk_mul_f32 v[26:27], v[6:7], v[48:49] op_sel_hi:[1,0]
	v_pk_mul_f32 v[24:25], v[52:53], v[18:19] op_sel:[0,1] op_sel_hi:[1,1]
	v_pk_fma_f32 v[8:9], v[8:9], v[54:55], v[24:25] op_sel_hi:[1,0,1]
	v_pk_fma_f32 v[26:27], v[8:9], v[48:49], v[26:27] op_sel:[0,1,0] op_sel_hi:[1,1,1]
	v_pk_mul_f32 v[22:23], v[52:53], v[20:21] op_sel:[0,0] op_sel_hi:[1,0]
	v_pk_fma_f32 v[10:11], v[10:11], v[54:55], v[22:23] op_sel_hi:[1,0,1]
	v_pk_fma_f32 v[26:27], v[10:11], v[50:51], v[26:27] op_sel:[0,0,0] op_sel_hi:[1,0,1]
	v_pk_mul_f32 v[24:25], v[52:53], v[20:21] op_sel:[0,1] op_sel_hi:[1,1]
	v_pk_fma_f32 v[12:13], v[12:13], v[54:55], v[24:25] op_sel_hi:[1,0,1]
	v_pk_fma_f32 v[26:27], v[12:13], v[50:51], v[26:27] op_sel:[0,1,0] op_sel_hi:[1,1,1]
	v_pk_fma_f32 v[14:15], v[14:15], v[54:55], v[18:19] op_sel_hi:[1,0,1]
	v_pk_fma_f32 v[16:17], v[16:17], v[54:55], v[20:21] op_sel_hi:[1,0,1]
	v_add_f32_dpp v26, v26, v26 quad_perm:[1,0,3,2] row_mask:0xf bank_mask:0xf bound_ctrl:1
	v_add_f32_dpp v27, v27, v27 quad_perm:[1,0,3,2] row_mask:0xf bank_mask:0xf bound_ctrl:1
	s_add_u32 s14, s14, 0x1000
	v_add_f32_dpp v26, v26, v26 quad_perm:[2,3,0,1] row_mask:0xf bank_mask:0xf bound_ctrl:1
	v_add_f32_dpp v27, v27, v27 quad_perm:[2,3,0,1] row_mask:0xf bank_mask:0xf bound_ctrl:1
	s_addc_u32 s15, s15, 0
	v_add_f32_dpp v26, v26, v26 row_half_mirror row_mask:0xf bank_mask:0xf bound_ctrl:1
	v_add_f32_dpp v27, v27, v27 row_half_mirror row_mask:0xf bank_mask:0xf bound_ctrl:1
	s_cmp_eq_u32 s21, 5
	v_add_f32_dpp v26, v26, v26 row_mirror row_mask:0xf bank_mask:0xf bound_ctrl:1
	v_add_f32_dpp v27, v27, v27 row_mirror row_mask:0xf bank_mask:0xf bound_ctrl:1
	s_cbranch_scc1 .Lml2_den0_5
.Lml2_back0_5:
	v_cvt_pk_bf16_f32 v28, v26, v27
	global_store_dword v4, v28, s[14:15] offset:-4096
	ds_read_b128 v[44:47], v2 offset:12032
	ds_read_b128 v[48:51], v2 offset:12288
	ds_read_b64 v[52:53], v3 offset:14336
	ds_read_b128 v[54:57], v1 offset:14960
	s_waitcnt lgkmcnt(4)
	v_pk_mul_f32 v[18:19], v[30:31], v[40:41] op_sel:[0,1] op_sel_hi:[1,1]
	v_pk_mul_f32 v[20:21], v[32:33], v[40:41] op_sel:[0,1] op_sel_hi:[1,1]
	v_pk_mul_f32 v[22:23], v[38:39], v[18:19] op_sel:[0,0] op_sel_hi:[1,0]
	v_pk_fma_f32 v[6:7], v[6:7], v[40:41], v[22:23] op_sel_hi:[1,0,1]
	v_pk_mul_f32 v[26:27], v[6:7], v[34:35] op_sel_hi:[1,0]
	v_pk_mul_f32 v[24:25], v[38:39], v[18:19] op_sel:[0,1] op_sel_hi:[1,1]
	v_pk_fma_f32 v[8:9], v[8:9], v[40:41], v[24:25] op_sel_hi:[1,0,1]
	v_pk_fma_f32 v[26:27], v[8:9], v[34:35], v[26:27] op_sel:[0,1,0] op_sel_hi:[1,1,1]
	v_pk_mul_f32 v[22:23], v[38:39], v[20:21] op_sel:[0,0] op_sel_hi:[1,0]
	v_pk_fma_f32 v[10:11], v[10:11], v[40:41], v[22:23] op_sel_hi:[1,0,1]
	v_pk_fma_f32 v[26:27], v[10:11], v[36:37], v[26:27] op_sel:[0,0,0] op_sel_hi:[1,0,1]
	v_pk_mul_f32 v[24:25], v[38:39], v[20:21] op_sel:[0,1] op_sel_hi:[1,1]
	v_pk_fma_f32 v[12:13], v[12:13], v[40:41], v[24:25] op_sel_hi:[1,0,1]
	v_pk_fma_f32 v[26:27], v[12:13], v[36:37], v[26:27] op_sel:[0,1,0] op_sel_hi:[1,1,1]
	v_pk_fma_f32 v[14:15], v[14:15], v[40:41], v[18:19] op_sel_hi:[1,0,1]
	v_pk_fma_f32 v[16:17], v[16:17], v[40:41], v[20:21] op_sel_hi:[1,0,1]
	v_add_f32_dpp v26, v26, v26 quad_perm:[1,0,3,2] row_mask:0xf bank_mask:0xf bound_ctrl:1
	v_add_f32_dpp v27, v27, v27 quad_perm:[1,0,3,2] row_mask:0xf bank_mask:0xf bound_ctrl:1
	s_add_u32 s14, s14, 0x1000
	v_add_f32_dpp v26, v26, v26 quad_perm:[2,3,0,1] row_mask:0xf bank_mask:0xf bound_ctrl:1
	v_add_f32_dpp v27, v27, v27 quad_perm:[2,3,0,1] row_mask:0xf bank_mask:0xf bound_ctrl:1
	s_addc_u32 s15, s15, 0
	v_add_f32_dpp v26, v26, v26 row_half_mirror row_mask:0xf bank_mask:0xf bound_ctrl:1
	v_add_f32_dpp v27, v27, v27 row_half_mirror row_mask:0xf bank_mask:0xf bound_ctrl:1
	s_cmp_eq_u32 s21, 6
	v_add_f32_dpp v26, v26, v26 row_mirror row_mask:0xf bank_mask:0xf bound_ctrl:1
	v_add_f32_dpp v27, v27, v27 row_mirror row_mask:0xf bank_mask:0xf bound_ctrl:1
	s_cbranch_scc1 .Lml2_den0_6
.Lml2_back0_6:
	v_cvt_pk_bf16_f32 v28, v26, v27
	global_store_dword v4, v28, s[14:15] offset:-4096
	ds_read_b128 v[30:33], v2 offset:24832
	ds_read_b128 v[34:37], v2 offset:25088
	ds_read_b64 v[38:39], v3 offset:28928
	ds_read_b128 v[40:43], v1 offset:31232
	s_waitcnt lgkmcnt(4)
	v_pk_mul_f32 v[18:19], v[44:45], v[54:55] op_sel:[0,1] op_sel_hi:[1,1]
	v_pk_mul_f32 v[20:21], v[46:47], v[54:55] op_sel:[0,1] op_sel_hi:[1,1]
	v_pk_mul_f32 v[22:23], v[52:53], v[18:19] op_sel:[0,0] op_sel_hi:[1,0]
	v_pk_fma_f32 v[6:7], v[6:7], v[54:55], v[22:23] op_sel_hi:[1,0,1]
	v_pk_mul_f32 v[26:27], v[6:7], v[48:49] op_sel_hi:[1,0]
	v_pk_mul_f32 v[24:25], v[52:53], v[18:19] op_sel:[0,1] op_sel_hi:[1,1]
	v_pk_fma_f32 v[8:9], v[8:9], v[54:55], v[24:25] op_sel_hi:[1,0,1]
	v_pk_fma_f32 v[26:27], v[8:9], v[48:49], v[26:27] op_sel:[0,1,0] op_sel_hi:[1,1,1]
	v_pk_mul_f32 v[22:23], v[52:53], v[20:21] op_sel:[0,0] op_sel_hi:[1,0]
	v_pk_fma_f32 v[10:11], v[10:11], v[54:55], v[22:23] op_sel_hi:[1,0,1]
	v_pk_fma_f32 v[26:27], v[10:11], v[50:51], v[26:27] op_sel:[0,0,0] op_sel_hi:[1,0,1]
	v_pk_mul_f32 v[24:25], v[52:53], v[20:21] op_sel:[0,1] op_sel_hi:[1,1]
	v_pk_fma_f32 v[12:13], v[12:13], v[54:55], v[24:25] op_sel_hi:[1,0,1]
	v_pk_fma_f32 v[26:27], v[12:13], v[50:51], v[26:27] op_sel:[0,1,0] op_sel_hi:[1,1,1]
	v_pk_fma_f32 v[14:15], v[14:15], v[54:55], v[18:19] op_sel_hi:[1,0,1]
	v_pk_fma_f32 v[16:17], v[16:17], v[54:55], v[20:21] op_sel_hi:[1,0,1]
	v_add_f32_dpp v26, v26, v26 quad_perm:[1,0,3,2] row_mask:0xf bank_mask:0xf bound_ctrl:1
	v_add_f32_dpp v27, v27, v27 quad_perm:[1,0,3,2] row_mask:0xf bank_mask:0xf bound_ctrl:1
	s_add_u32 s14, s14, 0x1000
	v_add_f32_dpp v26, v26, v26 quad_perm:[2,3,0,1] row_mask:0xf bank_mask:0xf bound_ctrl:1
	v_add_f32_dpp v27, v27, v27 quad_perm:[2,3,0,1] row_mask:0xf bank_mask:0xf bound_ctrl:1
	s_addc_u32 s15, s15, 0
	v_add_f32_dpp v26, v26, v26 row_half_mirror row_mask:0xf bank_mask:0xf bound_ctrl:1
	v_add_f32_dpp v27, v27, v27 row_half_mirror row_mask:0xf bank_mask:0xf bound_ctrl:1
	s_cmp_eq_u32 s21, 7
	v_add_f32_dpp v26, v26, v26 row_mirror row_mask:0xf bank_mask:0xf bound_ctrl:1
	v_add_f32_dpp v27, v27, v27 row_mirror row_mask:0xf bank_mask:0xf bound_ctrl:1
	s_cbranch_scc1 .Lml2_den0_7
.Lml2_back0_7:
	v_cvt_pk_bf16_f32 v28, v26, v27
	global_store_dword v4, v28, s[14:15] offset:-4096
	s_waitcnt vmcnt(8)
	v_lshlrev_b32_e32 v88, 16, v80
	v_lshlrev_b32_e32 v89, 16, v81
	v_and_b32_e32 v90, s17, v80
	v_and_b32_e32 v91, s17, v81
	v_lshlrev_b32_e32 v92, 16, v82
	v_and_b32_e32 v93, s17, v82
	v_lshlrev_b32_e32 v94, 16, v83
	v_and_b32_e32 v95, s17, v83
	v_lshlrev_b32_e32 v96, 16, v84
	v_and_b32_e32 v97, s17, v84
	ds_write_b128 v69, v[88:91] offset:33024
	ds_write_b64 v70, v[92:93] offset:33024
	ds_write_b64 v71, v[94:95] offset:33024
	ds_write_b64 v71, v[96:97] offset:33152
	ds_write_b32 v72, v85 offset:33024
	s_cmp_lg_u32 s36, 4
	s_cbranch_scc1 .Lml2_nsc2
	v_mov_b32_e32 v98, v87
	s_nop 1
	v_add_f32_dpp v98, v98, v98 row_shr:1 row_mask:0xf bank_mask:0xf bound_ctrl:1
	s_nop 1
	v_add_f32_dpp v98, v98, v98 row_shr:2 row_mask:0xf bank_mask:0xf bound_ctrl:1
	s_nop 1
	v_add_f32_dpp v98, v98, v98 row_shr:4 row_mask:0xf bank_mask:0xf bound_ctrl:1
	s_nop 1
	v_sub_f32_e32 v99, v86, v98
	s_nop 1
	v_max_f32_dpp v99, v99, v99 row_shr:1 row_mask:0xf bank_mask:0xf
	s_nop 1
	v_max_f32_dpp v99, v99, v99 row_shr:2 row_mask:0xf bank_mask:0xf
	s_nop 1
	v_max_f32_dpp v99, v99, v99 row_shr:4 row_mask:0xf bank_mask:0xf
	s_nop 1
	v_max_f32_e32 v99, v99, v0
	v_add_f32_e32 v103, v98, v99
	v_mov_b32_e32 v105, v0
	s_nop 1
	v_mov_b32_dpp v105, v103 row_shr:1 row_mask:0xf bank_mask:0xf
	v_sub_f32_e32 v104, v86, v103
	v_add_f32_e32 v105, v87, v105
	v_fma_f32 v104, v104, s29, v29
	v_sub_f32_e32 v105, v105, v103
	v_exp_f32_e32 v101, v104
	v_mul_f32_e32 v105, s29, v105
	v_mul_f32_e32 v104, 0xbfb8aa3b, v103
	v_exp_f32_e32 v100, v105
	v_exp_f32_e32 v102, v104
	v_readlane_b32 s4, v103, 7
	s_nop 3
	v_mov_b32_e32 v0, s4
	ds_write_b128 v73, v[100:103] offset:33024
.Lml2_nsc2:
	s_add_u32 s24, s24, 0x400
	s_addc_u32 s25, s25, 0
	s_sub_i32 s21, s21, 8
	s_add_i32 s16, s16, 8
	s_waitcnt lgkmcnt(0)
	s_barrier
	s_cmpk_lt_u32 s16, 0x800
	s_cbranch_scc0 .Lml2_done
	global_load_dword v80, v74, s[8:9]
	global_load_dword v81, v74, s[8:9] offset:-2048
	global_load_dword v83, v76, s[8:9] offset:2048
	global_load_dword v82, v75, s[10:11]
	global_load_dword v84, v77, s[10:11]
	global_load_dword v85, v78, s[12:13]
	s_cmp_lg_u32 s36, 4
	s_cbranch_scc1 .Lml2_nsl3
	global_load_dwordx2 v[86:87], v79, s[22:23]
.Lml2_nsl3:
	s_add_u32 s22, s22, 0x400
	s_addc_u32 s23, s23, 0
	s_add_u32 s8, s8, 0xc000
	s_addc_u32 s9, s9, 0
	s_add_u32 s10, s10, 0x20000
	s_addc_u32 s11, s11, 0
	s_add_u32 s12, s12, 0x400
	s_addc_u32 s13, s13, 0
	ds_read_b128 v[44:47], v2 offset:25344
	ds_read_b128 v[48:51], v2 offset:25600
	ds_read_b64 v[52:53], v3 offset:29184
	ds_read_b128 v[54:57], v1 offset:31248
	s_waitcnt lgkmcnt(4)
	v_pk_mul_f32 v[18:19], v[30:31], v[40:41] op_sel:[0,1] op_sel_hi:[1,1]
	v_pk_mul_f32 v[20:21], v[32:33], v[40:41] op_sel:[0,1] op_sel_hi:[1,1]
	v_pk_mul_f32 v[22:23], v[38:39], v[18:19] op_sel:[0,0] op_sel_hi:[1,0]
	v_pk_fma_f32 v[6:7], v[6:7], v[40:41], v[22:23] op_sel_hi:[1,0,1]
	v_pk_mul_f32 v[26:27], v[6:7], v[34:35] op_sel_hi:[1,0]
	v_pk_mul_f32 v[24:25], v[38:39], v[18:19] op_sel:[0,1] op_sel_hi:[1,1]
	v_pk_fma_f32 v[8:9], v[8:9], v[40:41], v[24:25] op_sel_hi:[1,0,1]
	v_pk_fma_f32 v[26:27], v[8:9], v[34:35], v[26:27] op_sel:[0,1,0] op_sel_hi:[1,1,1]
	v_pk_mul_f32 v[22:23], v[38:39], v[20:21] op_sel:[0,0] op_sel_hi:[1,0]
	v_pk_fma_f32 v[10:11], v[10:11], v[40:41], v[22:23] op_sel_hi:[1,0,1]
	v_pk_fma_f32 v[26:27], v[10:11], v[36:37], v[26:27] op_sel:[0,0,0] op_sel_hi:[1,0,1]
	v_pk_mul_f32 v[24:25], v[38:39], v[20:21] op_sel:[0,1] op_sel_hi:[1,1]
	v_pk_fma_f32 v[12:13], v[12:13], v[40:41], v[24:25] op_sel_hi:[1,0,1]
	v_pk_fma_f32 v[26:27], v[12:13], v[36:37], v[26:27] op_sel:[0,1,0] op_sel_hi:[1,1,1]
	v_pk_fma_f32 v[14:15], v[14:15], v[40:41], v[18:19] op_sel_hi:[1,0,1]
	v_pk_fma_f32 v[16:17], v[16:17], v[40:41], v[20:21] op_sel_hi:[1,0,1]
	v_add_f32_dpp v26, v26, v26 quad_perm:[1,0,3,2] row_mask:0xf bank_mask:0xf bound_ctrl:1
	v_add_f32_dpp v27, v27, v27 quad_perm:[1,0,3,2] row_mask:0xf bank_mask:0xf bound_ctrl:1
	s_add_u32 s14, s14, 0x1000
	v_add_f32_dpp v26, v26, v26 quad_perm:[2,3,0,1] row_mask:0xf bank_mask:0xf bound_ctrl:1
	v_add_f32_dpp v27, v27, v27 quad_perm:[2,3,0,1] row_mask:0xf bank_mask:0xf bound_ctrl:1
	s_addc_u32 s15, s15, 0
	v_add_f32_dpp v26, v26, v26 row_half_mirror row_mask:0xf bank_mask:0xf bound_ctrl:1
	v_add_f32_dpp v27, v27, v27 row_half_mirror row_mask:0xf bank_mask:0xf bound_ctrl:1
	s_cmp_eq_u32 s21, 0
	v_add_f32_dpp v26, v26, v26 row_mirror row_mask:0xf bank_mask:0xf bound_ctrl:1
	v_add_f32_dpp v27, v27, v27 row_mirror row_mask:0xf bank_mask:0xf bound_ctrl:1
	s_cbranch_scc1 .Lml2_den1_0
.Lml2_back1_0:
	v_cvt_pk_bf16_f32 v28, v26, v27
	global_store_dword v4, v28, s[14:15] offset:-4096
	ds_read_b128 v[30:33], v2 offset:25856
	ds_read_b128 v[34:37], v2 offset:26112
	ds_read_b64 v[38:39], v3 offset:29440
	ds_read_b128 v[40:43], v1 offset:31264
	s_waitcnt lgkmcnt(4)
	v_pk_mul_f32 v[18:19], v[44:45], v[54:55] op_sel:[0,1] op_sel_hi:[1,1]
	v_pk_mul_f32 v[20:21], v[46:47], v[54:55] op_sel:[0,1] op_sel_hi:[1,1]
	v_pk_mul_f32 v[22:23], v[52:53], v[18:19] op_sel:[0,0] op_sel_hi:[1,0]
	v_pk_fma_f32 v[6:7], v[6:7], v[54:55], v[22:23] op_sel_hi:[1,0,1]
	v_pk_mul_f32 v[26:27], v[6:7], v[48:49] op_sel_hi:[1,0]
	v_pk_mul_f32 v[24:25], v[52:53], v[18:19] op_sel:[0,1] op_sel_hi:[1,1]
	v_pk_fma_f32 v[8:9], v[8:9], v[54:55], v[24:25] op_sel_hi:[1,0,1]
	v_pk_fma_f32 v[26:27], v[8:9], v[48:49], v[26:27] op_sel:[0,1,0] op_sel_hi:[1,1,1]
	v_pk_mul_f32 v[22:23], v[52:53], v[20:21] op_sel:[0,0] op_sel_hi:[1,0]
	v_pk_fma_f32 v[10:11], v[10:11], v[54:55], v[22:23] op_sel_hi:[1,0,1]
	v_pk_fma_f32 v[26:27], v[10:11], v[50:51], v[26:27] op_sel:[0,0,0] op_sel_hi:[1,0,1]
	v_pk_mul_f32 v[24:25], v[52:53], v[20:21] op_sel:[0,1] op_sel_hi:[1,1]
	v_pk_fma_f32 v[12:13], v[12:13], v[54:55], v[24:25] op_sel_hi:[1,0,1]
	v_pk_fma_f32 v[26:27], v[12:13], v[50:51], v[26:27] op_sel:[0,1,0] op_sel_hi:[1,1,1]
	v_pk_fma_f32 v[14:15], v[14:15], v[54:55], v[18:19] op_sel_hi:[1,0,1]
	v_pk_fma_f32 v[16:17], v[16:17], v[54:55], v[20:21] op_sel_hi:[1,0,1]
	v_add_f32_dpp v26, v26, v26 quad_perm:[1,0,3,2] row_mask:0xf bank_mask:0xf bound_ctrl:1
	v_add_f32_dpp v27, v27, v27 quad_perm:[1,0,3,2] row_mask:0xf bank_mask:0xf bound_ctrl:1
	s_add_u32 s14, s14, 0x1000
	v_add_f32_dpp v26, v26, v26 quad_perm:[2,3,0,1] row_mask:0xf bank_mask:0xf bound_ctrl:1
	v_add_f32_dpp v27, v27, v27 quad_perm:[2,3,0,1] row_mask:0xf bank_mask:0xf bound_ctrl:1
	s_addc_u32 s15, s15, 0
	v_add_f32_dpp v26, v26, v26 row_half_mirror row_mask:0xf bank_mask:0xf bound_ctrl:1
	v_add_f32_dpp v27, v27, v27 row_half_mirror row_mask:0xf bank_mask:0xf bound_ctrl:1
	s_cmp_eq_u32 s21, 1
	v_add_f32_dpp v26, v26, v26 row_mirror row_mask:0xf bank_mask:0xf bound_ctrl:1
	v_add_f32_dpp v27, v27, v27 row_mirror row_mask:0xf bank_mask:0xf bound_ctrl:1
	s_cbranch_scc1 .Lml2_den1_1
.Lml2_back1_1:
	v_cvt_pk_bf16_f32 v28, v26, v27
	global_store_dword v4, v28, s[14:15] offset:-4096
	ds_read_b128 v[44:47], v2 offset:26368
	ds_read_b128 v[48:51], v2 offset:26624
	ds_read_b64 v[52:53], v3 offset:29696
	ds_read_b128 v[54:57], v1 offset:31280
	s_waitcnt lgkmcnt(4)
	v_pk_mul_f32 v[18:19], v[30:31], v[40:41] op_sel:[0,1] op_sel_hi:[1,1]
	v_pk_mul_f32 v[20:21], v[32:33], v[40:41] op_sel:[0,1] op_sel_hi:[1,1]
	v_pk_mul_f32 v[22:23], v[38:39], v[18:19] op_sel:[0,0] op_sel_hi:[1,0]
	v_pk_fma_f32 v[6:7], v[6:7], v[40:41], v[22:23] op_sel_hi:[1,0,1]
	v_pk_mul_f32 v[26:27], v[6:7], v[34:35] op_sel_hi:[1,0]
	v_pk_mul_f32 v[24:25], v[38:39], v[18:19] op_sel:[0,1] op_sel_hi:[1,1]
	v_pk_fma_f32 v[8:9], v[8:9], v[40:41], v[24:25] op_sel_hi:[1,0,1]
	v_pk_fma_f32 v[26:27], v[8:9], v[34:35], v[26:27] op_sel:[0,1,0] op_sel_hi:[1,1,1]
	v_pk_mul_f32 v[22:23], v[38:39], v[20:21] op_sel:[0,0] op_sel_hi:[1,0]
	v_pk_fma_f32 v[10:11], v[10:11], v[40:41], v[22:23] op_sel_hi:[1,0,1]
	v_pk_fma_f32 v[26:27], v[10:11], v[36:37], v[26:27] op_sel:[0,0,0] op_sel_hi:[1,0,1]
	v_pk_mul_f32 v[24:25], v[38:39], v[20:21] op_sel:[0,1] op_sel_hi:[1,1]
	v_pk_fma_f32 v[12:13], v[12:13], v[40:41], v[24:25] op_sel_hi:[1,0,1]
	v_pk_fma_f32 v[26:27], v[12:13], v[36:37], v[26:27] op_sel:[0,1,0] op_sel_hi:[1,1,1]
	v_pk_fma_f32 v[14:15], v[14:15], v[40:41], v[18:19] op_sel_hi:[1,0,1]
	v_pk_fma_f32 v[16:17], v[16:17], v[40:41], v[20:21] op_sel_hi:[1,0,1]
	v_add_f32_dpp v26, v26, v26 quad_perm:[1,0,3,2] row_mask:0xf bank_mask:0xf bound_ctrl:1
	v_add_f32_dpp v27, v27, v27 quad_perm:[1,0,3,2] row_mask:0xf bank_mask:0xf bound_ctrl:1
	s_add_u32 s14, s14, 0x1000
	v_add_f32_dpp v26, v26, v26 quad_perm:[2,3,0,1] row_mask:0xf bank_mask:0xf bound_ctrl:1
	v_add_f32_dpp v27, v27, v27 quad_perm:[2,3,0,1] row_mask:0xf bank_mask:0xf bound_ctrl:1
	s_addc_u32 s15, s15, 0
	v_add_f32_dpp v26, v26, v26 row_half_mirror row_mask:0xf bank_mask:0xf bound_ctrl:1
	v_add_f32_dpp v27, v27, v27 row_half_mirror row_mask:0xf bank_mask:0xf bound_ctrl:1
	s_cmp_eq_u32 s21, 2
	v_add_f32_dpp v26, v26, v26 row_mirror row_mask:0xf bank_mask:0xf bound_ctrl:1
	v_add_f32_dpp v27, v27, v27 row_mirror row_mask:0xf bank_mask:0xf bound_ctrl:1
	s_cbranch_scc1 .Lml2_den1_2
.Lml2_back1_2:
	v_cvt_pk_bf16_f32 v28, v26, v27
	global_store_dword v4, v28, s[14:15] offset:-4096
	ds_read_b128 v[30:33], v2 offset:26880
	ds_read_b128 v[34:37], v2 offset:27136
	ds_read_b64 v[38:39], v3 offset:29952
	ds_read_b128 v[40:43], v1 offset:31296
	s_waitcnt lgkmcnt(4)
	v_pk_mul_f32 v[18:19], v[44:45], v[54:55] op_sel:[0,1] op_sel_hi:[1,1]
	v_pk_mul_f32 v[20:21], v[46:47], v[54:55] op_sel:[0,1] op_sel_hi:[1,1]
	v_pk_mul_f32 v[22:23], v[52:53], v[18:19] op_sel:[0,0] op_sel_hi:[1,0]
	v_pk_fma_f32 v[6:7], v[6:7], v[54:55], v[22:23] op_sel_hi:[1,0,1]
	v_pk_mul_f32 v[26:27], v[6:7], v[48:49] op_sel_hi:[1,0]
	v_pk_mul_f32 v[24:25], v[52:53], v[18:19] op_sel:[0,1] op_sel_hi:[1,1]
	v_pk_fma_f32 v[8:9], v[8:9], v[54:55], v[24:25] op_sel_hi:[1,0,1]
	v_pk_fma_f32 v[26:27], v[8:9], v[48:49], v[26:27] op_sel:[0,1,0] op_sel_hi:[1,1,1]
	v_pk_mul_f32 v[22:23], v[52:53], v[20:21] op_sel:[0,0] op_sel_hi:[1,0]
	v_pk_fma_f32 v[10:11], v[10:11], v[54:55], v[22:23] op_sel_hi:[1,0,1]
	v_pk_fma_f32 v[26:27], v[10:11], v[50:51], v[26:27] op_sel:[0,0,0] op_sel_hi:[1,0,1]
	v_pk_mul_f32 v[24:25], v[52:53], v[20:21] op_sel:[0,1] op_sel_hi:[1,1]
	v_pk_fma_f32 v[12:13], v[12:13], v[54:55], v[24:25] op_sel_hi:[1,0,1]
	v_pk_fma_f32 v[26:27], v[12:13], v[50:51], v[26:27] op_sel:[0,1,0] op_sel_hi:[1,1,1]
	v_pk_fma_f32 v[14:15], v[14:15], v[54:55], v[18:19] op_sel_hi:[1,0,1]
	v_pk_fma_f32 v[16:17], v[16:17], v[54:55], v[20:21] op_sel_hi:[1,0,1]
	v_add_f32_dpp v26, v26, v26 quad_perm:[1,0,3,2] row_mask:0xf bank_mask:0xf bound_ctrl:1
	v_add_f32_dpp v27, v27, v27 quad_perm:[1,0,3,2] row_mask:0xf bank_mask:0xf bound_ctrl:1
	s_add_u32 s14, s14, 0x1000
	v_add_f32_dpp v26, v26, v26 quad_perm:[2,3,0,1] row_mask:0xf bank_mask:0xf bound_ctrl:1
	v_add_f32_dpp v27, v27, v27 quad_perm:[2,3,0,1] row_mask:0xf bank_mask:0xf bound_ctrl:1
	s_addc_u32 s15, s15, 0
	v_add_f32_dpp v26, v26, v26 row_half_mirror row_mask:0xf bank_mask:0xf bound_ctrl:1
	v_add_f32_dpp v27, v27, v27 row_half_mirror row_mask:0xf bank_mask:0xf bound_ctrl:1
	s_cmp_eq_u32 s21, 3
	v_add_f32_dpp v26, v26, v26 row_mirror row_mask:0xf bank_mask:0xf bound_ctrl:1
	v_add_f32_dpp v27, v27, v27 row_mirror row_mask:0xf bank_mask:0xf bound_ctrl:1
	s_cbranch_scc1 .Lml2_den1_3
.Lml2_back1_3:
	v_cvt_pk_bf16_f32 v28, v26, v27
	global_store_dword v4, v28, s[14:15] offset:-4096
	ds_read_b128 v[44:47], v2 offset:27392
	ds_read_b128 v[48:51], v2 offset:27648
	ds_read_b64 v[52:53], v3 offset:30208
	ds_read_b128 v[54:57], v1 offset:31312
	s_waitcnt lgkmcnt(4)
	v_pk_mul_f32 v[18:19], v[30:31], v[40:41] op_sel:[0,1] op_sel_hi:[1,1]
	v_pk_mul_f32 v[20:21], v[32:33], v[40:41] op_sel:[0,1] op_sel_hi:[1,1]
	v_pk_mul_f32 v[22:23], v[38:39], v[18:19] op_sel:[0,0] op_sel_hi:[1,0]
	v_pk_fma_f32 v[6:7], v[6:7], v[40:41], v[22:23] op_sel_hi:[1,0,1]
	v_pk_mul_f32 v[26:27], v[6:7], v[34:35] op_sel_hi:[1,0]
	v_pk_mul_f32 v[24:25], v[38:39], v[18:19] op_sel:[0,1] op_sel_hi:[1,1]
	v_pk_fma_f32 v[8:9], v[8:9], v[40:41], v[24:25] op_sel_hi:[1,0,1]
	v_pk_fma_f32 v[26:27], v[8:9], v[34:35], v[26:27] op_sel:[0,1,0] op_sel_hi:[1,1,1]
	v_pk_mul_f32 v[22:23], v[38:39], v[20:21] op_sel:[0,0] op_sel_hi:[1,0]
	v_pk_fma_f32 v[10:11], v[10:11], v[40:41], v[22:23] op_sel_hi:[1,0,1]
	v_pk_fma_f32 v[26:27], v[10:11], v[36:37], v[26:27] op_sel:[0,0,0] op_sel_hi:[1,0,1]
	v_pk_mul_f32 v[24:25], v[38:39], v[20:21] op_sel:[0,1] op_sel_hi:[1,1]
	v_pk_fma_f32 v[12:13], v[12:13], v[40:41], v[24:25] op_sel_hi:[1,0,1]
	v_pk_fma_f32 v[26:27], v[12:13], v[36:37], v[26:27] op_sel:[0,1,0] op_sel_hi:[1,1,1]
	v_pk_fma_f32 v[14:15], v[14:15], v[40:41], v[18:19] op_sel_hi:[1,0,1]
	v_pk_fma_f32 v[16:17], v[16:17], v[40:41], v[20:21] op_sel_hi:[1,0,1]
	v_add_f32_dpp v26, v26, v26 quad_perm:[1,0,3,2] row_mask:0xf bank_mask:0xf bound_ctrl:1
	v_add_f32_dpp v27, v27, v27 quad_perm:[1,0,3,2] row_mask:0xf bank_mask:0xf bound_ctrl:1
	s_add_u32 s14, s14, 0x1000
	v_add_f32_dpp v26, v26, v26 quad_perm:[2,3,0,1] row_mask:0xf bank_mask:0xf bound_ctrl:1
	v_add_f32_dpp v27, v27, v27 quad_perm:[2,3,0,1] row_mask:0xf bank_mask:0xf bound_ctrl:1
	s_addc_u32 s15, s15, 0
	v_add_f32_dpp v26, v26, v26 row_half_mirror row_mask:0xf bank_mask:0xf bound_ctrl:1
	v_add_f32_dpp v27, v27, v27 row_half_mirror row_mask:0xf bank_mask:0xf bound_ctrl:1
	s_cmp_eq_u32 s21, 4
	v_add_f32_dpp v26, v26, v26 row_mirror row_mask:0xf bank_mask:0xf bound_ctrl:1
	v_add_f32_dpp v27, v27, v27 row_mirror row_mask:0xf bank_mask:0xf bound_ctrl:1
	s_cbranch_scc1 .Lml2_den1_4
.Lml2_back1_4:
	v_cvt_pk_bf16_f32 v28, v26, v27
	global_store_dword v4, v28, s[14:15] offset:-4096
	ds_read_b128 v[30:33], v2 offset:27904
	ds_read_b128 v[34:37], v2 offset:28160
	ds_read_b64 v[38:39], v3 offset:30464
	ds_read_b128 v[40:43], v1 offset:31328
	s_waitcnt lgkmcnt(4)
	v_pk_mul_f32 v[18:19], v[44:45], v[54:55] op_sel:[0,1] op_sel_hi:[1,1]
	v_pk_mul_f32 v[20:21], v[46:47], v[54:55] op_sel:[0,1] op_sel_hi:[1,1]
	v_pk_mul_f32 v[22:23], v[52:53], v[18:19] op_sel:[0,0] op_sel_hi:[1,0]
	v_pk_fma_f32 v[6:7], v[6:7], v[54:55], v[22:23] op_sel_hi:[1,0,1]
	v_pk_mul_f32 v[26:27], v[6:7], v[48:49] op_sel_hi:[1,0]
	v_pk_mul_f32 v[24:25], v[52:53], v[18:19] op_sel:[0,1] op_sel_hi:[1,1]
	v_pk_fma_f32 v[8:9], v[8:9], v[54:55], v[24:25] op_sel_hi:[1,0,1]
	v_pk_fma_f32 v[26:27], v[8:9], v[48:49], v[26:27] op_sel:[0,1,0] op_sel_hi:[1,1,1]
	v_pk_mul_f32 v[22:23], v[52:53], v[20:21] op_sel:[0,0] op_sel_hi:[1,0]
	v_pk_fma_f32 v[10:11], v[10:11], v[54:55], v[22:23] op_sel_hi:[1,0,1]
	v_pk_fma_f32 v[26:27], v[10:11], v[50:51], v[26:27] op_sel:[0,0,0] op_sel_hi:[1,0,1]
	v_pk_mul_f32 v[24:25], v[52:53], v[20:21] op_sel:[0,1] op_sel_hi:[1,1]
	v_pk_fma_f32 v[12:13], v[12:13], v[54:55], v[24:25] op_sel_hi:[1,0,1]
	v_pk_fma_f32 v[26:27], v[12:13], v[50:51], v[26:27] op_sel:[0,1,0] op_sel_hi:[1,1,1]
	v_pk_fma_f32 v[14:15], v[14:15], v[54:55], v[18:19] op_sel_hi:[1,0,1]
	v_pk_fma_f32 v[16:17], v[16:17], v[54:55], v[20:21] op_sel_hi:[1,0,1]
	v_add_f32_dpp v26, v26, v26 quad_perm:[1,0,3,2] row_mask:0xf bank_mask:0xf bound_ctrl:1
	v_add_f32_dpp v27, v27, v27 quad_perm:[1,0,3,2] row_mask:0xf bank_mask:0xf bound_ctrl:1
	s_add_u32 s14, s14, 0x1000
	v_add_f32_dpp v26, v26, v26 quad_perm:[2,3,0,1] row_mask:0xf bank_mask:0xf bound_ctrl:1
	v_add_f32_dpp v27, v27, v27 quad_perm:[2,3,0,1] row_mask:0xf bank_mask:0xf bound_ctrl:1
	s_addc_u32 s15, s15, 0
	v_add_f32_dpp v26, v26, v26 row_half_mirror row_mask:0xf bank_mask:0xf bound_ctrl:1
	v_add_f32_dpp v27, v27, v27 row_half_mirror row_mask:0xf bank_mask:0xf bound_ctrl:1
	s_cmp_eq_u32 s21, 5
	v_add_f32_dpp v26, v26, v26 row_mirror row_mask:0xf bank_mask:0xf bound_ctrl:1
	v_add_f32_dpp v27, v27, v27 row_mirror row_mask:0xf bank_mask:0xf bound_ctrl:1
	s_cbranch_scc1 .Lml2_den1_5
.Lml2_back1_5:
	v_cvt_pk_bf16_f32 v28, v26, v27
	global_store_dword v4, v28, s[14:15] offset:-4096
	ds_read_b128 v[44:47], v2 offset:28416
	ds_read_b128 v[48:51], v2 offset:28672
	ds_read_b64 v[52:53], v3 offset:30720
	ds_read_b128 v[54:57], v1 offset:31344
	s_waitcnt lgkmcnt(4)
	v_pk_mul_f32 v[18:19], v[30:31], v[40:41] op_sel:[0,1] op_sel_hi:[1,1]
	v_pk_mul_f32 v[20:21], v[32:33], v[40:41] op_sel:[0,1] op_sel_hi:[1,1]
	v_pk_mul_f32 v[22:23], v[38:39], v[18:19] op_sel:[0,0] op_sel_hi:[1,0]
	v_pk_fma_f32 v[6:7], v[6:7], v[40:41], v[22:23] op_sel_hi:[1,0,1]
	v_pk_mul_f32 v[26:27], v[6:7], v[34:35] op_sel_hi:[1,0]
	v_pk_mul_f32 v[24:25], v[38:39], v[18:19] op_sel:[0,1] op_sel_hi:[1,1]
	v_pk_fma_f32 v[8:9], v[8:9], v[40:41], v[24:25] op_sel_hi:[1,0,1]
	v_pk_fma_f32 v[26:27], v[8:9], v[34:35], v[26:27] op_sel:[0,1,0] op_sel_hi:[1,1,1]
	v_pk_mul_f32 v[22:23], v[38:39], v[20:21] op_sel:[0,0] op_sel_hi:[1,0]
	v_pk_fma_f32 v[10:11], v[10:11], v[40:41], v[22:23] op_sel_hi:[1,0,1]
	v_pk_fma_f32 v[26:27], v[10:11], v[36:37], v[26:27] op_sel:[0,0,0] op_sel_hi:[1,0,1]
	v_pk_mul_f32 v[24:25], v[38:39], v[20:21] op_sel:[0,1] op_sel_hi:[1,1]
	v_pk_fma_f32 v[12:13], v[12:13], v[40:41], v[24:25] op_sel_hi:[1,0,1]
	v_pk_fma_f32 v[26:27], v[12:13], v[36:37], v[26:27] op_sel:[0,1,0] op_sel_hi:[1,1,1]
	v_pk_fma_f32 v[14:15], v[14:15], v[40:41], v[18:19] op_sel_hi:[1,0,1]
	v_pk_fma_f32 v[16:17], v[16:17], v[40:41], v[20:21] op_sel_hi:[1,0,1]
	v_add_f32_dpp v26, v26, v26 quad_perm:[1,0,3,2] row_mask:0xf bank_mask:0xf bound_ctrl:1
	v_add_f32_dpp v27, v27, v27 quad_perm:[1,0,3,2] row_mask:0xf bank_mask:0xf bound_ctrl:1
	s_add_u32 s14, s14, 0x1000
	v_add_f32_dpp v26, v26, v26 quad_perm:[2,3,0,1] row_mask:0xf bank_mask:0xf bound_ctrl:1
	v_add_f32_dpp v27, v27, v27 quad_perm:[2,3,0,1] row_mask:0xf bank_mask:0xf bound_ctrl:1
	s_addc_u32 s15, s15, 0
	v_add_f32_dpp v26, v26, v26 row_half_mirror row_mask:0xf bank_mask:0xf bound_ctrl:1
	v_add_f32_dpp v27, v27, v27 row_half_mirror row_mask:0xf bank_mask:0xf bound_ctrl:1
	s_cmp_eq_u32 s21, 6
	v_add_f32_dpp v26, v26, v26 row_mirror row_mask:0xf bank_mask:0xf bound_ctrl:1
	v_add_f32_dpp v27, v27, v27 row_mirror row_mask:0xf bank_mask:0xf bound_ctrl:1
	s_cbranch_scc1 .Lml2_den1_6
.Lml2_back1_6:
	v_cvt_pk_bf16_f32 v28, v26, v27
	global_store_dword v4, v28, s[14:15] offset:-4096
	ds_read_b128 v[30:33], v2 offset:41216
	ds_read_b128 v[34:37], v2 offset:41472
	ds_read_b64 v[38:39], v3 offset:45312
	ds_read_b128 v[40:43], v1 offset:47616
	s_waitcnt lgkmcnt(4)
	v_pk_mul_f32 v[18:19], v[44:45], v[54:55] op_sel:[0,1] op_sel_hi:[1,1]
	v_pk_mul_f32 v[20:21], v[46:47], v[54:55] op_sel:[0,1] op_sel_hi:[1,1]
	v_pk_mul_f32 v[22:23], v[52:53], v[18:19] op_sel:[0,0] op_sel_hi:[1,0]
	v_pk_fma_f32 v[6:7], v[6:7], v[54:55], v[22:23] op_sel_hi:[1,0,1]
	v_pk_mul_f32 v[26:27], v[6:7], v[48:49] op_sel_hi:[1,0]
	v_pk_mul_f32 v[24:25], v[52:53], v[18:19] op_sel:[0,1] op_sel_hi:[1,1]
	v_pk_fma_f32 v[8:9], v[8:9], v[54:55], v[24:25] op_sel_hi:[1,0,1]
	v_pk_fma_f32 v[26:27], v[8:9], v[48:49], v[26:27] op_sel:[0,1,0] op_sel_hi:[1,1,1]
	v_pk_mul_f32 v[22:23], v[52:53], v[20:21] op_sel:[0,0] op_sel_hi:[1,0]
	v_pk_fma_f32 v[10:11], v[10:11], v[54:55], v[22:23] op_sel_hi:[1,0,1]
	v_pk_fma_f32 v[26:27], v[10:11], v[50:51], v[26:27] op_sel:[0,0,0] op_sel_hi:[1,0,1]
	v_pk_mul_f32 v[24:25], v[52:53], v[20:21] op_sel:[0,1] op_sel_hi:[1,1]
	v_pk_fma_f32 v[12:13], v[12:13], v[54:55], v[24:25] op_sel_hi:[1,0,1]
	v_pk_fma_f32 v[26:27], v[12:13], v[50:51], v[26:27] op_sel:[0,1,0] op_sel_hi:[1,1,1]
	v_pk_fma_f32 v[14:15], v[14:15], v[54:55], v[18:19] op_sel_hi:[1,0,1]
	v_pk_fma_f32 v[16:17], v[16:17], v[54:55], v[20:21] op_sel_hi:[1,0,1]
	v_add_f32_dpp v26, v26, v26 quad_perm:[1,0,3,2] row_mask:0xf bank_mask:0xf bound_ctrl:1
	v_add_f32_dpp v27, v27, v27 quad_perm:[1,0,3,2] row_mask:0xf bank_mask:0xf bound_ctrl:1
	s_add_u32 s14, s14, 0x1000
	v_add_f32_dpp v26, v26, v26 quad_perm:[2,3,0,1] row_mask:0xf bank_mask:0xf bound_ctrl:1
	v_add_f32_dpp v27, v27, v27 quad_perm:[2,3,0,1] row_mask:0xf bank_mask:0xf bound_ctrl:1
	s_addc_u32 s15, s15, 0
	v_add_f32_dpp v26, v26, v26 row_half_mirror row_mask:0xf bank_mask:0xf bound_ctrl:1
	v_add_f32_dpp v27, v27, v27 row_half_mirror row_mask:0xf bank_mask:0xf bound_ctrl:1
	s_cmp_eq_u32 s21, 7
	v_add_f32_dpp v26, v26, v26 row_mirror row_mask:0xf bank_mask:0xf bound_ctrl:1
	v_add_f32_dpp v27, v27, v27 row_mirror row_mask:0xf bank_mask:0xf bound_ctrl:1
	s_cbranch_scc1 .Lml2_den1_7
.Lml2_back1_7:
	v_cvt_pk_bf16_f32 v28, v26, v27
	global_store_dword v4, v28, s[14:15] offset:-4096
	s_waitcnt vmcnt(8)
	v_lshlrev_b32_e32 v88, 16, v80
	v_lshlrev_b32_e32 v89, 16, v81
	v_and_b32_e32 v90, s17, v80
	v_and_b32_e32 v91, s17, v81
	v_lshlrev_b32_e32 v92, 16, v82
	v_and_b32_e32 v93, s17, v82
	v_lshlrev_b32_e32 v94, 16, v83
	v_and_b32_e32 v95, s17, v83
	v_lshlrev_b32_e32 v96, 16, v84
	v_and_b32_e32 v97, s17, v84
	ds_write_b128 v69, v[88:91] offset:256
	ds_write_b64 v70, v[92:93] offset:256
	ds_write_b64 v71, v[94:95] offset:256
	ds_write_b64 v71, v[96:97] offset:384
	ds_write_b32 v72, v85 offset:256
	s_cmp_lg_u32 s36, 4
	s_cbranch_scc1 .Lml2_nsc3
	v_mov_b32_e32 v98, v87
	s_nop 1
	v_add_f32_dpp v98, v98, v98 row_shr:1 row_mask:0xf bank_mask:0xf bound_ctrl:1
	s_nop 1
	v_add_f32_dpp v98, v98, v98 row_shr:2 row_mask:0xf bank_mask:0xf bound_ctrl:1
	s_nop 1
	v_add_f32_dpp v98, v98, v98 row_shr:4 row_mask:0xf bank_mask:0xf bound_ctrl:1
	s_nop 1
	v_sub_f32_e32 v99, v86, v98
	s_nop 1
	v_max_f32_dpp v99, v99, v99 row_shr:1 row_mask:0xf bank_mask:0xf
	s_nop 1
	v_max_f32_dpp v99, v99, v99 row_shr:2 row_mask:0xf bank_mask:0xf
	s_nop 1
	v_max_f32_dpp v99, v99, v99 row_shr:4 row_mask:0xf bank_mask:0xf
	s_nop 1
	v_max_f32_e32 v99, v99, v0
	v_add_f32_e32 v103, v98, v99
	v_mov_b32_e32 v105, v0
	s_nop 1
	v_mov_b32_dpp v105, v103 row_shr:1 row_mask:0xf bank_mask:0xf
	v_sub_f32_e32 v104, v86, v103
	v_add_f32_e32 v105, v87, v105
	v_fma_f32 v104, v104, s29, v29
	v_sub_f32_e32 v105, v105, v103
	v_exp_f32_e32 v101, v104
	v_mul_f32_e32 v105, s29, v105
	v_mul_f32_e32 v104, 0xbfb8aa3b, v103
	v_exp_f32_e32 v100, v105
	v_exp_f32_e32 v102, v104
	v_readlane_b32 s4, v103, 7
	s_nop 3
	v_mov_b32_e32 v0, s4
	ds_write_b128 v73, v[100:103] offset:256

.Lml2_nsl4:
	s_add_u32 s22, s22, 0x400
	s_addc_u32 s23, s23, 0
	s_add_u32 s8, s8, 0xc000
	s_addc_u32 s9, s9, 0
	s_add_u32 s10, s10, 0x20000
	s_addc_u32 s11, s11, 0
	s_add_u32 s12, s12, 0x400
	s_addc_u32 s13, s13, 0
	ds_read_b128 v[44:47], v2 offset:41728
	ds_read_b128 v[48:51], v2 offset:41984
	ds_read_b64 v[52:53], v3 offset:45568
	ds_read_b128 v[54:57], v1 offset:47632
	s_waitcnt lgkmcnt(4)
	v_pk_mul_f32 v[18:19], v[30:31], v[40:41] op_sel:[0,1] op_sel_hi:[1,1]
	v_pk_mul_f32 v[20:21], v[32:33], v[40:41] op_sel:[0,1] op_sel_hi:[1,1]
	v_pk_mul_f32 v[22:23], v[38:39], v[18:19] op_sel:[0,0] op_sel_hi:[1,0]
	v_pk_fma_f32 v[6:7], v[6:7], v[40:41], v[22:23] op_sel_hi:[1,0,1]
	v_pk_mul_f32 v[26:27], v[6:7], v[34:35] op_sel_hi:[1,0]
	v_pk_mul_f32 v[24:25], v[38:39], v[18:19] op_sel:[0,1] op_sel_hi:[1,1]
	v_pk_fma_f32 v[8:9], v[8:9], v[40:41], v[24:25] op_sel_hi:[1,0,1]
	v_pk_fma_f32 v[26:27], v[8:9], v[34:35], v[26:27] op_sel:[0,1,0] op_sel_hi:[1,1,1]
	v_pk_mul_f32 v[22:23], v[38:39], v[20:21] op_sel:[0,0] op_sel_hi:[1,0]
	v_pk_fma_f32 v[10:11], v[10:11], v[40:41], v[22:23] op_sel_hi:[1,0,1]
	v_pk_fma_f32 v[26:27], v[10:11], v[36:37], v[26:27] op_sel:[0,0,0] op_sel_hi:[1,0,1]
	v_pk_mul_f32 v[24:25], v[38:39], v[20:21] op_sel:[0,1] op_sel_hi:[1,1]
	v_pk_fma_f32 v[12:13], v[12:13], v[40:41], v[24:25] op_sel_hi:[1,0,1]
	v_pk_fma_f32 v[26:27], v[12:13], v[36:37], v[26:27] op_sel:[0,1,0] op_sel_hi:[1,1,1]
	v_pk_fma_f32 v[14:15], v[14:15], v[40:41], v[18:19] op_sel_hi:[1,0,1]
	v_pk_fma_f32 v[16:17], v[16:17], v[40:41], v[20:21] op_sel_hi:[1,0,1]
	v_add_f32_dpp v26, v26, v26 quad_perm:[1,0,3,2] row_mask:0xf bank_mask:0xf bound_ctrl:1
	v_add_f32_dpp v27, v27, v27 quad_perm:[1,0,3,2] row_mask:0xf bank_mask:0xf bound_ctrl:1
	s_add_u32 s14, s14, 0x1000
	v_add_f32_dpp v26, v26, v26 quad_perm:[2,3,0,1] row_mask:0xf bank_mask:0xf bound_ctrl:1
	v_add_f32_dpp v27, v27, v27 quad_perm:[2,3,0,1] row_mask:0xf bank_mask:0xf bound_ctrl:1
	s_addc_u32 s15, s15, 0
	v_add_f32_dpp v26, v26, v26 row_half_mirror row_mask:0xf bank_mask:0xf bound_ctrl:1
	v_add_f32_dpp v27, v27, v27 row_half_mirror row_mask:0xf bank_mask:0xf bound_ctrl:1
	s_cmp_eq_u32 s21, 0
	v_add_f32_dpp v26, v26, v26 row_mirror row_mask:0xf bank_mask:0xf bound_ctrl:1
	v_add_f32_dpp v27, v27, v27 row_mirror row_mask:0xf bank_mask:0xf bound_ctrl:1
	s_cbranch_scc1 .Lml2_den2_0
.Lml2_back2_0:
	v_cvt_pk_bf16_f32 v28, v26, v27
	global_store_dword v4, v28, s[14:15] offset:-4096
	ds_read_b128 v[30:33], v2 offset:42240
	ds_read_b128 v[34:37], v2 offset:42496
	ds_read_b64 v[38:39], v3 offset:45824
	ds_read_b128 v[40:43], v1 offset:47648
	s_waitcnt lgkmcnt(4)
	v_pk_mul_f32 v[18:19], v[44:45], v[54:55] op_sel:[0,1] op_sel_hi:[1,1]
	v_pk_mul_f32 v[20:21], v[46:47], v[54:55] op_sel:[0,1] op_sel_hi:[1,1]
	v_pk_mul_f32 v[22:23], v[52:53], v[18:19] op_sel:[0,0] op_sel_hi:[1,0]
	v_pk_fma_f32 v[6:7], v[6:7], v[54:55], v[22:23] op_sel_hi:[1,0,1]
	v_pk_mul_f32 v[26:27], v[6:7], v[48:49] op_sel_hi:[1,0]
	v_pk_mul_f32 v[24:25], v[52:53], v[18:19] op_sel:[0,1] op_sel_hi:[1,1]
	v_pk_fma_f32 v[8:9], v[8:9], v[54:55], v[24:25] op_sel_hi:[1,0,1]
	v_pk_fma_f32 v[26:27], v[8:9], v[48:49], v[26:27] op_sel:[0,1,0] op_sel_hi:[1,1,1]
	v_pk_mul_f32 v[22:23], v[52:53], v[20:21] op_sel:[0,0] op_sel_hi:[1,0]
	v_pk_fma_f32 v[10:11], v[10:11], v[54:55], v[22:23] op_sel_hi:[1,0,1]
	v_pk_fma_f32 v[26:27], v[10:11], v[50:51], v[26:27] op_sel:[0,0,0] op_sel_hi:[1,0,1]
	v_pk_mul_f32 v[24:25], v[52:53], v[20:21] op_sel:[0,1] op_sel_hi:[1,1]
	v_pk_fma_f32 v[12:13], v[12:13], v[54:55], v[24:25] op_sel_hi:[1,0,1]
	v_pk_fma_f32 v[26:27], v[12:13], v[50:51], v[26:27] op_sel:[0,1,0] op_sel_hi:[1,1,1]
	v_pk_fma_f32 v[14:15], v[14:15], v[54:55], v[18:19] op_sel_hi:[1,0,1]
	v_pk_fma_f32 v[16:17], v[16:17], v[54:55], v[20:21] op_sel_hi:[1,0,1]
	v_add_f32_dpp v26, v26, v26 quad_perm:[1,0,3,2] row_mask:0xf bank_mask:0xf bound_ctrl:1
	v_add_f32_dpp v27, v27, v27 quad_perm:[1,0,3,2] row_mask:0xf bank_mask:0xf bound_ctrl:1
	s_add_u32 s14, s14, 0x1000
	v_add_f32_dpp v26, v26, v26 quad_perm:[2,3,0,1] row_mask:0xf bank_mask:0xf bound_ctrl:1
	v_add_f32_dpp v27, v27, v27 quad_perm:[2,3,0,1] row_mask:0xf bank_mask:0xf bound_ctrl:1
	s_addc_u32 s15, s15, 0
	v_add_f32_dpp v26, v26, v26 row_half_mirror row_mask:0xf bank_mask:0xf bound_ctrl:1
	v_add_f32_dpp v27, v27, v27 row_half_mirror row_mask:0xf bank_mask:0xf bound_ctrl:1
	s_cmp_eq_u32 s21, 1
	v_add_f32_dpp v26, v26, v26 row_mirror row_mask:0xf bank_mask:0xf bound_ctrl:1
	v_add_f32_dpp v27, v27, v27 row_mirror row_mask:0xf bank_mask:0xf bound_ctrl:1
	s_cbranch_scc1 .Lml2_den2_1
.Lml2_back2_1:
	v_cvt_pk_bf16_f32 v28, v26, v27
	global_store_dword v4, v28, s[14:15] offset:-4096
	ds_read_b128 v[44:47], v2 offset:42752
	ds_read_b128 v[48:51], v2 offset:43008
	ds_read_b64 v[52:53], v3 offset:46080
	ds_read_b128 v[54:57], v1 offset:47664
	s_waitcnt lgkmcnt(4)
	v_pk_mul_f32 v[18:19], v[30:31], v[40:41] op_sel:[0,1] op_sel_hi:[1,1]
	v_pk_mul_f32 v[20:21], v[32:33], v[40:41] op_sel:[0,1] op_sel_hi:[1,1]
	v_pk_mul_f32 v[22:23], v[38:39], v[18:19] op_sel:[0,0] op_sel_hi:[1,0]
	v_pk_fma_f32 v[6:7], v[6:7], v[40:41], v[22:23] op_sel_hi:[1,0,1]
	v_pk_mul_f32 v[26:27], v[6:7], v[34:35] op_sel_hi:[1,0]
	v_pk_mul_f32 v[24:25], v[38:39], v[18:19] op_sel:[0,1] op_sel_hi:[1,1]
	v_pk_fma_f32 v[8:9], v[8:9], v[40:41], v[24:25] op_sel_hi:[1,0,1]
	v_pk_fma_f32 v[26:27], v[8:9], v[34:35], v[26:27] op_sel:[0,1,0] op_sel_hi:[1,1,1]
	v_pk_mul_f32 v[22:23], v[38:39], v[20:21] op_sel:[0,0] op_sel_hi:[1,0]
	v_pk_fma_f32 v[10:11], v[10:11], v[40:41], v[22:23] op_sel_hi:[1,0,1]
	v_pk_fma_f32 v[26:27], v[10:11], v[36:37], v[26:27] op_sel:[0,0,0] op_sel_hi:[1,0,1]
	v_pk_mul_f32 v[24:25], v[38:39], v[20:21] op_sel:[0,1] op_sel_hi:[1,1]
	v_pk_fma_f32 v[12:13], v[12:13], v[40:41], v[24:25] op_sel_hi:[1,0,1]
	v_pk_fma_f32 v[26:27], v[12:13], v[36:37], v[26:27] op_sel:[0,1,0] op_sel_hi:[1,1,1]
	v_pk_fma_f32 v[14:15], v[14:15], v[40:41], v[18:19] op_sel_hi:[1,0,1]
	v_pk_fma_f32 v[16:17], v[16:17], v[40:41], v[20:21] op_sel_hi:[1,0,1]
	v_add_f32_dpp v26, v26, v26 quad_perm:[1,0,3,2] row_mask:0xf bank_mask:0xf bound_ctrl:1
	v_add_f32_dpp v27, v27, v27 quad_perm:[1,0,3,2] row_mask:0xf bank_mask:0xf bound_ctrl:1
	s_add_u32 s14, s14, 0x1000
	v_add_f32_dpp v26, v26, v26 quad_perm:[2,3,0,1] row_mask:0xf bank_mask:0xf bound_ctrl:1
	v_add_f32_dpp v27, v27, v27 quad_perm:[2,3,0,1] row_mask:0xf bank_mask:0xf bound_ctrl:1
	s_addc_u32 s15, s15, 0
	v_add_f32_dpp v26, v26, v26 row_half_mirror row_mask:0xf bank_mask:0xf bound_ctrl:1
	v_add_f32_dpp v27, v27, v27 row_half_mirror row_mask:0xf bank_mask:0xf bound_ctrl:1
	s_cmp_eq_u32 s21, 2
	v_add_f32_dpp v26, v26, v26 row_mirror row_mask:0xf bank_mask:0xf bound_ctrl:1
	v_add_f32_dpp v27, v27, v27 row_mirror row_mask:0xf bank_mask:0xf bound_ctrl:1
	s_cbranch_scc1 .Lml2_den2_2
.Lml2_back2_2:
	v_cvt_pk_bf16_f32 v28, v26, v27
	global_store_dword v4, v28, s[14:15] offset:-4096
	ds_read_b128 v[30:33], v2 offset:43264
	ds_read_b128 v[34:37], v2 offset:43520
	ds_read_b64 v[38:39], v3 offset:46336
	ds_read_b128 v[40:43], v1 offset:47680
	s_waitcnt lgkmcnt(4)
	v_pk_mul_f32 v[18:19], v[44:45], v[54:55] op_sel:[0,1] op_sel_hi:[1,1]
	v_pk_mul_f32 v[20:21], v[46:47], v[54:55] op_sel:[0,1] op_sel_hi:[1,1]
	v_pk_mul_f32 v[22:23], v[52:53], v[18:19] op_sel:[0,0] op_sel_hi:[1,0]
	v_pk_fma_f32 v[6:7], v[6:7], v[54:55], v[22:23] op_sel_hi:[1,0,1]
	v_pk_mul_f32 v[26:27], v[6:7], v[48:49] op_sel_hi:[1,0]
	v_pk_mul_f32 v[24:25], v[52:53], v[18:19] op_sel:[0,1] op_sel_hi:[1,1]
	v_pk_fma_f32 v[8:9], v[8:9], v[54:55], v[24:25] op_sel_hi:[1,0,1]
	v_pk_fma_f32 v[26:27], v[8:9], v[48:49], v[26:27] op_sel:[0,1,0] op_sel_hi:[1,1,1]
	v_pk_mul_f32 v[22:23], v[52:53], v[20:21] op_sel:[0,0] op_sel_hi:[1,0]
	v_pk_fma_f32 v[10:11], v[10:11], v[54:55], v[22:23] op_sel_hi:[1,0,1]
	v_pk_fma_f32 v[26:27], v[10:11], v[50:51], v[26:27] op_sel:[0,0,0] op_sel_hi:[1,0,1]
	v_pk_mul_f32 v[24:25], v[52:53], v[20:21] op_sel:[0,1] op_sel_hi:[1,1]
	v_pk_fma_f32 v[12:13], v[12:13], v[54:55], v[24:25] op_sel_hi:[1,0,1]
	v_pk_fma_f32 v[26:27], v[12:13], v[50:51], v[26:27] op_sel:[0,1,0] op_sel_hi:[1,1,1]
	v_pk_fma_f32 v[14:15], v[14:15], v[54:55], v[18:19] op_sel_hi:[1,0,1]
	v_pk_fma_f32 v[16:17], v[16:17], v[54:55], v[20:21] op_sel_hi:[1,0,1]
	v_add_f32_dpp v26, v26, v26 quad_perm:[1,0,3,2] row_mask:0xf bank_mask:0xf bound_ctrl:1
	v_add_f32_dpp v27, v27, v27 quad_perm:[1,0,3,2] row_mask:0xf bank_mask:0xf bound_ctrl:1
	s_add_u32 s14, s14, 0x1000
	v_add_f32_dpp v26, v26, v26 quad_perm:[2,3,0,1] row_mask:0xf bank_mask:0xf bound_ctrl:1
	v_add_f32_dpp v27, v27, v27 quad_perm:[2,3,0,1] row_mask:0xf bank_mask:0xf bound_ctrl:1
	s_addc_u32 s15, s15, 0
	v_add_f32_dpp v26, v26, v26 row_half_mirror row_mask:0xf bank_mask:0xf bound_ctrl:1
	v_add_f32_dpp v27, v27, v27 row_half_mirror row_mask:0xf bank_mask:0xf bound_ctrl:1
	s_cmp_eq_u32 s21, 3
	v_add_f32_dpp v26, v26, v26 row_mirror row_mask:0xf bank_mask:0xf bound_ctrl:1
	v_add_f32_dpp v27, v27, v27 row_mirror row_mask:0xf bank_mask:0xf bound_ctrl:1
	s_cbranch_scc1 .Lml2_den2_3
.Lml2_back2_3:
	v_cvt_pk_bf16_f32 v28, v26, v27
	global_store_dword v4, v28, s[14:15] offset:-4096
	ds_read_b128 v[44:47], v2 offset:43776
	ds_read_b128 v[48:51], v2 offset:44032
	ds_read_b64 v[52:53], v3 offset:46592
	ds_read_b128 v[54:57], v1 offset:47696
	s_waitcnt lgkmcnt(4)
	v_pk_mul_f32 v[18:19], v[30:31], v[40:41] op_sel:[0,1] op_sel_hi:[1,1]
	v_pk_mul_f32 v[20:21], v[32:33], v[40:41] op_sel:[0,1] op_sel_hi:[1,1]
	v_pk_mul_f32 v[22:23], v[38:39], v[18:19] op_sel:[0,0] op_sel_hi:[1,0]
	v_pk_fma_f32 v[6:7], v[6:7], v[40:41], v[22:23] op_sel_hi:[1,0,1]
	v_pk_mul_f32 v[26:27], v[6:7], v[34:35] op_sel_hi:[1,0]
	v_pk_mul_f32 v[24:25], v[38:39], v[18:19] op_sel:[0,1] op_sel_hi:[1,1]
	v_pk_fma_f32 v[8:9], v[8:9], v[40:41], v[24:25] op_sel_hi:[1,0,1]
	v_pk_fma_f32 v[26:27], v[8:9], v[34:35], v[26:27] op_sel:[0,1,0] op_sel_hi:[1,1,1]
	v_pk_mul_f32 v[22:23], v[38:39], v[20:21] op_sel:[0,0] op_sel_hi:[1,0]
	v_pk_fma_f32 v[10:11], v[10:11], v[40:41], v[22:23] op_sel_hi:[1,0,1]
	v_pk_fma_f32 v[26:27], v[10:11], v[36:37], v[26:27] op_sel:[0,0,0] op_sel_hi:[1,0,1]
	v_pk_mul_f32 v[24:25], v[38:39], v[20:21] op_sel:[0,1] op_sel_hi:[1,1]
	v_pk_fma_f32 v[12:13], v[12:13], v[40:41], v[24:25] op_sel_hi:[1,0,1]
	v_pk_fma_f32 v[26:27], v[12:13], v[36:37], v[26:27] op_sel:[0,1,0] op_sel_hi:[1,1,1]
	v_pk_fma_f32 v[14:15], v[14:15], v[40:41], v[18:19] op_sel_hi:[1,0,1]
	v_pk_fma_f32 v[16:17], v[16:17], v[40:41], v[20:21] op_sel_hi:[1,0,1]
	v_add_f32_dpp v26, v26, v26 quad_perm:[1,0,3,2] row_mask:0xf bank_mask:0xf bound_ctrl:1
	v_add_f32_dpp v27, v27, v27 quad_perm:[1,0,3,2] row_mask:0xf bank_mask:0xf bound_ctrl:1
	s_add_u32 s14, s14, 0x1000
	v_add_f32_dpp v26, v26, v26 quad_perm:[2,3,0,1] row_mask:0xf bank_mask:0xf bound_ctrl:1
	v_add_f32_dpp v27, v27, v27 quad_perm:[2,3,0,1] row_mask:0xf bank_mask:0xf bound_ctrl:1
	s_addc_u32 s15, s15, 0
	v_add_f32_dpp v26, v26, v26 row_half_mirror row_mask:0xf bank_mask:0xf bound_ctrl:1
	v_add_f32_dpp v27, v27, v27 row_half_mirror row_mask:0xf bank_mask:0xf bound_ctrl:1
	s_cmp_eq_u32 s21, 4
	v_add_f32_dpp v26, v26, v26 row_mirror row_mask:0xf bank_mask:0xf bound_ctrl:1
	v_add_f32_dpp v27, v27, v27 row_mirror row_mask:0xf bank_mask:0xf bound_ctrl:1
	s_cbranch_scc1 .Lml2_den2_4
.Lml2_back2_4:
	v_cvt_pk_bf16_f32 v28, v26, v27
	global_store_dword v4, v28, s[14:15] offset:-4096
	ds_read_b128 v[30:33], v2 offset:44288
	ds_read_b128 v[34:37], v2 offset:44544
	ds_read_b64 v[38:39], v3 offset:46848
	ds_read_b128 v[40:43], v1 offset:47712
	s_waitcnt lgkmcnt(4)
	v_pk_mul_f32 v[18:19], v[44:45], v[54:55] op_sel:[0,1] op_sel_hi:[1,1]
	v_pk_mul_f32 v[20:21], v[46:47], v[54:55] op_sel:[0,1] op_sel_hi:[1,1]
	v_pk_mul_f32 v[22:23], v[52:53], v[18:19] op_sel:[0,0] op_sel_hi:[1,0]
	v_pk_fma_f32 v[6:7], v[6:7], v[54:55], v[22:23] op_sel_hi:[1,0,1]
	v_pk_mul_f32 v[26:27], v[6:7], v[48:49] op_sel_hi:[1,0]
	v_pk_mul_f32 v[24:25], v[52:53], v[18:19] op_sel:[0,1] op_sel_hi:[1,1]
	v_pk_fma_f32 v[8:9], v[8:9], v[54:55], v[24:25] op_sel_hi:[1,0,1]
	v_pk_fma_f32 v[26:27], v[8:9], v[48:49], v[26:27] op_sel:[0,1,0] op_sel_hi:[1,1,1]
	v_pk_mul_f32 v[22:23], v[52:53], v[20:21] op_sel:[0,0] op_sel_hi:[1,0]
	v_pk_fma_f32 v[10:11], v[10:11], v[54:55], v[22:23] op_sel_hi:[1,0,1]
	v_pk_fma_f32 v[26:27], v[10:11], v[50:51], v[26:27] op_sel:[0,0,0] op_sel_hi:[1,0,1]
	v_pk_mul_f32 v[24:25], v[52:53], v[20:21] op_sel:[0,1] op_sel_hi:[1,1]
	v_pk_fma_f32 v[12:13], v[12:13], v[54:55], v[24:25] op_sel_hi:[1,0,1]
	v_pk_fma_f32 v[26:27], v[12:13], v[50:51], v[26:27] op_sel:[0,1,0] op_sel_hi:[1,1,1]
	v_pk_fma_f32 v[14:15], v[14:15], v[54:55], v[18:19] op_sel_hi:[1,0,1]
	v_pk_fma_f32 v[16:17], v[16:17], v[54:55], v[20:21] op_sel_hi:[1,0,1]
	v_add_f32_dpp v26, v26, v26 quad_perm:[1,0,3,2] row_mask:0xf bank_mask:0xf bound_ctrl:1
	v_add_f32_dpp v27, v27, v27 quad_perm:[1,0,3,2] row_mask:0xf bank_mask:0xf bound_ctrl:1
	s_add_u32 s14, s14, 0x1000
	v_add_f32_dpp v26, v26, v26 quad_perm:[2,3,0,1] row_mask:0xf bank_mask:0xf bound_ctrl:1
	v_add_f32_dpp v27, v27, v27 quad_perm:[2,3,0,1] row_mask:0xf bank_mask:0xf bound_ctrl:1
	s_addc_u32 s15, s15, 0
	v_add_f32_dpp v26, v26, v26 row_half_mirror row_mask:0xf bank_mask:0xf bound_ctrl:1
	v_add_f32_dpp v27, v27, v27 row_half_mirror row_mask:0xf bank_mask:0xf bound_ctrl:1
	s_cmp_eq_u32 s21, 5
	v_add_f32_dpp v26, v26, v26 row_mirror row_mask:0xf bank_mask:0xf bound_ctrl:1
	v_add_f32_dpp v27, v27, v27 row_mirror row_mask:0xf bank_mask:0xf bound_ctrl:1
	s_cbranch_scc1 .Lml2_den2_5
.Lml2_back2_5:
	v_cvt_pk_bf16_f32 v28, v26, v27
	global_store_dword v4, v28, s[14:15] offset:-4096
	ds_read_b128 v[44:47], v2 offset:44800
	ds_read_b128 v[48:51], v2 offset:45056
	ds_read_b64 v[52:53], v3 offset:47104
	ds_read_b128 v[54:57], v1 offset:47728
	s_waitcnt lgkmcnt(4)
	v_pk_mul_f32 v[18:19], v[30:31], v[40:41] op_sel:[0,1] op_sel_hi:[1,1]
	v_pk_mul_f32 v[20:21], v[32:33], v[40:41] op_sel:[0,1] op_sel_hi:[1,1]
	v_pk_mul_f32 v[22:23], v[38:39], v[18:19] op_sel:[0,0] op_sel_hi:[1,0]
	v_pk_fma_f32 v[6:7], v[6:7], v[40:41], v[22:23] op_sel_hi:[1,0,1]
	v_pk_mul_f32 v[26:27], v[6:7], v[34:35] op_sel_hi:[1,0]
	v_pk_mul_f32 v[24:25], v[38:39], v[18:19] op_sel:[0,1] op_sel_hi:[1,1]
	v_pk_fma_f32 v[8:9], v[8:9], v[40:41], v[24:25] op_sel_hi:[1,0,1]
	v_pk_fma_f32 v[26:27], v[8:9], v[34:35], v[26:27] op_sel:[0,1,0] op_sel_hi:[1,1,1]
	v_pk_mul_f32 v[22:23], v[38:39], v[20:21] op_sel:[0,0] op_sel_hi:[1,0]
	v_pk_fma_f32 v[10:11], v[10:11], v[40:41], v[22:23] op_sel_hi:[1,0,1]
	v_pk_fma_f32 v[26:27], v[10:11], v[36:37], v[26:27] op_sel:[0,0,0] op_sel_hi:[1,0,1]
	v_pk_mul_f32 v[24:25], v[38:39], v[20:21] op_sel:[0,1] op_sel_hi:[1,1]
	v_pk_fma_f32 v[12:13], v[12:13], v[40:41], v[24:25] op_sel_hi:[1,0,1]
	v_pk_fma_f32 v[26:27], v[12:13], v[36:37], v[26:27] op_sel:[0,1,0] op_sel_hi:[1,1,1]
	v_pk_fma_f32 v[14:15], v[14:15], v[40:41], v[18:19] op_sel_hi:[1,0,1]
	v_pk_fma_f32 v[16:17], v[16:17], v[40:41], v[20:21] op_sel_hi:[1,0,1]
	v_add_f32_dpp v26, v26, v26 quad_perm:[1,0,3,2] row_mask:0xf bank_mask:0xf bound_ctrl:1
	v_add_f32_dpp v27, v27, v27 quad_perm:[1,0,3,2] row_mask:0xf bank_mask:0xf bound_ctrl:1
	s_add_u32 s14, s14, 0x1000
	v_add_f32_dpp v26, v26, v26 quad_perm:[2,3,0,1] row_mask:0xf bank_mask:0xf bound_ctrl:1
	v_add_f32_dpp v27, v27, v27 quad_perm:[2,3,0,1] row_mask:0xf bank_mask:0xf bound_ctrl:1
	s_addc_u32 s15, s15, 0
	v_add_f32_dpp v26, v26, v26 row_half_mirror row_mask:0xf bank_mask:0xf bound_ctrl:1
	v_add_f32_dpp v27, v27, v27 row_half_mirror row_mask:0xf bank_mask:0xf bound_ctrl:1
	s_cmp_eq_u32 s21, 6
	v_add_f32_dpp v26, v26, v26 row_mirror row_mask:0xf bank_mask:0xf bound_ctrl:1
	v_add_f32_dpp v27, v27, v27 row_mirror row_mask:0xf bank_mask:0xf bound_ctrl:1
	s_cbranch_scc1 .Lml2_den2_6
.Lml2_back2_6:
	v_cvt_pk_bf16_f32 v28, v26, v27
	global_store_dword v4, v28, s[14:15] offset:-4096
	ds_read_b128 v[30:33], v2 offset:8448
	ds_read_b128 v[34:37], v2 offset:8704
	ds_read_b64 v[38:39], v3 offset:12544
	ds_read_b128 v[40:43], v1 offset:14848
	s_waitcnt lgkmcnt(4)
	v_pk_mul_f32 v[18:19], v[44:45], v[54:55] op_sel:[0,1] op_sel_hi:[1,1]
	v_pk_mul_f32 v[20:21], v[46:47], v[54:55] op_sel:[0,1] op_sel_hi:[1,1]
	v_pk_mul_f32 v[22:23], v[52:53], v[18:19] op_sel:[0,0] op_sel_hi:[1,0]
	v_pk_fma_f32 v[6:7], v[6:7], v[54:55], v[22:23] op_sel_hi:[1,0,1]
	v_pk_mul_f32 v[26:27], v[6:7], v[48:49] op_sel_hi:[1,0]
	v_pk_mul_f32 v[24:25], v[52:53], v[18:19] op_sel:[0,1] op_sel_hi:[1,1]
	v_pk_fma_f32 v[8:9], v[8:9], v[54:55], v[24:25] op_sel_hi:[1,0,1]
	v_pk_fma_f32 v[26:27], v[8:9], v[48:49], v[26:27] op_sel:[0,1,0] op_sel_hi:[1,1,1]
	v_pk_mul_f32 v[22:23], v[52:53], v[20:21] op_sel:[0,0] op_sel_hi:[1,0]
	v_pk_fma_f32 v[10:11], v[10:11], v[54:55], v[22:23] op_sel_hi:[1,0,1]
	v_pk_fma_f32 v[26:27], v[10:11], v[50:51], v[26:27] op_sel:[0,0,0] op_sel_hi:[1,0,1]
	v_pk_mul_f32 v[24:25], v[52:53], v[20:21] op_sel:[0,1] op_sel_hi:[1,1]
	v_pk_fma_f32 v[12:13], v[12:13], v[54:55], v[24:25] op_sel_hi:[1,0,1]
	v_pk_fma_f32 v[26:27], v[12:13], v[50:51], v[26:27] op_sel:[0,1,0] op_sel_hi:[1,1,1]
	v_pk_fma_f32 v[14:15], v[14:15], v[54:55], v[18:19] op_sel_hi:[1,0,1]
	v_pk_fma_f32 v[16:17], v[16:17], v[54:55], v[20:21] op_sel_hi:[1,0,1]
	v_add_f32_dpp v26, v26, v26 quad_perm:[1,0,3,2] row_mask:0xf bank_mask:0xf bound_ctrl:1
	v_add_f32_dpp v27, v27, v27 quad_perm:[1,0,3,2] row_mask:0xf bank_mask:0xf bound_ctrl:1
	s_add_u32 s14, s14, 0x1000
	v_add_f32_dpp v26, v26, v26 quad_perm:[2,3,0,1] row_mask:0xf bank_mask:0xf bound_ctrl:1
	v_add_f32_dpp v27, v27, v27 quad_perm:[2,3,0,1] row_mask:0xf bank_mask:0xf bound_ctrl:1
	s_addc_u32 s15, s15, 0
	v_add_f32_dpp v26, v26, v26 row_half_mirror row_mask:0xf bank_mask:0xf bound_ctrl:1
	v_add_f32_dpp v27, v27, v27 row_half_mirror row_mask:0xf bank_mask:0xf bound_ctrl:1
	s_cmp_eq_u32 s21, 7
	v_add_f32_dpp v26, v26, v26 row_mirror row_mask:0xf bank_mask:0xf bound_ctrl:1
	v_add_f32_dpp v27, v27, v27 row_mirror row_mask:0xf bank_mask:0xf bound_ctrl:1
	s_cbranch_scc1 .Lml2_den2_7
.Lml2_back2_7:
	v_cvt_pk_bf16_f32 v28, v26, v27
	global_store_dword v4, v28, s[14:15] offset:-4096
	s_waitcnt vmcnt(8)
	v_lshlrev_b32_e32 v88, 16, v80
	v_lshlrev_b32_e32 v89, 16, v81
	v_and_b32_e32 v90, s17, v80
	v_and_b32_e32 v91, s17, v81
	v_lshlrev_b32_e32 v92, 16, v82
	v_and_b32_e32 v93, s17, v82
	v_lshlrev_b32_e32 v94, 16, v83
	v_and_b32_e32 v95, s17, v83
	v_lshlrev_b32_e32 v96, 16, v84
	v_and_b32_e32 v97, s17, v84
	ds_write_b128 v69, v[88:91] offset:16640
	ds_write_b64 v70, v[92:93] offset:16640
	ds_write_b64 v71, v[94:95] offset:16640
	ds_write_b64 v71, v[96:97] offset:16768
	ds_write_b32 v72, v85 offset:16640
	s_cmp_lg_u32 s36, 4
	s_cbranch_scc1 .Lml2_nsc4
	v_mov_b32_e32 v98, v87
	s_nop 1
	v_add_f32_dpp v98, v98, v98 row_shr:1 row_mask:0xf bank_mask:0xf bound_ctrl:1
	s_nop 1
	v_add_f32_dpp v98, v98, v98 row_shr:2 row_mask:0xf bank_mask:0xf bound_ctrl:1
	s_nop 1
	v_add_f32_dpp v98, v98, v98 row_shr:4 row_mask:0xf bank_mask:0xf bound_ctrl:1
	s_nop 1
	v_sub_f32_e32 v99, v86, v98
	s_nop 1
	v_max_f32_dpp v99, v99, v99 row_shr:1 row_mask:0xf bank_mask:0xf
	s_nop 1
	v_max_f32_dpp v99, v99, v99 row_shr:2 row_mask:0xf bank_mask:0xf
	s_nop 1
	v_max_f32_dpp v99, v99, v99 row_shr:4 row_mask:0xf bank_mask:0xf
	s_nop 1
	v_max_f32_e32 v99, v99, v0
	v_add_f32_e32 v103, v98, v99
	v_mov_b32_e32 v105, v0
	s_nop 1
	v_mov_b32_dpp v105, v103 row_shr:1 row_mask:0xf bank_mask:0xf
	v_sub_f32_e32 v104, v86, v103
	v_add_f32_e32 v105, v87, v105
	v_fma_f32 v104, v104, s29, v29
	v_sub_f32_e32 v105, v105, v103
	v_exp_f32_e32 v101, v104
	v_mul_f32_e32 v105, s29, v105
	v_mul_f32_e32 v104, 0xbfb8aa3b, v103
	v_exp_f32_e32 v100, v105
	v_exp_f32_e32 v102, v104
	v_readlane_b32 s4, v103, 7
	s_nop 3
	v_mov_b32_e32 v0, s4
	ds_write_b128 v73, v[100:103] offset:16640
.Lml2_nsc4:
	s_add_u32 s24, s24, 0x400
	s_addc_u32 s25, s25, 0
	s_sub_i32 s21, s21, 8
	s_add_i32 s16, s16, 8
	s_waitcnt lgkmcnt(0)
	s_barrier
	s_cmpk_lt_u32 s16, 0x800
	s_cbranch_scc1 .Lml2_loop
.Lml2_done:
	s_lshr_b32 s2, s30, 4
	s_lshl_b32 s4, s2, 15
	s_add_u32 s4, s4, 0x44c8000
	s_add_u32 s0, s34, s4
	s_addc_u32 s1, s35, 0
	v_and_b32_e32 v104, 15, v198
	v_lshlrev_b32_e32 v105, 11, v104
	v_lshl_add_u32 v105, v4, 1, v105
	global_store_dwordx2 v105, v[6:7], s[0:1] offset:0
	global_store_dwordx2 v105, v[8:9], s[0:1] offset:512
	global_store_dwordx2 v105, v[10:11], s[0:1] offset:1024
	global_store_dwordx2 v105, v[12:13], s[0:1] offset:1536
	s_cmp_lg_u32 s31, 0
	s_cbranch_scc1 .Lml2_nonm
	s_lshl_b32 s4, s2, 8
	s_add_u32 s4, s4, 0x46c8000
	s_add_u32 s0, s34, s4
	s_addc_u32 s1, s35, 0
	v_lshlrev_b32_e32 v104, 4, v104
	global_store_dwordx2 v104, v[14:15], s[0:1]
	global_store_dwordx2 v104, v[16:17], s[0:1] offset:8
	s_lshl_b32 s4, s2, 2
	s_add_u32 s4, s4, 0x46cc000
	s_add_u32 s0, s34, s4
	s_addc_u32 s1, s35, 0
	global_store_dword v1, v57, s[0:1]

.Lml2_den0_7:
	v_pk_mul_f32 v[22:23], v[14:15], v[48:49]
	v_pk_fma_f32 v[22:23], v[16:17], v[50:51], v[22:23]
	s_nop 0
	v_add_f32_e32 v22, v22, v23
	s_nop 1
	v_add_f32_dpp v22, v22, v22 quad_perm:[1,0,3,2] row_mask:0xf bank_mask:0xf bound_ctrl:1
	s_nop 1
	v_add_f32_dpp v22, v22, v22 quad_perm:[2,3,0,1] row_mask:0xf bank_mask:0xf bound_ctrl:1
	s_nop 1
	v_add_f32_dpp v22, v22, v22 row_half_mirror row_mask:0xf bank_mask:0xf bound_ctrl:1
	s_nop 1
	v_add_f32_dpp v22, v22, v22 row_mirror row_mask:0xf bank_mask:0xf bound_ctrl:1
	v_max_f32_e64 v22, |v22|, v56
	v_rcp_f32_e32 v22, v22
	s_add_i32 s21, s21, 16
	global_store_dword v1, v22, s[24:25] offset:904
	s_branch .Lml2_back0_7
.Lml2_den1_0:
	v_pk_mul_f32 v[22:23], v[14:15], v[34:35]
	v_pk_fma_f32 v[22:23], v[16:17], v[36:37], v[22:23]
	s_nop 0
	v_add_f32_e32 v22, v22, v23
	s_nop 1
	v_add_f32_dpp v22, v22, v22 quad_perm:[1,0,3,2] row_mask:0xf bank_mask:0xf bound_ctrl:1
	s_nop 1
	v_add_f32_dpp v22, v22, v22 quad_perm:[2,3,0,1] row_mask:0xf bank_mask:0xf bound_ctrl:1
	s_nop 1
	v_add_f32_dpp v22, v22, v22 row_half_mirror row_mask:0xf bank_mask:0xf bound_ctrl:1
	s_nop 1
	v_add_f32_dpp v22, v22, v22 row_mirror row_mask:0xf bank_mask:0xf bound_ctrl:1
	v_max_f32_e64 v22, |v22|, v42
	v_rcp_f32_e32 v22, v22
	s_add_i32 s21, s21, 16
	global_store_dword v1, v22, s[24:25] offset:8
	s_branch .Lml2_back1_0

.Lml2_den1_7:
	v_pk_mul_f32 v[22:23], v[14:15], v[48:49]
	v_pk_fma_f32 v[22:23], v[16:17], v[50:51], v[22:23]
	s_nop 0
	v_add_f32_e32 v22, v22, v23
	s_nop 1
	v_add_f32_dpp v22, v22, v22 quad_perm:[1,0,3,2] row_mask:0xf bank_mask:0xf bound_ctrl:1
	s_nop 1
	v_add_f32_dpp v22, v22, v22 quad_perm:[2,3,0,1] row_mask:0xf bank_mask:0xf bound_ctrl:1
	s_nop 1
	v_add_f32_dpp v22, v22, v22 row_half_mirror row_mask:0xf bank_mask:0xf bound_ctrl:1
	s_nop 1
	v_add_f32_dpp v22, v22, v22 row_mirror row_mask:0xf bank_mask:0xf bound_ctrl:1
	v_max_f32_e64 v22, |v22|, v56
	v_rcp_f32_e32 v22, v22
	s_add_i32 s21, s21, 16
	global_store_dword v1, v22, s[24:25] offset:904
	s_branch .Lml2_back1_7
.Lml2_den2_0:
	v_pk_mul_f32 v[22:23], v[14:15], v[34:35]
	v_pk_fma_f32 v[22:23], v[16:17], v[36:37], v[22:23]
	s_nop 0
	v_add_f32_e32 v22, v22, v23
	s_nop 1
	v_add_f32_dpp v22, v22, v22 quad_perm:[1,0,3,2] row_mask:0xf bank_mask:0xf bound_ctrl:1
	s_nop 1
	v_add_f32_dpp v22, v22, v22 quad_perm:[2,3,0,1] row_mask:0xf bank_mask:0xf bound_ctrl:1
	s_nop 1
	v_add_f32_dpp v22, v22, v22 row_half_mirror row_mask:0xf bank_mask:0xf bound_ctrl:1
	s_nop 1
	v_add_f32_dpp v22, v22, v22 row_mirror row_mask:0xf bank_mask:0xf bound_ctrl:1
	v_max_f32_e64 v22, |v22|, v42
	v_rcp_f32_e32 v22, v22
	s_add_i32 s21, s21, 16
	global_store_dword v1, v22, s[24:25] offset:8
	s_branch .Lml2_back2_0

.Lgd2_item:
	s_lshr_b32 s2, s27, 4
	s_and_b32 s3, s27, 15
	s_lshl_b32 s4, s3, 4
	v_lshl_add_u32 v154, v5, 2, s4
	v_lshl_add_u32 v153, v154, 1, v4
	s_and_b32 s4, s3, 3
	s_lshl_b32 s4, s4, 5
	v_lshl_add_u32 v3, v5, 3, s4
	s_and_b32 s4, s3, 12
	s_lshl_b32 s4, s4, 4
	v_min_u32_e32 v155, 15, v198
	v_lshl_add_u32 v104, v155, 2, s4
	s_and_b32 s5, s2, 7
	s_lshl_b32 s3, s5, 7
	s_add_u32 s4, s4, s3
	s_add_u32 s4, s4, 2048
	v_lshl_add_u32 v105, v155, 2, s4
	s_lshr_b32 s4, s2, 3
	v_readlane_b32 s3, v255, 15
	s_mul_i32 s6, s4, 0xc00000
	s_mul_i32 s7, s3, 0x1800
	s_add_u32 s6, s6, s7
	s_lshl_b32 s7, s5, 8
	s_add_u32 s6, s6, s7
	s_add_u32 s6, s6, 0xb38d900
	s_add_u32 s8, s24, s6
	s_addc_u32 s9, s25, 0
	s_lshl_b32 s6, s4, 25
	s_lshl_b32 s7, s3, 14
	s_add_u32 s6, s6, s7
	s_lshl_b32 s7, s5, 7
	s_add_u32 s6, s6, s7
	s_add_u32 s6, s6, 62659584
	s_add_u32 s10, s22, s6
	s_addc_u32 s11, s23, 0
	s_lshl_b32 s6, s4, 18
	s_lshl_b32 s7, s3, 7
	s_add_u32 s6, s6, s7
	s_lshl_b32 s7, s5, 4
	s_add_u32 s6, s6, s7
	s_add_u32 s6, s6, 0x37b8400
	s_add_u32 s12, s22, s6
	s_addc_u32 s13, s23, 0
	s_lshl_b32 s6, s4, 23
	s_lshl_b32 s7, s5, 8
	s_add_u32 s6, s6, s7
	s_add_u32 s6, s6, 333186048
	s_add_u32 s14, s22, s6
	s_addc_u32 s15, s23, 0
	s_movk_i32 s18, 256
	s_movk_i32 s19, 16640
	s_mov_b32 s20, 33024
	v_add_u32_e32 v28, s18, v32
	v_add_u32_e32 v29, s18, v33
	v_add_u32_e32 v30, s18, v34
	v_add_u32_e32 v31, s18, v35
	global_load_dword v108, v36, s[8:9]
	global_load_dword v109, v36, s[8:9] offset:-2048
	global_load_dword v111, v104, s[8:9] offset:2048
	global_load_dword v110, v37, s[10:11]
	global_load_dword v112, v105, s[10:11]
	global_load_dword v113, v106, s[12:13]
	s_add_u32 s8, s8, 0xc000
	s_addc_u32 s9, s9, 0
	s_add_u32 s10, s10, 0x20000
	s_addc_u32 s11, s11, 0
	s_add_u32 s12, s12, 0x400
	s_addc_u32 s13, s13, 0
	s_waitcnt vmcnt(0)
	v_lshlrev_b32_e32 v116, 16, v108
	v_lshlrev_b32_e32 v117, 16, v109
	v_and_b32_e32 v118, s17, v108
	v_and_b32_e32 v119, s17, v109
	v_lshlrev_b32_e32 v120, 16, v110
	v_and_b32_e32 v121, s17, v110
	v_lshlrev_b32_e32 v122, 16, v111
	v_and_b32_e32 v123, s17, v111
	v_lshlrev_b32_e32 v124, 16, v112
	v_and_b32_e32 v125, s17, v112
	ds_write_b128 v32, v[116:119] offset:256
	ds_write_b64 v33, v[120:121] offset:256
	ds_write_b64 v34, v[122:123] offset:256
	ds_write_b64 v34, v[124:125] offset:384
	ds_write_b32 v35, v113 offset:256
	v_add_u32_e32 v28, s19, v32
	v_add_u32_e32 v29, s19, v33
	v_add_u32_e32 v30, s19, v34
	v_add_u32_e32 v31, s19, v35
	global_load_dword v108, v36, s[8:9]
	global_load_dword v109, v36, s[8:9] offset:-2048
	global_load_dword v111, v104, s[8:9] offset:2048
	global_load_dword v110, v37, s[10:11]
	global_load_dword v112, v105, s[10:11]
	global_load_dword v113, v106, s[12:13]
	s_add_u32 s8, s8, 0xc000
	s_addc_u32 s9, s9, 0
	s_add_u32 s10, s10, 0x20000
	s_addc_u32 s11, s11, 0
	s_add_u32 s12, s12, 0x400
	s_addc_u32 s13, s13, 0
	s_waitcnt vmcnt(0)
	v_lshlrev_b32_e32 v116, 16, v108
	v_lshlrev_b32_e32 v117, 16, v109
	v_and_b32_e32 v118, s17, v108
	v_and_b32_e32 v119, s17, v109
	v_lshlrev_b32_e32 v120, 16, v110
	v_and_b32_e32 v121, s17, v110
	v_lshlrev_b32_e32 v122, 16, v111
	v_and_b32_e32 v123, s17, v111
	v_lshlrev_b32_e32 v124, 16, v112
	v_and_b32_e32 v125, s17, v112
	ds_write_b128 v32, v[116:119] offset:16640
	ds_write_b64 v33, v[120:121] offset:16640
	ds_write_b64 v34, v[122:123] offset:16640
	ds_write_b64 v34, v[124:125] offset:16768
	ds_write_b32 v35, v113 offset:16640
	v_add_u32_e32 v28, s20, v32
	v_add_u32_e32 v29, s20, v33
	v_add_u32_e32 v30, s20, v34
	v_add_u32_e32 v31, s20, v35
	v_add_u32_e32 v22, s18, v2
	v_add_u32_e32 v23, s18, v3
	v_mov_b32_e32 v24, s18
	v_add_u32_e32 v25, s19, v2
	v_add_u32_e32 v26, s19, v3
	v_mov_b32_e32 v27, s19
	v_mov_b32_e32 v6, 0
	v_mov_b32_e32 v7, 0
	v_mov_b32_e32 v8, 0
	v_mov_b32_e32 v9, 0
	v_mov_b32_e32 v10, 0
	v_mov_b32_e32 v11, 0
	v_mov_b32_e32 v12, 0
	v_mov_b32_e32 v13, 0
	v_mov_b32_e32 v14, 0
	v_mov_b32_e32 v15, 0
	v_mov_b32_e32 v16, 0
	v_mov_b32_e32 v17, 0
	v_mov_b32_e32 v18, 0
	v_mov_b32_e32 v19, 0
	v_mov_b32_e32 v20, 0
	v_mov_b32_e32 v21, 0
	v_mov_b32_e32 v51, 1.0
	s_mov_b32 s16, 0
	s_waitcnt vmcnt(0) lgkmcnt(0)
	s_barrier
	s_setprio 1
	ds_read_b128 v[56:59], v2 offset:256
	ds_read_b128 v[60:63], v2 offset:512
	ds_read_b128 v[64:67], v2 offset:768
	ds_read_b128 v[68:71], v2 offset:1024
	ds_read_b64 v[72:73], v3 offset:12544
	ds_read_b128 v[76:79], v1 offset:14592
.Lgd2_loop:
	global_load_dword v108, v36, s[8:9]
	global_load_dword v109, v36, s[8:9] offset:-2048
	global_load_dword v111, v104, s[8:9] offset:2048
	global_load_dword v110, v37, s[10:11]
	global_load_dword v112, v105, s[10:11]
	global_load_dword v113, v106, s[12:13]
	s_add_u32 s8, s8, 0xc000
	s_addc_u32 s9, s9, 0
	s_add_u32 s10, s10, 0x20000
	s_addc_u32 s11, s11, 0
	s_add_u32 s12, s12, 0x400
	s_addc_u32 s13, s13, 0
	s_waitcnt lgkmcnt(0)
	v_pk_mul_f32 v[38:39], v[6:7], v[56:57] op_sel_hi:[1,0]
	v_pk_mul_f32 v[40:41], v[6:7], v[56:57] op_sel:[0,1] op_sel_hi:[1,1]
	v_pk_fma_f32 v[38:39], v[8:9], v[58:59], v[38:39] op_sel_hi:[1,0,1]
	v_pk_fma_f32 v[40:41], v[8:9], v[58:59], v[40:41] op_sel:[0,1,0] op_sel_hi:[1,1,1]
	v_pk_fma_f32 v[38:39], v[10:11], v[60:61], v[38:39] op_sel_hi:[1,0,1]
	v_pk_fma_f32 v[40:41], v[10:11], v[60:61], v[40:41] op_sel:[0,1,0] op_sel_hi:[1,1,1]
	v_pk_fma_f32 v[38:39], v[12:13], v[62:63], v[38:39] op_sel_hi:[1,0,1]
	v_pk_fma_f32 v[40:41], v[12:13], v[62:63], v[40:41] op_sel:[0,1,0] op_sel_hi:[1,1,1]
	v_pk_fma_f32 v[38:39], v[14:15], v[64:65], v[38:39] op_sel_hi:[1,0,1]
	v_pk_fma_f32 v[40:41], v[14:15], v[64:65], v[40:41] op_sel:[0,1,0] op_sel_hi:[1,1,1]
	v_pk_fma_f32 v[38:39], v[16:17], v[66:67], v[38:39] op_sel_hi:[1,0,1]
	v_pk_fma_f32 v[40:41], v[16:17], v[66:67], v[40:41] op_sel:[0,1,0] op_sel_hi:[1,1,1]
	v_pk_fma_f32 v[38:39], v[18:19], v[68:69], v[38:39] op_sel_hi:[1,0,1]
	v_pk_fma_f32 v[40:41], v[18:19], v[68:69], v[40:41] op_sel:[0,1,0] op_sel_hi:[1,1,1]
	v_pk_fma_f32 v[38:39], v[20:21], v[70:71], v[38:39] op_sel_hi:[1,0,1]
	v_pk_fma_f32 v[40:41], v[20:21], v[70:71], v[40:41] op_sel:[0,1,0] op_sel_hi:[1,1,1]
	v_mul_f32_e32 v50, v76, v51
	v_add_f32_dpp v38, v38, v38 row_ror:8 row_mask:0xf bank_mask:0x3 bound_ctrl:1
	v_add_f32_dpp v39, v39, v39 row_ror:8 row_mask:0xf bank_mask:0x3 bound_ctrl:1
	v_add_f32_dpp v38, v40, v40 row_ror:8 row_mask:0xf bank_mask:0xc bound_ctrl:1
	v_add_f32_dpp v39, v41, v41 row_ror:8 row_mask:0xf bank_mask:0xc bound_ctrl:1
	ds_read_b128 v[80:83], v2 offset:1280
	v_add_f32_dpp v38, v38, v38 row_half_mirror row_mask:0xf bank_mask:0x5 bound_ctrl:1
	v_add_f32_dpp v38, v39, v39 row_half_mirror row_mask:0xf bank_mask:0xa bound_ctrl:1
	ds_read_b128 v[84:87], v2 offset:1536
	ds_read_b128 v[88:91], v2 offset:1792
	v_add_f32_dpp v38, v38, v38 quad_perm:[1,0,3,2] row_mask:0xf bank_mask:0xf bound_ctrl:1
	ds_read_b128 v[92:95], v2 offset:2048
	ds_read_b64 v[96:97], v3 offset:12800
	v_add_f32_dpp v38, v38, v38 quad_perm:[2,3,0,1] row_mask:0xf bank_mask:0xf bound_ctrl:1
	ds_read_b128 v[100:103], v1 offset:14608
	v_cmp_gt_f32_e32 vcc, 0x2b8cbccc, v50
	v_fmac_f32_dpp v72, -v38, v50 row_newbcast:0 row_mask:0xf bank_mask:0xf bound_ctrl:1
	v_fmac_f32_dpp v73, -v38, v50 row_newbcast:4 row_mask:0xf bank_mask:0xf bound_ctrl:1
	v_pk_mul_f32 v[44:45], v[72:73], v[76:77] op_sel:[0,1] op_sel_hi:[1,1]
	v_pk_mul_f32 v[48:49], v[44:45], v[78:79] op_sel_hi:[1,0]
	v_rcp_f32_e32 v52, v50
	s_add_u32 s14, s14, 0x1000
	s_addc_u32 s15, s15, 0
	v_fmac_f32_dpp v48, v38, v50 row_newbcast:8 row_mask:0xf bank_mask:0xf bound_ctrl:1
	v_fmac_f32_dpp v49, v38, v50 row_newbcast:12 row_mask:0xf bank_mask:0xf bound_ctrl:1
	s_cbranch_vccnz .Lgd2_rare0_0
.Lgd2_back0_0:
	v_cvt_pk_bf16_f32 v54, v48, v49
	v_pk_mul_f32 v[46:47], v[44:45], v[52:53] op_sel_hi:[1,0]
	v_pk_fma_f32 v[6:7], v[56:57], v[46:47], v[6:7] op_sel_hi:[0,1,1]
	v_pk_fma_f32 v[8:9], v[58:59], v[46:47], v[8:9] op_sel_hi:[0,1,1]
	v_pk_fma_f32 v[10:11], v[60:61], v[46:47], v[10:11] op_sel_hi:[0,1,1]
	v_pk_fma_f32 v[12:13], v[62:63], v[46:47], v[12:13] op_sel_hi:[0,1,1]
	v_pk_fma_f32 v[14:15], v[64:65], v[46:47], v[14:15] op_sel_hi:[0,1,1]
	v_pk_fma_f32 v[16:17], v[66:67], v[46:47], v[16:17] op_sel_hi:[0,1,1]
	v_pk_fma_f32 v[18:19], v[68:69], v[46:47], v[18:19] op_sel_hi:[0,1,1]
	v_pk_fma_f32 v[20:21], v[70:71], v[46:47], v[20:21] op_sel_hi:[0,1,1]
	global_store_dword v154, v54, s[14:15] offset:-4096
	s_waitcnt lgkmcnt(0)
	v_pk_mul_f32 v[38:39], v[6:7], v[80:81] op_sel_hi:[1,0]
	v_pk_mul_f32 v[40:41], v[6:7], v[80:81] op_sel:[0,1] op_sel_hi:[1,1]
	v_pk_fma_f32 v[38:39], v[8:9], v[82:83], v[38:39] op_sel_hi:[1,0,1]
	v_pk_fma_f32 v[40:41], v[8:9], v[82:83], v[40:41] op_sel:[0,1,0] op_sel_hi:[1,1,1]
	v_pk_fma_f32 v[38:39], v[10:11], v[84:85], v[38:39] op_sel_hi:[1,0,1]
	v_pk_fma_f32 v[40:41], v[10:11], v[84:85], v[40:41] op_sel:[0,1,0] op_sel_hi:[1,1,1]
	v_pk_fma_f32 v[38:39], v[12:13], v[86:87], v[38:39] op_sel_hi:[1,0,1]
	v_pk_fma_f32 v[40:41], v[12:13], v[86:87], v[40:41] op_sel:[0,1,0] op_sel_hi:[1,1,1]
	v_pk_fma_f32 v[38:39], v[14:15], v[88:89], v[38:39] op_sel_hi:[1,0,1]
	v_pk_fma_f32 v[40:41], v[14:15], v[88:89], v[40:41] op_sel:[0,1,0] op_sel_hi:[1,1,1]
	v_pk_fma_f32 v[38:39], v[16:17], v[90:91], v[38:39] op_sel_hi:[1,0,1]
	v_pk_fma_f32 v[40:41], v[16:17], v[90:91], v[40:41] op_sel:[0,1,0] op_sel_hi:[1,1,1]
	v_pk_fma_f32 v[38:39], v[18:19], v[92:93], v[38:39] op_sel_hi:[1,0,1]
	v_pk_fma_f32 v[40:41], v[18:19], v[92:93], v[40:41] op_sel:[0,1,0] op_sel_hi:[1,1,1]
	v_pk_fma_f32 v[38:39], v[20:21], v[94:95], v[38:39] op_sel_hi:[1,0,1]
	v_pk_fma_f32 v[40:41], v[20:21], v[94:95], v[40:41] op_sel:[0,1,0] op_sel_hi:[1,1,1]
	v_mul_f32_e32 v51, v100, v50
	v_add_f32_dpp v38, v38, v38 row_ror:8 row_mask:0xf bank_mask:0x3 bound_ctrl:1
	v_add_f32_dpp v39, v39, v39 row_ror:8 row_mask:0xf bank_mask:0x3 bound_ctrl:1
	v_add_f32_dpp v38, v40, v40 row_ror:8 row_mask:0xf bank_mask:0xc bound_ctrl:1
	v_add_f32_dpp v39, v41, v41 row_ror:8 row_mask:0xf bank_mask:0xc bound_ctrl:1
	ds_read_b128 v[56:59], v2 offset:2304
	v_add_f32_dpp v38, v38, v38 row_half_mirror row_mask:0xf bank_mask:0x5 bound_ctrl:1
	v_add_f32_dpp v38, v39, v39 row_half_mirror row_mask:0xf bank_mask:0xa bound_ctrl:1
	ds_read_b128 v[60:63], v2 offset:2560
	ds_read_b128 v[64:67], v2 offset:2816
	v_add_f32_dpp v38, v38, v38 quad_perm:[1,0,3,2] row_mask:0xf bank_mask:0xf bound_ctrl:1
	ds_read_b128 v[68:71], v2 offset:3072
	ds_read_b64 v[72:73], v3 offset:13056
	v_add_f32_dpp v38, v38, v38 quad_perm:[2,3,0,1] row_mask:0xf bank_mask:0xf bound_ctrl:1
	ds_read_b128 v[76:79], v1 offset:14624
	v_cmp_gt_f32_e32 vcc, 0x2b8cbccc, v51
	v_fmac_f32_dpp v96, -v38, v51 row_newbcast:0 row_mask:0xf bank_mask:0xf bound_ctrl:1
	v_fmac_f32_dpp v97, -v38, v51 row_newbcast:4 row_mask:0xf bank_mask:0xf bound_ctrl:1
	v_pk_mul_f32 v[44:45], v[96:97], v[100:101] op_sel:[0,1] op_sel_hi:[1,1]
	v_pk_mul_f32 v[48:49], v[44:45], v[102:103] op_sel_hi:[1,0]
	v_rcp_f32_e32 v52, v51
	s_add_u32 s14, s14, 0x1000
	s_addc_u32 s15, s15, 0
	v_fmac_f32_dpp v48, v38, v51 row_newbcast:8 row_mask:0xf bank_mask:0xf bound_ctrl:1
	v_fmac_f32_dpp v49, v38, v51 row_newbcast:12 row_mask:0xf bank_mask:0xf bound_ctrl:1
	s_cbranch_vccnz .Lgd2_rare0_1
.Lgd2_back0_1:
	v_cvt_pk_bf16_f32 v54, v48, v49
	v_pk_mul_f32 v[46:47], v[44:45], v[52:53] op_sel_hi:[1,0]
	v_pk_fma_f32 v[6:7], v[80:81], v[46:47], v[6:7] op_sel_hi:[0,1,1]
	v_pk_fma_f32 v[8:9], v[82:83], v[46:47], v[8:9] op_sel_hi:[0,1,1]
	v_pk_fma_f32 v[10:11], v[84:85], v[46:47], v[10:11] op_sel_hi:[0,1,1]
	v_pk_fma_f32 v[12:13], v[86:87], v[46:47], v[12:13] op_sel_hi:[0,1,1]
	v_pk_fma_f32 v[14:15], v[88:89], v[46:47], v[14:15] op_sel_hi:[0,1,1]
	v_pk_fma_f32 v[16:17], v[90:91], v[46:47], v[16:17] op_sel_hi:[0,1,1]
	v_pk_fma_f32 v[18:19], v[92:93], v[46:47], v[18:19] op_sel_hi:[0,1,1]
	v_pk_fma_f32 v[20:21], v[94:95], v[46:47], v[20:21] op_sel_hi:[0,1,1]
	global_store_dword v154, v54, s[14:15] offset:-4096
	s_waitcnt lgkmcnt(0)
	v_pk_mul_f32 v[38:39], v[6:7], v[56:57] op_sel_hi:[1,0]
	v_pk_mul_f32 v[40:41], v[6:7], v[56:57] op_sel:[0,1] op_sel_hi:[1,1]
	v_pk_fma_f32 v[38:39], v[8:9], v[58:59], v[38:39] op_sel_hi:[1,0,1]
	v_pk_fma_f32 v[40:41], v[8:9], v[58:59], v[40:41] op_sel:[0,1,0] op_sel_hi:[1,1,1]
	v_pk_fma_f32 v[38:39], v[10:11], v[60:61], v[38:39] op_sel_hi:[1,0,1]
	v_pk_fma_f32 v[40:41], v[10:11], v[60:61], v[40:41] op_sel:[0,1,0] op_sel_hi:[1,1,1]
	v_pk_fma_f32 v[38:39], v[12:13], v[62:63], v[38:39] op_sel_hi:[1,0,1]
	v_pk_fma_f32 v[40:41], v[12:13], v[62:63], v[40:41] op_sel:[0,1,0] op_sel_hi:[1,1,1]
	v_pk_fma_f32 v[38:39], v[14:15], v[64:65], v[38:39] op_sel_hi:[1,0,1]
	v_pk_fma_f32 v[40:41], v[14:15], v[64:65], v[40:41] op_sel:[0,1,0] op_sel_hi:[1,1,1]
	v_pk_fma_f32 v[38:39], v[16:17], v[66:67], v[38:39] op_sel_hi:[1,0,1]
	v_pk_fma_f32 v[40:41], v[16:17], v[66:67], v[40:41] op_sel:[0,1,0] op_sel_hi:[1,1,1]
	v_pk_fma_f32 v[38:39], v[18:19], v[68:69], v[38:39] op_sel_hi:[1,0,1]
	v_pk_fma_f32 v[40:41], v[18:19], v[68:69], v[40:41] op_sel:[0,1,0] op_sel_hi:[1,1,1]
	v_pk_fma_f32 v[38:39], v[20:21], v[70:71], v[38:39] op_sel_hi:[1,0,1]
	v_pk_fma_f32 v[40:41], v[20:21], v[70:71], v[40:41] op_sel:[0,1,0] op_sel_hi:[1,1,1]
	v_mul_f32_e32 v50, v76, v51
	v_add_f32_dpp v38, v38, v38 row_ror:8 row_mask:0xf bank_mask:0x3 bound_ctrl:1
	v_add_f32_dpp v39, v39, v39 row_ror:8 row_mask:0xf bank_mask:0x3 bound_ctrl:1
	v_add_f32_dpp v38, v40, v40 row_ror:8 row_mask:0xf bank_mask:0xc bound_ctrl:1
	v_add_f32_dpp v39, v41, v41 row_ror:8 row_mask:0xf bank_mask:0xc bound_ctrl:1
	ds_read_b128 v[80:83], v2 offset:3328
	v_add_f32_dpp v38, v38, v38 row_half_mirror row_mask:0xf bank_mask:0x5 bound_ctrl:1
	v_add_f32_dpp v38, v39, v39 row_half_mirror row_mask:0xf bank_mask:0xa bound_ctrl:1
	ds_read_b128 v[84:87], v2 offset:3584
	ds_read_b128 v[88:91], v2 offset:3840
	v_add_f32_dpp v38, v38, v38 quad_perm:[1,0,3,2] row_mask:0xf bank_mask:0xf bound_ctrl:1
	ds_read_b128 v[92:95], v2 offset:4096
	ds_read_b64 v[96:97], v3 offset:13312
	v_add_f32_dpp v38, v38, v38 quad_perm:[2,3,0,1] row_mask:0xf bank_mask:0xf bound_ctrl:1
	ds_read_b128 v[100:103], v1 offset:14640
	v_cmp_gt_f32_e32 vcc, 0x2b8cbccc, v50
	v_fmac_f32_dpp v72, -v38, v50 row_newbcast:0 row_mask:0xf bank_mask:0xf bound_ctrl:1
	v_fmac_f32_dpp v73, -v38, v50 row_newbcast:4 row_mask:0xf bank_mask:0xf bound_ctrl:1
	v_pk_mul_f32 v[44:45], v[72:73], v[76:77] op_sel:[0,1] op_sel_hi:[1,1]
	v_pk_mul_f32 v[48:49], v[44:45], v[78:79] op_sel_hi:[1,0]
	v_rcp_f32_e32 v52, v50
	s_add_u32 s14, s14, 0x1000
	s_addc_u32 s15, s15, 0
	v_fmac_f32_dpp v48, v38, v50 row_newbcast:8 row_mask:0xf bank_mask:0xf bound_ctrl:1
	v_fmac_f32_dpp v49, v38, v50 row_newbcast:12 row_mask:0xf bank_mask:0xf bound_ctrl:1
	s_cbranch_vccnz .Lgd2_rare0_2
.Lgd2_back0_2:
	v_cvt_pk_bf16_f32 v54, v48, v49
	v_pk_mul_f32 v[46:47], v[44:45], v[52:53] op_sel_hi:[1,0]
	v_pk_fma_f32 v[6:7], v[56:57], v[46:47], v[6:7] op_sel_hi:[0,1,1]
	v_pk_fma_f32 v[8:9], v[58:59], v[46:47], v[8:9] op_sel_hi:[0,1,1]
	v_pk_fma_f32 v[10:11], v[60:61], v[46:47], v[10:11] op_sel_hi:[0,1,1]
	v_pk_fma_f32 v[12:13], v[62:63], v[46:47], v[12:13] op_sel_hi:[0,1,1]
	v_pk_fma_f32 v[14:15], v[64:65], v[46:47], v[14:15] op_sel_hi:[0,1,1]
	v_pk_fma_f32 v[16:17], v[66:67], v[46:47], v[16:17] op_sel_hi:[0,1,1]
	v_pk_fma_f32 v[18:19], v[68:69], v[46:47], v[18:19] op_sel_hi:[0,1,1]
	v_pk_fma_f32 v[20:21], v[70:71], v[46:47], v[20:21] op_sel_hi:[0,1,1]
	global_store_dword v154, v54, s[14:15] offset:-4096
	s_waitcnt lgkmcnt(0)
	v_pk_mul_f32 v[38:39], v[6:7], v[80:81] op_sel_hi:[1,0]
	v_pk_mul_f32 v[40:41], v[6:7], v[80:81] op_sel:[0,1] op_sel_hi:[1,1]
	v_pk_fma_f32 v[38:39], v[8:9], v[82:83], v[38:39] op_sel_hi:[1,0,1]
	v_pk_fma_f32 v[40:41], v[8:9], v[82:83], v[40:41] op_sel:[0,1,0] op_sel_hi:[1,1,1]
	v_pk_fma_f32 v[38:39], v[10:11], v[84:85], v[38:39] op_sel_hi:[1,0,1]
	v_pk_fma_f32 v[40:41], v[10:11], v[84:85], v[40:41] op_sel:[0,1,0] op_sel_hi:[1,1,1]
	v_pk_fma_f32 v[38:39], v[12:13], v[86:87], v[38:39] op_sel_hi:[1,0,1]
	v_pk_fma_f32 v[40:41], v[12:13], v[86:87], v[40:41] op_sel:[0,1,0] op_sel_hi:[1,1,1]
	v_pk_fma_f32 v[38:39], v[14:15], v[88:89], v[38:39] op_sel_hi:[1,0,1]
	v_pk_fma_f32 v[40:41], v[14:15], v[88:89], v[40:41] op_sel:[0,1,0] op_sel_hi:[1,1,1]
	v_pk_fma_f32 v[38:39], v[16:17], v[90:91], v[38:39] op_sel_hi:[1,0,1]
	v_pk_fma_f32 v[40:41], v[16:17], v[90:91], v[40:41] op_sel:[0,1,0] op_sel_hi:[1,1,1]
	v_pk_fma_f32 v[38:39], v[18:19], v[92:93], v[38:39] op_sel_hi:[1,0,1]
	v_pk_fma_f32 v[40:41], v[18:19], v[92:93], v[40:41] op_sel:[0,1,0] op_sel_hi:[1,1,1]
	v_pk_fma_f32 v[38:39], v[20:21], v[94:95], v[38:39] op_sel_hi:[1,0,1]
	v_pk_fma_f32 v[40:41], v[20:21], v[94:95], v[40:41] op_sel:[0,1,0] op_sel_hi:[1,1,1]
	v_mul_f32_e32 v51, v100, v50
	v_add_f32_dpp v38, v38, v38 row_ror:8 row_mask:0xf bank_mask:0x3 bound_ctrl:1
	v_add_f32_dpp v39, v39, v39 row_ror:8 row_mask:0xf bank_mask:0x3 bound_ctrl:1
	v_add_f32_dpp v38, v40, v40 row_ror:8 row_mask:0xf bank_mask:0xc bound_ctrl:1
	v_add_f32_dpp v39, v41, v41 row_ror:8 row_mask:0xf bank_mask:0xc bound_ctrl:1
	ds_read_b128 v[56:59], v2 offset:4352
	v_add_f32_dpp v38, v38, v38 row_half_mirror row_mask:0xf bank_mask:0x5 bound_ctrl:1
	v_add_f32_dpp v38, v39, v39 row_half_mirror row_mask:0xf bank_mask:0xa bound_ctrl:1
	ds_read_b128 v[60:63], v2 offset:4608
	ds_read_b128 v[64:67], v2 offset:4864
	v_add_f32_dpp v38, v38, v38 quad_perm:[1,0,3,2] row_mask:0xf bank_mask:0xf bound_ctrl:1
	ds_read_b128 v[68:71], v2 offset:5120
	ds_read_b64 v[72:73], v3 offset:13568
	v_add_f32_dpp v38, v38, v38 quad_perm:[2,3,0,1] row_mask:0xf bank_mask:0xf bound_ctrl:1
	ds_read_b128 v[76:79], v1 offset:14656
	v_cmp_gt_f32_e32 vcc, 0x2b8cbccc, v51
	v_fmac_f32_dpp v96, -v38, v51 row_newbcast:0 row_mask:0xf bank_mask:0xf bound_ctrl:1
	v_fmac_f32_dpp v97, -v38, v51 row_newbcast:4 row_mask:0xf bank_mask:0xf bound_ctrl:1
	v_pk_mul_f32 v[44:45], v[96:97], v[100:101] op_sel:[0,1] op_sel_hi:[1,1]
	v_pk_mul_f32 v[48:49], v[44:45], v[102:103] op_sel_hi:[1,0]
	v_rcp_f32_e32 v52, v51
	s_add_u32 s14, s14, 0x1000
	s_addc_u32 s15, s15, 0
	v_fmac_f32_dpp v48, v38, v51 row_newbcast:8 row_mask:0xf bank_mask:0xf bound_ctrl:1
	v_fmac_f32_dpp v49, v38, v51 row_newbcast:12 row_mask:0xf bank_mask:0xf bound_ctrl:1
	s_cbranch_vccnz .Lgd2_rare0_3
.Lgd2_back0_3:
	v_cvt_pk_bf16_f32 v54, v48, v49
	v_pk_mul_f32 v[46:47], v[44:45], v[52:53] op_sel_hi:[1,0]
	v_pk_fma_f32 v[6:7], v[80:81], v[46:47], v[6:7] op_sel_hi:[0,1,1]
	v_pk_fma_f32 v[8:9], v[82:83], v[46:47], v[8:9] op_sel_hi:[0,1,1]
	v_pk_fma_f32 v[10:11], v[84:85], v[46:47], v[10:11] op_sel_hi:[0,1,1]
	v_pk_fma_f32 v[12:13], v[86:87], v[46:47], v[12:13] op_sel_hi:[0,1,1]
	v_pk_fma_f32 v[14:15], v[88:89], v[46:47], v[14:15] op_sel_hi:[0,1,1]
	v_pk_fma_f32 v[16:17], v[90:91], v[46:47], v[16:17] op_sel_hi:[0,1,1]
	v_pk_fma_f32 v[18:19], v[92:93], v[46:47], v[18:19] op_sel_hi:[0,1,1]
	v_pk_fma_f32 v[20:21], v[94:95], v[46:47], v[20:21] op_sel_hi:[0,1,1]
	global_store_dword v154, v54, s[14:15] offset:-4096
	s_waitcnt lgkmcnt(0)
	v_pk_mul_f32 v[38:39], v[6:7], v[56:57] op_sel_hi:[1,0]
	v_pk_mul_f32 v[40:41], v[6:7], v[56:57] op_sel:[0,1] op_sel_hi:[1,1]
	v_pk_fma_f32 v[38:39], v[8:9], v[58:59], v[38:39] op_sel_hi:[1,0,1]
	v_pk_fma_f32 v[40:41], v[8:9], v[58:59], v[40:41] op_sel:[0,1,0] op_sel_hi:[1,1,1]
	v_pk_fma_f32 v[38:39], v[10:11], v[60:61], v[38:39] op_sel_hi:[1,0,1]
	v_pk_fma_f32 v[40:41], v[10:11], v[60:61], v[40:41] op_sel:[0,1,0] op_sel_hi:[1,1,1]
	v_pk_fma_f32 v[38:39], v[12:13], v[62:63], v[38:39] op_sel_hi:[1,0,1]
	v_pk_fma_f32 v[40:41], v[12:13], v[62:63], v[40:41] op_sel:[0,1,0] op_sel_hi:[1,1,1]
	v_pk_fma_f32 v[38:39], v[14:15], v[64:65], v[38:39] op_sel_hi:[1,0,1]
	v_pk_fma_f32 v[40:41], v[14:15], v[64:65], v[40:41] op_sel:[0,1,0] op_sel_hi:[1,1,1]
	v_pk_fma_f32 v[38:39], v[16:17], v[66:67], v[38:39] op_sel_hi:[1,0,1]
	v_pk_fma_f32 v[40:41], v[16:17], v[66:67], v[40:41] op_sel:[0,1,0] op_sel_hi:[1,1,1]
	v_pk_fma_f32 v[38:39], v[18:19], v[68:69], v[38:39] op_sel_hi:[1,0,1]
	v_pk_fma_f32 v[40:41], v[18:19], v[68:69], v[40:41] op_sel:[0,1,0] op_sel_hi:[1,1,1]
	v_pk_fma_f32 v[38:39], v[20:21], v[70:71], v[38:39] op_sel_hi:[1,0,1]
	v_pk_fma_f32 v[40:41], v[20:21], v[70:71], v[40:41] op_sel:[0,1,0] op_sel_hi:[1,1,1]
	v_mul_f32_e32 v50, v76, v51
	v_add_f32_dpp v38, v38, v38 row_ror:8 row_mask:0xf bank_mask:0x3 bound_ctrl:1
	v_add_f32_dpp v39, v39, v39 row_ror:8 row_mask:0xf bank_mask:0x3 bound_ctrl:1
	v_add_f32_dpp v38, v40, v40 row_ror:8 row_mask:0xf bank_mask:0xc bound_ctrl:1
	v_add_f32_dpp v39, v41, v41 row_ror:8 row_mask:0xf bank_mask:0xc bound_ctrl:1
	ds_read_b128 v[80:83], v2 offset:5376
	v_add_f32_dpp v38, v38, v38 row_half_mirror row_mask:0xf bank_mask:0x5 bound_ctrl:1
	v_add_f32_dpp v38, v39, v39 row_half_mirror row_mask:0xf bank_mask:0xa bound_ctrl:1
	ds_read_b128 v[84:87], v2 offset:5632
	ds_read_b128 v[88:91], v2 offset:5888
	v_add_f32_dpp v38, v38, v38 quad_perm:[1,0,3,2] row_mask:0xf bank_mask:0xf bound_ctrl:1
	ds_read_b128 v[92:95], v2 offset:6144
	ds_read_b64 v[96:97], v3 offset:13824
	v_add_f32_dpp v38, v38, v38 quad_perm:[2,3,0,1] row_mask:0xf bank_mask:0xf bound_ctrl:1
	ds_read_b128 v[100:103], v1 offset:14672
	v_cmp_gt_f32_e32 vcc, 0x2b8cbccc, v50
	v_fmac_f32_dpp v72, -v38, v50 row_newbcast:0 row_mask:0xf bank_mask:0xf bound_ctrl:1
	v_fmac_f32_dpp v73, -v38, v50 row_newbcast:4 row_mask:0xf bank_mask:0xf bound_ctrl:1
	v_pk_mul_f32 v[44:45], v[72:73], v[76:77] op_sel:[0,1] op_sel_hi:[1,1]
	v_pk_mul_f32 v[48:49], v[44:45], v[78:79] op_sel_hi:[1,0]
	v_rcp_f32_e32 v52, v50
	s_add_u32 s14, s14, 0x1000
	s_addc_u32 s15, s15, 0
	v_fmac_f32_dpp v48, v38, v50 row_newbcast:8 row_mask:0xf bank_mask:0xf bound_ctrl:1
	v_fmac_f32_dpp v49, v38, v50 row_newbcast:12 row_mask:0xf bank_mask:0xf bound_ctrl:1
	s_cbranch_vccnz .Lgd2_rare0_4
.Lgd2_back0_4:
	v_cvt_pk_bf16_f32 v54, v48, v49
	v_pk_mul_f32 v[46:47], v[44:45], v[52:53] op_sel_hi:[1,0]
	v_pk_fma_f32 v[6:7], v[56:57], v[46:47], v[6:7] op_sel_hi:[0,1,1]
	v_pk_fma_f32 v[8:9], v[58:59], v[46:47], v[8:9] op_sel_hi:[0,1,1]
	v_pk_fma_f32 v[10:11], v[60:61], v[46:47], v[10:11] op_sel_hi:[0,1,1]
	v_pk_fma_f32 v[12:13], v[62:63], v[46:47], v[12:13] op_sel_hi:[0,1,1]
	v_pk_fma_f32 v[14:15], v[64:65], v[46:47], v[14:15] op_sel_hi:[0,1,1]
	v_pk_fma_f32 v[16:17], v[66:67], v[46:47], v[16:17] op_sel_hi:[0,1,1]
	v_pk_fma_f32 v[18:19], v[68:69], v[46:47], v[18:19] op_sel_hi:[0,1,1]
	v_pk_fma_f32 v[20:21], v[70:71], v[46:47], v[20:21] op_sel_hi:[0,1,1]
	global_store_dword v154, v54, s[14:15] offset:-4096
	s_waitcnt lgkmcnt(0)
	v_pk_mul_f32 v[38:39], v[6:7], v[80:81] op_sel_hi:[1,0]
	v_pk_mul_f32 v[40:41], v[6:7], v[80:81] op_sel:[0,1] op_sel_hi:[1,1]
	v_pk_fma_f32 v[38:39], v[8:9], v[82:83], v[38:39] op_sel_hi:[1,0,1]
	v_pk_fma_f32 v[40:41], v[8:9], v[82:83], v[40:41] op_sel:[0,1,0] op_sel_hi:[1,1,1]
	v_pk_fma_f32 v[38:39], v[10:11], v[84:85], v[38:39] op_sel_hi:[1,0,1]
	v_pk_fma_f32 v[40:41], v[10:11], v[84:85], v[40:41] op_sel:[0,1,0] op_sel_hi:[1,1,1]
	v_pk_fma_f32 v[38:39], v[12:13], v[86:87], v[38:39] op_sel_hi:[1,0,1]
	v_pk_fma_f32 v[40:41], v[12:13], v[86:87], v[40:41] op_sel:[0,1,0] op_sel_hi:[1,1,1]
	v_pk_fma_f32 v[38:39], v[14:15], v[88:89], v[38:39] op_sel_hi:[1,0,1]
	v_pk_fma_f32 v[40:41], v[14:15], v[88:89], v[40:41] op_sel:[0,1,0] op_sel_hi:[1,1,1]
	v_pk_fma_f32 v[38:39], v[16:17], v[90:91], v[38:39] op_sel_hi:[1,0,1]
	v_pk_fma_f32 v[40:41], v[16:17], v[90:91], v[40:41] op_sel:[0,1,0] op_sel_hi:[1,1,1]
	v_pk_fma_f32 v[38:39], v[18:19], v[92:93], v[38:39] op_sel_hi:[1,0,1]
	v_pk_fma_f32 v[40:41], v[18:19], v[92:93], v[40:41] op_sel:[0,1,0] op_sel_hi:[1,1,1]
	v_pk_fma_f32 v[38:39], v[20:21], v[94:95], v[38:39] op_sel_hi:[1,0,1]
	v_pk_fma_f32 v[40:41], v[20:21], v[94:95], v[40:41] op_sel:[0,1,0] op_sel_hi:[1,1,1]
	v_mul_f32_e32 v51, v100, v50
	v_add_f32_dpp v38, v38, v38 row_ror:8 row_mask:0xf bank_mask:0x3 bound_ctrl:1
	v_add_f32_dpp v39, v39, v39 row_ror:8 row_mask:0xf bank_mask:0x3 bound_ctrl:1
	v_add_f32_dpp v38, v40, v40 row_ror:8 row_mask:0xf bank_mask:0xc bound_ctrl:1
	v_add_f32_dpp v39, v41, v41 row_ror:8 row_mask:0xf bank_mask:0xc bound_ctrl:1
	ds_read_b128 v[56:59], v2 offset:6400
	v_add_f32_dpp v38, v38, v38 row_half_mirror row_mask:0xf bank_mask:0x5 bound_ctrl:1
	v_add_f32_dpp v38, v39, v39 row_half_mirror row_mask:0xf bank_mask:0xa bound_ctrl:1
	ds_read_b128 v[60:63], v2 offset:6656
	ds_read_b128 v[64:67], v2 offset:6912
	v_add_f32_dpp v38, v38, v38 quad_perm:[1,0,3,2] row_mask:0xf bank_mask:0xf bound_ctrl:1
	ds_read_b128 v[68:71], v2 offset:7168
	ds_read_b64 v[72:73], v3 offset:14080
	v_add_f32_dpp v38, v38, v38 quad_perm:[2,3,0,1] row_mask:0xf bank_mask:0xf bound_ctrl:1
	ds_read_b128 v[76:79], v1 offset:14688
	v_cmp_gt_f32_e32 vcc, 0x2b8cbccc, v51
	v_fmac_f32_dpp v96, -v38, v51 row_newbcast:0 row_mask:0xf bank_mask:0xf bound_ctrl:1
	v_fmac_f32_dpp v97, -v38, v51 row_newbcast:4 row_mask:0xf bank_mask:0xf bound_ctrl:1
	v_pk_mul_f32 v[44:45], v[96:97], v[100:101] op_sel:[0,1] op_sel_hi:[1,1]
	v_pk_mul_f32 v[48:49], v[44:45], v[102:103] op_sel_hi:[1,0]
	v_rcp_f32_e32 v52, v51
	s_add_u32 s14, s14, 0x1000
	s_addc_u32 s15, s15, 0
	v_fmac_f32_dpp v48, v38, v51 row_newbcast:8 row_mask:0xf bank_mask:0xf bound_ctrl:1
	v_fmac_f32_dpp v49, v38, v51 row_newbcast:12 row_mask:0xf bank_mask:0xf bound_ctrl:1
	s_cbranch_vccnz .Lgd2_rare0_5
.Lgd2_back0_5:
	v_cvt_pk_bf16_f32 v54, v48, v49
	v_pk_mul_f32 v[46:47], v[44:45], v[52:53] op_sel_hi:[1,0]
	v_pk_fma_f32 v[6:7], v[80:81], v[46:47], v[6:7] op_sel_hi:[0,1,1]
	v_pk_fma_f32 v[8:9], v[82:83], v[46:47], v[8:9] op_sel_hi:[0,1,1]
	v_pk_fma_f32 v[10:11], v[84:85], v[46:47], v[10:11] op_sel_hi:[0,1,1]
	v_pk_fma_f32 v[12:13], v[86:87], v[46:47], v[12:13] op_sel_hi:[0,1,1]
	v_pk_fma_f32 v[14:15], v[88:89], v[46:47], v[14:15] op_sel_hi:[0,1,1]
	v_pk_fma_f32 v[16:17], v[90:91], v[46:47], v[16:17] op_sel_hi:[0,1,1]
	v_pk_fma_f32 v[18:19], v[92:93], v[46:47], v[18:19] op_sel_hi:[0,1,1]
	v_pk_fma_f32 v[20:21], v[94:95], v[46:47], v[20:21] op_sel_hi:[0,1,1]
	global_store_dword v154, v54, s[14:15] offset:-4096
	s_waitcnt lgkmcnt(0)
	v_pk_mul_f32 v[38:39], v[6:7], v[56:57] op_sel_hi:[1,0]
	v_pk_mul_f32 v[40:41], v[6:7], v[56:57] op_sel:[0,1] op_sel_hi:[1,1]
	v_pk_fma_f32 v[38:39], v[8:9], v[58:59], v[38:39] op_sel_hi:[1,0,1]
	v_pk_fma_f32 v[40:41], v[8:9], v[58:59], v[40:41] op_sel:[0,1,0] op_sel_hi:[1,1,1]
	v_pk_fma_f32 v[38:39], v[10:11], v[60:61], v[38:39] op_sel_hi:[1,0,1]
	v_pk_fma_f32 v[40:41], v[10:11], v[60:61], v[40:41] op_sel:[0,1,0] op_sel_hi:[1,1,1]
	v_pk_fma_f32 v[38:39], v[12:13], v[62:63], v[38:39] op_sel_hi:[1,0,1]
	v_pk_fma_f32 v[40:41], v[12:13], v[62:63], v[40:41] op_sel:[0,1,0] op_sel_hi:[1,1,1]
	v_pk_fma_f32 v[38:39], v[14:15], v[64:65], v[38:39] op_sel_hi:[1,0,1]
	v_pk_fma_f32 v[40:41], v[14:15], v[64:65], v[40:41] op_sel:[0,1,0] op_sel_hi:[1,1,1]
	v_pk_fma_f32 v[38:39], v[16:17], v[66:67], v[38:39] op_sel_hi:[1,0,1]
	v_pk_fma_f32 v[40:41], v[16:17], v[66:67], v[40:41] op_sel:[0,1,0] op_sel_hi:[1,1,1]
	v_pk_fma_f32 v[38:39], v[18:19], v[68:69], v[38:39] op_sel_hi:[1,0,1]
	v_pk_fma_f32 v[40:41], v[18:19], v[68:69], v[40:41] op_sel:[0,1,0] op_sel_hi:[1,1,1]
	v_pk_fma_f32 v[38:39], v[20:21], v[70:71], v[38:39] op_sel_hi:[1,0,1]
	v_pk_fma_f32 v[40:41], v[20:21], v[70:71], v[40:41] op_sel:[0,1,0] op_sel_hi:[1,1,1]
	v_mul_f32_e32 v50, v76, v51
	v_add_f32_dpp v38, v38, v38 row_ror:8 row_mask:0xf bank_mask:0x3 bound_ctrl:1
	v_add_f32_dpp v39, v39, v39 row_ror:8 row_mask:0xf bank_mask:0x3 bound_ctrl:1
	v_add_f32_dpp v38, v40, v40 row_ror:8 row_mask:0xf bank_mask:0xc bound_ctrl:1
	v_add_f32_dpp v39, v41, v41 row_ror:8 row_mask:0xf bank_mask:0xc bound_ctrl:1
	ds_read_b128 v[80:83], v2 offset:7424
	v_add_f32_dpp v38, v38, v38 row_half_mirror row_mask:0xf bank_mask:0x5 bound_ctrl:1
	v_add_f32_dpp v38, v39, v39 row_half_mirror row_mask:0xf bank_mask:0xa bound_ctrl:1
	ds_read_b128 v[84:87], v2 offset:7680
	ds_read_b128 v[88:91], v2 offset:7936
	v_add_f32_dpp v38, v38, v38 quad_perm:[1,0,3,2] row_mask:0xf bank_mask:0xf bound_ctrl:1
	ds_read_b128 v[92:95], v2 offset:8192
	ds_read_b64 v[96:97], v3 offset:14336
	v_add_f32_dpp v38, v38, v38 quad_perm:[2,3,0,1] row_mask:0xf bank_mask:0xf bound_ctrl:1
	ds_read_b128 v[100:103], v1 offset:14704
	v_cmp_gt_f32_e32 vcc, 0x2b8cbccc, v50
	v_fmac_f32_dpp v72, -v38, v50 row_newbcast:0 row_mask:0xf bank_mask:0xf bound_ctrl:1
	v_fmac_f32_dpp v73, -v38, v50 row_newbcast:4 row_mask:0xf bank_mask:0xf bound_ctrl:1
	v_pk_mul_f32 v[44:45], v[72:73], v[76:77] op_sel:[0,1] op_sel_hi:[1,1]
	v_pk_mul_f32 v[48:49], v[44:45], v[78:79] op_sel_hi:[1,0]
	v_rcp_f32_e32 v52, v50
	s_add_u32 s14, s14, 0x1000
	s_addc_u32 s15, s15, 0
	v_fmac_f32_dpp v48, v38, v50 row_newbcast:8 row_mask:0xf bank_mask:0xf bound_ctrl:1
	v_fmac_f32_dpp v49, v38, v50 row_newbcast:12 row_mask:0xf bank_mask:0xf bound_ctrl:1
	s_cbranch_vccnz .Lgd2_rare0_6
.Lgd2_back0_6:
	v_cvt_pk_bf16_f32 v54, v48, v49
	v_pk_mul_f32 v[46:47], v[44:45], v[52:53] op_sel_hi:[1,0]
	v_pk_fma_f32 v[6:7], v[56:57], v[46:47], v[6:7] op_sel_hi:[0,1,1]
	v_pk_fma_f32 v[8:9], v[58:59], v[46:47], v[8:9] op_sel_hi:[0,1,1]
	v_pk_fma_f32 v[10:11], v[60:61], v[46:47], v[10:11] op_sel_hi:[0,1,1]
	v_pk_fma_f32 v[12:13], v[62:63], v[46:47], v[12:13] op_sel_hi:[0,1,1]
	v_pk_fma_f32 v[14:15], v[64:65], v[46:47], v[14:15] op_sel_hi:[0,1,1]
	v_pk_fma_f32 v[16:17], v[66:67], v[46:47], v[16:17] op_sel_hi:[0,1,1]
	v_pk_fma_f32 v[18:19], v[68:69], v[46:47], v[18:19] op_sel_hi:[0,1,1]
	v_pk_fma_f32 v[20:21], v[70:71], v[46:47], v[20:21] op_sel_hi:[0,1,1]
	global_store_dword v154, v54, s[14:15] offset:-4096
	s_waitcnt lgkmcnt(0)
	v_pk_mul_f32 v[38:39], v[6:7], v[80:81] op_sel_hi:[1,0]
	v_pk_mul_f32 v[40:41], v[6:7], v[80:81] op_sel:[0,1] op_sel_hi:[1,1]
	v_pk_fma_f32 v[38:39], v[8:9], v[82:83], v[38:39] op_sel_hi:[1,0,1]
	v_pk_fma_f32 v[40:41], v[8:9], v[82:83], v[40:41] op_sel:[0,1,0] op_sel_hi:[1,1,1]
	v_pk_fma_f32 v[38:39], v[10:11], v[84:85], v[38:39] op_sel_hi:[1,0,1]
	v_pk_fma_f32 v[40:41], v[10:11], v[84:85], v[40:41] op_sel:[0,1,0] op_sel_hi:[1,1,1]
	v_pk_fma_f32 v[38:39], v[12:13], v[86:87], v[38:39] op_sel_hi:[1,0,1]
	v_pk_fma_f32 v[40:41], v[12:13], v[86:87], v[40:41] op_sel:[0,1,0] op_sel_hi:[1,1,1]
	v_pk_fma_f32 v[38:39], v[14:15], v[88:89], v[38:39] op_sel_hi:[1,0,1]
	v_pk_fma_f32 v[40:41], v[14:15], v[88:89], v[40:41] op_sel:[0,1,0] op_sel_hi:[1,1,1]
	v_pk_fma_f32 v[38:39], v[16:17], v[90:91], v[38:39] op_sel_hi:[1,0,1]
	v_pk_fma_f32 v[40:41], v[16:17], v[90:91], v[40:41] op_sel:[0,1,0] op_sel_hi:[1,1,1]
	v_pk_fma_f32 v[38:39], v[18:19], v[92:93], v[38:39] op_sel_hi:[1,0,1]
	v_pk_fma_f32 v[40:41], v[18:19], v[92:93], v[40:41] op_sel:[0,1,0] op_sel_hi:[1,1,1]
	v_pk_fma_f32 v[38:39], v[20:21], v[94:95], v[38:39] op_sel_hi:[1,0,1]
	v_pk_fma_f32 v[40:41], v[20:21], v[94:95], v[40:41] op_sel:[0,1,0] op_sel_hi:[1,1,1]
	v_mul_f32_e32 v51, v100, v50
	v_add_f32_dpp v38, v38, v38 row_ror:8 row_mask:0xf bank_mask:0x3 bound_ctrl:1
	v_add_f32_dpp v39, v39, v39 row_ror:8 row_mask:0xf bank_mask:0x3 bound_ctrl:1
	v_add_f32_dpp v38, v40, v40 row_ror:8 row_mask:0xf bank_mask:0xc bound_ctrl:1
	v_add_f32_dpp v39, v41, v41 row_ror:8 row_mask:0xf bank_mask:0xc bound_ctrl:1
	ds_read_b128 v[56:59], v2 offset:16640
	v_add_f32_dpp v38, v38, v38 row_half_mirror row_mask:0xf bank_mask:0x5 bound_ctrl:1
	v_add_f32_dpp v38, v39, v39 row_half_mirror row_mask:0xf bank_mask:0xa bound_ctrl:1
	ds_read_b128 v[60:63], v2 offset:16896
	ds_read_b128 v[64:67], v2 offset:17152
	v_add_f32_dpp v38, v38, v38 quad_perm:[1,0,3,2] row_mask:0xf bank_mask:0xf bound_ctrl:1
	ds_read_b128 v[68:71], v2 offset:17408
	ds_read_b64 v[72:73], v3 offset:28928
	v_add_f32_dpp v38, v38, v38 quad_perm:[2,3,0,1] row_mask:0xf bank_mask:0xf bound_ctrl:1
	ds_read_b128 v[76:79], v1 offset:30976
	v_cmp_gt_f32_e32 vcc, 0x2b8cbccc, v51
	v_fmac_f32_dpp v96, -v38, v51 row_newbcast:0 row_mask:0xf bank_mask:0xf bound_ctrl:1
	v_fmac_f32_dpp v97, -v38, v51 row_newbcast:4 row_mask:0xf bank_mask:0xf bound_ctrl:1
	v_pk_mul_f32 v[44:45], v[96:97], v[100:101] op_sel:[0,1] op_sel_hi:[1,1]
	v_pk_mul_f32 v[48:49], v[44:45], v[102:103] op_sel_hi:[1,0]
	v_rcp_f32_e32 v52, v51
	s_add_u32 s14, s14, 0x1000
	s_addc_u32 s15, s15, 0
	v_fmac_f32_dpp v48, v38, v51 row_newbcast:8 row_mask:0xf bank_mask:0xf bound_ctrl:1
	v_fmac_f32_dpp v49, v38, v51 row_newbcast:12 row_mask:0xf bank_mask:0xf bound_ctrl:1
	s_cbranch_vccnz .Lgd2_rare0_7
.Lgd2_back0_7:
	v_cvt_pk_bf16_f32 v54, v48, v49
	v_pk_mul_f32 v[46:47], v[44:45], v[52:53] op_sel_hi:[1,0]
	v_pk_fma_f32 v[6:7], v[80:81], v[46:47], v[6:7] op_sel_hi:[0,1,1]
	v_pk_fma_f32 v[8:9], v[82:83], v[46:47], v[8:9] op_sel_hi:[0,1,1]
	v_pk_fma_f32 v[10:11], v[84:85], v[46:47], v[10:11] op_sel_hi:[0,1,1]
	v_pk_fma_f32 v[12:13], v[86:87], v[46:47], v[12:13] op_sel_hi:[0,1,1]
	v_pk_fma_f32 v[14:15], v[88:89], v[46:47], v[14:15] op_sel_hi:[0,1,1]
	v_pk_fma_f32 v[16:17], v[90:91], v[46:47], v[16:17] op_sel_hi:[0,1,1]
	v_pk_fma_f32 v[18:19], v[92:93], v[46:47], v[18:19] op_sel_hi:[0,1,1]
	v_pk_fma_f32 v[20:21], v[94:95], v[46:47], v[20:21] op_sel_hi:[0,1,1]
	global_store_dword v154, v54, s[14:15] offset:-4096
	s_waitcnt vmcnt(8)
	v_lshlrev_b32_e32 v116, 16, v108
	v_lshlrev_b32_e32 v117, 16, v109
	v_and_b32_e32 v118, s17, v108
	v_and_b32_e32 v119, s17, v109
	v_lshlrev_b32_e32 v120, 16, v110
	v_and_b32_e32 v121, s17, v110
	v_lshlrev_b32_e32 v122, 16, v111
	v_and_b32_e32 v123, s17, v111
	v_lshlrev_b32_e32 v124, 16, v112
	v_and_b32_e32 v125, s17, v112
	ds_write_b128 v32, v[116:119] offset:33024
	ds_write_b64 v33, v[120:121] offset:33024
	ds_write_b64 v34, v[122:123] offset:33024
	ds_write_b64 v34, v[124:125] offset:33152
	ds_write_b32 v35, v113 offset:33024
	s_add_i32 s16, s16, 8
	s_waitcnt lgkmcnt(0)
	s_barrier
	s_cmpk_lt_u32 s16, 0x800
	s_cbranch_scc0 .Lgd2_done
	global_load_dword v108, v36, s[8:9]
	global_load_dword v109, v36, s[8:9] offset:-2048
	global_load_dword v111, v104, s[8:9] offset:2048
	global_load_dword v110, v37, s[10:11]
	global_load_dword v112, v105, s[10:11]
	global_load_dword v113, v106, s[12:13]
	s_add_u32 s8, s8, 0xc000
	s_addc_u32 s9, s9, 0
	s_add_u32 s10, s10, 0x20000
	s_addc_u32 s11, s11, 0
	s_add_u32 s12, s12, 0x400
	s_addc_u32 s13, s13, 0
	s_waitcnt lgkmcnt(0)
	v_pk_mul_f32 v[38:39], v[6:7], v[56:57] op_sel_hi:[1,0]
	v_pk_mul_f32 v[40:41], v[6:7], v[56:57] op_sel:[0,1] op_sel_hi:[1,1]
	v_pk_fma_f32 v[38:39], v[8:9], v[58:59], v[38:39] op_sel_hi:[1,0,1]
	v_pk_fma_f32 v[40:41], v[8:9], v[58:59], v[40:41] op_sel:[0,1,0] op_sel_hi:[1,1,1]
	v_pk_fma_f32 v[38:39], v[10:11], v[60:61], v[38:39] op_sel_hi:[1,0,1]
	v_pk_fma_f32 v[40:41], v[10:11], v[60:61], v[40:41] op_sel:[0,1,0] op_sel_hi:[1,1,1]
	v_pk_fma_f32 v[38:39], v[12:13], v[62:63], v[38:39] op_sel_hi:[1,0,1]
	v_pk_fma_f32 v[40:41], v[12:13], v[62:63], v[40:41] op_sel:[0,1,0] op_sel_hi:[1,1,1]
	v_pk_fma_f32 v[38:39], v[14:15], v[64:65], v[38:39] op_sel_hi:[1,0,1]
	v_pk_fma_f32 v[40:41], v[14:15], v[64:65], v[40:41] op_sel:[0,1,0] op_sel_hi:[1,1,1]
	v_pk_fma_f32 v[38:39], v[16:17], v[66:67], v[38:39] op_sel_hi:[1,0,1]
	v_pk_fma_f32 v[40:41], v[16:17], v[66:67], v[40:41] op_sel:[0,1,0] op_sel_hi:[1,1,1]
	v_pk_fma_f32 v[38:39], v[18:19], v[68:69], v[38:39] op_sel_hi:[1,0,1]
	v_pk_fma_f32 v[40:41], v[18:19], v[68:69], v[40:41] op_sel:[0,1,0] op_sel_hi:[1,1,1]
	v_pk_fma_f32 v[38:39], v[20:21], v[70:71], v[38:39] op_sel_hi:[1,0,1]
	v_pk_fma_f32 v[40:41], v[20:21], v[70:71], v[40:41] op_sel:[0,1,0] op_sel_hi:[1,1,1]
	v_mul_f32_e32 v50, v76, v51
	v_add_f32_dpp v38, v38, v38 row_ror:8 row_mask:0xf bank_mask:0x3 bound_ctrl:1
	v_add_f32_dpp v39, v39, v39 row_ror:8 row_mask:0xf bank_mask:0x3 bound_ctrl:1
	v_add_f32_dpp v38, v40, v40 row_ror:8 row_mask:0xf bank_mask:0xc bound_ctrl:1
	v_add_f32_dpp v39, v41, v41 row_ror:8 row_mask:0xf bank_mask:0xc bound_ctrl:1
	ds_read_b128 v[80:83], v2 offset:17664
	v_add_f32_dpp v38, v38, v38 row_half_mirror row_mask:0xf bank_mask:0x5 bound_ctrl:1
	v_add_f32_dpp v38, v39, v39 row_half_mirror row_mask:0xf bank_mask:0xa bound_ctrl:1
	ds_read_b128 v[84:87], v2 offset:17920
	ds_read_b128 v[88:91], v2 offset:18176
	v_add_f32_dpp v38, v38, v38 quad_perm:[1,0,3,2] row_mask:0xf bank_mask:0xf bound_ctrl:1
	ds_read_b128 v[92:95], v2 offset:18432
	ds_read_b64 v[96:97], v3 offset:29184
	v_add_f32_dpp v38, v38, v38 quad_perm:[2,3,0,1] row_mask:0xf bank_mask:0xf bound_ctrl:1
	ds_read_b128 v[100:103], v1 offset:30992
	v_cmp_gt_f32_e32 vcc, 0x2b8cbccc, v50
	v_fmac_f32_dpp v72, -v38, v50 row_newbcast:0 row_mask:0xf bank_mask:0xf bound_ctrl:1
	v_fmac_f32_dpp v73, -v38, v50 row_newbcast:4 row_mask:0xf bank_mask:0xf bound_ctrl:1
	v_pk_mul_f32 v[44:45], v[72:73], v[76:77] op_sel:[0,1] op_sel_hi:[1,1]
	v_pk_mul_f32 v[48:49], v[44:45], v[78:79] op_sel_hi:[1,0]
	v_rcp_f32_e32 v52, v50
	s_add_u32 s14, s14, 0x1000
	s_addc_u32 s15, s15, 0
	v_fmac_f32_dpp v48, v38, v50 row_newbcast:8 row_mask:0xf bank_mask:0xf bound_ctrl:1
	v_fmac_f32_dpp v49, v38, v50 row_newbcast:12 row_mask:0xf bank_mask:0xf bound_ctrl:1
	s_cbranch_vccnz .Lgd2_rare1_0
.Lgd2_back1_0:
	v_cvt_pk_bf16_f32 v54, v48, v49
	v_pk_mul_f32 v[46:47], v[44:45], v[52:53] op_sel_hi:[1,0]
	v_pk_fma_f32 v[6:7], v[56:57], v[46:47], v[6:7] op_sel_hi:[0,1,1]
	v_pk_fma_f32 v[8:9], v[58:59], v[46:47], v[8:9] op_sel_hi:[0,1,1]
	v_pk_fma_f32 v[10:11], v[60:61], v[46:47], v[10:11] op_sel_hi:[0,1,1]
	v_pk_fma_f32 v[12:13], v[62:63], v[46:47], v[12:13] op_sel_hi:[0,1,1]
	v_pk_fma_f32 v[14:15], v[64:65], v[46:47], v[14:15] op_sel_hi:[0,1,1]
	v_pk_fma_f32 v[16:17], v[66:67], v[46:47], v[16:17] op_sel_hi:[0,1,1]
	v_pk_fma_f32 v[18:19], v[68:69], v[46:47], v[18:19] op_sel_hi:[0,1,1]
	v_pk_fma_f32 v[20:21], v[70:71], v[46:47], v[20:21] op_sel_hi:[0,1,1]
	global_store_dword v154, v54, s[14:15] offset:-4096
	s_waitcnt lgkmcnt(0)
	v_pk_mul_f32 v[38:39], v[6:7], v[80:81] op_sel_hi:[1,0]
	v_pk_mul_f32 v[40:41], v[6:7], v[80:81] op_sel:[0,1] op_sel_hi:[1,1]
	v_pk_fma_f32 v[38:39], v[8:9], v[82:83], v[38:39] op_sel_hi:[1,0,1]
	v_pk_fma_f32 v[40:41], v[8:9], v[82:83], v[40:41] op_sel:[0,1,0] op_sel_hi:[1,1,1]
	v_pk_fma_f32 v[38:39], v[10:11], v[84:85], v[38:39] op_sel_hi:[1,0,1]
	v_pk_fma_f32 v[40:41], v[10:11], v[84:85], v[40:41] op_sel:[0,1,0] op_sel_hi:[1,1,1]
	v_pk_fma_f32 v[38:39], v[12:13], v[86:87], v[38:39] op_sel_hi:[1,0,1]
	v_pk_fma_f32 v[40:41], v[12:13], v[86:87], v[40:41] op_sel:[0,1,0] op_sel_hi:[1,1,1]
	v_pk_fma_f32 v[38:39], v[14:15], v[88:89], v[38:39] op_sel_hi:[1,0,1]
	v_pk_fma_f32 v[40:41], v[14:15], v[88:89], v[40:41] op_sel:[0,1,0] op_sel_hi:[1,1,1]
	v_pk_fma_f32 v[38:39], v[16:17], v[90:91], v[38:39] op_sel_hi:[1,0,1]
	v_pk_fma_f32 v[40:41], v[16:17], v[90:91], v[40:41] op_sel:[0,1,0] op_sel_hi:[1,1,1]
	v_pk_fma_f32 v[38:39], v[18:19], v[92:93], v[38:39] op_sel_hi:[1,0,1]
	v_pk_fma_f32 v[40:41], v[18:19], v[92:93], v[40:41] op_sel:[0,1,0] op_sel_hi:[1,1,1]
	v_pk_fma_f32 v[38:39], v[20:21], v[94:95], v[38:39] op_sel_hi:[1,0,1]
	v_pk_fma_f32 v[40:41], v[20:21], v[94:95], v[40:41] op_sel:[0,1,0] op_sel_hi:[1,1,1]
	v_mul_f32_e32 v51, v100, v50
	v_add_f32_dpp v38, v38, v38 row_ror:8 row_mask:0xf bank_mask:0x3 bound_ctrl:1
	v_add_f32_dpp v39, v39, v39 row_ror:8 row_mask:0xf bank_mask:0x3 bound_ctrl:1
	v_add_f32_dpp v38, v40, v40 row_ror:8 row_mask:0xf bank_mask:0xc bound_ctrl:1
	v_add_f32_dpp v39, v41, v41 row_ror:8 row_mask:0xf bank_mask:0xc bound_ctrl:1
	ds_read_b128 v[56:59], v2 offset:18688
	v_add_f32_dpp v38, v38, v38 row_half_mirror row_mask:0xf bank_mask:0x5 bound_ctrl:1
	v_add_f32_dpp v38, v39, v39 row_half_mirror row_mask:0xf bank_mask:0xa bound_ctrl:1
	ds_read_b128 v[60:63], v2 offset:18944
	ds_read_b128 v[64:67], v2 offset:19200
	v_add_f32_dpp v38, v38, v38 quad_perm:[1,0,3,2] row_mask:0xf bank_mask:0xf bound_ctrl:1
	ds_read_b128 v[68:71], v2 offset:19456
	ds_read_b64 v[72:73], v3 offset:29440
	v_add_f32_dpp v38, v38, v38 quad_perm:[2,3,0,1] row_mask:0xf bank_mask:0xf bound_ctrl:1
	ds_read_b128 v[76:79], v1 offset:31008
	v_cmp_gt_f32_e32 vcc, 0x2b8cbccc, v51
	v_fmac_f32_dpp v96, -v38, v51 row_newbcast:0 row_mask:0xf bank_mask:0xf bound_ctrl:1
	v_fmac_f32_dpp v97, -v38, v51 row_newbcast:4 row_mask:0xf bank_mask:0xf bound_ctrl:1
	v_pk_mul_f32 v[44:45], v[96:97], v[100:101] op_sel:[0,1] op_sel_hi:[1,1]
	v_pk_mul_f32 v[48:49], v[44:45], v[102:103] op_sel_hi:[1,0]
	v_rcp_f32_e32 v52, v51
	s_add_u32 s14, s14, 0x1000
	s_addc_u32 s15, s15, 0
	v_fmac_f32_dpp v48, v38, v51 row_newbcast:8 row_mask:0xf bank_mask:0xf bound_ctrl:1
	v_fmac_f32_dpp v49, v38, v51 row_newbcast:12 row_mask:0xf bank_mask:0xf bound_ctrl:1
	s_cbranch_vccnz .Lgd2_rare1_1
.Lgd2_back1_1:
	v_cvt_pk_bf16_f32 v54, v48, v49
	v_pk_mul_f32 v[46:47], v[44:45], v[52:53] op_sel_hi:[1,0]
	v_pk_fma_f32 v[6:7], v[80:81], v[46:47], v[6:7] op_sel_hi:[0,1,1]
	v_pk_fma_f32 v[8:9], v[82:83], v[46:47], v[8:9] op_sel_hi:[0,1,1]
	v_pk_fma_f32 v[10:11], v[84:85], v[46:47], v[10:11] op_sel_hi:[0,1,1]
	v_pk_fma_f32 v[12:13], v[86:87], v[46:47], v[12:13] op_sel_hi:[0,1,1]
	v_pk_fma_f32 v[14:15], v[88:89], v[46:47], v[14:15] op_sel_hi:[0,1,1]
	v_pk_fma_f32 v[16:17], v[90:91], v[46:47], v[16:17] op_sel_hi:[0,1,1]
	v_pk_fma_f32 v[18:19], v[92:93], v[46:47], v[18:19] op_sel_hi:[0,1,1]
	v_pk_fma_f32 v[20:21], v[94:95], v[46:47], v[20:21] op_sel_hi:[0,1,1]
	global_store_dword v154, v54, s[14:15] offset:-4096
	s_waitcnt lgkmcnt(0)
	v_pk_mul_f32 v[38:39], v[6:7], v[56:57] op_sel_hi:[1,0]
	v_pk_mul_f32 v[40:41], v[6:7], v[56:57] op_sel:[0,1] op_sel_hi:[1,1]
	v_pk_fma_f32 v[38:39], v[8:9], v[58:59], v[38:39] op_sel_hi:[1,0,1]
	v_pk_fma_f32 v[40:41], v[8:9], v[58:59], v[40:41] op_sel:[0,1,0] op_sel_hi:[1,1,1]
	v_pk_fma_f32 v[38:39], v[10:11], v[60:61], v[38:39] op_sel_hi:[1,0,1]
	v_pk_fma_f32 v[40:41], v[10:11], v[60:61], v[40:41] op_sel:[0,1,0] op_sel_hi:[1,1,1]
	v_pk_fma_f32 v[38:39], v[12:13], v[62:63], v[38:39] op_sel_hi:[1,0,1]
	v_pk_fma_f32 v[40:41], v[12:13], v[62:63], v[40:41] op_sel:[0,1,0] op_sel_hi:[1,1,1]
	v_pk_fma_f32 v[38:39], v[14:15], v[64:65], v[38:39] op_sel_hi:[1,0,1]
	v_pk_fma_f32 v[40:41], v[14:15], v[64:65], v[40:41] op_sel:[0,1,0] op_sel_hi:[1,1,1]
	v_pk_fma_f32 v[38:39], v[16:17], v[66:67], v[38:39] op_sel_hi:[1,0,1]
	v_pk_fma_f32 v[40:41], v[16:17], v[66:67], v[40:41] op_sel:[0,1,0] op_sel_hi:[1,1,1]
	v_pk_fma_f32 v[38:39], v[18:19], v[68:69], v[38:39] op_sel_hi:[1,0,1]
	v_pk_fma_f32 v[40:41], v[18:19], v[68:69], v[40:41] op_sel:[0,1,0] op_sel_hi:[1,1,1]
	v_pk_fma_f32 v[38:39], v[20:21], v[70:71], v[38:39] op_sel_hi:[1,0,1]
	v_pk_fma_f32 v[40:41], v[20:21], v[70:71], v[40:41] op_sel:[0,1,0] op_sel_hi:[1,1,1]
	v_mul_f32_e32 v50, v76, v51
	v_add_f32_dpp v38, v38, v38 row_ror:8 row_mask:0xf bank_mask:0x3 bound_ctrl:1
	v_add_f32_dpp v39, v39, v39 row_ror:8 row_mask:0xf bank_mask:0x3 bound_ctrl:1
	v_add_f32_dpp v38, v40, v40 row_ror:8 row_mask:0xf bank_mask:0xc bound_ctrl:1
	v_add_f32_dpp v39, v41, v41 row_ror:8 row_mask:0xf bank_mask:0xc bound_ctrl:1
	ds_read_b128 v[80:83], v2 offset:19712
	v_add_f32_dpp v38, v38, v38 row_half_mirror row_mask:0xf bank_mask:0x5 bound_ctrl:1
	v_add_f32_dpp v38, v39, v39 row_half_mirror row_mask:0xf bank_mask:0xa bound_ctrl:1
	ds_read_b128 v[84:87], v2 offset:19968
	ds_read_b128 v[88:91], v2 offset:20224
	v_add_f32_dpp v38, v38, v38 quad_perm:[1,0,3,2] row_mask:0xf bank_mask:0xf bound_ctrl:1
	ds_read_b128 v[92:95], v2 offset:20480
	ds_read_b64 v[96:97], v3 offset:29696
	v_add_f32_dpp v38, v38, v38 quad_perm:[2,3,0,1] row_mask:0xf bank_mask:0xf bound_ctrl:1
	ds_read_b128 v[100:103], v1 offset:31024
	v_cmp_gt_f32_e32 vcc, 0x2b8cbccc, v50
	v_fmac_f32_dpp v72, -v38, v50 row_newbcast:0 row_mask:0xf bank_mask:0xf bound_ctrl:1
	v_fmac_f32_dpp v73, -v38, v50 row_newbcast:4 row_mask:0xf bank_mask:0xf bound_ctrl:1
	v_pk_mul_f32 v[44:45], v[72:73], v[76:77] op_sel:[0,1] op_sel_hi:[1,1]
	v_pk_mul_f32 v[48:49], v[44:45], v[78:79] op_sel_hi:[1,0]
	v_rcp_f32_e32 v52, v50
	s_add_u32 s14, s14, 0x1000
	s_addc_u32 s15, s15, 0
	v_fmac_f32_dpp v48, v38, v50 row_newbcast:8 row_mask:0xf bank_mask:0xf bound_ctrl:1
	v_fmac_f32_dpp v49, v38, v50 row_newbcast:12 row_mask:0xf bank_mask:0xf bound_ctrl:1
	s_cbranch_vccnz .Lgd2_rare1_2
.Lgd2_back1_2:
	v_cvt_pk_bf16_f32 v54, v48, v49
	v_pk_mul_f32 v[46:47], v[44:45], v[52:53] op_sel_hi:[1,0]
	v_pk_fma_f32 v[6:7], v[56:57], v[46:47], v[6:7] op_sel_hi:[0,1,1]
	v_pk_fma_f32 v[8:9], v[58:59], v[46:47], v[8:9] op_sel_hi:[0,1,1]
	v_pk_fma_f32 v[10:11], v[60:61], v[46:47], v[10:11] op_sel_hi:[0,1,1]
	v_pk_fma_f32 v[12:13], v[62:63], v[46:47], v[12:13] op_sel_hi:[0,1,1]
	v_pk_fma_f32 v[14:15], v[64:65], v[46:47], v[14:15] op_sel_hi:[0,1,1]
	v_pk_fma_f32 v[16:17], v[66:67], v[46:47], v[16:17] op_sel_hi:[0,1,1]
	v_pk_fma_f32 v[18:19], v[68:69], v[46:47], v[18:19] op_sel_hi:[0,1,1]
	v_pk_fma_f32 v[20:21], v[70:71], v[46:47], v[20:21] op_sel_hi:[0,1,1]
	global_store_dword v154, v54, s[14:15] offset:-4096
	s_waitcnt lgkmcnt(0)
	v_pk_mul_f32 v[38:39], v[6:7], v[80:81] op_sel_hi:[1,0]
	v_pk_mul_f32 v[40:41], v[6:7], v[80:81] op_sel:[0,1] op_sel_hi:[1,1]
	v_pk_fma_f32 v[38:39], v[8:9], v[82:83], v[38:39] op_sel_hi:[1,0,1]
	v_pk_fma_f32 v[40:41], v[8:9], v[82:83], v[40:41] op_sel:[0,1,0] op_sel_hi:[1,1,1]
	v_pk_fma_f32 v[38:39], v[10:11], v[84:85], v[38:39] op_sel_hi:[1,0,1]
	v_pk_fma_f32 v[40:41], v[10:11], v[84:85], v[40:41] op_sel:[0,1,0] op_sel_hi:[1,1,1]
	v_pk_fma_f32 v[38:39], v[12:13], v[86:87], v[38:39] op_sel_hi:[1,0,1]
	v_pk_fma_f32 v[40:41], v[12:13], v[86:87], v[40:41] op_sel:[0,1,0] op_sel_hi:[1,1,1]
	v_pk_fma_f32 v[38:39], v[14:15], v[88:89], v[38:39] op_sel_hi:[1,0,1]
	v_pk_fma_f32 v[40:41], v[14:15], v[88:89], v[40:41] op_sel:[0,1,0] op_sel_hi:[1,1,1]
	v_pk_fma_f32 v[38:39], v[16:17], v[90:91], v[38:39] op_sel_hi:[1,0,1]
	v_pk_fma_f32 v[40:41], v[16:17], v[90:91], v[40:41] op_sel:[0,1,0] op_sel_hi:[1,1,1]
	v_pk_fma_f32 v[38:39], v[18:19], v[92:93], v[38:39] op_sel_hi:[1,0,1]
	v_pk_fma_f32 v[40:41], v[18:19], v[92:93], v[40:41] op_sel:[0,1,0] op_sel_hi:[1,1,1]
	v_pk_fma_f32 v[38:39], v[20:21], v[94:95], v[38:39] op_sel_hi:[1,0,1]
	v_pk_fma_f32 v[40:41], v[20:21], v[94:95], v[40:41] op_sel:[0,1,0] op_sel_hi:[1,1,1]
	v_mul_f32_e32 v51, v100, v50
	v_add_f32_dpp v38, v38, v38 row_ror:8 row_mask:0xf bank_mask:0x3 bound_ctrl:1
	v_add_f32_dpp v39, v39, v39 row_ror:8 row_mask:0xf bank_mask:0x3 bound_ctrl:1
	v_add_f32_dpp v38, v40, v40 row_ror:8 row_mask:0xf bank_mask:0xc bound_ctrl:1
	v_add_f32_dpp v39, v41, v41 row_ror:8 row_mask:0xf bank_mask:0xc bound_ctrl:1
	ds_read_b128 v[56:59], v2 offset:20736
	v_add_f32_dpp v38, v38, v38 row_half_mirror row_mask:0xf bank_mask:0x5 bound_ctrl:1
	v_add_f32_dpp v38, v39, v39 row_half_mirror row_mask:0xf bank_mask:0xa bound_ctrl:1
	ds_read_b128 v[60:63], v2 offset:20992
	ds_read_b128 v[64:67], v2 offset:21248
	v_add_f32_dpp v38, v38, v38 quad_perm:[1,0,3,2] row_mask:0xf bank_mask:0xf bound_ctrl:1
	ds_read_b128 v[68:71], v2 offset:21504
	ds_read_b64 v[72:73], v3 offset:29952
	v_add_f32_dpp v38, v38, v38 quad_perm:[2,3,0,1] row_mask:0xf bank_mask:0xf bound_ctrl:1
	ds_read_b128 v[76:79], v1 offset:31040
	v_cmp_gt_f32_e32 vcc, 0x2b8cbccc, v51
	v_fmac_f32_dpp v96, -v38, v51 row_newbcast:0 row_mask:0xf bank_mask:0xf bound_ctrl:1
	v_fmac_f32_dpp v97, -v38, v51 row_newbcast:4 row_mask:0xf bank_mask:0xf bound_ctrl:1
	v_pk_mul_f32 v[44:45], v[96:97], v[100:101] op_sel:[0,1] op_sel_hi:[1,1]
	v_pk_mul_f32 v[48:49], v[44:45], v[102:103] op_sel_hi:[1,0]
	v_rcp_f32_e32 v52, v51
	s_add_u32 s14, s14, 0x1000
	s_addc_u32 s15, s15, 0
	v_fmac_f32_dpp v48, v38, v51 row_newbcast:8 row_mask:0xf bank_mask:0xf bound_ctrl:1
	v_fmac_f32_dpp v49, v38, v51 row_newbcast:12 row_mask:0xf bank_mask:0xf bound_ctrl:1
	s_cbranch_vccnz .Lgd2_rare1_3
.Lgd2_back1_3:
	v_cvt_pk_bf16_f32 v54, v48, v49
	v_pk_mul_f32 v[46:47], v[44:45], v[52:53] op_sel_hi:[1,0]
	v_pk_fma_f32 v[6:7], v[80:81], v[46:47], v[6:7] op_sel_hi:[0,1,1]
	v_pk_fma_f32 v[8:9], v[82:83], v[46:47], v[8:9] op_sel_hi:[0,1,1]
	v_pk_fma_f32 v[10:11], v[84:85], v[46:47], v[10:11] op_sel_hi:[0,1,1]
	v_pk_fma_f32 v[12:13], v[86:87], v[46:47], v[12:13] op_sel_hi:[0,1,1]
	v_pk_fma_f32 v[14:15], v[88:89], v[46:47], v[14:15] op_sel_hi:[0,1,1]
	v_pk_fma_f32 v[16:17], v[90:91], v[46:47], v[16:17] op_sel_hi:[0,1,1]
	v_pk_fma_f32 v[18:19], v[92:93], v[46:47], v[18:19] op_sel_hi:[0,1,1]
	v_pk_fma_f32 v[20:21], v[94:95], v[46:47], v[20:21] op_sel_hi:[0,1,1]
	global_store_dword v154, v54, s[14:15] offset:-4096
	s_waitcnt lgkmcnt(0)
	v_pk_mul_f32 v[38:39], v[6:7], v[56:57] op_sel_hi:[1,0]
	v_pk_mul_f32 v[40:41], v[6:7], v[56:57] op_sel:[0,1] op_sel_hi:[1,1]
	v_pk_fma_f32 v[38:39], v[8:9], v[58:59], v[38:39] op_sel_hi:[1,0,1]
	v_pk_fma_f32 v[40:41], v[8:9], v[58:59], v[40:41] op_sel:[0,1,0] op_sel_hi:[1,1,1]
	v_pk_fma_f32 v[38:39], v[10:11], v[60:61], v[38:39] op_sel_hi:[1,0,1]
	v_pk_fma_f32 v[40:41], v[10:11], v[60:61], v[40:41] op_sel:[0,1,0] op_sel_hi:[1,1,1]
	v_pk_fma_f32 v[38:39], v[12:13], v[62:63], v[38:39] op_sel_hi:[1,0,1]
	v_pk_fma_f32 v[40:41], v[12:13], v[62:63], v[40:41] op_sel:[0,1,0] op_sel_hi:[1,1,1]
	v_pk_fma_f32 v[38:39], v[14:15], v[64:65], v[38:39] op_sel_hi:[1,0,1]
	v_pk_fma_f32 v[40:41], v[14:15], v[64:65], v[40:41] op_sel:[0,1,0] op_sel_hi:[1,1,1]
	v_pk_fma_f32 v[38:39], v[16:17], v[66:67], v[38:39] op_sel_hi:[1,0,1]
	v_pk_fma_f32 v[40:41], v[16:17], v[66:67], v[40:41] op_sel:[0,1,0] op_sel_hi:[1,1,1]
	v_pk_fma_f32 v[38:39], v[18:19], v[68:69], v[38:39] op_sel_hi:[1,0,1]
	v_pk_fma_f32 v[40:41], v[18:19], v[68:69], v[40:41] op_sel:[0,1,0] op_sel_hi:[1,1,1]
	v_pk_fma_f32 v[38:39], v[20:21], v[70:71], v[38:39] op_sel_hi:[1,0,1]
	v_pk_fma_f32 v[40:41], v[20:21], v[70:71], v[40:41] op_sel:[0,1,0] op_sel_hi:[1,1,1]
	v_mul_f32_e32 v50, v76, v51
	v_add_f32_dpp v38, v38, v38 row_ror:8 row_mask:0xf bank_mask:0x3 bound_ctrl:1
	v_add_f32_dpp v39, v39, v39 row_ror:8 row_mask:0xf bank_mask:0x3 bound_ctrl:1
	v_add_f32_dpp v38, v40, v40 row_ror:8 row_mask:0xf bank_mask:0xc bound_ctrl:1
	v_add_f32_dpp v39, v41, v41 row_ror:8 row_mask:0xf bank_mask:0xc bound_ctrl:1
	ds_read_b128 v[80:83], v2 offset:21760
	v_add_f32_dpp v38, v38, v38 row_half_mirror row_mask:0xf bank_mask:0x5 bound_ctrl:1
	v_add_f32_dpp v38, v39, v39 row_half_mirror row_mask:0xf bank_mask:0xa bound_ctrl:1
	ds_read_b128 v[84:87], v2 offset:22016
	ds_read_b128 v[88:91], v2 offset:22272
	v_add_f32_dpp v38, v38, v38 quad_perm:[1,0,3,2] row_mask:0xf bank_mask:0xf bound_ctrl:1
	ds_read_b128 v[92:95], v2 offset:22528
	ds_read_b64 v[96:97], v3 offset:30208
	v_add_f32_dpp v38, v38, v38 quad_perm:[2,3,0,1] row_mask:0xf bank_mask:0xf bound_ctrl:1
	ds_read_b128 v[100:103], v1 offset:31056
	v_cmp_gt_f32_e32 vcc, 0x2b8cbccc, v50
	v_fmac_f32_dpp v72, -v38, v50 row_newbcast:0 row_mask:0xf bank_mask:0xf bound_ctrl:1
	v_fmac_f32_dpp v73, -v38, v50 row_newbcast:4 row_mask:0xf bank_mask:0xf bound_ctrl:1
	v_pk_mul_f32 v[44:45], v[72:73], v[76:77] op_sel:[0,1] op_sel_hi:[1,1]
	v_pk_mul_f32 v[48:49], v[44:45], v[78:79] op_sel_hi:[1,0]
	v_rcp_f32_e32 v52, v50
	s_add_u32 s14, s14, 0x1000
	s_addc_u32 s15, s15, 0
	v_fmac_f32_dpp v48, v38, v50 row_newbcast:8 row_mask:0xf bank_mask:0xf bound_ctrl:1
	v_fmac_f32_dpp v49, v38, v50 row_newbcast:12 row_mask:0xf bank_mask:0xf bound_ctrl:1
	s_cbranch_vccnz .Lgd2_rare1_4
.Lgd2_back1_4:
	v_cvt_pk_bf16_f32 v54, v48, v49
	v_pk_mul_f32 v[46:47], v[44:45], v[52:53] op_sel_hi:[1,0]
	v_pk_fma_f32 v[6:7], v[56:57], v[46:47], v[6:7] op_sel_hi:[0,1,1]
	v_pk_fma_f32 v[8:9], v[58:59], v[46:47], v[8:9] op_sel_hi:[0,1,1]
	v_pk_fma_f32 v[10:11], v[60:61], v[46:47], v[10:11] op_sel_hi:[0,1,1]
	v_pk_fma_f32 v[12:13], v[62:63], v[46:47], v[12:13] op_sel_hi:[0,1,1]
	v_pk_fma_f32 v[14:15], v[64:65], v[46:47], v[14:15] op_sel_hi:[0,1,1]
	v_pk_fma_f32 v[16:17], v[66:67], v[46:47], v[16:17] op_sel_hi:[0,1,1]
	v_pk_fma_f32 v[18:19], v[68:69], v[46:47], v[18:19] op_sel_hi:[0,1,1]
	v_pk_fma_f32 v[20:21], v[70:71], v[46:47], v[20:21] op_sel_hi:[0,1,1]
	global_store_dword v154, v54, s[14:15] offset:-4096
	s_waitcnt lgkmcnt(0)
	v_pk_mul_f32 v[38:39], v[6:7], v[80:81] op_sel_hi:[1,0]
	v_pk_mul_f32 v[40:41], v[6:7], v[80:81] op_sel:[0,1] op_sel_hi:[1,1]
	v_pk_fma_f32 v[38:39], v[8:9], v[82:83], v[38:39] op_sel_hi:[1,0,1]
	v_pk_fma_f32 v[40:41], v[8:9], v[82:83], v[40:41] op_sel:[0,1,0] op_sel_hi:[1,1,1]
	v_pk_fma_f32 v[38:39], v[10:11], v[84:85], v[38:39] op_sel_hi:[1,0,1]
	v_pk_fma_f32 v[40:41], v[10:11], v[84:85], v[40:41] op_sel:[0,1,0] op_sel_hi:[1,1,1]
	v_pk_fma_f32 v[38:39], v[12:13], v[86:87], v[38:39] op_sel_hi:[1,0,1]
	v_pk_fma_f32 v[40:41], v[12:13], v[86:87], v[40:41] op_sel:[0,1,0] op_sel_hi:[1,1,1]
	v_pk_fma_f32 v[38:39], v[14:15], v[88:89], v[38:39] op_sel_hi:[1,0,1]
	v_pk_fma_f32 v[40:41], v[14:15], v[88:89], v[40:41] op_sel:[0,1,0] op_sel_hi:[1,1,1]
	v_pk_fma_f32 v[38:39], v[16:17], v[90:91], v[38:39] op_sel_hi:[1,0,1]
	v_pk_fma_f32 v[40:41], v[16:17], v[90:91], v[40:41] op_sel:[0,1,0] op_sel_hi:[1,1,1]
	v_pk_fma_f32 v[38:39], v[18:19], v[92:93], v[38:39] op_sel_hi:[1,0,1]
	v_pk_fma_f32 v[40:41], v[18:19], v[92:93], v[40:41] op_sel:[0,1,0] op_sel_hi:[1,1,1]
	v_pk_fma_f32 v[38:39], v[20:21], v[94:95], v[38:39] op_sel_hi:[1,0,1]
	v_pk_fma_f32 v[40:41], v[20:21], v[94:95], v[40:41] op_sel:[0,1,0] op_sel_hi:[1,1,1]
	v_mul_f32_e32 v51, v100, v50
	v_add_f32_dpp v38, v38, v38 row_ror:8 row_mask:0xf bank_mask:0x3 bound_ctrl:1
	v_add_f32_dpp v39, v39, v39 row_ror:8 row_mask:0xf bank_mask:0x3 bound_ctrl:1
	v_add_f32_dpp v38, v40, v40 row_ror:8 row_mask:0xf bank_mask:0xc bound_ctrl:1
	v_add_f32_dpp v39, v41, v41 row_ror:8 row_mask:0xf bank_mask:0xc bound_ctrl:1
	ds_read_b128 v[56:59], v2 offset:22784
	v_add_f32_dpp v38, v38, v38 row_half_mirror row_mask:0xf bank_mask:0x5 bound_ctrl:1
	v_add_f32_dpp v38, v39, v39 row_half_mirror row_mask:0xf bank_mask:0xa bound_ctrl:1
	ds_read_b128 v[60:63], v2 offset:23040
	ds_read_b128 v[64:67], v2 offset:23296
	v_add_f32_dpp v38, v38, v38 quad_perm:[1,0,3,2] row_mask:0xf bank_mask:0xf bound_ctrl:1
	ds_read_b128 v[68:71], v2 offset:23552
	ds_read_b64 v[72:73], v3 offset:30464
	v_add_f32_dpp v38, v38, v38 quad_perm:[2,3,0,1] row_mask:0xf bank_mask:0xf bound_ctrl:1
	ds_read_b128 v[76:79], v1 offset:31072
	v_cmp_gt_f32_e32 vcc, 0x2b8cbccc, v51
	v_fmac_f32_dpp v96, -v38, v51 row_newbcast:0 row_mask:0xf bank_mask:0xf bound_ctrl:1
	v_fmac_f32_dpp v97, -v38, v51 row_newbcast:4 row_mask:0xf bank_mask:0xf bound_ctrl:1
	v_pk_mul_f32 v[44:45], v[96:97], v[100:101] op_sel:[0,1] op_sel_hi:[1,1]
	v_pk_mul_f32 v[48:49], v[44:45], v[102:103] op_sel_hi:[1,0]
	v_rcp_f32_e32 v52, v51
	s_add_u32 s14, s14, 0x1000
	s_addc_u32 s15, s15, 0
	v_fmac_f32_dpp v48, v38, v51 row_newbcast:8 row_mask:0xf bank_mask:0xf bound_ctrl:1
	v_fmac_f32_dpp v49, v38, v51 row_newbcast:12 row_mask:0xf bank_mask:0xf bound_ctrl:1
	s_cbranch_vccnz .Lgd2_rare1_5
.Lgd2_back1_5:
	v_cvt_pk_bf16_f32 v54, v48, v49
	v_pk_mul_f32 v[46:47], v[44:45], v[52:53] op_sel_hi:[1,0]
	v_pk_fma_f32 v[6:7], v[80:81], v[46:47], v[6:7] op_sel_hi:[0,1,1]
	v_pk_fma_f32 v[8:9], v[82:83], v[46:47], v[8:9] op_sel_hi:[0,1,1]
	v_pk_fma_f32 v[10:11], v[84:85], v[46:47], v[10:11] op_sel_hi:[0,1,1]
	v_pk_fma_f32 v[12:13], v[86:87], v[46:47], v[12:13] op_sel_hi:[0,1,1]
	v_pk_fma_f32 v[14:15], v[88:89], v[46:47], v[14:15] op_sel_hi:[0,1,1]
	v_pk_fma_f32 v[16:17], v[90:91], v[46:47], v[16:17] op_sel_hi:[0,1,1]
	v_pk_fma_f32 v[18:19], v[92:93], v[46:47], v[18:19] op_sel_hi:[0,1,1]
	v_pk_fma_f32 v[20:21], v[94:95], v[46:47], v[20:21] op_sel_hi:[0,1,1]
	global_store_dword v154, v54, s[14:15] offset:-4096
	s_waitcnt lgkmcnt(0)
	v_pk_mul_f32 v[38:39], v[6:7], v[56:57] op_sel_hi:[1,0]
	v_pk_mul_f32 v[40:41], v[6:7], v[56:57] op_sel:[0,1] op_sel_hi:[1,1]
	v_pk_fma_f32 v[38:39], v[8:9], v[58:59], v[38:39] op_sel_hi:[1,0,1]
	v_pk_fma_f32 v[40:41], v[8:9], v[58:59], v[40:41] op_sel:[0,1,0] op_sel_hi:[1,1,1]
	v_pk_fma_f32 v[38:39], v[10:11], v[60:61], v[38:39] op_sel_hi:[1,0,1]
	v_pk_fma_f32 v[40:41], v[10:11], v[60:61], v[40:41] op_sel:[0,1,0] op_sel_hi:[1,1,1]
	v_pk_fma_f32 v[38:39], v[12:13], v[62:63], v[38:39] op_sel_hi:[1,0,1]
	v_pk_fma_f32 v[40:41], v[12:13], v[62:63], v[40:41] op_sel:[0,1,0] op_sel_hi:[1,1,1]
	v_pk_fma_f32 v[38:39], v[14:15], v[64:65], v[38:39] op_sel_hi:[1,0,1]
	v_pk_fma_f32 v[40:41], v[14:15], v[64:65], v[40:41] op_sel:[0,1,0] op_sel_hi:[1,1,1]
	v_pk_fma_f32 v[38:39], v[16:17], v[66:67], v[38:39] op_sel_hi:[1,0,1]
	v_pk_fma_f32 v[40:41], v[16:17], v[66:67], v[40:41] op_sel:[0,1,0] op_sel_hi:[1,1,1]
	v_pk_fma_f32 v[38:39], v[18:19], v[68:69], v[38:39] op_sel_hi:[1,0,1]
	v_pk_fma_f32 v[40:41], v[18:19], v[68:69], v[40:41] op_sel:[0,1,0] op_sel_hi:[1,1,1]
	v_pk_fma_f32 v[38:39], v[20:21], v[70:71], v[38:39] op_sel_hi:[1,0,1]
	v_pk_fma_f32 v[40:41], v[20:21], v[70:71], v[40:41] op_sel:[0,1,0] op_sel_hi:[1,1,1]
	v_mul_f32_e32 v50, v76, v51
	v_add_f32_dpp v38, v38, v38 row_ror:8 row_mask:0xf bank_mask:0x3 bound_ctrl:1
	v_add_f32_dpp v39, v39, v39 row_ror:8 row_mask:0xf bank_mask:0x3 bound_ctrl:1
	v_add_f32_dpp v38, v40, v40 row_ror:8 row_mask:0xf bank_mask:0xc bound_ctrl:1
	v_add_f32_dpp v39, v41, v41 row_ror:8 row_mask:0xf bank_mask:0xc bound_ctrl:1
	ds_read_b128 v[80:83], v2 offset:23808
	v_add_f32_dpp v38, v38, v38 row_half_mirror row_mask:0xf bank_mask:0x5 bound_ctrl:1
	v_add_f32_dpp v38, v39, v39 row_half_mirror row_mask:0xf bank_mask:0xa bound_ctrl:1
	ds_read_b128 v[84:87], v2 offset:24064
	ds_read_b128 v[88:91], v2 offset:24320
	v_add_f32_dpp v38, v38, v38 quad_perm:[1,0,3,2] row_mask:0xf bank_mask:0xf bound_ctrl:1
	ds_read_b128 v[92:95], v2 offset:24576
	ds_read_b64 v[96:97], v3 offset:30720
	v_add_f32_dpp v38, v38, v38 quad_perm:[2,3,0,1] row_mask:0xf bank_mask:0xf bound_ctrl:1
	ds_read_b128 v[100:103], v1 offset:31088
	v_cmp_gt_f32_e32 vcc, 0x2b8cbccc, v50
	v_fmac_f32_dpp v72, -v38, v50 row_newbcast:0 row_mask:0xf bank_mask:0xf bound_ctrl:1
	v_fmac_f32_dpp v73, -v38, v50 row_newbcast:4 row_mask:0xf bank_mask:0xf bound_ctrl:1
	v_pk_mul_f32 v[44:45], v[72:73], v[76:77] op_sel:[0,1] op_sel_hi:[1,1]
	v_pk_mul_f32 v[48:49], v[44:45], v[78:79] op_sel_hi:[1,0]
	v_rcp_f32_e32 v52, v50
	s_add_u32 s14, s14, 0x1000
	s_addc_u32 s15, s15, 0
	v_fmac_f32_dpp v48, v38, v50 row_newbcast:8 row_mask:0xf bank_mask:0xf bound_ctrl:1
	v_fmac_f32_dpp v49, v38, v50 row_newbcast:12 row_mask:0xf bank_mask:0xf bound_ctrl:1
	s_cbranch_vccnz .Lgd2_rare1_6
.Lgd2_back1_6:
	v_cvt_pk_bf16_f32 v54, v48, v49
	v_pk_mul_f32 v[46:47], v[44:45], v[52:53] op_sel_hi:[1,0]
	v_pk_fma_f32 v[6:7], v[56:57], v[46:47], v[6:7] op_sel_hi:[0,1,1]
	v_pk_fma_f32 v[8:9], v[58:59], v[46:47], v[8:9] op_sel_hi:[0,1,1]
	v_pk_fma_f32 v[10:11], v[60:61], v[46:47], v[10:11] op_sel_hi:[0,1,1]
	v_pk_fma_f32 v[12:13], v[62:63], v[46:47], v[12:13] op_sel_hi:[0,1,1]
	v_pk_fma_f32 v[14:15], v[64:65], v[46:47], v[14:15] op_sel_hi:[0,1,1]
	v_pk_fma_f32 v[16:17], v[66:67], v[46:47], v[16:17] op_sel_hi:[0,1,1]
	v_pk_fma_f32 v[18:19], v[68:69], v[46:47], v[18:19] op_sel_hi:[0,1,1]
	v_pk_fma_f32 v[20:21], v[70:71], v[46:47], v[20:21] op_sel_hi:[0,1,1]
	global_store_dword v154, v54, s[14:15] offset:-4096
	s_waitcnt lgkmcnt(0)
	v_pk_mul_f32 v[38:39], v[6:7], v[80:81] op_sel_hi:[1,0]
	v_pk_mul_f32 v[40:41], v[6:7], v[80:81] op_sel:[0,1] op_sel_hi:[1,1]
	v_pk_fma_f32 v[38:39], v[8:9], v[82:83], v[38:39] op_sel_hi:[1,0,1]
	v_pk_fma_f32 v[40:41], v[8:9], v[82:83], v[40:41] op_sel:[0,1,0] op_sel_hi:[1,1,1]
	v_pk_fma_f32 v[38:39], v[10:11], v[84:85], v[38:39] op_sel_hi:[1,0,1]
	v_pk_fma_f32 v[40:41], v[10:11], v[84:85], v[40:41] op_sel:[0,1,0] op_sel_hi:[1,1,1]
	v_pk_fma_f32 v[38:39], v[12:13], v[86:87], v[38:39] op_sel_hi:[1,0,1]
	v_pk_fma_f32 v[40:41], v[12:13], v[86:87], v[40:41] op_sel:[0,1,0] op_sel_hi:[1,1,1]
	v_pk_fma_f32 v[38:39], v[14:15], v[88:89], v[38:39] op_sel_hi:[1,0,1]
	v_pk_fma_f32 v[40:41], v[14:15], v[88:89], v[40:41] op_sel:[0,1,0] op_sel_hi:[1,1,1]
	v_pk_fma_f32 v[38:39], v[16:17], v[90:91], v[38:39] op_sel_hi:[1,0,1]
	v_pk_fma_f32 v[40:41], v[16:17], v[90:91], v[40:41] op_sel:[0,1,0] op_sel_hi:[1,1,1]
	v_pk_fma_f32 v[38:39], v[18:19], v[92:93], v[38:39] op_sel_hi:[1,0,1]
	v_pk_fma_f32 v[40:41], v[18:19], v[92:93], v[40:41] op_sel:[0,1,0] op_sel_hi:[1,1,1]
	v_pk_fma_f32 v[38:39], v[20:21], v[94:95], v[38:39] op_sel_hi:[1,0,1]
	v_pk_fma_f32 v[40:41], v[20:21], v[94:95], v[40:41] op_sel:[0,1,0] op_sel_hi:[1,1,1]
	v_mul_f32_e32 v51, v100, v50
	v_add_f32_dpp v38, v38, v38 row_ror:8 row_mask:0xf bank_mask:0x3 bound_ctrl:1
	v_add_f32_dpp v39, v39, v39 row_ror:8 row_mask:0xf bank_mask:0x3 bound_ctrl:1
	v_add_f32_dpp v38, v40, v40 row_ror:8 row_mask:0xf bank_mask:0xc bound_ctrl:1
	v_add_f32_dpp v39, v41, v41 row_ror:8 row_mask:0xf bank_mask:0xc bound_ctrl:1
	ds_read_b128 v[56:59], v2 offset:33024
	v_add_f32_dpp v38, v38, v38 row_half_mirror row_mask:0xf bank_mask:0x5 bound_ctrl:1
	v_add_f32_dpp v38, v39, v39 row_half_mirror row_mask:0xf bank_mask:0xa bound_ctrl:1
	ds_read_b128 v[60:63], v2 offset:33280
	ds_read_b128 v[64:67], v2 offset:33536
	v_add_f32_dpp v38, v38, v38 quad_perm:[1,0,3,2] row_mask:0xf bank_mask:0xf bound_ctrl:1
	ds_read_b128 v[68:71], v2 offset:33792
	ds_read_b64 v[72:73], v3 offset:45312
	v_add_f32_dpp v38, v38, v38 quad_perm:[2,3,0,1] row_mask:0xf bank_mask:0xf bound_ctrl:1
	ds_read_b128 v[76:79], v1 offset:47360
	v_cmp_gt_f32_e32 vcc, 0x2b8cbccc, v51
	v_fmac_f32_dpp v96, -v38, v51 row_newbcast:0 row_mask:0xf bank_mask:0xf bound_ctrl:1
	v_fmac_f32_dpp v97, -v38, v51 row_newbcast:4 row_mask:0xf bank_mask:0xf bound_ctrl:1
	v_pk_mul_f32 v[44:45], v[96:97], v[100:101] op_sel:[0,1] op_sel_hi:[1,1]
	v_pk_mul_f32 v[48:49], v[44:45], v[102:103] op_sel_hi:[1,0]
	v_rcp_f32_e32 v52, v51
	s_add_u32 s14, s14, 0x1000
	s_addc_u32 s15, s15, 0
	v_fmac_f32_dpp v48, v38, v51 row_newbcast:8 row_mask:0xf bank_mask:0xf bound_ctrl:1
	v_fmac_f32_dpp v49, v38, v51 row_newbcast:12 row_mask:0xf bank_mask:0xf bound_ctrl:1
	s_cbranch_vccnz .Lgd2_rare1_7
.Lgd2_back1_7:
	v_cvt_pk_bf16_f32 v54, v48, v49
	v_pk_mul_f32 v[46:47], v[44:45], v[52:53] op_sel_hi:[1,0]
	v_pk_fma_f32 v[6:7], v[80:81], v[46:47], v[6:7] op_sel_hi:[0,1,1]
	v_pk_fma_f32 v[8:9], v[82:83], v[46:47], v[8:9] op_sel_hi:[0,1,1]
	v_pk_fma_f32 v[10:11], v[84:85], v[46:47], v[10:11] op_sel_hi:[0,1,1]
	v_pk_fma_f32 v[12:13], v[86:87], v[46:47], v[12:13] op_sel_hi:[0,1,1]
	v_pk_fma_f32 v[14:15], v[88:89], v[46:47], v[14:15] op_sel_hi:[0,1,1]
	v_pk_fma_f32 v[16:17], v[90:91], v[46:47], v[16:17] op_sel_hi:[0,1,1]
	v_pk_fma_f32 v[18:19], v[92:93], v[46:47], v[18:19] op_sel_hi:[0,1,1]
	v_pk_fma_f32 v[20:21], v[94:95], v[46:47], v[20:21] op_sel_hi:[0,1,1]
	global_store_dword v154, v54, s[14:15] offset:-4096
	s_waitcnt vmcnt(8)
	v_lshlrev_b32_e32 v116, 16, v108
	v_lshlrev_b32_e32 v117, 16, v109
	v_and_b32_e32 v118, s17, v108
	v_and_b32_e32 v119, s17, v109
	v_lshlrev_b32_e32 v120, 16, v110
	v_and_b32_e32 v121, s17, v110
	v_lshlrev_b32_e32 v122, 16, v111
	v_and_b32_e32 v123, s17, v111
	v_lshlrev_b32_e32 v124, 16, v112
	v_and_b32_e32 v125, s17, v112
	ds_write_b128 v32, v[116:119] offset:256
	ds_write_b64 v33, v[120:121] offset:256
	ds_write_b64 v34, v[122:123] offset:256
	ds_write_b64 v34, v[124:125] offset:384
	ds_write_b32 v35, v113 offset:256
	s_add_i32 s16, s16, 8
	s_waitcnt lgkmcnt(0)
	s_barrier
	s_cmpk_lt_u32 s16, 0x800
	s_cbranch_scc0 .Lgd2_done
	global_load_dword v108, v36, s[8:9]
	global_load_dword v109, v36, s[8:9] offset:-2048
	global_load_dword v111, v104, s[8:9] offset:2048
	global_load_dword v110, v37, s[10:11]
	global_load_dword v112, v105, s[10:11]
	global_load_dword v113, v106, s[12:13]
	s_add_u32 s8, s8, 0xc000
	s_addc_u32 s9, s9, 0
	s_add_u32 s10, s10, 0x20000
	s_addc_u32 s11, s11, 0
	s_add_u32 s12, s12, 0x400
	s_addc_u32 s13, s13, 0
	s_waitcnt lgkmcnt(0)
	v_pk_mul_f32 v[38:39], v[6:7], v[56:57] op_sel_hi:[1,0]
	v_pk_mul_f32 v[40:41], v[6:7], v[56:57] op_sel:[0,1] op_sel_hi:[1,1]
	v_pk_fma_f32 v[38:39], v[8:9], v[58:59], v[38:39] op_sel_hi:[1,0,1]
	v_pk_fma_f32 v[40:41], v[8:9], v[58:59], v[40:41] op_sel:[0,1,0] op_sel_hi:[1,1,1]
	v_pk_fma_f32 v[38:39], v[10:11], v[60:61], v[38:39] op_sel_hi:[1,0,1]
	v_pk_fma_f32 v[40:41], v[10:11], v[60:61], v[40:41] op_sel:[0,1,0] op_sel_hi:[1,1,1]
	v_pk_fma_f32 v[38:39], v[12:13], v[62:63], v[38:39] op_sel_hi:[1,0,1]
	v_pk_fma_f32 v[40:41], v[12:13], v[62:63], v[40:41] op_sel:[0,1,0] op_sel_hi:[1,1,1]
	v_pk_fma_f32 v[38:39], v[14:15], v[64:65], v[38:39] op_sel_hi:[1,0,1]
	v_pk_fma_f32 v[40:41], v[14:15], v[64:65], v[40:41] op_sel:[0,1,0] op_sel_hi:[1,1,1]
	v_pk_fma_f32 v[38:39], v[16:17], v[66:67], v[38:39] op_sel_hi:[1,0,1]
	v_pk_fma_f32 v[40:41], v[16:17], v[66:67], v[40:41] op_sel:[0,1,0] op_sel_hi:[1,1,1]
	v_pk_fma_f32 v[38:39], v[18:19], v[68:69], v[38:39] op_sel_hi:[1,0,1]
	v_pk_fma_f32 v[40:41], v[18:19], v[68:69], v[40:41] op_sel:[0,1,0] op_sel_hi:[1,1,1]
	v_pk_fma_f32 v[38:39], v[20:21], v[70:71], v[38:39] op_sel_hi:[1,0,1]
	v_pk_fma_f32 v[40:41], v[20:21], v[70:71], v[40:41] op_sel:[0,1,0] op_sel_hi:[1,1,1]
	v_mul_f32_e32 v50, v76, v51
	v_add_f32_dpp v38, v38, v38 row_ror:8 row_mask:0xf bank_mask:0x3 bound_ctrl:1
	v_add_f32_dpp v39, v39, v39 row_ror:8 row_mask:0xf bank_mask:0x3 bound_ctrl:1
	v_add_f32_dpp v38, v40, v40 row_ror:8 row_mask:0xf bank_mask:0xc bound_ctrl:1
	v_add_f32_dpp v39, v41, v41 row_ror:8 row_mask:0xf bank_mask:0xc bound_ctrl:1
	ds_read_b128 v[80:83], v2 offset:34048
	v_add_f32_dpp v38, v38, v38 row_half_mirror row_mask:0xf bank_mask:0x5 bound_ctrl:1
	v_add_f32_dpp v38, v39, v39 row_half_mirror row_mask:0xf bank_mask:0xa bound_ctrl:1
	ds_read_b128 v[84:87], v2 offset:34304
	ds_read_b128 v[88:91], v2 offset:34560
	v_add_f32_dpp v38, v38, v38 quad_perm:[1,0,3,2] row_mask:0xf bank_mask:0xf bound_ctrl:1
	ds_read_b128 v[92:95], v2 offset:34816
	ds_read_b64 v[96:97], v3 offset:45568
	v_add_f32_dpp v38, v38, v38 quad_perm:[2,3,0,1] row_mask:0xf bank_mask:0xf bound_ctrl:1
	ds_read_b128 v[100:103], v1 offset:47376
	v_cmp_gt_f32_e32 vcc, 0x2b8cbccc, v50
	v_fmac_f32_dpp v72, -v38, v50 row_newbcast:0 row_mask:0xf bank_mask:0xf bound_ctrl:1
	v_fmac_f32_dpp v73, -v38, v50 row_newbcast:4 row_mask:0xf bank_mask:0xf bound_ctrl:1
	v_pk_mul_f32 v[44:45], v[72:73], v[76:77] op_sel:[0,1] op_sel_hi:[1,1]
	v_pk_mul_f32 v[48:49], v[44:45], v[78:79] op_sel_hi:[1,0]
	v_rcp_f32_e32 v52, v50
	s_add_u32 s14, s14, 0x1000
	s_addc_u32 s15, s15, 0
	v_fmac_f32_dpp v48, v38, v50 row_newbcast:8 row_mask:0xf bank_mask:0xf bound_ctrl:1
	v_fmac_f32_dpp v49, v38, v50 row_newbcast:12 row_mask:0xf bank_mask:0xf bound_ctrl:1
	s_cbranch_vccnz .Lgd2_rare2_0
.Lgd2_back2_0:
	v_cvt_pk_bf16_f32 v54, v48, v49
	v_pk_mul_f32 v[46:47], v[44:45], v[52:53] op_sel_hi:[1,0]
	v_pk_fma_f32 v[6:7], v[56:57], v[46:47], v[6:7] op_sel_hi:[0,1,1]
	v_pk_fma_f32 v[8:9], v[58:59], v[46:47], v[8:9] op_sel_hi:[0,1,1]
	v_pk_fma_f32 v[10:11], v[60:61], v[46:47], v[10:11] op_sel_hi:[0,1,1]
	v_pk_fma_f32 v[12:13], v[62:63], v[46:47], v[12:13] op_sel_hi:[0,1,1]
	v_pk_fma_f32 v[14:15], v[64:65], v[46:47], v[14:15] op_sel_hi:[0,1,1]
	v_pk_fma_f32 v[16:17], v[66:67], v[46:47], v[16:17] op_sel_hi:[0,1,1]
	v_pk_fma_f32 v[18:19], v[68:69], v[46:47], v[18:19] op_sel_hi:[0,1,1]
	v_pk_fma_f32 v[20:21], v[70:71], v[46:47], v[20:21] op_sel_hi:[0,1,1]
	global_store_dword v154, v54, s[14:15] offset:-4096
	s_waitcnt lgkmcnt(0)
	v_pk_mul_f32 v[38:39], v[6:7], v[80:81] op_sel_hi:[1,0]
	v_pk_mul_f32 v[40:41], v[6:7], v[80:81] op_sel:[0,1] op_sel_hi:[1,1]
	v_pk_fma_f32 v[38:39], v[8:9], v[82:83], v[38:39] op_sel_hi:[1,0,1]
	v_pk_fma_f32 v[40:41], v[8:9], v[82:83], v[40:41] op_sel:[0,1,0] op_sel_hi:[1,1,1]
	v_pk_fma_f32 v[38:39], v[10:11], v[84:85], v[38:39] op_sel_hi:[1,0,1]
	v_pk_fma_f32 v[40:41], v[10:11], v[84:85], v[40:41] op_sel:[0,1,0] op_sel_hi:[1,1,1]
	v_pk_fma_f32 v[38:39], v[12:13], v[86:87], v[38:39] op_sel_hi:[1,0,1]
	v_pk_fma_f32 v[40:41], v[12:13], v[86:87], v[40:41] op_sel:[0,1,0] op_sel_hi:[1,1,1]
	v_pk_fma_f32 v[38:39], v[14:15], v[88:89], v[38:39] op_sel_hi:[1,0,1]
	v_pk_fma_f32 v[40:41], v[14:15], v[88:89], v[40:41] op_sel:[0,1,0] op_sel_hi:[1,1,1]
	v_pk_fma_f32 v[38:39], v[16:17], v[90:91], v[38:39] op_sel_hi:[1,0,1]
	v_pk_fma_f32 v[40:41], v[16:17], v[90:91], v[40:41] op_sel:[0,1,0] op_sel_hi:[1,1,1]
	v_pk_fma_f32 v[38:39], v[18:19], v[92:93], v[38:39] op_sel_hi:[1,0,1]
	v_pk_fma_f32 v[40:41], v[18:19], v[92:93], v[40:41] op_sel:[0,1,0] op_sel_hi:[1,1,1]
	v_pk_fma_f32 v[38:39], v[20:21], v[94:95], v[38:39] op_sel_hi:[1,0,1]
	v_pk_fma_f32 v[40:41], v[20:21], v[94:95], v[40:41] op_sel:[0,1,0] op_sel_hi:[1,1,1]
	v_mul_f32_e32 v51, v100, v50
	v_add_f32_dpp v38, v38, v38 row_ror:8 row_mask:0xf bank_mask:0x3 bound_ctrl:1
	v_add_f32_dpp v39, v39, v39 row_ror:8 row_mask:0xf bank_mask:0x3 bound_ctrl:1
	v_add_f32_dpp v38, v40, v40 row_ror:8 row_mask:0xf bank_mask:0xc bound_ctrl:1
	v_add_f32_dpp v39, v41, v41 row_ror:8 row_mask:0xf bank_mask:0xc bound_ctrl:1
	ds_read_b128 v[56:59], v2 offset:35072
	v_add_f32_dpp v38, v38, v38 row_half_mirror row_mask:0xf bank_mask:0x5 bound_ctrl:1
	v_add_f32_dpp v38, v39, v39 row_half_mirror row_mask:0xf bank_mask:0xa bound_ctrl:1
	ds_read_b128 v[60:63], v2 offset:35328
	ds_read_b128 v[64:67], v2 offset:35584
	v_add_f32_dpp v38, v38, v38 quad_perm:[1,0,3,2] row_mask:0xf bank_mask:0xf bound_ctrl:1
	ds_read_b128 v[68:71], v2 offset:35840
	ds_read_b64 v[72:73], v3 offset:45824
	v_add_f32_dpp v38, v38, v38 quad_perm:[2,3,0,1] row_mask:0xf bank_mask:0xf bound_ctrl:1
	ds_read_b128 v[76:79], v1 offset:47392
	v_cmp_gt_f32_e32 vcc, 0x2b8cbccc, v51
	v_fmac_f32_dpp v96, -v38, v51 row_newbcast:0 row_mask:0xf bank_mask:0xf bound_ctrl:1
	v_fmac_f32_dpp v97, -v38, v51 row_newbcast:4 row_mask:0xf bank_mask:0xf bound_ctrl:1
	v_pk_mul_f32 v[44:45], v[96:97], v[100:101] op_sel:[0,1] op_sel_hi:[1,1]
	v_pk_mul_f32 v[48:49], v[44:45], v[102:103] op_sel_hi:[1,0]
	v_rcp_f32_e32 v52, v51
	s_add_u32 s14, s14, 0x1000
	s_addc_u32 s15, s15, 0
	v_fmac_f32_dpp v48, v38, v51 row_newbcast:8 row_mask:0xf bank_mask:0xf bound_ctrl:1
	v_fmac_f32_dpp v49, v38, v51 row_newbcast:12 row_mask:0xf bank_mask:0xf bound_ctrl:1
	s_cbranch_vccnz .Lgd2_rare2_1
.Lgd2_back2_1:
	v_cvt_pk_bf16_f32 v54, v48, v49
	v_pk_mul_f32 v[46:47], v[44:45], v[52:53] op_sel_hi:[1,0]
	v_pk_fma_f32 v[6:7], v[80:81], v[46:47], v[6:7] op_sel_hi:[0,1,1]
	v_pk_fma_f32 v[8:9], v[82:83], v[46:47], v[8:9] op_sel_hi:[0,1,1]
	v_pk_fma_f32 v[10:11], v[84:85], v[46:47], v[10:11] op_sel_hi:[0,1,1]
	v_pk_fma_f32 v[12:13], v[86:87], v[46:47], v[12:13] op_sel_hi:[0,1,1]
	v_pk_fma_f32 v[14:15], v[88:89], v[46:47], v[14:15] op_sel_hi:[0,1,1]
	v_pk_fma_f32 v[16:17], v[90:91], v[46:47], v[16:17] op_sel_hi:[0,1,1]
	v_pk_fma_f32 v[18:19], v[92:93], v[46:47], v[18:19] op_sel_hi:[0,1,1]
	v_pk_fma_f32 v[20:21], v[94:95], v[46:47], v[20:21] op_sel_hi:[0,1,1]
	global_store_dword v154, v54, s[14:15] offset:-4096
	s_waitcnt lgkmcnt(0)
	v_pk_mul_f32 v[38:39], v[6:7], v[56:57] op_sel_hi:[1,0]
	v_pk_mul_f32 v[40:41], v[6:7], v[56:57] op_sel:[0,1] op_sel_hi:[1,1]
	v_pk_fma_f32 v[38:39], v[8:9], v[58:59], v[38:39] op_sel_hi:[1,0,1]
	v_pk_fma_f32 v[40:41], v[8:9], v[58:59], v[40:41] op_sel:[0,1,0] op_sel_hi:[1,1,1]
	v_pk_fma_f32 v[38:39], v[10:11], v[60:61], v[38:39] op_sel_hi:[1,0,1]
	v_pk_fma_f32 v[40:41], v[10:11], v[60:61], v[40:41] op_sel:[0,1,0] op_sel_hi:[1,1,1]
	v_pk_fma_f32 v[38:39], v[12:13], v[62:63], v[38:39] op_sel_hi:[1,0,1]
	v_pk_fma_f32 v[40:41], v[12:13], v[62:63], v[40:41] op_sel:[0,1,0] op_sel_hi:[1,1,1]
	v_pk_fma_f32 v[38:39], v[14:15], v[64:65], v[38:39] op_sel_hi:[1,0,1]
	v_pk_fma_f32 v[40:41], v[14:15], v[64:65], v[40:41] op_sel:[0,1,0] op_sel_hi:[1,1,1]
	v_pk_fma_f32 v[38:39], v[16:17], v[66:67], v[38:39] op_sel_hi:[1,0,1]
	v_pk_fma_f32 v[40:41], v[16:17], v[66:67], v[40:41] op_sel:[0,1,0] op_sel_hi:[1,1,1]
	v_pk_fma_f32 v[38:39], v[18:19], v[68:69], v[38:39] op_sel_hi:[1,0,1]
	v_pk_fma_f32 v[40:41], v[18:19], v[68:69], v[40:41] op_sel:[0,1,0] op_sel_hi:[1,1,1]
	v_pk_fma_f32 v[38:39], v[20:21], v[70:71], v[38:39] op_sel_hi:[1,0,1]
	v_pk_fma_f32 v[40:41], v[20:21], v[70:71], v[40:41] op_sel:[0,1,0] op_sel_hi:[1,1,1]
	v_mul_f32_e32 v50, v76, v51
	v_add_f32_dpp v38, v38, v38 row_ror:8 row_mask:0xf bank_mask:0x3 bound_ctrl:1
	v_add_f32_dpp v39, v39, v39 row_ror:8 row_mask:0xf bank_mask:0x3 bound_ctrl:1
	v_add_f32_dpp v38, v40, v40 row_ror:8 row_mask:0xf bank_mask:0xc bound_ctrl:1
	v_add_f32_dpp v39, v41, v41 row_ror:8 row_mask:0xf bank_mask:0xc bound_ctrl:1
	ds_read_b128 v[80:83], v2 offset:36096
	v_add_f32_dpp v38, v38, v38 row_half_mirror row_mask:0xf bank_mask:0x5 bound_ctrl:1
	v_add_f32_dpp v38, v39, v39 row_half_mirror row_mask:0xf bank_mask:0xa bound_ctrl:1
	ds_read_b128 v[84:87], v2 offset:36352
	ds_read_b128 v[88:91], v2 offset:36608
	v_add_f32_dpp v38, v38, v38 quad_perm:[1,0,3,2] row_mask:0xf bank_mask:0xf bound_ctrl:1
	ds_read_b128 v[92:95], v2 offset:36864
	ds_read_b64 v[96:97], v3 offset:46080
	v_add_f32_dpp v38, v38, v38 quad_perm:[2,3,0,1] row_mask:0xf bank_mask:0xf bound_ctrl:1
	ds_read_b128 v[100:103], v1 offset:47408
	v_cmp_gt_f32_e32 vcc, 0x2b8cbccc, v50
	v_fmac_f32_dpp v72, -v38, v50 row_newbcast:0 row_mask:0xf bank_mask:0xf bound_ctrl:1
	v_fmac_f32_dpp v73, -v38, v50 row_newbcast:4 row_mask:0xf bank_mask:0xf bound_ctrl:1
	v_pk_mul_f32 v[44:45], v[72:73], v[76:77] op_sel:[0,1] op_sel_hi:[1,1]
	v_pk_mul_f32 v[48:49], v[44:45], v[78:79] op_sel_hi:[1,0]
	v_rcp_f32_e32 v52, v50
	s_add_u32 s14, s14, 0x1000
	s_addc_u32 s15, s15, 0
	v_fmac_f32_dpp v48, v38, v50 row_newbcast:8 row_mask:0xf bank_mask:0xf bound_ctrl:1
	v_fmac_f32_dpp v49, v38, v50 row_newbcast:12 row_mask:0xf bank_mask:0xf bound_ctrl:1
	s_cbranch_vccnz .Lgd2_rare2_2
.Lgd2_back2_2:
	v_cvt_pk_bf16_f32 v54, v48, v49
	v_pk_mul_f32 v[46:47], v[44:45], v[52:53] op_sel_hi:[1,0]
	v_pk_fma_f32 v[6:7], v[56:57], v[46:47], v[6:7] op_sel_hi:[0,1,1]
	v_pk_fma_f32 v[8:9], v[58:59], v[46:47], v[8:9] op_sel_hi:[0,1,1]
	v_pk_fma_f32 v[10:11], v[60:61], v[46:47], v[10:11] op_sel_hi:[0,1,1]
	v_pk_fma_f32 v[12:13], v[62:63], v[46:47], v[12:13] op_sel_hi:[0,1,1]
	v_pk_fma_f32 v[14:15], v[64:65], v[46:47], v[14:15] op_sel_hi:[0,1,1]
	v_pk_fma_f32 v[16:17], v[66:67], v[46:47], v[16:17] op_sel_hi:[0,1,1]
	v_pk_fma_f32 v[18:19], v[68:69], v[46:47], v[18:19] op_sel_hi:[0,1,1]
	v_pk_fma_f32 v[20:21], v[70:71], v[46:47], v[20:21] op_sel_hi:[0,1,1]
	global_store_dword v154, v54, s[14:15] offset:-4096
	s_waitcnt lgkmcnt(0)
	v_pk_mul_f32 v[38:39], v[6:7], v[80:81] op_sel_hi:[1,0]
	v_pk_mul_f32 v[40:41], v[6:7], v[80:81] op_sel:[0,1] op_sel_hi:[1,1]
	v_pk_fma_f32 v[38:39], v[8:9], v[82:83], v[38:39] op_sel_hi:[1,0,1]
	v_pk_fma_f32 v[40:41], v[8:9], v[82:83], v[40:41] op_sel:[0,1,0] op_sel_hi:[1,1,1]
	v_pk_fma_f32 v[38:39], v[10:11], v[84:85], v[38:39] op_sel_hi:[1,0,1]
	v_pk_fma_f32 v[40:41], v[10:11], v[84:85], v[40:41] op_sel:[0,1,0] op_sel_hi:[1,1,1]
	v_pk_fma_f32 v[38:39], v[12:13], v[86:87], v[38:39] op_sel_hi:[1,0,1]
	v_pk_fma_f32 v[40:41], v[12:13], v[86:87], v[40:41] op_sel:[0,1,0] op_sel_hi:[1,1,1]
	v_pk_fma_f32 v[38:39], v[14:15], v[88:89], v[38:39] op_sel_hi:[1,0,1]
	v_pk_fma_f32 v[40:41], v[14:15], v[88:89], v[40:41] op_sel:[0,1,0] op_sel_hi:[1,1,1]
	v_pk_fma_f32 v[38:39], v[16:17], v[90:91], v[38:39] op_sel_hi:[1,0,1]
	v_pk_fma_f32 v[40:41], v[16:17], v[90:91], v[40:41] op_sel:[0,1,0] op_sel_hi:[1,1,1]
	v_pk_fma_f32 v[38:39], v[18:19], v[92:93], v[38:39] op_sel_hi:[1,0,1]
	v_pk_fma_f32 v[40:41], v[18:19], v[92:93], v[40:41] op_sel:[0,1,0] op_sel_hi:[1,1,1]
	v_pk_fma_f32 v[38:39], v[20:21], v[94:95], v[38:39] op_sel_hi:[1,0,1]
	v_pk_fma_f32 v[40:41], v[20:21], v[94:95], v[40:41] op_sel:[0,1,0] op_sel_hi:[1,1,1]
	v_mul_f32_e32 v51, v100, v50
	v_add_f32_dpp v38, v38, v38 row_ror:8 row_mask:0xf bank_mask:0x3 bound_ctrl:1
	v_add_f32_dpp v39, v39, v39 row_ror:8 row_mask:0xf bank_mask:0x3 bound_ctrl:1
	v_add_f32_dpp v38, v40, v40 row_ror:8 row_mask:0xf bank_mask:0xc bound_ctrl:1
	v_add_f32_dpp v39, v41, v41 row_ror:8 row_mask:0xf bank_mask:0xc bound_ctrl:1
	ds_read_b128 v[56:59], v2 offset:37120
	v_add_f32_dpp v38, v38, v38 row_half_mirror row_mask:0xf bank_mask:0x5 bound_ctrl:1
	v_add_f32_dpp v38, v39, v39 row_half_mirror row_mask:0xf bank_mask:0xa bound_ctrl:1
	ds_read_b128 v[60:63], v2 offset:37376
	ds_read_b128 v[64:67], v2 offset:37632
	v_add_f32_dpp v38, v38, v38 quad_perm:[1,0,3,2] row_mask:0xf bank_mask:0xf bound_ctrl:1
	ds_read_b128 v[68:71], v2 offset:37888
	ds_read_b64 v[72:73], v3 offset:46336
	v_add_f32_dpp v38, v38, v38 quad_perm:[2,3,0,1] row_mask:0xf bank_mask:0xf bound_ctrl:1
	ds_read_b128 v[76:79], v1 offset:47424
	v_cmp_gt_f32_e32 vcc, 0x2b8cbccc, v51
	v_fmac_f32_dpp v96, -v38, v51 row_newbcast:0 row_mask:0xf bank_mask:0xf bound_ctrl:1
	v_fmac_f32_dpp v97, -v38, v51 row_newbcast:4 row_mask:0xf bank_mask:0xf bound_ctrl:1
	v_pk_mul_f32 v[44:45], v[96:97], v[100:101] op_sel:[0,1] op_sel_hi:[1,1]
	v_pk_mul_f32 v[48:49], v[44:45], v[102:103] op_sel_hi:[1,0]
	v_rcp_f32_e32 v52, v51
	s_add_u32 s14, s14, 0x1000
	s_addc_u32 s15, s15, 0
	v_fmac_f32_dpp v48, v38, v51 row_newbcast:8 row_mask:0xf bank_mask:0xf bound_ctrl:1
	v_fmac_f32_dpp v49, v38, v51 row_newbcast:12 row_mask:0xf bank_mask:0xf bound_ctrl:1
	s_cbranch_vccnz .Lgd2_rare2_3
.Lgd2_back2_3:
	v_cvt_pk_bf16_f32 v54, v48, v49
	v_pk_mul_f32 v[46:47], v[44:45], v[52:53] op_sel_hi:[1,0]
	v_pk_fma_f32 v[6:7], v[80:81], v[46:47], v[6:7] op_sel_hi:[0,1,1]
	v_pk_fma_f32 v[8:9], v[82:83], v[46:47], v[8:9] op_sel_hi:[0,1,1]
	v_pk_fma_f32 v[10:11], v[84:85], v[46:47], v[10:11] op_sel_hi:[0,1,1]
	v_pk_fma_f32 v[12:13], v[86:87], v[46:47], v[12:13] op_sel_hi:[0,1,1]
	v_pk_fma_f32 v[14:15], v[88:89], v[46:47], v[14:15] op_sel_hi:[0,1,1]
	v_pk_fma_f32 v[16:17], v[90:91], v[46:47], v[16:17] op_sel_hi:[0,1,1]
	v_pk_fma_f32 v[18:19], v[92:93], v[46:47], v[18:19] op_sel_hi:[0,1,1]
	v_pk_fma_f32 v[20:21], v[94:95], v[46:47], v[20:21] op_sel_hi:[0,1,1]
	global_store_dword v154, v54, s[14:15] offset:-4096
	s_waitcnt lgkmcnt(0)
	v_pk_mul_f32 v[38:39], v[6:7], v[56:57] op_sel_hi:[1,0]
	v_pk_mul_f32 v[40:41], v[6:7], v[56:57] op_sel:[0,1] op_sel_hi:[1,1]
	v_pk_fma_f32 v[38:39], v[8:9], v[58:59], v[38:39] op_sel_hi:[1,0,1]
	v_pk_fma_f32 v[40:41], v[8:9], v[58:59], v[40:41] op_sel:[0,1,0] op_sel_hi:[1,1,1]
	v_pk_fma_f32 v[38:39], v[10:11], v[60:61], v[38:39] op_sel_hi:[1,0,1]
	v_pk_fma_f32 v[40:41], v[10:11], v[60:61], v[40:41] op_sel:[0,1,0] op_sel_hi:[1,1,1]
	v_pk_fma_f32 v[38:39], v[12:13], v[62:63], v[38:39] op_sel_hi:[1,0,1]
	v_pk_fma_f32 v[40:41], v[12:13], v[62:63], v[40:41] op_sel:[0,1,0] op_sel_hi:[1,1,1]
	v_pk_fma_f32 v[38:39], v[14:15], v[64:65], v[38:39] op_sel_hi:[1,0,1]
	v_pk_fma_f32 v[40:41], v[14:15], v[64:65], v[40:41] op_sel:[0,1,0] op_sel_hi:[1,1,1]
	v_pk_fma_f32 v[38:39], v[16:17], v[66:67], v[38:39] op_sel_hi:[1,0,1]
	v_pk_fma_f32 v[40:41], v[16:17], v[66:67], v[40:41] op_sel:[0,1,0] op_sel_hi:[1,1,1]
	v_pk_fma_f32 v[38:39], v[18:19], v[68:69], v[38:39] op_sel_hi:[1,0,1]
	v_pk_fma_f32 v[40:41], v[18:19], v[68:69], v[40:41] op_sel:[0,1,0] op_sel_hi:[1,1,1]
	v_pk_fma_f32 v[38:39], v[20:21], v[70:71], v[38:39] op_sel_hi:[1,0,1]
	v_pk_fma_f32 v[40:41], v[20:21], v[70:71], v[40:41] op_sel:[0,1,0] op_sel_hi:[1,1,1]
	v_mul_f32_e32 v50, v76, v51
	v_add_f32_dpp v38, v38, v38 row_ror:8 row_mask:0xf bank_mask:0x3 bound_ctrl:1
	v_add_f32_dpp v39, v39, v39 row_ror:8 row_mask:0xf bank_mask:0x3 bound_ctrl:1
	v_add_f32_dpp v38, v40, v40 row_ror:8 row_mask:0xf bank_mask:0xc bound_ctrl:1
	v_add_f32_dpp v39, v41, v41 row_ror:8 row_mask:0xf bank_mask:0xc bound_ctrl:1
	ds_read_b128 v[80:83], v2 offset:38144
	v_add_f32_dpp v38, v38, v38 row_half_mirror row_mask:0xf bank_mask:0x5 bound_ctrl:1
	v_add_f32_dpp v38, v39, v39 row_half_mirror row_mask:0xf bank_mask:0xa bound_ctrl:1
	ds_read_b128 v[84:87], v2 offset:38400
	ds_read_b128 v[88:91], v2 offset:38656
	v_add_f32_dpp v38, v38, v38 quad_perm:[1,0,3,2] row_mask:0xf bank_mask:0xf bound_ctrl:1
	ds_read_b128 v[92:95], v2 offset:38912
	ds_read_b64 v[96:97], v3 offset:46592
	v_add_f32_dpp v38, v38, v38 quad_perm:[2,3,0,1] row_mask:0xf bank_mask:0xf bound_ctrl:1
	ds_read_b128 v[100:103], v1 offset:47440
	v_cmp_gt_f32_e32 vcc, 0x2b8cbccc, v50
	v_fmac_f32_dpp v72, -v38, v50 row_newbcast:0 row_mask:0xf bank_mask:0xf bound_ctrl:1
	v_fmac_f32_dpp v73, -v38, v50 row_newbcast:4 row_mask:0xf bank_mask:0xf bound_ctrl:1
	v_pk_mul_f32 v[44:45], v[72:73], v[76:77] op_sel:[0,1] op_sel_hi:[1,1]
	v_pk_mul_f32 v[48:49], v[44:45], v[78:79] op_sel_hi:[1,0]
	v_rcp_f32_e32 v52, v50
	s_add_u32 s14, s14, 0x1000
	s_addc_u32 s15, s15, 0
	v_fmac_f32_dpp v48, v38, v50 row_newbcast:8 row_mask:0xf bank_mask:0xf bound_ctrl:1
	v_fmac_f32_dpp v49, v38, v50 row_newbcast:12 row_mask:0xf bank_mask:0xf bound_ctrl:1
	s_cbranch_vccnz .Lgd2_rare2_4
.Lgd2_back2_4:
	v_cvt_pk_bf16_f32 v54, v48, v49
	v_pk_mul_f32 v[46:47], v[44:45], v[52:53] op_sel_hi:[1,0]
	v_pk_fma_f32 v[6:7], v[56:57], v[46:47], v[6:7] op_sel_hi:[0,1,1]
	v_pk_fma_f32 v[8:9], v[58:59], v[46:47], v[8:9] op_sel_hi:[0,1,1]
	v_pk_fma_f32 v[10:11], v[60:61], v[46:47], v[10:11] op_sel_hi:[0,1,1]
	v_pk_fma_f32 v[12:13], v[62:63], v[46:47], v[12:13] op_sel_hi:[0,1,1]
	v_pk_fma_f32 v[14:15], v[64:65], v[46:47], v[14:15] op_sel_hi:[0,1,1]
	v_pk_fma_f32 v[16:17], v[66:67], v[46:47], v[16:17] op_sel_hi:[0,1,1]
	v_pk_fma_f32 v[18:19], v[68:69], v[46:47], v[18:19] op_sel_hi:[0,1,1]
	v_pk_fma_f32 v[20:21], v[70:71], v[46:47], v[20:21] op_sel_hi:[0,1,1]
	global_store_dword v154, v54, s[14:15] offset:-4096
	s_waitcnt lgkmcnt(0)
	v_pk_mul_f32 v[38:39], v[6:7], v[80:81] op_sel_hi:[1,0]
	v_pk_mul_f32 v[40:41], v[6:7], v[80:81] op_sel:[0,1] op_sel_hi:[1,1]
	v_pk_fma_f32 v[38:39], v[8:9], v[82:83], v[38:39] op_sel_hi:[1,0,1]
	v_pk_fma_f32 v[40:41], v[8:9], v[82:83], v[40:41] op_sel:[0,1,0] op_sel_hi:[1,1,1]
	v_pk_fma_f32 v[38:39], v[10:11], v[84:85], v[38:39] op_sel_hi:[1,0,1]
	v_pk_fma_f32 v[40:41], v[10:11], v[84:85], v[40:41] op_sel:[0,1,0] op_sel_hi:[1,1,1]
	v_pk_fma_f32 v[38:39], v[12:13], v[86:87], v[38:39] op_sel_hi:[1,0,1]
	v_pk_fma_f32 v[40:41], v[12:13], v[86:87], v[40:41] op_sel:[0,1,0] op_sel_hi:[1,1,1]
	v_pk_fma_f32 v[38:39], v[14:15], v[88:89], v[38:39] op_sel_hi:[1,0,1]
	v_pk_fma_f32 v[40:41], v[14:15], v[88:89], v[40:41] op_sel:[0,1,0] op_sel_hi:[1,1,1]
	v_pk_fma_f32 v[38:39], v[16:17], v[90:91], v[38:39] op_sel_hi:[1,0,1]
	v_pk_fma_f32 v[40:41], v[16:17], v[90:91], v[40:41] op_sel:[0,1,0] op_sel_hi:[1,1,1]
	v_pk_fma_f32 v[38:39], v[18:19], v[92:93], v[38:39] op_sel_hi:[1,0,1]
	v_pk_fma_f32 v[40:41], v[18:19], v[92:93], v[40:41] op_sel:[0,1,0] op_sel_hi:[1,1,1]
	v_pk_fma_f32 v[38:39], v[20:21], v[94:95], v[38:39] op_sel_hi:[1,0,1]
	v_pk_fma_f32 v[40:41], v[20:21], v[94:95], v[40:41] op_sel:[0,1,0] op_sel_hi:[1,1,1]
	v_mul_f32_e32 v51, v100, v50
	v_add_f32_dpp v38, v38, v38 row_ror:8 row_mask:0xf bank_mask:0x3 bound_ctrl:1
	v_add_f32_dpp v39, v39, v39 row_ror:8 row_mask:0xf bank_mask:0x3 bound_ctrl:1
	v_add_f32_dpp v38, v40, v40 row_ror:8 row_mask:0xf bank_mask:0xc bound_ctrl:1
	v_add_f32_dpp v39, v41, v41 row_ror:8 row_mask:0xf bank_mask:0xc bound_ctrl:1
	ds_read_b128 v[56:59], v2 offset:39168
	v_add_f32_dpp v38, v38, v38 row_half_mirror row_mask:0xf bank_mask:0x5 bound_ctrl:1
	v_add_f32_dpp v38, v39, v39 row_half_mirror row_mask:0xf bank_mask:0xa bound_ctrl:1
	ds_read_b128 v[60:63], v2 offset:39424
	ds_read_b128 v[64:67], v2 offset:39680
	v_add_f32_dpp v38, v38, v38 quad_perm:[1,0,3,2] row_mask:0xf bank_mask:0xf bound_ctrl:1
	ds_read_b128 v[68:71], v2 offset:39936
	ds_read_b64 v[72:73], v3 offset:46848
	v_add_f32_dpp v38, v38, v38 quad_perm:[2,3,0,1] row_mask:0xf bank_mask:0xf bound_ctrl:1
	ds_read_b128 v[76:79], v1 offset:47456
	v_cmp_gt_f32_e32 vcc, 0x2b8cbccc, v51
	v_fmac_f32_dpp v96, -v38, v51 row_newbcast:0 row_mask:0xf bank_mask:0xf bound_ctrl:1
	v_fmac_f32_dpp v97, -v38, v51 row_newbcast:4 row_mask:0xf bank_mask:0xf bound_ctrl:1
	v_pk_mul_f32 v[44:45], v[96:97], v[100:101] op_sel:[0,1] op_sel_hi:[1,1]
	v_pk_mul_f32 v[48:49], v[44:45], v[102:103] op_sel_hi:[1,0]
	v_rcp_f32_e32 v52, v51
	s_add_u32 s14, s14, 0x1000
	s_addc_u32 s15, s15, 0
	v_fmac_f32_dpp v48, v38, v51 row_newbcast:8 row_mask:0xf bank_mask:0xf bound_ctrl:1
	v_fmac_f32_dpp v49, v38, v51 row_newbcast:12 row_mask:0xf bank_mask:0xf bound_ctrl:1
	s_cbranch_vccnz .Lgd2_rare2_5
.Lgd2_back2_5:
	v_cvt_pk_bf16_f32 v54, v48, v49
	v_pk_mul_f32 v[46:47], v[44:45], v[52:53] op_sel_hi:[1,0]
	v_pk_fma_f32 v[6:7], v[80:81], v[46:47], v[6:7] op_sel_hi:[0,1,1]
	v_pk_fma_f32 v[8:9], v[82:83], v[46:47], v[8:9] op_sel_hi:[0,1,1]
	v_pk_fma_f32 v[10:11], v[84:85], v[46:47], v[10:11] op_sel_hi:[0,1,1]
	v_pk_fma_f32 v[12:13], v[86:87], v[46:47], v[12:13] op_sel_hi:[0,1,1]
	v_pk_fma_f32 v[14:15], v[88:89], v[46:47], v[14:15] op_sel_hi:[0,1,1]
	v_pk_fma_f32 v[16:17], v[90:91], v[46:47], v[16:17] op_sel_hi:[0,1,1]
	v_pk_fma_f32 v[18:19], v[92:93], v[46:47], v[18:19] op_sel_hi:[0,1,1]
	v_pk_fma_f32 v[20:21], v[94:95], v[46:47], v[20:21] op_sel_hi:[0,1,1]
	global_store_dword v154, v54, s[14:15] offset:-4096
	s_waitcnt lgkmcnt(0)
	v_pk_mul_f32 v[38:39], v[6:7], v[56:57] op_sel_hi:[1,0]
	v_pk_mul_f32 v[40:41], v[6:7], v[56:57] op_sel:[0,1] op_sel_hi:[1,1]
	v_pk_fma_f32 v[38:39], v[8:9], v[58:59], v[38:39] op_sel_hi:[1,0,1]
	v_pk_fma_f32 v[40:41], v[8:9], v[58:59], v[40:41] op_sel:[0,1,0] op_sel_hi:[1,1,1]
	v_pk_fma_f32 v[38:39], v[10:11], v[60:61], v[38:39] op_sel_hi:[1,0,1]
	v_pk_fma_f32 v[40:41], v[10:11], v[60:61], v[40:41] op_sel:[0,1,0] op_sel_hi:[1,1,1]
	v_pk_fma_f32 v[38:39], v[12:13], v[62:63], v[38:39] op_sel_hi:[1,0,1]
	v_pk_fma_f32 v[40:41], v[12:13], v[62:63], v[40:41] op_sel:[0,1,0] op_sel_hi:[1,1,1]
	v_pk_fma_f32 v[38:39], v[14:15], v[64:65], v[38:39] op_sel_hi:[1,0,1]
	v_pk_fma_f32 v[40:41], v[14:15], v[64:65], v[40:41] op_sel:[0,1,0] op_sel_hi:[1,1,1]
	v_pk_fma_f32 v[38:39], v[16:17], v[66:67], v[38:39] op_sel_hi:[1,0,1]
	v_pk_fma_f32 v[40:41], v[16:17], v[66:67], v[40:41] op_sel:[0,1,0] op_sel_hi:[1,1,1]
	v_pk_fma_f32 v[38:39], v[18:19], v[68:69], v[38:39] op_sel_hi:[1,0,1]
	v_pk_fma_f32 v[40:41], v[18:19], v[68:69], v[40:41] op_sel:[0,1,0] op_sel_hi:[1,1,1]
	v_pk_fma_f32 v[38:39], v[20:21], v[70:71], v[38:39] op_sel_hi:[1,0,1]
	v_pk_fma_f32 v[40:41], v[20:21], v[70:71], v[40:41] op_sel:[0,1,0] op_sel_hi:[1,1,1]
	v_mul_f32_e32 v50, v76, v51
	v_add_f32_dpp v38, v38, v38 row_ror:8 row_mask:0xf bank_mask:0x3 bound_ctrl:1
	v_add_f32_dpp v39, v39, v39 row_ror:8 row_mask:0xf bank_mask:0x3 bound_ctrl:1
	v_add_f32_dpp v38, v40, v40 row_ror:8 row_mask:0xf bank_mask:0xc bound_ctrl:1
	v_add_f32_dpp v39, v41, v41 row_ror:8 row_mask:0xf bank_mask:0xc bound_ctrl:1
	ds_read_b128 v[80:83], v2 offset:40192
	v_add_f32_dpp v38, v38, v38 row_half_mirror row_mask:0xf bank_mask:0x5 bound_ctrl:1
	v_add_f32_dpp v38, v39, v39 row_half_mirror row_mask:0xf bank_mask:0xa bound_ctrl:1
	ds_read_b128 v[84:87], v2 offset:40448
	ds_read_b128 v[88:91], v2 offset:40704
	v_add_f32_dpp v38, v38, v38 quad_perm:[1,0,3,2] row_mask:0xf bank_mask:0xf bound_ctrl:1
	ds_read_b128 v[92:95], v2 offset:40960
	ds_read_b64 v[96:97], v3 offset:47104
	v_add_f32_dpp v38, v38, v38 quad_perm:[2,3,0,1] row_mask:0xf bank_mask:0xf bound_ctrl:1
	ds_read_b128 v[100:103], v1 offset:47472
	v_cmp_gt_f32_e32 vcc, 0x2b8cbccc, v50
	v_fmac_f32_dpp v72, -v38, v50 row_newbcast:0 row_mask:0xf bank_mask:0xf bound_ctrl:1
	v_fmac_f32_dpp v73, -v38, v50 row_newbcast:4 row_mask:0xf bank_mask:0xf bound_ctrl:1
	v_pk_mul_f32 v[44:45], v[72:73], v[76:77] op_sel:[0,1] op_sel_hi:[1,1]
	v_pk_mul_f32 v[48:49], v[44:45], v[78:79] op_sel_hi:[1,0]
	v_rcp_f32_e32 v52, v50
	s_add_u32 s14, s14, 0x1000
	s_addc_u32 s15, s15, 0
	v_fmac_f32_dpp v48, v38, v50 row_newbcast:8 row_mask:0xf bank_mask:0xf bound_ctrl:1
	v_fmac_f32_dpp v49, v38, v50 row_newbcast:12 row_mask:0xf bank_mask:0xf bound_ctrl:1
	s_cbranch_vccnz .Lgd2_rare2_6
.Lgd2_back2_6:
	v_cvt_pk_bf16_f32 v54, v48, v49
	v_pk_mul_f32 v[46:47], v[44:45], v[52:53] op_sel_hi:[1,0]
	v_pk_fma_f32 v[6:7], v[56:57], v[46:47], v[6:7] op_sel_hi:[0,1,1]
	v_pk_fma_f32 v[8:9], v[58:59], v[46:47], v[8:9] op_sel_hi:[0,1,1]
	v_pk_fma_f32 v[10:11], v[60:61], v[46:47], v[10:11] op_sel_hi:[0,1,1]
	v_pk_fma_f32 v[12:13], v[62:63], v[46:47], v[12:13] op_sel_hi:[0,1,1]
	v_pk_fma_f32 v[14:15], v[64:65], v[46:47], v[14:15] op_sel_hi:[0,1,1]
	v_pk_fma_f32 v[16:17], v[66:67], v[46:47], v[16:17] op_sel_hi:[0,1,1]
	v_pk_fma_f32 v[18:19], v[68:69], v[46:47], v[18:19] op_sel_hi:[0,1,1]
	v_pk_fma_f32 v[20:21], v[70:71], v[46:47], v[20:21] op_sel_hi:[0,1,1]
	global_store_dword v154, v54, s[14:15] offset:-4096
	s_waitcnt lgkmcnt(0)
	v_pk_mul_f32 v[38:39], v[6:7], v[80:81] op_sel_hi:[1,0]
	v_pk_mul_f32 v[40:41], v[6:7], v[80:81] op_sel:[0,1] op_sel_hi:[1,1]
	v_pk_fma_f32 v[38:39], v[8:9], v[82:83], v[38:39] op_sel_hi:[1,0,1]
	v_pk_fma_f32 v[40:41], v[8:9], v[82:83], v[40:41] op_sel:[0,1,0] op_sel_hi:[1,1,1]
	v_pk_fma_f32 v[38:39], v[10:11], v[84:85], v[38:39] op_sel_hi:[1,0,1]
	v_pk_fma_f32 v[40:41], v[10:11], v[84:85], v[40:41] op_sel:[0,1,0] op_sel_hi:[1,1,1]
	v_pk_fma_f32 v[38:39], v[12:13], v[86:87], v[38:39] op_sel_hi:[1,0,1]
	v_pk_fma_f32 v[40:41], v[12:13], v[86:87], v[40:41] op_sel:[0,1,0] op_sel_hi:[1,1,1]
	v_pk_fma_f32 v[38:39], v[14:15], v[88:89], v[38:39] op_sel_hi:[1,0,1]
	v_pk_fma_f32 v[40:41], v[14:15], v[88:89], v[40:41] op_sel:[0,1,0] op_sel_hi:[1,1,1]
	v_pk_fma_f32 v[38:39], v[16:17], v[90:91], v[38:39] op_sel_hi:[1,0,1]
	v_pk_fma_f32 v[40:41], v[16:17], v[90:91], v[40:41] op_sel:[0,1,0] op_sel_hi:[1,1,1]
	v_pk_fma_f32 v[38:39], v[18:19], v[92:93], v[38:39] op_sel_hi:[1,0,1]
	v_pk_fma_f32 v[40:41], v[18:19], v[92:93], v[40:41] op_sel:[0,1,0] op_sel_hi:[1,1,1]
	v_pk_fma_f32 v[38:39], v[20:21], v[94:95], v[38:39] op_sel_hi:[1,0,1]
	v_pk_fma_f32 v[40:41], v[20:21], v[94:95], v[40:41] op_sel:[0,1,0] op_sel_hi:[1,1,1]
	v_mul_f32_e32 v51, v100, v50
	v_add_f32_dpp v38, v38, v38 row_ror:8 row_mask:0xf bank_mask:0x3 bound_ctrl:1
	v_add_f32_dpp v39, v39, v39 row_ror:8 row_mask:0xf bank_mask:0x3 bound_ctrl:1
	v_add_f32_dpp v38, v40, v40 row_ror:8 row_mask:0xf bank_mask:0xc bound_ctrl:1
	v_add_f32_dpp v39, v41, v41 row_ror:8 row_mask:0xf bank_mask:0xc bound_ctrl:1
	ds_read_b128 v[56:59], v2 offset:256
	v_add_f32_dpp v38, v38, v38 row_half_mirror row_mask:0xf bank_mask:0x5 bound_ctrl:1
	v_add_f32_dpp v38, v39, v39 row_half_mirror row_mask:0xf bank_mask:0xa bound_ctrl:1
	ds_read_b128 v[60:63], v2 offset:512
	ds_read_b128 v[64:67], v2 offset:768
	v_add_f32_dpp v38, v38, v38 quad_perm:[1,0,3,2] row_mask:0xf bank_mask:0xf bound_ctrl:1
	ds_read_b128 v[68:71], v2 offset:1024
	ds_read_b64 v[72:73], v3 offset:12544
	v_add_f32_dpp v38, v38, v38 quad_perm:[2,3,0,1] row_mask:0xf bank_mask:0xf bound_ctrl:1
	ds_read_b128 v[76:79], v1 offset:14592
	v_cmp_gt_f32_e32 vcc, 0x2b8cbccc, v51
	v_fmac_f32_dpp v96, -v38, v51 row_newbcast:0 row_mask:0xf bank_mask:0xf bound_ctrl:1
	v_fmac_f32_dpp v97, -v38, v51 row_newbcast:4 row_mask:0xf bank_mask:0xf bound_ctrl:1
	v_pk_mul_f32 v[44:45], v[96:97], v[100:101] op_sel:[0,1] op_sel_hi:[1,1]
	v_pk_mul_f32 v[48:49], v[44:45], v[102:103] op_sel_hi:[1,0]
	v_rcp_f32_e32 v52, v51
	s_add_u32 s14, s14, 0x1000
	s_addc_u32 s15, s15, 0
	v_fmac_f32_dpp v48, v38, v51 row_newbcast:8 row_mask:0xf bank_mask:0xf bound_ctrl:1
	v_fmac_f32_dpp v49, v38, v51 row_newbcast:12 row_mask:0xf bank_mask:0xf bound_ctrl:1
	s_cbranch_vccnz .Lgd2_rare2_7
.Lgd2_back2_7:
	v_cvt_pk_bf16_f32 v54, v48, v49
	v_pk_mul_f32 v[46:47], v[44:45], v[52:53] op_sel_hi:[1,0]
	v_pk_fma_f32 v[6:7], v[80:81], v[46:47], v[6:7] op_sel_hi:[0,1,1]
	v_pk_fma_f32 v[8:9], v[82:83], v[46:47], v[8:9] op_sel_hi:[0,1,1]
	v_pk_fma_f32 v[10:11], v[84:85], v[46:47], v[10:11] op_sel_hi:[0,1,1]
	v_pk_fma_f32 v[12:13], v[86:87], v[46:47], v[12:13] op_sel_hi:[0,1,1]
	v_pk_fma_f32 v[14:15], v[88:89], v[46:47], v[14:15] op_sel_hi:[0,1,1]
	v_pk_fma_f32 v[16:17], v[90:91], v[46:47], v[16:17] op_sel_hi:[0,1,1]
	v_pk_fma_f32 v[18:19], v[92:93], v[46:47], v[18:19] op_sel_hi:[0,1,1]
	v_pk_fma_f32 v[20:21], v[94:95], v[46:47], v[20:21] op_sel_hi:[0,1,1]
	global_store_dword v154, v54, s[14:15] offset:-4096
	s_waitcnt vmcnt(8)
	v_lshlrev_b32_e32 v116, 16, v108
	v_lshlrev_b32_e32 v117, 16, v109
	v_and_b32_e32 v118, s17, v108
	v_and_b32_e32 v119, s17, v109
	v_lshlrev_b32_e32 v120, 16, v110
	v_and_b32_e32 v121, s17, v110
	v_lshlrev_b32_e32 v122, 16, v111
	v_and_b32_e32 v123, s17, v111
	v_lshlrev_b32_e32 v124, 16, v112
	v_and_b32_e32 v125, s17, v112
	ds_write_b128 v32, v[116:119] offset:16640
	ds_write_b64 v33, v[120:121] offset:16640
	ds_write_b64 v34, v[122:123] offset:16640
	ds_write_b64 v34, v[124:125] offset:16768
	ds_write_b32 v35, v113 offset:16640
	s_add_i32 s16, s16, 8
	s_waitcnt lgkmcnt(0)
	s_barrier
	s_cmpk_lt_u32 s16, 0x800
	s_cbranch_scc1 .Lgd2_loop
.Lgd2_done:
	s_setprio 0
	s_lshr_b32 s2, s27, 4
	s_lshl_b32 s4, s2, 16
	s_add_u32 s4, s4, 0x4080000
	s_add_u32 s0, s24, s4
	s_addc_u32 s1, s25, 0
	v_pk_mul_f32 v[108:109], v[6:7], v[50:51] op_sel:[0,1] op_sel_hi:[1,1]
	global_store_dwordx2 v153, v[108:109], s[0:1] offset:0
	v_pk_mul_f32 v[110:111], v[8:9], v[50:51] op_sel:[0,1] op_sel_hi:[1,1]
	global_store_dwordx2 v153, v[110:111], s[0:1] offset:512
	v_pk_mul_f32 v[108:109], v[10:11], v[50:51] op_sel:[0,1] op_sel_hi:[1,1]
	global_store_dwordx2 v153, v[108:109], s[0:1] offset:1024
	v_pk_mul_f32 v[110:111], v[12:13], v[50:51] op_sel:[0,1] op_sel_hi:[1,1]
	global_store_dwordx2 v153, v[110:111], s[0:1] offset:1536
	v_pk_mul_f32 v[108:109], v[14:15], v[50:51] op_sel:[0,1] op_sel_hi:[1,1]
	global_store_dwordx2 v153, v[108:109], s[0:1] offset:2048
	v_pk_mul_f32 v[110:111], v[16:17], v[50:51] op_sel:[0,1] op_sel_hi:[1,1]
	global_store_dwordx2 v153, v[110:111], s[0:1] offset:2560
	v_pk_mul_f32 v[108:109], v[18:19], v[50:51] op_sel:[0,1] op_sel_hi:[1,1]
	global_store_dwordx2 v153, v[108:109], s[0:1] offset:3072
	v_pk_mul_f32 v[110:111], v[20:21], v[50:51] op_sel:[0,1] op_sel_hi:[1,1]
	global_store_dwordx2 v153, v[110:111], s[0:1] offset:3584
	s_add_i32 s27, s27, s28
	s_waitcnt vmcnt(0)
	s_cmpk_lt_i32 s27, 0x400
	s_cbranch_scc1 .Lgd2_item
	s_branch .LBB0_232
